# post-MMA s_barrier moved up by one MFMA in all GEMM main loops (barrier latency hidden under the last MFMA)
# speedup vs baseline: 1.0045x; 1.0045x over previous
; #define PG8_STAGE(bufoff, gbase, voff) do { _Pragma("unroll") for (int _i = 0; _i < 2; ++_i) \
;         __builtin_amdgcn_global_load_lds((const unsigned*)((const char*)(gbase) + (voff)[_i]), (LAS unsigned*)(lds + (bufoff) + ldsw + _i * 8192), 16, 0, 0); } while (0)
; #define PG8_LDA(dst, b, h) do { _Pragma("unroll") for (int m = 0; m < 4; ++m) _Pragma("unroll") for (int k = 0; k < 2; ++k) dst[m][k] = *(const LAS bf16x8*)(lds + PG8_SA(b, h) + aoff + m * 2048 + k * 1024); } while (0)
; #define PG8_LDB(dst, b, h) do { _Pragma("unroll") for (int n = 0; n < 2; ++n) _Pragma("unroll") for (int k = 0; k < 2; ++k) dst[n][k] = *(const LAS bf16x8*)(lds + PG8_SB(b, h) + boff + n * 2048 + k * 1024); } while (0)
; #define PG8_MMA(ai, bj, At, Bt) do { __builtin_amdgcn_s_setprio(1); _Pragma("unroll") for (int m = 0; m < 4; ++m) _Pragma("unroll") for (int n = 0; n < 2; ++n) _Pragma("unroll") for (int k = 0; k < 2; ++k) \
;         acc[ai][bj][m][n] = __builtin_amdgcn_mfma_f32_16x16x32_bf16(Bt[n][k], At[m][k], acc[ai][bj][m][n], 0, 0, 0); __builtin_amdgcn_s_setprio(0); } while (0)
; #define PG8_WAIT_L(n) asm volatile("s_waitcnt lgkmcnt(" #n ")" ::: "memory")
; #define PG8_BAR __builtin_amdgcn_s_barrier()
; #define PG8_SCHED __builtin_amdgcn_sched_barrier(0)
; #define PG8_STAGE(bufoff, gbase, voff) do { _Pragma("unroll") for (int _i = 0; _i < 2; ++_i) \
;         __builtin_amdgcn_global_load_lds((const unsigned*)((const char*)(gbase) + (voff)[_i]), (LAS unsigned*)(lds + (bufoff) + ldsw + _i * 8192), 16, 0, 0); } while (0)
; #define PG8_LDA(dst, b, h) do { _Pragma("unroll") for (int m = 0; m < 4; ++m) _Pragma("unroll") for (int k = 0; k < 2; ++k) dst[m][k] = *(const LAS bf16x8*)(lds + PG8_SA(b, h) + aoff + m * 2048 + k * 1024); } while (0)
; template <class Epi>
; DI void gemm_phase(LAS unsigned char* lds, const Gemm g, const StaticOrder S, const Epi E) {
;     ...
;             PG8_LDB(B0, 0, 0); PG8_SCHED; PG8_LDA(At, 0, 0); PG8_STAGE(PG8_SA(1, 1), a1 + hstep, voffA);
;             PG8_WAIT_L(8); PG8_BAR; PG8_WAIT_L(0); PG8_MMA(0, 0, At, B0); PG8_BAR; PG8_SCHED;
;             PG8_LDB(B1, 0, 1); PG8_STAGE(PG8_SB(0, 0), b2, voffB);
;             PG8_BAR; PG8_WAIT_L(0); PG8_MMA(0, 1, At, B1); PG8_BAR;
;             PG8_LDA(At, 0, 1); PG8_STAGE(PG8_SA(0, 0), a2, voffA);
;             PG8_BAR; PG8_WAIT_L(0); PG8_MMA(1, 0, At, B0); PG8_BAR; PG8_SCHED;
.LBB0_107:
	ds_read_b128 v[152:155], v149
	ds_read_b128 v[156:159], v149 offset:1024
	ds_read_b128 v[160:163], v149 offset:2048
	ds_read_b128 v[164:167], v149 offset:3072
	s_add_u32 s14, s76, 0xfffc0080
	s_addc_u32 s15, s77, -1
	s_cmp_eq_u32 s97, 12
	s_cselect_b32 s81, s11, s15
	s_cselect_b32 s80, s93, s14
	s_cselect_b32 s79, s9, s96
	s_cselect_b32 s78, s94, s95
	v_lshl_add_u64 v[144:145], s[76:77], 0, v[136:137]
	s_add_i32 m0, s29, 0xc000
	ds_read_b128 v[168:171], v150
	ds_read_b128 v[172:175], v150 offset:1024
	ds_read_b128 v[176:179], v150 offset:2048
	ds_read_b128 v[180:183], v150 offset:3072
	ds_read_b128 v[184:187], v150 offset:4096
	ds_read_b128 v[188:191], v150 offset:5120
	ds_read_b128 v[192:195], v150 offset:6144
	ds_read_b128 v[196:199], v150 offset:7168
	global_load_lds_dwordx4 v[144:145], off
	v_lshl_add_u64 v[144:145], s[76:77], 0, v[138:139]
	s_add_i32 m0, s29, 0xe000
	s_nop 0
	global_load_lds_dwordx4 v[144:145], off
	s_waitcnt lgkmcnt(8)
	s_barrier
	s_waitcnt lgkmcnt(0)
	s_setprio 1
	s_waitcnt lgkmcnt(0)
	v_mfma_f32_16x16x32_bf16 v[124:127], v[152:155], v[168:171], v[124:127]
	v_mfma_f32_16x16x32_bf16 v[116:119], v[160:163], v[168:171], v[116:119]
	v_mfma_f32_16x16x32_bf16 v[108:111], v[152:155], v[176:179], v[108:111]
	v_mfma_f32_16x16x32_bf16 v[100:103], v[160:163], v[176:179], v[100:103]
	v_mfma_f32_16x16x32_bf16 v[92:95], v[152:155], v[184:187], v[92:95]
	v_mfma_f32_16x16x32_bf16 v[84:87], v[160:163], v[184:187], v[84:87]
	v_mfma_f32_16x16x32_bf16 v[76:79], v[152:155], v[192:195], v[76:79]
	v_mfma_f32_16x16x32_bf16 v[68:71], v[160:163], v[192:195], v[68:71]
	v_mfma_f32_16x16x32_bf16 v[124:127], v[156:159], v[172:175], v[124:127]
	v_mfma_f32_16x16x32_bf16 v[116:119], v[164:167], v[172:175], v[116:119]
	v_mfma_f32_16x16x32_bf16 v[108:111], v[156:159], v[180:183], v[108:111]
	v_mfma_f32_16x16x32_bf16 v[100:103], v[164:167], v[180:183], v[100:103]
	v_mfma_f32_16x16x32_bf16 v[92:95], v[156:159], v[188:191], v[92:95]
	v_mfma_f32_16x16x32_bf16 v[84:87], v[164:167], v[188:191], v[84:87]
	v_mfma_f32_16x16x32_bf16 v[76:79], v[156:159], v[196:199], v[76:79]
	s_barrier
	v_mfma_f32_16x16x32_bf16 v[68:71], v[164:167], v[196:199], v[68:71]
	s_setprio 0
	s_add_i32 s14, s89, s7
	v_lshl_add_u64 v[144:145], s[78:79], 0, v[132:133]
	s_mov_b32 m0, s14
	ds_read_b128 v[200:203], v151
	ds_read_b128 v[204:207], v151 offset:1024
	ds_read_b128 v[208:211], v151 offset:2048
	ds_read_b128 v[212:215], v151 offset:3072
	global_load_lds_dwordx4 v[144:145], off
	v_lshl_add_u64 v[216:217], s[78:79], 0, v[128:129]
	s_add_i32 m0, s14, 0x2000
	s_nop 0
	global_load_lds_dwordx4 v[216:217], off
	s_barrier
	s_waitcnt lgkmcnt(0)
	s_setprio 1
	s_waitcnt lgkmcnt(0)
	v_mfma_f32_16x16x32_bf16 v[120:123], v[200:203], v[168:171], v[120:123]
	v_mfma_f32_16x16x32_bf16 v[112:115], v[208:211], v[168:171], v[112:115]
	v_mfma_f32_16x16x32_bf16 v[104:107], v[200:203], v[176:179], v[104:107]
	v_mfma_f32_16x16x32_bf16 v[96:99], v[208:211], v[176:179], v[96:99]
	v_mfma_f32_16x16x32_bf16 v[88:91], v[200:203], v[184:187], v[88:91]
	v_mfma_f32_16x16x32_bf16 v[80:83], v[208:211], v[184:187], v[80:83]
	v_mfma_f32_16x16x32_bf16 v[72:75], v[200:203], v[192:195], v[72:75]
	v_mfma_f32_16x16x32_bf16 v[64:67], v[208:211], v[192:195], v[64:67]
	v_mfma_f32_16x16x32_bf16 v[120:123], v[204:207], v[172:175], v[120:123]
	v_mfma_f32_16x16x32_bf16 v[112:115], v[212:215], v[172:175], v[112:115]
	v_mfma_f32_16x16x32_bf16 v[104:107], v[204:207], v[180:183], v[104:107]
	v_mfma_f32_16x16x32_bf16 v[96:99], v[212:215], v[180:183], v[96:99]
	v_mfma_f32_16x16x32_bf16 v[88:91], v[204:207], v[188:191], v[88:91]
	v_mfma_f32_16x16x32_bf16 v[80:83], v[212:215], v[188:191], v[80:83]
	v_mfma_f32_16x16x32_bf16 v[72:75], v[204:207], v[196:199], v[72:75]
	s_barrier
	v_mfma_f32_16x16x32_bf16 v[64:67], v[212:215], v[196:199], v[64:67]
	s_setprio 0
	s_mov_b32 m0, s29
	v_lshl_add_u64 v[218:219], s[80:81], 0, v[134:135]
	ds_read_b128 v[168:171], v150 offset:16384
	ds_read_b128 v[172:175], v150 offset:17408
	ds_read_b128 v[176:179], v150 offset:18432
	ds_read_b128 v[180:183], v150 offset:19456
	ds_read_b128 v[184:187], v150 offset:20480
	ds_read_b128 v[188:191], v150 offset:21504
	ds_read_b128 v[192:195], v150 offset:22528
	ds_read_b128 v[196:199], v150 offset:23552
	global_load_lds_dwordx4 v[218:219], off
	v_lshl_add_u64 v[220:221], s[80:81], 0, v[130:131]
	s_mov_b32 m0, s59
	s_nop 0
	global_load_lds_dwordx4 v[220:221], off
	s_barrier
	s_waitcnt lgkmcnt(0)
	s_setprio 1
	s_waitcnt lgkmcnt(0)
	v_mfma_f32_16x16x32_bf16 v[60:63], v[152:155], v[168:171], v[60:63]
	v_mfma_f32_16x16x32_bf16 v[52:55], v[160:163], v[168:171], v[52:55]
	v_mfma_f32_16x16x32_bf16 v[44:47], v[152:155], v[176:179], v[44:47]
	v_mfma_f32_16x16x32_bf16 v[36:39], v[160:163], v[176:179], v[36:39]
	v_mfma_f32_16x16x32_bf16 v[28:31], v[152:155], v[184:187], v[28:31]
	v_mfma_f32_16x16x32_bf16 v[20:23], v[160:163], v[184:187], v[20:23]
	v_mfma_f32_16x16x32_bf16 v[12:15], v[152:155], v[192:195], v[12:15]
	v_mfma_f32_16x16x32_bf16 v[4:7], v[160:163], v[192:195], v[4:7]
	v_mfma_f32_16x16x32_bf16 v[60:63], v[156:159], v[172:175], v[60:63]
	v_mfma_f32_16x16x32_bf16 v[52:55], v[164:167], v[172:175], v[52:55]
	v_mfma_f32_16x16x32_bf16 v[44:47], v[156:159], v[180:183], v[44:47]
	v_mfma_f32_16x16x32_bf16 v[36:39], v[164:167], v[180:183], v[36:39]
	v_mfma_f32_16x16x32_bf16 v[28:31], v[156:159], v[188:191], v[28:31]
	v_mfma_f32_16x16x32_bf16 v[20:23], v[164:167], v[188:191], v[20:23]
	v_mfma_f32_16x16x32_bf16 v[12:15], v[156:159], v[196:199], v[12:15]
	s_barrier
; #define PG8_STAGE(bufoff, gbase, voff) do { _Pragma("unroll") for (int _i = 0; _i < 2; ++_i) \
;         __builtin_amdgcn_global_load_lds((const unsigned*)((const char*)(gbase) + (voff)[_i]), (LAS unsigned*)(lds + (bufoff) + ldsw + _i * 8192), 16, 0, 0); } while (0)
; #define PG8_LDA(dst, b, h) do { _Pragma("unroll") for (int m = 0; m < 4; ++m) _Pragma("unroll") for (int k = 0; k < 2; ++k) dst[m][k] = *(const LAS bf16x8*)(lds + PG8_SA(b, h) + aoff + m * 2048 + k * 1024); } while (0)
; #define PG8_LDB(dst, b, h) do { _Pragma("unroll") for (int n = 0; n < 2; ++n) _Pragma("unroll") for (int k = 0; k < 2; ++k) dst[n][k] = *(const LAS bf16x8*)(lds + PG8_SB(b, h) + boff + n * 2048 + k * 1024); } while (0)
; #define PG8_MMA(ai, bj, At, Bt) do { __builtin_amdgcn_s_setprio(1); _Pragma("unroll") for (int m = 0; m < 4; ++m) _Pragma("unroll") for (int n = 0; n < 2; ++n) _Pragma("unroll") for (int k = 0; k < 2; ++k) \
;         acc[ai][bj][m][n] = __builtin_amdgcn_mfma_f32_16x16x32_bf16(Bt[n][k], At[m][k], acc[ai][bj][m][n], 0, 0, 0); __builtin_amdgcn_s_setprio(0); } while (0)
; #define PG8_WAIT_V(n) asm volatile("s_waitcnt vmcnt(" #n ")" ::: "memory")
; #define PG8_WAIT_L(n) asm volatile("s_waitcnt lgkmcnt(" #n ")" ::: "memory")
; #define PG8_BAR __builtin_amdgcn_s_barrier()
; #define PG8_SCHED __builtin_amdgcn_sched_barrier(0)
; #define PG8_STAGE(bufoff, gbase, voff) do { _Pragma("unroll") for (int _i = 0; _i < 2; ++_i) \
;         __builtin_amdgcn_global_load_lds((const unsigned*)((const char*)(gbase) + (voff)[_i]), (LAS unsigned*)(lds + (bufoff) + ldsw + _i * 8192), 16, 0, 0); } while (0)
; #define PG8_LDA(dst, b, h) do { _Pragma("unroll") for (int m = 0; m < 4; ++m) _Pragma("unroll") for (int k = 0; k < 2; ++k) dst[m][k] = *(const LAS bf16x8*)(lds + PG8_SA(b, h) + aoff + m * 2048 + k * 1024); } while (0)
; template <class Epi>
; DI void gemm_phase(LAS unsigned char* lds, const Gemm g, const StaticOrder S, const Epi E) {
;     ...
;             PG8_BAR; PG8_WAIT_L(0); PG8_MMA(1, 0, At, B0); PG8_BAR; PG8_SCHED;
;             PG8_STAGE(PG8_SB(0, 1), b2 + hstep, voffB);
;             PG8_WAIT_V(6); PG8_BAR; PG8_MMA(1, 1, At, B1); PG8_BAR;
;             PG8_LDB(B0, 1, 0); PG8_SCHED; PG8_LDA(At, 1, 0); PG8_STAGE(PG8_SA(0, 1), a2 + hstep, voffA);
;             PG8_WAIT_L(8); PG8_BAR; PG8_WAIT_L(0); PG8_MMA(0, 0, At, B0); PG8_BAR; PG8_SCHED;
	v_mfma_f32_16x16x32_bf16 v[4:7], v[164:167], v[196:199], v[4:7]
	s_setprio 0
	s_add_u32 s14, s78, 0x40000
	s_addc_u32 s15, s79, 0
	s_add_i32 s35, s90, s7
	v_lshl_add_u64 v[152:153], s[14:15], 0, v[132:133]
	s_mov_b32 m0, s35
	s_nop 0
	global_load_lds_dwordx4 v[152:153], off
	v_lshl_add_u64 v[152:153], s[14:15], 0, v[128:129]
	s_add_i32 m0, s35, 0x2000
	s_nop 0
	global_load_lds_dwordx4 v[152:153], off
	s_waitcnt vmcnt(6)
	s_barrier
	s_setprio 1
	v_mfma_f32_16x16x32_bf16 v[56:59], v[200:203], v[168:171], v[56:59]
	v_mfma_f32_16x16x32_bf16 v[48:51], v[208:211], v[168:171], v[48:51]
	v_mfma_f32_16x16x32_bf16 v[40:43], v[200:203], v[176:179], v[40:43]
	v_mfma_f32_16x16x32_bf16 v[32:35], v[208:211], v[176:179], v[32:35]
	v_mfma_f32_16x16x32_bf16 v[24:27], v[200:203], v[184:187], v[24:27]
	v_mfma_f32_16x16x32_bf16 v[16:19], v[208:211], v[184:187], v[16:19]
	v_mfma_f32_16x16x32_bf16 v[8:11], v[200:203], v[192:195], v[8:11]
	v_mfma_f32_16x16x32_bf16 v[0:3], v[208:211], v[192:195], v[0:3]
	v_mfma_f32_16x16x32_bf16 v[56:59], v[204:207], v[172:175], v[56:59]
	v_mfma_f32_16x16x32_bf16 v[48:51], v[212:215], v[172:175], v[48:51]
	v_mfma_f32_16x16x32_bf16 v[40:43], v[204:207], v[180:183], v[40:43]
	v_mfma_f32_16x16x32_bf16 v[32:35], v[212:215], v[180:183], v[32:35]
	v_mfma_f32_16x16x32_bf16 v[24:27], v[204:207], v[188:191], v[24:27]
	v_mfma_f32_16x16x32_bf16 v[16:19], v[212:215], v[188:191], v[16:19]
	v_mfma_f32_16x16x32_bf16 v[8:11], v[204:207], v[196:199], v[8:11]
	s_barrier
	v_mfma_f32_16x16x32_bf16 v[0:3], v[212:215], v[196:199], v[0:3]
	s_setprio 0
	s_add_i32 s35, 0, 0x18000
	v_add_u32_e32 v164, s35, v147
	ds_read_b128 v[152:155], v164
	ds_read_b128 v[156:159], v164 offset:1024
	ds_read_b128 v[160:163], v164 offset:2048
	ds_read_b128 v[164:167], v164 offset:3072
	s_add_u32 s14, s80, 0x40000
	s_addc_u32 s15, s81, 0
	s_mov_b32 m0, s82
	v_lshl_add_u64 v[200:201], s[14:15], 0, v[134:135]
	ds_read_b128 v[168:171], v150 offset:32768
	ds_read_b128 v[172:175], v150 offset:33792
	ds_read_b128 v[176:179], v150 offset:34816
	ds_read_b128 v[180:183], v150 offset:35840
	ds_read_b128 v[184:187], v150 offset:36864
	ds_read_b128 v[188:191], v150 offset:37888
	ds_read_b128 v[192:195], v150 offset:38912
	ds_read_b128 v[196:199], v150 offset:39936
	global_load_lds_dwordx4 v[200:201], off
	v_lshl_add_u64 v[200:201], s[14:15], 0, v[130:131]
	s_mov_b32 m0, s83
	s_nop 0
	global_load_lds_dwordx4 v[200:201], off
	s_waitcnt lgkmcnt(8)
	s_barrier
	s_waitcnt lgkmcnt(0)
	s_setprio 1
	s_waitcnt lgkmcnt(0)
	v_mfma_f32_16x16x32_bf16 v[124:127], v[152:155], v[168:171], v[124:127]
	v_mfma_f32_16x16x32_bf16 v[116:119], v[160:163], v[168:171], v[116:119]
	v_mfma_f32_16x16x32_bf16 v[108:111], v[152:155], v[176:179], v[108:111]
	v_mfma_f32_16x16x32_bf16 v[100:103], v[160:163], v[176:179], v[100:103]
	v_mfma_f32_16x16x32_bf16 v[92:95], v[152:155], v[184:187], v[92:95]
	v_mfma_f32_16x16x32_bf16 v[84:87], v[160:163], v[184:187], v[84:87]
	v_mfma_f32_16x16x32_bf16 v[76:79], v[152:155], v[192:195], v[76:79]
	v_mfma_f32_16x16x32_bf16 v[68:71], v[160:163], v[192:195], v[68:71]
	v_mfma_f32_16x16x32_bf16 v[124:127], v[156:159], v[172:175], v[124:127]
	v_mfma_f32_16x16x32_bf16 v[116:119], v[164:167], v[172:175], v[116:119]
	v_mfma_f32_16x16x32_bf16 v[108:111], v[156:159], v[180:183], v[108:111]
	v_mfma_f32_16x16x32_bf16 v[100:103], v[164:167], v[180:183], v[100:103]
	v_mfma_f32_16x16x32_bf16 v[92:95], v[156:159], v[188:191], v[92:95]
	v_mfma_f32_16x16x32_bf16 v[84:87], v[164:167], v[188:191], v[84:87]
	v_mfma_f32_16x16x32_bf16 v[76:79], v[156:159], v[196:199], v[76:79]
	s_barrier
	v_mfma_f32_16x16x32_bf16 v[68:71], v[164:167], v[196:199], v[68:71]
	s_setprio 0
	s_add_i32 s80, 0, 0x1c000
	s_add_i32 s14, s35, s7
	v_add_u32_e32 v212, s80, v147
	v_lshl_add_u64 v[144:145], v[144:145], 0, s[4:5]
	s_mov_b32 m0, s14
	ds_read_b128 v[200:203], v212
	ds_read_b128 v[204:207], v212 offset:1024
	ds_read_b128 v[208:211], v212 offset:2048
	ds_read_b128 v[212:215], v212 offset:3072
	global_load_lds_dwordx4 v[144:145], off
	v_lshl_add_u64 v[144:145], v[216:217], 0, s[4:5]
	s_add_i32 m0, s14, 0x2000
	s_nop 0
	global_load_lds_dwordx4 v[144:145], off
	s_barrier
	s_waitcnt lgkmcnt(0)
	s_setprio 1
	s_waitcnt lgkmcnt(0)
	v_mfma_f32_16x16x32_bf16 v[120:123], v[200:203], v[168:171], v[120:123]
	v_mfma_f32_16x16x32_bf16 v[112:115], v[208:211], v[168:171], v[112:115]
	v_mfma_f32_16x16x32_bf16 v[104:107], v[200:203], v[176:179], v[104:107]
	v_mfma_f32_16x16x32_bf16 v[96:99], v[208:211], v[176:179], v[96:99]
	v_mfma_f32_16x16x32_bf16 v[88:91], v[200:203], v[184:187], v[88:91]
	v_mfma_f32_16x16x32_bf16 v[80:83], v[208:211], v[184:187], v[80:83]
	v_mfma_f32_16x16x32_bf16 v[72:75], v[200:203], v[192:195], v[72:75]
	v_mfma_f32_16x16x32_bf16 v[64:67], v[208:211], v[192:195], v[64:67]
	v_mfma_f32_16x16x32_bf16 v[120:123], v[204:207], v[172:175], v[120:123]
	v_mfma_f32_16x16x32_bf16 v[112:115], v[212:215], v[172:175], v[112:115]
	v_mfma_f32_16x16x32_bf16 v[104:107], v[204:207], v[180:183], v[104:107]
	v_mfma_f32_16x16x32_bf16 v[96:99], v[212:215], v[180:183], v[96:99]
	v_mfma_f32_16x16x32_bf16 v[88:91], v[204:207], v[188:191], v[88:91]
	v_mfma_f32_16x16x32_bf16 v[80:83], v[212:215], v[188:191], v[80:83]
	v_mfma_f32_16x16x32_bf16 v[72:75], v[204:207], v[196:199], v[72:75]
	s_barrier
	v_mfma_f32_16x16x32_bf16 v[64:67], v[212:215], v[196:199], v[64:67]
	s_setprio 0
	s_mov_b32 m0, s85
	v_lshl_add_u64 v[144:145], v[218:219], 0, s[4:5]
	ds_read_b128 v[168:171], v150 offset:49152
	ds_read_b128 v[172:175], v150 offset:50176
	ds_read_b128 v[176:179], v150 offset:51200
	ds_read_b128 v[180:183], v150 offset:52224
	ds_read_b128 v[184:187], v150 offset:53248
	ds_read_b128 v[188:191], v150 offset:54272
	ds_read_b128 v[192:195], v150 offset:55296
	ds_read_b128 v[196:199], v150 offset:56320
	global_load_lds_dwordx4 v[144:145], off
	v_lshl_add_u64 v[144:145], v[220:221], 0, s[4:5]
	s_mov_b32 m0, s86
	s_nop 0
	global_load_lds_dwordx4 v[144:145], off
	s_barrier
; DI unsigned pk_bf16(float lo, float hi) { f32x2 v = {lo, hi}; return __builtin_bit_cast(unsigned, __builtin_convertvector(v, bf16v2)); }
; DI float fast_silu(float x) { return x * fast_sigmoid(x); }
; #define PG8_STAGE(bufoff, gbase, voff) do { _Pragma("unroll") for (int _i = 0; _i < 2; ++_i) \
;         __builtin_amdgcn_global_load_lds((const unsigned*)((const char*)(gbase) + (voff)[_i]), (LAS unsigned*)(lds + (bufoff) + ldsw + _i * 8192), 16, 0, 0); } while (0)
; #define PG8_LDA(dst, b, h) do { _Pragma("unroll") for (int m = 0; m < 4; ++m) _Pragma("unroll") for (int k = 0; k < 2; ++k) dst[m][k] = *(const LAS bf16x8*)(lds + PG8_SA(b, h) + aoff + m * 2048 + k * 1024); } while (0)
; #define PG8_LDB(dst, b, h) do { _Pragma("unroll") for (int n = 0; n < 2; ++n) _Pragma("unroll") for (int k = 0; k < 2; ++k) dst[n][k] = *(const LAS bf16x8*)(lds + PG8_SB(b, h) + boff + n * 2048 + k * 1024); } while (0)
; #define PG8_WAIT_V(n) asm volatile("s_waitcnt vmcnt(" #n ")" ::: "memory")
; #define PG8_WAIT_L(n) asm volatile("s_waitcnt lgkmcnt(" #n ")" ::: "memory")
; #define PG8_BAR __builtin_amdgcn_s_barrier()
; template <class Epi>
; DI void gemm_phase(LAS unsigned char* lds, const Gemm g, const StaticOrder S, const Epi E) {
;     ...
;             PG8_WAIT_L(8); PG8_BAR; PG8_WAIT_L(0); PG8_MMA(0, 0, At, B0); PG8_BAR; PG8_SCHED;
;             PG8_LDB(B1, 1, 1); PG8_STAGE(PG8_SB(1, 0), b3, voffB);
;             PG8_BAR; PG8_WAIT_L(0); PG8_MMA(0, 1, At, B1); PG8_BAR;
;             PG8_LDA(At, 1, 1); PG8_STAGE(PG8_SA(1, 0), a3, voffA);
;             PG8_BAR; PG8_WAIT_L(0); PG8_MMA(1, 0, At, B0); PG8_BAR; PG8_SCHED;
;             PG8_STAGE(PG8_SB(1, 1), b3 + hstep, voffB);
;             PG8_WAIT_V(6); PG8_BAR; PG8_MMA(1, 1, At, B1); PG8_BAR;
;     DI void operator()(AccRef acc, const Unit& u, int wr, int wc, int fr, int fq) const {
;     ...
;                 const f32x4 a0 = acc[ai][0][m][0] * r, a1 = acc[ai][0][m][1] * r, b0 = acc[ai][1][m][0] * r, b1 = acc[ai][1][m][1] * r;
;                 u32x4 w;
;                 w.x = pk_bf16(fast_silu(a0[0]) * b0[0], fast_silu(a0[1]) * b0[1]); w.y = pk_bf16(fast_silu(a0[2]) * b0[2], fast_silu(a0[3]) * b0[3]);
;                 w.z = pk_bf16(fast_silu(a1[0]) * b1[0], fast_silu(a1[1]) * b1[1]); w.w = pk_bf16(fast_silu(a1[2]) * b1[2], fast_silu(a1[3]) * b1[3]);
;                 *(u32x4*)(G + (size_t)row * DFF + col) = w;
	s_waitcnt lgkmcnt(0)
	s_setprio 1
	s_waitcnt lgkmcnt(0)
	v_mfma_f32_16x16x32_bf16 v[60:63], v[152:155], v[168:171], v[60:63]
	v_mfma_f32_16x16x32_bf16 v[52:55], v[160:163], v[168:171], v[52:55]
	v_mfma_f32_16x16x32_bf16 v[44:47], v[152:155], v[176:179], v[44:47]
	v_mfma_f32_16x16x32_bf16 v[36:39], v[160:163], v[176:179], v[36:39]
	v_mfma_f32_16x16x32_bf16 v[28:31], v[152:155], v[184:187], v[28:31]
	v_mfma_f32_16x16x32_bf16 v[20:23], v[160:163], v[184:187], v[20:23]
	v_mfma_f32_16x16x32_bf16 v[12:15], v[152:155], v[192:195], v[12:15]
	v_mfma_f32_16x16x32_bf16 v[4:7], v[160:163], v[192:195], v[4:7]
	v_mfma_f32_16x16x32_bf16 v[60:63], v[156:159], v[172:175], v[60:63]
	v_mfma_f32_16x16x32_bf16 v[52:55], v[164:167], v[172:175], v[52:55]
	v_mfma_f32_16x16x32_bf16 v[44:47], v[156:159], v[180:183], v[44:47]
	v_mfma_f32_16x16x32_bf16 v[36:39], v[164:167], v[180:183], v[36:39]
	v_mfma_f32_16x16x32_bf16 v[28:31], v[156:159], v[188:191], v[28:31]
	v_mfma_f32_16x16x32_bf16 v[20:23], v[164:167], v[188:191], v[20:23]
	v_mfma_f32_16x16x32_bf16 v[12:15], v[156:159], v[196:199], v[12:15]
	s_barrier
	v_mfma_f32_16x16x32_bf16 v[4:7], v[164:167], v[196:199], v[4:7]
	s_setprio 0
	s_add_u32 s14, s78, 0x40080
	s_addc_u32 s15, s79, 0
	s_add_i32 s35, s80, s7
	v_lshl_add_u64 v[144:145], s[14:15], 0, v[132:133]
	s_mov_b32 m0, s35
	s_nop 0
	global_load_lds_dwordx4 v[144:145], off
	v_lshl_add_u64 v[144:145], s[14:15], 0, v[128:129]
	s_add_i32 m0, s35, 0x2000
	s_nop 0
	global_load_lds_dwordx4 v[144:145], off
	s_waitcnt vmcnt(6)
	s_barrier
	s_setprio 1
	v_mfma_f32_16x16x32_bf16 v[56:59], v[200:203], v[168:171], v[56:59]
	v_mfma_f32_16x16x32_bf16 v[48:51], v[208:211], v[168:171], v[48:51]
	v_mfma_f32_16x16x32_bf16 v[40:43], v[200:203], v[176:179], v[40:43]
	v_mfma_f32_16x16x32_bf16 v[32:35], v[208:211], v[176:179], v[32:35]
	v_mfma_f32_16x16x32_bf16 v[24:27], v[200:203], v[184:187], v[24:27]
	v_mfma_f32_16x16x32_bf16 v[16:19], v[208:211], v[184:187], v[16:19]
	v_mfma_f32_16x16x32_bf16 v[8:11], v[200:203], v[192:195], v[8:11]
	v_mfma_f32_16x16x32_bf16 v[0:3], v[208:211], v[192:195], v[0:3]
	v_mfma_f32_16x16x32_bf16 v[56:59], v[204:207], v[172:175], v[56:59]
	v_mfma_f32_16x16x32_bf16 v[48:51], v[212:215], v[172:175], v[48:51]
	v_mfma_f32_16x16x32_bf16 v[40:43], v[204:207], v[180:183], v[40:43]
	v_mfma_f32_16x16x32_bf16 v[32:35], v[212:215], v[180:183], v[32:35]
	v_mfma_f32_16x16x32_bf16 v[24:27], v[204:207], v[188:191], v[24:27]
	v_mfma_f32_16x16x32_bf16 v[16:19], v[212:215], v[188:191], v[16:19]
	v_mfma_f32_16x16x32_bf16 v[8:11], v[204:207], v[196:199], v[8:11]
	s_barrier
	v_mfma_f32_16x16x32_bf16 v[0:3], v[212:215], v[196:199], v[0:3]
	s_setprio 0
	s_add_i32 s97, s97, 2
	s_add_u32 s76, s76, 0x100
	s_addc_u32 s77, s77, 0
	s_add_u32 s95, s95, 0x100
	s_addc_u32 s96, s96, 0
	s_cmp_gt_u32 s97, 13
	s_cbranch_scc0 .LBB0_107
	v_mul_f32_e32 v153, 0xbfb8aa3b, v124
	v_exp_f32_e32 v153, v153
	v_mul_f32_e32 v154, 0xbfb8aa3b, v125
	v_exp_f32_e32 v155, v154
	v_lshl_or_b32 v144, s92, 7, v148
	v_add_f32_e32 v153, 1.0, v153
	v_rcp_f32_e32 v154, v153
	v_add_f32_e32 v153, 1.0, v155
	v_mul_f32_e32 v155, 0xbfb8aa3b, v126
	v_exp_f32_e32 v156, v155
	v_mul_f32_e32 v155, 0xbfb8aa3b, v127
	v_exp_f32_e32 v157, v155
	v_rcp_f32_e32 v155, v153
	v_add_f32_e32 v153, 1.0, v156
	v_rcp_f32_e32 v156, v153
	v_add_f32_e32 v153, 1.0, v157
	v_rcp_f32_e32 v157, v153
	v_pk_mul_f32 v[124:125], v[124:125], v[154:155]
	v_ashrrev_i32_e32 v145, 31, v144
	v_pk_mul_f32 v[120:121], v[124:125], v[120:121]
	v_pk_mul_f32 v[124:125], v[126:127], v[156:157]
	v_cvt_pk_bf16_f32 v120, v120, v121
	v_mul_f32_e32 v121, 0xbfb8aa3b, v116
	v_pk_mul_f32 v[122:123], v[124:125], v[122:123]
	v_exp_f32_e32 v124, v121
	v_mul_f32_e32 v121, 0xbfb8aa3b, v117
	v_exp_f32_e32 v125, v121
	v_cvt_pk_bf16_f32 v121, v122, v123
	v_add_f32_e32 v122, 1.0, v124
	v_mul_f32_e32 v124, 0xbfb8aa3b, v118
	v_add_f32_e32 v123, 1.0, v125
	v_mul_f32_e32 v125, 0xbfb8aa3b, v119
	v_exp_f32_e32 v124, v124
	v_exp_f32_e32 v125, v125
	v_rcp_f32_e32 v122, v122
	v_rcp_f32_e32 v123, v123
	v_add_f32_e32 v124, 1.0, v124
	v_add_f32_e32 v125, 1.0, v125
	v_rcp_f32_e32 v124, v124
	v_rcp_f32_e32 v125, v125
	v_pk_mul_f32 v[116:117], v[116:117], v[122:123]
	v_lshl_add_u32 v152, s28, 8, v146
	v_pk_mul_f32 v[112:113], v[116:117], v[112:113]
	v_lshl_add_u64 v[144:145], v[144:145], 1, s[54:55]
	v_cvt_pk_bf16_f32 v122, v112, v113
	v_pk_mul_f32 v[112:113], v[118:119], v[124:125]
	v_or_b32_e32 v116, 16, v152
	v_pk_mul_f32 v[112:113], v[112:113], v[114:115]
	v_mul_f32_e32 v114, 0xbfb8aa3b, v110
	v_cvt_pk_bf16_f32 v123, v112, v113
	v_mad_i64_i32 v[112:113], s[14:15], v152, s91, v[144:145]
	global_store_dwordx4 v[112:113], v[120:123], off
	v_mul_f32_e32 v112, 0xbfb8aa3b, v108
	v_mul_f32_e32 v113, 0xbfb8aa3b, v109
	v_exp_f32_e32 v112, v112
	v_exp_f32_e32 v113, v113
	v_mul_f32_e32 v115, 0xbfb8aa3b, v111
	v_exp_f32_e32 v114, v114
	v_exp_f32_e32 v115, v115
	v_add_f32_e32 v112, 1.0, v112
	v_add_f32_e32 v113, 1.0, v113
	v_rcp_f32_e32 v112, v112
	v_rcp_f32_e32 v113, v113
	v_add_f32_e32 v114, 1.0, v114
	v_add_f32_e32 v115, 1.0, v115
	v_rcp_f32_e32 v114, v114
	v_rcp_f32_e32 v115, v115
	v_pk_mul_f32 v[108:109], v[108:109], v[112:113]
	s_and_b64 vcc, exec, s[0:1]
	v_pk_mul_f32 v[104:105], v[108:109], v[104:105]
	v_pk_mul_f32 v[108:109], v[110:111], v[114:115]
	v_cvt_pk_bf16_f32 v104, v104, v105
	v_mul_f32_e32 v105, 0xbfb8aa3b, v100
	v_pk_mul_f32 v[106:107], v[108:109], v[106:107]
	v_exp_f32_e32 v108, v105
	v_mul_f32_e32 v105, 0xbfb8aa3b, v101
	v_exp_f32_e32 v109, v105
	v_cvt_pk_bf16_f32 v105, v106, v107
	v_add_f32_e32 v106, 1.0, v108
	v_mul_f32_e32 v108, 0xbfb8aa3b, v102
	v_add_f32_e32 v107, 1.0, v109
; DI unsigned pk_bf16(float lo, float hi) { f32x2 v = {lo, hi}; return __builtin_bit_cast(unsigned, __builtin_convertvector(v, bf16v2)); }
; DI float fast_silu(float x) { return x * fast_sigmoid(x); }
;     DI void operator()(AccRef acc, const Unit& u, int wr, int wc, int fr, int fq) const {
;     ...
;             for (int m = 0; m < 4; ++m) {
;                 const int row = row0 + ai * 128 + m * 16;
;                 const float r = RS ? rsc.r[ai][m] : 1.0f;
;                 const f32x4 a0 = acc[ai][0][m][0] * r, a1 = acc[ai][0][m][1] * r, b0 = acc[ai][1][m][0] * r, b1 = acc[ai][1][m][1] * r;
;                 u32x4 w;
;                 w.x = pk_bf16(fast_silu(a0[0]) * b0[0], fast_silu(a0[1]) * b0[1]); w.y = pk_bf16(fast_silu(a0[2]) * b0[2], fast_silu(a0[3]) * b0[3]);
;                 w.z = pk_bf16(fast_silu(a1[0]) * b1[0], fast_silu(a1[1]) * b1[1]); w.w = pk_bf16(fast_silu(a1[2]) * b1[2], fast_silu(a1[3]) * b1[3]);
;                 *(u32x4*)(G + (size_t)row * DFF + col) = w;
;             }
	v_mul_f32_e32 v109, 0xbfb8aa3b, v103
	v_exp_f32_e32 v108, v108
	v_exp_f32_e32 v109, v109
	v_rcp_f32_e32 v106, v106
	v_rcp_f32_e32 v107, v107
	v_add_f32_e32 v108, 1.0, v108
	v_add_f32_e32 v109, 1.0, v109
	v_rcp_f32_e32 v108, v108
	v_rcp_f32_e32 v109, v109
	v_pk_mul_f32 v[100:101], v[100:101], v[106:107]
	s_mov_b32 s92, s8
	v_pk_mul_f32 v[96:97], v[100:101], v[96:97]
	v_or_b32_e32 v100, 32, v152
	v_cvt_pk_bf16_f32 v106, v96, v97
	v_pk_mul_f32 v[96:97], v[102:103], v[108:109]
	s_mov_b32 s28, s10
	v_pk_mul_f32 v[96:97], v[96:97], v[98:99]
	v_mul_f32_e32 v98, 0xbfb8aa3b, v94
	v_cvt_pk_bf16_f32 v107, v96, v97
	v_mad_i64_i32 v[96:97], s[14:15], v116, s91, v[144:145]
	global_store_dwordx4 v[96:97], v[104:107], off
	v_mul_f32_e32 v96, 0xbfb8aa3b, v92
	v_mul_f32_e32 v97, 0xbfb8aa3b, v93
	v_exp_f32_e32 v96, v96
	v_exp_f32_e32 v97, v97
	v_mul_f32_e32 v99, 0xbfb8aa3b, v95
	v_exp_f32_e32 v98, v98
	v_exp_f32_e32 v99, v99
	v_add_f32_e32 v96, 1.0, v96
	v_add_f32_e32 v97, 1.0, v97
	v_rcp_f32_e32 v96, v96
	v_rcp_f32_e32 v97, v97
	v_add_f32_e32 v98, 1.0, v98
	v_add_f32_e32 v99, 1.0, v99
	v_rcp_f32_e32 v98, v98
	v_rcp_f32_e32 v99, v99
	v_pk_mul_f32 v[92:93], v[92:93], v[96:97]
	s_mov_b64 s[78:79], s[26:27]
	v_pk_mul_f32 v[88:89], v[92:93], v[88:89]
	v_pk_mul_f32 v[92:93], v[94:95], v[98:99]
	v_cvt_pk_bf16_f32 v88, v88, v89
	v_mul_f32_e32 v89, 0xbfb8aa3b, v84
	v_pk_mul_f32 v[90:91], v[92:93], v[90:91]
	v_exp_f32_e32 v92, v89
	v_mul_f32_e32 v89, 0xbfb8aa3b, v85
	v_exp_f32_e32 v93, v89
	v_cvt_pk_bf16_f32 v89, v90, v91
	v_add_f32_e32 v90, 1.0, v92
	v_mul_f32_e32 v92, 0xbfb8aa3b, v86
	v_add_f32_e32 v91, 1.0, v93
	v_mul_f32_e32 v93, 0xbfb8aa3b, v87
	v_exp_f32_e32 v92, v92
	v_exp_f32_e32 v93, v93
	v_rcp_f32_e32 v90, v90
	v_rcp_f32_e32 v91, v91
	v_add_f32_e32 v92, 1.0, v92
	v_add_f32_e32 v93, 1.0, v93
	v_rcp_f32_e32 v92, v92
	v_rcp_f32_e32 v93, v93
	v_pk_mul_f32 v[84:85], v[84:85], v[90:91]
	s_mov_b64 s[76:77], s[24:25]
	v_pk_mul_f32 v[80:81], v[84:85], v[80:81]
	v_or_b32_e32 v84, 48, v152
	v_cvt_pk_bf16_f32 v90, v80, v81
	v_pk_mul_f32 v[80:81], v[86:87], v[92:93]
	s_nop 0
	v_pk_mul_f32 v[80:81], v[80:81], v[82:83]
	v_mul_f32_e32 v82, 0xbfb8aa3b, v78
	v_cvt_pk_bf16_f32 v91, v80, v81
	v_mad_i64_i32 v[80:81], s[14:15], v100, s91, v[144:145]
	global_store_dwordx4 v[80:81], v[88:91], off
	v_mul_f32_e32 v80, 0xbfb8aa3b, v76
	v_mul_f32_e32 v81, 0xbfb8aa3b, v77
	v_exp_f32_e32 v80, v80
	v_exp_f32_e32 v81, v81
	v_mul_f32_e32 v83, 0xbfb8aa3b, v79
	v_exp_f32_e32 v82, v82
	v_exp_f32_e32 v83, v83
	v_add_f32_e32 v80, 1.0, v80
	v_add_f32_e32 v81, 1.0, v81
	v_rcp_f32_e32 v80, v80
	v_rcp_f32_e32 v81, v81
	v_add_f32_e32 v82, 1.0, v82
	v_add_f32_e32 v83, 1.0, v83
	v_rcp_f32_e32 v82, v82
	v_rcp_f32_e32 v83, v83
	v_pk_mul_f32 v[76:77], v[76:77], v[80:81]
	s_nop 0
	v_pk_mul_f32 v[72:73], v[76:77], v[72:73]
	v_pk_mul_f32 v[76:77], v[78:79], v[82:83]
	v_cvt_pk_bf16_f32 v72, v72, v73
	v_mul_f32_e32 v73, 0xbfb8aa3b, v68
	v_pk_mul_f32 v[74:75], v[76:77], v[74:75]
	v_exp_f32_e32 v76, v73
	v_mul_f32_e32 v73, 0xbfb8aa3b, v69
	v_exp_f32_e32 v77, v73
	v_cvt_pk_bf16_f32 v73, v74, v75
	v_add_f32_e32 v74, 1.0, v76
	v_mul_f32_e32 v76, 0xbfb8aa3b, v70
	v_add_f32_e32 v75, 1.0, v77
	v_mul_f32_e32 v77, 0xbfb8aa3b, v71
	v_exp_f32_e32 v76, v76
	v_exp_f32_e32 v77, v77
	v_rcp_f32_e32 v74, v74
	v_rcp_f32_e32 v75, v75
	v_add_f32_e32 v76, 1.0, v76
	v_add_f32_e32 v77, 1.0, v77
	v_rcp_f32_e32 v76, v76
	v_rcp_f32_e32 v77, v77
	v_pk_mul_f32 v[68:69], v[68:69], v[74:75]
	s_nop 0
	v_pk_mul_f32 v[64:65], v[68:69], v[64:65]
	v_add_u32_e32 v68, 0x80, v152
	v_cvt_pk_bf16_f32 v74, v64, v65
	v_pk_mul_f32 v[64:65], v[70:71], v[76:77]
	s_nop 0
	v_pk_mul_f32 v[64:65], v[64:65], v[66:67]
	v_mul_f32_e32 v66, 0xbfb8aa3b, v62
	v_cvt_pk_bf16_f32 v75, v64, v65
	v_mad_i64_i32 v[64:65], s[14:15], v84, s91, v[144:145]
	global_store_dwordx4 v[64:65], v[72:75], off
	v_mul_f32_e32 v64, 0xbfb8aa3b, v60
	v_mul_f32_e32 v65, 0xbfb8aa3b, v61
	v_exp_f32_e32 v64, v64
	v_exp_f32_e32 v65, v65
	v_mul_f32_e32 v67, 0xbfb8aa3b, v63
	v_exp_f32_e32 v66, v66
	v_exp_f32_e32 v67, v67
	v_add_f32_e32 v64, 1.0, v64
	v_add_f32_e32 v65, 1.0, v65
	v_rcp_f32_e32 v64, v64
	v_rcp_f32_e32 v65, v65
	v_add_f32_e32 v66, 1.0, v66
	v_add_f32_e32 v67, 1.0, v67
	v_rcp_f32_e32 v66, v66
	v_rcp_f32_e32 v67, v67
	v_pk_mul_f32 v[60:61], v[60:61], v[64:65]
	s_nop 0
	v_pk_mul_f32 v[56:57], v[60:61], v[56:57]
	v_pk_mul_f32 v[60:61], v[62:63], v[66:67]
	v_cvt_pk_bf16_f32 v56, v56, v57
	v_mul_f32_e32 v57, 0xbfb8aa3b, v52
	v_pk_mul_f32 v[58:59], v[60:61], v[58:59]
	v_exp_f32_e32 v60, v57
	v_mul_f32_e32 v57, 0xbfb8aa3b, v53
	v_exp_f32_e32 v61, v57
	v_cvt_pk_bf16_f32 v57, v58, v59
	v_add_f32_e32 v58, 1.0, v60
	v_mul_f32_e32 v60, 0xbfb8aa3b, v54
	v_add_f32_e32 v59, 1.0, v61
	v_mul_f32_e32 v61, 0xbfb8aa3b, v55
	v_exp_f32_e32 v60, v60
	v_exp_f32_e32 v61, v61
	v_rcp_f32_e32 v58, v58
	v_rcp_f32_e32 v59, v59
	v_add_f32_e32 v60, 1.0, v60
	v_add_f32_e32 v61, 1.0, v61
	v_rcp_f32_e32 v60, v60
	v_rcp_f32_e32 v61, v61
	v_pk_mul_f32 v[52:53], v[52:53], v[58:59]
	s_nop 0
	v_pk_mul_f32 v[48:49], v[52:53], v[48:49]
; DI unsigned pk_bf16(float lo, float hi) { f32x2 v = {lo, hi}; return __builtin_bit_cast(unsigned, __builtin_convertvector(v, bf16v2)); }
; DI float fast_silu(float x) { return x * fast_sigmoid(x); }
; #define PG8_WAIT_V(n) asm volatile("s_waitcnt vmcnt(" #n ")" ::: "memory")
; #define PG8_BAR __builtin_amdgcn_s_barrier()
; #define PG8_WAIT_V(n) asm volatile("s_waitcnt vmcnt(" #n ")" ::: "memory")
; #define PG8_BAR __builtin_amdgcn_s_barrier()
; template <class Epi>
; DI void gemm_phase(LAS unsigned char* lds, const Gemm g, const StaticOrder S, const Epi E) {
;     ...
;         E(acc, cur, wr, wc, fr, fq);
;         if (!has_next) break;
; #pragma unroll
;         for (int a = 0; a < 2; ++a)
; #pragma unroll
;             for (int b = 0; b < 2; ++b)
; #pragma unroll
;                 for (int m = 0; m < 4; ++m)
; #pragma unroll
;                     for (int n = 0; n < 2; ++n) acc[a][b][m][n] = (f32x4){0.f, 0.f, 0.f, 0.f};
;         cur = nxt; cA = nA; cB = nB; ++ui;
;     }
;     PG8_WAIT_V(0);
;     if (wr == 0) PG8_BAR;
;     PG8_BAR;
;     DI void operator()(AccRef acc, const Unit& u, int wr, int wc, int fr, int fq) const {
;     ...
;             for (int m = 0; m < 4; ++m) {
;                 const int row = row0 + ai * 128 + m * 16;
;                 const float r = RS ? rsc.r[ai][m] : 1.0f;
;                 const f32x4 a0 = acc[ai][0][m][0] * r, a1 = acc[ai][0][m][1] * r, b0 = acc[ai][1][m][0] * r, b1 = acc[ai][1][m][1] * r;
;                 u32x4 w;
;                 w.x = pk_bf16(fast_silu(a0[0]) * b0[0], fast_silu(a0[1]) * b0[1]); w.y = pk_bf16(fast_silu(a0[2]) * b0[2], fast_silu(a0[3]) * b0[3]);
;                 w.z = pk_bf16(fast_silu(a1[0]) * b1[0], fast_silu(a1[1]) * b1[1]); w.w = pk_bf16(fast_silu(a1[2]) * b1[2], fast_silu(a1[3]) * b1[3]);
;                 *(u32x4*)(G + (size_t)row * DFF + col) = w;
;             }
	v_add_u32_e32 v52, 0x90, v152
	v_cvt_pk_bf16_f32 v58, v48, v49
	v_pk_mul_f32 v[48:49], v[54:55], v[60:61]
	s_nop 0
	v_pk_mul_f32 v[48:49], v[48:49], v[50:51]
	v_mul_f32_e32 v50, 0xbfb8aa3b, v46
	v_cvt_pk_bf16_f32 v59, v48, v49
	v_mad_i64_i32 v[48:49], s[14:15], v68, s91, v[144:145]
	global_store_dwordx4 v[48:49], v[56:59], off
	v_mul_f32_e32 v48, 0xbfb8aa3b, v44
	v_mul_f32_e32 v49, 0xbfb8aa3b, v45
	v_exp_f32_e32 v48, v48
	v_exp_f32_e32 v49, v49
	v_mul_f32_e32 v51, 0xbfb8aa3b, v47
	v_exp_f32_e32 v50, v50
	v_exp_f32_e32 v51, v51
	v_add_f32_e32 v48, 1.0, v48
	v_add_f32_e32 v49, 1.0, v49
	v_rcp_f32_e32 v48, v48
	v_rcp_f32_e32 v49, v49
	v_add_f32_e32 v50, 1.0, v50
	v_add_f32_e32 v51, 1.0, v51
	v_rcp_f32_e32 v50, v50
	v_rcp_f32_e32 v51, v51
	v_pk_mul_f32 v[44:45], v[44:45], v[48:49]
	s_nop 0
	v_pk_mul_f32 v[40:41], v[44:45], v[40:41]
	v_pk_mul_f32 v[44:45], v[46:47], v[50:51]
	v_cvt_pk_bf16_f32 v40, v40, v41
	v_mul_f32_e32 v41, 0xbfb8aa3b, v36
	v_pk_mul_f32 v[42:43], v[44:45], v[42:43]
	v_exp_f32_e32 v44, v41
	v_mul_f32_e32 v41, 0xbfb8aa3b, v37
	v_exp_f32_e32 v45, v41
	v_cvt_pk_bf16_f32 v41, v42, v43
	v_add_f32_e32 v42, 1.0, v44
	v_mul_f32_e32 v44, 0xbfb8aa3b, v38
	v_add_f32_e32 v43, 1.0, v45
	v_mul_f32_e32 v45, 0xbfb8aa3b, v39
	v_exp_f32_e32 v44, v44
	v_exp_f32_e32 v45, v45
	v_rcp_f32_e32 v42, v42
	v_rcp_f32_e32 v43, v43
	v_add_f32_e32 v44, 1.0, v44
	v_add_f32_e32 v45, 1.0, v45
	v_rcp_f32_e32 v44, v44
	v_rcp_f32_e32 v45, v45
	v_pk_mul_f32 v[36:37], v[36:37], v[42:43]
	s_nop 0
	v_pk_mul_f32 v[32:33], v[36:37], v[32:33]
	v_add_u32_e32 v36, 0xa0, v152
	v_cvt_pk_bf16_f32 v42, v32, v33
	v_pk_mul_f32 v[32:33], v[38:39], v[44:45]
	s_nop 0
	v_pk_mul_f32 v[32:33], v[32:33], v[34:35]
	v_mul_f32_e32 v34, 0xbfb8aa3b, v30
	v_cvt_pk_bf16_f32 v43, v32, v33
	v_mad_i64_i32 v[32:33], s[14:15], v52, s91, v[144:145]
	global_store_dwordx4 v[32:33], v[40:43], off
	v_mul_f32_e32 v32, 0xbfb8aa3b, v28
	v_mul_f32_e32 v33, 0xbfb8aa3b, v29
	v_exp_f32_e32 v32, v32
	v_exp_f32_e32 v33, v33
	v_mul_f32_e32 v35, 0xbfb8aa3b, v31
	v_exp_f32_e32 v34, v34
	v_exp_f32_e32 v35, v35
	v_add_f32_e32 v32, 1.0, v32
	v_add_f32_e32 v33, 1.0, v33
	v_rcp_f32_e32 v32, v32
	v_rcp_f32_e32 v33, v33
	v_add_f32_e32 v34, 1.0, v34
	v_add_f32_e32 v35, 1.0, v35
	v_rcp_f32_e32 v34, v34
	v_rcp_f32_e32 v35, v35
	v_pk_mul_f32 v[28:29], v[28:29], v[32:33]
	s_nop 0
	v_pk_mul_f32 v[24:25], v[28:29], v[24:25]
	v_pk_mul_f32 v[28:29], v[30:31], v[34:35]
	v_cvt_pk_bf16_f32 v24, v24, v25
	v_mul_f32_e32 v25, 0xbfb8aa3b, v20
	v_pk_mul_f32 v[26:27], v[28:29], v[26:27]
	v_exp_f32_e32 v28, v25
	v_mul_f32_e32 v25, 0xbfb8aa3b, v21
	v_exp_f32_e32 v29, v25
	v_cvt_pk_bf16_f32 v25, v26, v27
	v_add_f32_e32 v26, 1.0, v28
	v_mul_f32_e32 v28, 0xbfb8aa3b, v22
	v_add_f32_e32 v27, 1.0, v29
	v_mul_f32_e32 v29, 0xbfb8aa3b, v23
	v_exp_f32_e32 v28, v28
	v_exp_f32_e32 v29, v29
	v_rcp_f32_e32 v26, v26
	v_rcp_f32_e32 v27, v27
	v_add_f32_e32 v28, 1.0, v28
	v_add_f32_e32 v29, 1.0, v29
	v_rcp_f32_e32 v28, v28
	v_rcp_f32_e32 v29, v29
	v_pk_mul_f32 v[20:21], v[20:21], v[26:27]
	s_nop 0
	v_pk_mul_f32 v[16:17], v[20:21], v[16:17]
	v_add_u32_e32 v20, 0xb0, v152
	v_cvt_pk_bf16_f32 v26, v16, v17
	v_pk_mul_f32 v[16:17], v[22:23], v[28:29]
	s_nop 0
	v_pk_mul_f32 v[16:17], v[16:17], v[18:19]
	v_mul_f32_e32 v18, 0xbfb8aa3b, v14
	v_cvt_pk_bf16_f32 v27, v16, v17
	v_mad_i64_i32 v[16:17], s[14:15], v36, s91, v[144:145]
	global_store_dwordx4 v[16:17], v[24:27], off
	v_mul_f32_e32 v16, 0xbfb8aa3b, v12
	v_mul_f32_e32 v17, 0xbfb8aa3b, v13
	v_exp_f32_e32 v16, v16
	v_exp_f32_e32 v17, v17
	v_mul_f32_e32 v19, 0xbfb8aa3b, v15
	v_exp_f32_e32 v18, v18
	v_exp_f32_e32 v19, v19
	v_add_f32_e32 v16, 1.0, v16
	v_add_f32_e32 v17, 1.0, v17
	v_rcp_f32_e32 v16, v16
	v_rcp_f32_e32 v17, v17
	v_add_f32_e32 v18, 1.0, v18
	v_add_f32_e32 v19, 1.0, v19
	v_rcp_f32_e32 v18, v18
	v_rcp_f32_e32 v19, v19
	v_pk_mul_f32 v[12:13], v[12:13], v[16:17]
	s_nop 0
	v_pk_mul_f32 v[8:9], v[12:13], v[8:9]
	v_pk_mul_f32 v[12:13], v[14:15], v[18:19]
	v_cvt_pk_bf16_f32 v8, v8, v9
	v_mul_f32_e32 v9, 0xbfb8aa3b, v4
	v_pk_mul_f32 v[10:11], v[12:13], v[10:11]
	v_exp_f32_e32 v12, v9
	v_mul_f32_e32 v9, 0xbfb8aa3b, v5
	v_exp_f32_e32 v13, v9
	v_cvt_pk_bf16_f32 v9, v10, v11
	v_add_f32_e32 v10, 1.0, v12
	v_mul_f32_e32 v12, 0xbfb8aa3b, v6
	v_add_f32_e32 v11, 1.0, v13
	v_mul_f32_e32 v13, 0xbfb8aa3b, v7
	v_exp_f32_e32 v12, v12
	v_exp_f32_e32 v13, v13
	v_rcp_f32_e32 v10, v10
	v_rcp_f32_e32 v11, v11
	v_add_f32_e32 v12, 1.0, v12
	v_add_f32_e32 v13, 1.0, v13
	v_rcp_f32_e32 v12, v12
	v_rcp_f32_e32 v13, v13
	v_pk_mul_f32 v[4:5], v[4:5], v[10:11]
	s_nop 0
	v_pk_mul_f32 v[0:1], v[4:5], v[0:1]
	s_nop 0
	v_cvt_pk_bf16_f32 v10, v0, v1
	v_pk_mul_f32 v[0:1], v[6:7], v[12:13]
	s_nop 0
	v_pk_mul_f32 v[0:1], v[0:1], v[2:3]
	s_nop 0
	v_cvt_pk_bf16_f32 v11, v0, v1
	v_mad_i64_i32 v[0:1], s[14:15], v20, s91, v[144:145]
	global_store_dwordx4 v[0:1], v[8:11], off
	s_cbranch_vccz .LBB0_104
	s_waitcnt vmcnt(0)
	v_readlane_b32 s92, v243, 8
	s_cmpk_gt_u32 s6, 0xff
	v_readlane_b32 s93, v243, 9
	s_cbranch_scc1 .LBB0_111
	s_barrier

; #define PG8_STAGE(bufoff, gbase, voff) do { _Pragma("unroll") for (int _i = 0; _i < 2; ++_i) \
;         __builtin_amdgcn_global_load_lds((const unsigned*)((const char*)(gbase) + (voff)[_i]), (LAS unsigned*)(lds + (bufoff) + ldsw + _i * 8192), 16, 0, 0); } while (0)
; #define PG8_LDA(dst, b, h) do { _Pragma("unroll") for (int m = 0; m < 4; ++m) _Pragma("unroll") for (int k = 0; k < 2; ++k) dst[m][k] = *(const LAS bf16x8*)(lds + PG8_SA(b, h) + aoff + m * 2048 + k * 1024); } while (0)
; #define PG8_LDB(dst, b, h) do { _Pragma("unroll") for (int n = 0; n < 2; ++n) _Pragma("unroll") for (int k = 0; k < 2; ++k) dst[n][k] = *(const LAS bf16x8*)(lds + PG8_SB(b, h) + boff + n * 2048 + k * 1024); } while (0)
; #define PG8_MMA(ai, bj, At, Bt) do { __builtin_amdgcn_s_setprio(1); _Pragma("unroll") for (int m = 0; m < 4; ++m) _Pragma("unroll") for (int n = 0; n < 2; ++n) _Pragma("unroll") for (int k = 0; k < 2; ++k) \
;         acc[ai][bj][m][n] = __builtin_amdgcn_mfma_f32_16x16x32_bf16(Bt[n][k], At[m][k], acc[ai][bj][m][n], 0, 0, 0); __builtin_amdgcn_s_setprio(0); } while (0)
; #define PG8_WAIT_L(n) asm volatile("s_waitcnt lgkmcnt(" #n ")" ::: "memory")
; #define PG8_BAR __builtin_amdgcn_s_barrier()
; #define PG8_SCHED __builtin_amdgcn_sched_barrier(0)
; #define PG8_STAGE(bufoff, gbase, voff) do { _Pragma("unroll") for (int _i = 0; _i < 2; ++_i) \
;         __builtin_amdgcn_global_load_lds((const unsigned*)((const char*)(gbase) + (voff)[_i]), (LAS unsigned*)(lds + (bufoff) + ldsw + _i * 8192), 16, 0, 0); } while (0)
; #define PG8_LDA(dst, b, h) do { _Pragma("unroll") for (int m = 0; m < 4; ++m) _Pragma("unroll") for (int k = 0; k < 2; ++k) dst[m][k] = *(const LAS bf16x8*)(lds + PG8_SA(b, h) + aoff + m * 2048 + k * 1024); } while (0)
; template <class Epi>
; DI void gemm_phase(LAS unsigned char* lds, const Gemm g, const StaticOrder S, const Epi E) {
;     ...
;             PG8_LDB(B0, 0, 0); PG8_SCHED; PG8_LDA(At, 0, 0); PG8_STAGE(PG8_SA(1, 1), a1 + hstep, voffA);
;             PG8_WAIT_L(8); PG8_BAR; PG8_WAIT_L(0); PG8_MMA(0, 0, At, B0); PG8_BAR; PG8_SCHED;
;             PG8_LDB(B1, 0, 1); PG8_STAGE(PG8_SB(0, 0), b2, voffB);
;             PG8_BAR; PG8_WAIT_L(0); PG8_MMA(0, 1, At, B1); PG8_BAR;
;             PG8_LDA(At, 0, 1); PG8_STAGE(PG8_SA(0, 0), a2, voffA);
;             PG8_BAR; PG8_WAIT_L(0); PG8_MMA(1, 0, At, B0); PG8_BAR; PG8_SCHED;
.LBB0_186:
	ds_read_b128 v[128:131], v207
	ds_read_b128 v[132:135], v207 offset:1024
	ds_read_b128 v[136:139], v207 offset:2048
	ds_read_b128 v[140:143], v207 offset:3072
	s_add_u32 s76, s28, 0x100
	s_addc_u32 s77, s29, 0
	s_cmp_eq_u32 s97, 40
	s_cselect_b32 s81, s9, s77
	s_cselect_b32 s80, s8, s76
	s_cselect_b32 s79, s11, s7
	s_cselect_b32 s78, s10, s6
	v_lshl_add_u64 v[192:193], s[28:29], 0, v[184:185]
	s_add_i32 m0, s82, 0xc000
	ds_read_b128 v[144:147], v208
	ds_read_b128 v[148:151], v208 offset:1024
	ds_read_b128 v[152:155], v208 offset:2048
	ds_read_b128 v[156:159], v208 offset:3072
	ds_read_b128 v[160:163], v208 offset:4096
	ds_read_b128 v[164:167], v208 offset:5120
	ds_read_b128 v[168:171], v208 offset:6144
	ds_read_b128 v[172:175], v208 offset:7168
	global_load_lds_dwordx4 v[192:193], off
	v_lshl_add_u64 v[192:193], s[28:29], 0, v[186:187]
	s_add_i32 m0, s82, 0xe000
	s_nop 0
	global_load_lds_dwordx4 v[192:193], off
	s_waitcnt lgkmcnt(8)
	s_barrier
	s_waitcnt lgkmcnt(0)
	s_setprio 1
	s_waitcnt lgkmcnt(0)
	v_mfma_f32_16x16x32_bf16 v[124:127], v[128:131], v[144:147], v[124:127]
	v_mfma_f32_16x16x32_bf16 v[120:123], v[136:139], v[144:147], v[120:123]
	v_mfma_f32_16x16x32_bf16 v[108:111], v[128:131], v[152:155], v[108:111]
	v_mfma_f32_16x16x32_bf16 v[104:107], v[136:139], v[152:155], v[104:107]
	v_mfma_f32_16x16x32_bf16 v[92:95], v[128:131], v[160:163], v[92:95]
	v_mfma_f32_16x16x32_bf16 v[88:91], v[136:139], v[160:163], v[88:91]
	v_mfma_f32_16x16x32_bf16 v[76:79], v[128:131], v[168:171], v[76:79]
	v_mfma_f32_16x16x32_bf16 v[72:75], v[136:139], v[168:171], v[72:75]
	v_mfma_f32_16x16x32_bf16 v[124:127], v[132:135], v[148:151], v[124:127]
	v_mfma_f32_16x16x32_bf16 v[120:123], v[140:143], v[148:151], v[120:123]
	v_mfma_f32_16x16x32_bf16 v[108:111], v[132:135], v[156:159], v[108:111]
	v_mfma_f32_16x16x32_bf16 v[104:107], v[140:143], v[156:159], v[104:107]
	v_mfma_f32_16x16x32_bf16 v[92:95], v[132:135], v[164:167], v[92:95]
	v_mfma_f32_16x16x32_bf16 v[88:91], v[140:143], v[164:167], v[88:91]
	v_mfma_f32_16x16x32_bf16 v[76:79], v[132:135], v[172:175], v[76:79]
	s_barrier
	v_mfma_f32_16x16x32_bf16 v[72:75], v[140:143], v[172:175], v[72:75]
	s_setprio 0
	s_add_i32 s14, s91, s59
	v_lshl_add_u64 v[216:217], s[78:79], 0, v[178:179]
	s_mov_b32 m0, s14
	ds_read_b128 v[192:195], v209
	ds_read_b128 v[196:199], v209 offset:1024
	ds_read_b128 v[200:203], v209 offset:2048
	ds_read_b128 v[212:215], v209 offset:3072
	global_load_lds_dwordx4 v[216:217], off
	v_lshl_add_u64 v[218:219], s[78:79], 0, v[182:183]
	s_add_i32 m0, s14, 0x2000
	s_nop 0
	global_load_lds_dwordx4 v[218:219], off
	s_barrier
	s_waitcnt lgkmcnt(0)
	s_setprio 1
	s_waitcnt lgkmcnt(0)
	v_mfma_f32_16x16x32_bf16 v[116:119], v[192:195], v[144:147], v[116:119]
	v_mfma_f32_16x16x32_bf16 v[112:115], v[200:203], v[144:147], v[112:115]
	v_mfma_f32_16x16x32_bf16 v[100:103], v[192:195], v[152:155], v[100:103]
	v_mfma_f32_16x16x32_bf16 v[96:99], v[200:203], v[152:155], v[96:99]
	v_mfma_f32_16x16x32_bf16 v[84:87], v[192:195], v[160:163], v[84:87]
	v_mfma_f32_16x16x32_bf16 v[80:83], v[200:203], v[160:163], v[80:83]
	v_mfma_f32_16x16x32_bf16 v[68:71], v[192:195], v[168:171], v[68:71]
	v_mfma_f32_16x16x32_bf16 v[64:67], v[200:203], v[168:171], v[64:67]
	v_mfma_f32_16x16x32_bf16 v[116:119], v[196:199], v[148:151], v[116:119]
	v_mfma_f32_16x16x32_bf16 v[112:115], v[212:215], v[148:151], v[112:115]
	v_mfma_f32_16x16x32_bf16 v[100:103], v[196:199], v[156:159], v[100:103]
	v_mfma_f32_16x16x32_bf16 v[96:99], v[212:215], v[156:159], v[96:99]
	v_mfma_f32_16x16x32_bf16 v[84:87], v[196:199], v[164:167], v[84:87]
	v_mfma_f32_16x16x32_bf16 v[80:83], v[212:215], v[164:167], v[80:83]
	v_mfma_f32_16x16x32_bf16 v[68:71], v[196:199], v[172:175], v[68:71]
	s_barrier
	v_mfma_f32_16x16x32_bf16 v[64:67], v[212:215], v[172:175], v[64:67]
	s_setprio 0
	s_mov_b32 m0, s82
	v_lshl_add_u64 v[220:221], s[80:81], 0, v[176:177]
	ds_read_b128 v[144:147], v208 offset:16384
	ds_read_b128 v[148:151], v208 offset:17408
	ds_read_b128 v[152:155], v208 offset:18432
	ds_read_b128 v[156:159], v208 offset:19456
	ds_read_b128 v[160:163], v208 offset:20480
	ds_read_b128 v[164:167], v208 offset:21504
	ds_read_b128 v[168:171], v208 offset:22528
	ds_read_b128 v[172:175], v208 offset:23552
	global_load_lds_dwordx4 v[220:221], off
	v_lshl_add_u64 v[224:225], s[80:81], 0, v[180:181]
	s_mov_b32 m0, s83
	s_nop 0
	global_load_lds_dwordx4 v[224:225], off
	s_barrier
	s_waitcnt lgkmcnt(0)
	s_setprio 1
	s_waitcnt lgkmcnt(0)
	v_mfma_f32_16x16x32_bf16 v[60:63], v[128:131], v[144:147], v[60:63]
	v_mfma_f32_16x16x32_bf16 v[56:59], v[136:139], v[144:147], v[56:59]
	v_mfma_f32_16x16x32_bf16 v[44:47], v[128:131], v[152:155], v[44:47]
	v_mfma_f32_16x16x32_bf16 v[40:43], v[136:139], v[152:155], v[40:43]
	v_mfma_f32_16x16x32_bf16 v[28:31], v[128:131], v[160:163], v[28:31]
	v_mfma_f32_16x16x32_bf16 v[24:27], v[136:139], v[160:163], v[24:27]
	v_mfma_f32_16x16x32_bf16 v[12:15], v[128:131], v[168:171], v[12:15]
	v_mfma_f32_16x16x32_bf16 v[8:11], v[136:139], v[168:171], v[8:11]
	v_mfma_f32_16x16x32_bf16 v[60:63], v[132:135], v[148:151], v[60:63]
	v_mfma_f32_16x16x32_bf16 v[56:59], v[140:143], v[148:151], v[56:59]
	v_mfma_f32_16x16x32_bf16 v[44:47], v[132:135], v[156:159], v[44:47]
	v_mfma_f32_16x16x32_bf16 v[40:43], v[140:143], v[156:159], v[40:43]
	v_mfma_f32_16x16x32_bf16 v[28:31], v[132:135], v[164:167], v[28:31]
	v_mfma_f32_16x16x32_bf16 v[24:27], v[140:143], v[164:167], v[24:27]
	v_mfma_f32_16x16x32_bf16 v[12:15], v[132:135], v[172:175], v[12:15]
	s_barrier
; #define PG8_STAGE(bufoff, gbase, voff) do { _Pragma("unroll") for (int _i = 0; _i < 2; ++_i) \
;         __builtin_amdgcn_global_load_lds((const unsigned*)((const char*)(gbase) + (voff)[_i]), (LAS unsigned*)(lds + (bufoff) + ldsw + _i * 8192), 16, 0, 0); } while (0)
; #define PG8_LDA(dst, b, h) do { _Pragma("unroll") for (int m = 0; m < 4; ++m) _Pragma("unroll") for (int k = 0; k < 2; ++k) dst[m][k] = *(const LAS bf16x8*)(lds + PG8_SA(b, h) + aoff + m * 2048 + k * 1024); } while (0)
; #define PG8_LDB(dst, b, h) do { _Pragma("unroll") for (int n = 0; n < 2; ++n) _Pragma("unroll") for (int k = 0; k < 2; ++k) dst[n][k] = *(const LAS bf16x8*)(lds + PG8_SB(b, h) + boff + n * 2048 + k * 1024); } while (0)
; #define PG8_MMA(ai, bj, At, Bt) do { __builtin_amdgcn_s_setprio(1); _Pragma("unroll") for (int m = 0; m < 4; ++m) _Pragma("unroll") for (int n = 0; n < 2; ++n) _Pragma("unroll") for (int k = 0; k < 2; ++k) \
;         acc[ai][bj][m][n] = __builtin_amdgcn_mfma_f32_16x16x32_bf16(Bt[n][k], At[m][k], acc[ai][bj][m][n], 0, 0, 0); __builtin_amdgcn_s_setprio(0); } while (0)
; #define PG8_WAIT_V(n) asm volatile("s_waitcnt vmcnt(" #n ")" ::: "memory")
; #define PG8_WAIT_L(n) asm volatile("s_waitcnt lgkmcnt(" #n ")" ::: "memory")
; #define PG8_BAR __builtin_amdgcn_s_barrier()
; #define PG8_SCHED __builtin_amdgcn_sched_barrier(0)
; #define PG8_STAGE(bufoff, gbase, voff) do { _Pragma("unroll") for (int _i = 0; _i < 2; ++_i) \
;         __builtin_amdgcn_global_load_lds((const unsigned*)((const char*)(gbase) + (voff)[_i]), (LAS unsigned*)(lds + (bufoff) + ldsw + _i * 8192), 16, 0, 0); } while (0)
; #define PG8_LDA(dst, b, h) do { _Pragma("unroll") for (int m = 0; m < 4; ++m) _Pragma("unroll") for (int k = 0; k < 2; ++k) dst[m][k] = *(const LAS bf16x8*)(lds + PG8_SA(b, h) + aoff + m * 2048 + k * 1024); } while (0)
; template <class Epi>
; DI void gemm_phase(LAS unsigned char* lds, const Gemm g, const StaticOrder S, const Epi E) {
;     ...
;             PG8_BAR; PG8_WAIT_L(0); PG8_MMA(1, 0, At, B0); PG8_BAR; PG8_SCHED;
;             PG8_STAGE(PG8_SB(0, 1), b2 + hstep, voffB);
;             PG8_WAIT_V(6); PG8_BAR; PG8_MMA(1, 1, At, B1); PG8_BAR;
;             PG8_LDB(B0, 1, 0); PG8_SCHED; PG8_LDA(At, 1, 0); PG8_STAGE(PG8_SA(0, 1), a2 + hstep, voffA);
;             PG8_WAIT_L(8); PG8_BAR; PG8_WAIT_L(0); PG8_MMA(0, 0, At, B0); PG8_BAR; PG8_SCHED;
	v_mfma_f32_16x16x32_bf16 v[8:11], v[140:143], v[172:175], v[8:11]
	s_setprio 0
	s_add_u32 s14, s78, 0xb0000
	s_addc_u32 s15, s79, 0
	s_add_i32 s28, s92, s59
	v_lshl_add_u64 v[128:129], s[14:15], 0, v[178:179]
	s_mov_b32 m0, s28
	s_nop 0
	global_load_lds_dwordx4 v[128:129], off
	v_lshl_add_u64 v[128:129], s[14:15], 0, v[182:183]
	s_add_i32 m0, s28, 0x2000
	s_nop 0
	global_load_lds_dwordx4 v[128:129], off
	s_waitcnt vmcnt(6)
	s_barrier
	s_setprio 1
	v_mfma_f32_16x16x32_bf16 v[52:55], v[192:195], v[144:147], v[52:55]
	v_mfma_f32_16x16x32_bf16 v[48:51], v[200:203], v[144:147], v[48:51]
	v_mfma_f32_16x16x32_bf16 v[36:39], v[192:195], v[152:155], v[36:39]
	v_mfma_f32_16x16x32_bf16 v[32:35], v[200:203], v[152:155], v[32:35]
	v_mfma_f32_16x16x32_bf16 v[20:23], v[192:195], v[160:163], v[20:23]
	v_mfma_f32_16x16x32_bf16 v[16:19], v[200:203], v[160:163], v[16:19]
	v_mfma_f32_16x16x32_bf16 v[4:7], v[192:195], v[168:171], v[4:7]
	v_mfma_f32_16x16x32_bf16 v[0:3], v[200:203], v[168:171], v[0:3]
	v_mfma_f32_16x16x32_bf16 v[52:55], v[196:199], v[148:151], v[52:55]
	v_mfma_f32_16x16x32_bf16 v[48:51], v[212:215], v[148:151], v[48:51]
	v_mfma_f32_16x16x32_bf16 v[36:39], v[196:199], v[156:159], v[36:39]
	v_mfma_f32_16x16x32_bf16 v[32:35], v[212:215], v[156:159], v[32:35]
	v_mfma_f32_16x16x32_bf16 v[20:23], v[196:199], v[164:167], v[20:23]
	v_mfma_f32_16x16x32_bf16 v[16:19], v[212:215], v[164:167], v[16:19]
	v_mfma_f32_16x16x32_bf16 v[4:7], v[196:199], v[172:175], v[4:7]
	s_barrier
	v_mfma_f32_16x16x32_bf16 v[0:3], v[212:215], v[172:175], v[0:3]
	s_setprio 0
	s_add_i32 s28, 0, 0x18000
	v_add_u32_e32 v140, s28, v205
	ds_read_b128 v[128:131], v140
	ds_read_b128 v[132:135], v140 offset:1024
	ds_read_b128 v[136:139], v140 offset:2048
	ds_read_b128 v[140:143], v140 offset:3072
	s_add_u32 s14, s80, 0xb0000
	s_addc_u32 s15, s81, 0
	s_mov_b32 m0, s84
	v_lshl_add_u64 v[192:193], s[14:15], 0, v[176:177]
	ds_read_b128 v[144:147], v208 offset:32768
	ds_read_b128 v[148:151], v208 offset:33792
	ds_read_b128 v[152:155], v208 offset:34816
	ds_read_b128 v[156:159], v208 offset:35840
	ds_read_b128 v[160:163], v208 offset:36864
	ds_read_b128 v[164:167], v208 offset:37888
	ds_read_b128 v[168:171], v208 offset:38912
	ds_read_b128 v[172:175], v208 offset:39936
	global_load_lds_dwordx4 v[192:193], off
	v_lshl_add_u64 v[192:193], s[14:15], 0, v[180:181]
	s_mov_b32 m0, s85
	s_nop 0
	global_load_lds_dwordx4 v[192:193], off
	s_waitcnt lgkmcnt(8)
	s_barrier
	s_waitcnt lgkmcnt(0)
	s_setprio 1
	s_waitcnt lgkmcnt(0)
	v_mfma_f32_16x16x32_bf16 v[124:127], v[128:131], v[144:147], v[124:127]
	v_mfma_f32_16x16x32_bf16 v[120:123], v[136:139], v[144:147], v[120:123]
	v_mfma_f32_16x16x32_bf16 v[108:111], v[128:131], v[152:155], v[108:111]
	v_mfma_f32_16x16x32_bf16 v[104:107], v[136:139], v[152:155], v[104:107]
	v_mfma_f32_16x16x32_bf16 v[92:95], v[128:131], v[160:163], v[92:95]
	v_mfma_f32_16x16x32_bf16 v[88:91], v[136:139], v[160:163], v[88:91]
	v_mfma_f32_16x16x32_bf16 v[76:79], v[128:131], v[168:171], v[76:79]
	v_mfma_f32_16x16x32_bf16 v[72:75], v[136:139], v[168:171], v[72:75]
	v_mfma_f32_16x16x32_bf16 v[124:127], v[132:135], v[148:151], v[124:127]
	v_mfma_f32_16x16x32_bf16 v[120:123], v[140:143], v[148:151], v[120:123]
	v_mfma_f32_16x16x32_bf16 v[108:111], v[132:135], v[156:159], v[108:111]
	v_mfma_f32_16x16x32_bf16 v[104:107], v[140:143], v[156:159], v[104:107]
	v_mfma_f32_16x16x32_bf16 v[92:95], v[132:135], v[164:167], v[92:95]
	v_mfma_f32_16x16x32_bf16 v[88:91], v[140:143], v[164:167], v[88:91]
	v_mfma_f32_16x16x32_bf16 v[76:79], v[132:135], v[172:175], v[76:79]
	s_barrier
	v_mfma_f32_16x16x32_bf16 v[72:75], v[140:143], v[172:175], v[72:75]
	s_setprio 0
	s_add_i32 s29, 0, 0x1c000
	s_add_i32 s14, s28, s59
	v_add_u32_e32 v211, s29, v205
	v_lshl_add_u64 v[216:217], v[216:217], 0, s[24:25]
	s_mov_b32 m0, s14
	ds_read_b128 v[192:195], v211
	ds_read_b128 v[196:199], v211 offset:1024
	ds_read_b128 v[200:203], v211 offset:2048
	ds_read_b128 v[212:215], v211 offset:3072
	global_load_lds_dwordx4 v[216:217], off
	v_lshl_add_u64 v[216:217], v[218:219], 0, s[24:25]
	s_add_i32 m0, s14, 0x2000
	s_nop 0
	global_load_lds_dwordx4 v[216:217], off
	s_barrier
	s_waitcnt lgkmcnt(0)
	s_setprio 1
	s_waitcnt lgkmcnt(0)
	v_mfma_f32_16x16x32_bf16 v[116:119], v[192:195], v[144:147], v[116:119]
	v_mfma_f32_16x16x32_bf16 v[112:115], v[200:203], v[144:147], v[112:115]
	v_mfma_f32_16x16x32_bf16 v[100:103], v[192:195], v[152:155], v[100:103]
	v_mfma_f32_16x16x32_bf16 v[96:99], v[200:203], v[152:155], v[96:99]
	v_mfma_f32_16x16x32_bf16 v[84:87], v[192:195], v[160:163], v[84:87]
	v_mfma_f32_16x16x32_bf16 v[80:83], v[200:203], v[160:163], v[80:83]
	v_mfma_f32_16x16x32_bf16 v[68:71], v[192:195], v[168:171], v[68:71]
	v_mfma_f32_16x16x32_bf16 v[64:67], v[200:203], v[168:171], v[64:67]
	v_mfma_f32_16x16x32_bf16 v[116:119], v[196:199], v[148:151], v[116:119]
	v_mfma_f32_16x16x32_bf16 v[112:115], v[212:215], v[148:151], v[112:115]
	v_mfma_f32_16x16x32_bf16 v[100:103], v[196:199], v[156:159], v[100:103]
	v_mfma_f32_16x16x32_bf16 v[96:99], v[212:215], v[156:159], v[96:99]
	v_mfma_f32_16x16x32_bf16 v[84:87], v[196:199], v[164:167], v[84:87]
	v_mfma_f32_16x16x32_bf16 v[80:83], v[212:215], v[164:167], v[80:83]
	v_mfma_f32_16x16x32_bf16 v[68:71], v[196:199], v[172:175], v[68:71]
	s_barrier
	v_mfma_f32_16x16x32_bf16 v[64:67], v[212:215], v[172:175], v[64:67]
	s_setprio 0
	s_mov_b32 m0, s87
	v_lshl_add_u64 v[216:217], v[220:221], 0, s[24:25]
	ds_read_b128 v[144:147], v208 offset:49152
	ds_read_b128 v[148:151], v208 offset:50176
	ds_read_b128 v[152:155], v208 offset:51200
	ds_read_b128 v[156:159], v208 offset:52224
	ds_read_b128 v[160:163], v208 offset:53248
	ds_read_b128 v[164:167], v208 offset:54272
	ds_read_b128 v[168:171], v208 offset:55296
	ds_read_b128 v[172:175], v208 offset:56320
	global_load_lds_dwordx4 v[216:217], off
	v_lshl_add_u64 v[216:217], v[224:225], 0, s[24:25]
	s_mov_b32 m0, s88
	s_nop 0
	global_load_lds_dwordx4 v[216:217], off
	s_barrier
; DI unsigned pk_bf16(float lo, float hi) { f32x2 v = {lo, hi}; return __builtin_bit_cast(unsigned, __builtin_convertvector(v, bf16v2)); }
; template <class Epi>
; DI void gemm_phase(LAS unsigned char* lds, const Gemm g, const StaticOrder S, const Epi E) {
;     ...
;             PG8_WAIT_L(8); PG8_BAR; PG8_WAIT_L(0); PG8_MMA(0, 0, At, B0); PG8_BAR; PG8_SCHED;
;             PG8_LDB(B1, 1, 1); PG8_STAGE(PG8_SB(1, 0), b3, voffB);
;             PG8_BAR; PG8_WAIT_L(0); PG8_MMA(0, 1, At, B1); PG8_BAR;
;             PG8_LDA(At, 1, 1); PG8_STAGE(PG8_SA(1, 0), a3, voffA);
;             PG8_BAR; PG8_WAIT_L(0); PG8_MMA(1, 0, At, B0); PG8_BAR; PG8_SCHED;
;             PG8_STAGE(PG8_SB(1, 1), b3 + hstep, voffB);
;             PG8_WAIT_V(6); PG8_BAR; PG8_MMA(1, 1, At, B1); PG8_BAR;
;     DI void operator()(AccRef acc, const Unit& u, int wr, int wc, int fr, int fq) const {
;     ...
; #pragma unroll
;         for (int ai = 0; ai < 2; ++ai) {
;             f32x4 bv[4][2][2];
; #pragma unroll
;             for (int m = 0; m < 4; ++m)
; #pragma unroll
;                 for (int bj = 0; bj < 2; ++bj) {
;                     const size_t o = (size_t)(row0 + ai * 128 + m * 16) * DM + col0 + bj * 128;
;                     if (BASEF32) { bv[m][bj][0] = *(const f32x4*)(basef + o); bv[m][bj][1] = *(const f32x4*)(basef + o + 4); }
;                     else { const u32x4 h = *(const u32x4*)(xnb + o); bv[m][bj][0] = bf_lo4(h); bv[m][bj][1] = bf_hi4(h); }
;                 }
; #pragma unroll
;             for (int m = 0; m < 4; ++m) {
;                 const int row = row0 + ai * 128 + m * 16;
;                 float q = 0.f;
; #pragma unroll
;                 for (int bj = 0; bj < 2; ++bj) {
;                     const size_t o = (size_t)row * DM + col0 + bj * 128;
;                     const f32x4 r0 = bv[m][bj][0] + scale * acc[ai][bj][m][0], r1 = bv[m][bj][1] + scale * acc[ai][bj][m][1];
;                     u32x4 w; w.x = pk_bf16(r0[0], r0[1]); w.y = pk_bf16(r0[2], r0[3]); w.z = pk_bf16(r1[0], r1[1]); w.w = pk_bf16(r1[2], r1[3]);
;                     *(u32x4*)(xnb + o) = w;
;                     if (STATS) q += r0[0] * r0[0] + r0[1] * r0[1] + r0[2] * r0[2] + r0[3] * r0[3] + r1[0] * r1[0] + r1[1] * r1[1] + r1[2] * r1[2] + r1[3] * r1[3];
;                 }
;                 if (STATS) { q += __shfl_xor(q, 16); q += __shfl_xor(q, 32); if (fq == 0) atomicAdd(ss + row, q); }
	s_waitcnt lgkmcnt(0)
	s_setprio 1
	s_waitcnt lgkmcnt(0)
	v_mfma_f32_16x16x32_bf16 v[60:63], v[128:131], v[144:147], v[60:63]
	v_mfma_f32_16x16x32_bf16 v[56:59], v[136:139], v[144:147], v[56:59]
	v_mfma_f32_16x16x32_bf16 v[44:47], v[128:131], v[152:155], v[44:47]
	v_mfma_f32_16x16x32_bf16 v[40:43], v[136:139], v[152:155], v[40:43]
	v_mfma_f32_16x16x32_bf16 v[28:31], v[128:131], v[160:163], v[28:31]
	v_mfma_f32_16x16x32_bf16 v[24:27], v[136:139], v[160:163], v[24:27]
	v_mfma_f32_16x16x32_bf16 v[12:15], v[128:131], v[168:171], v[12:15]
	v_mfma_f32_16x16x32_bf16 v[8:11], v[136:139], v[168:171], v[8:11]
	v_mfma_f32_16x16x32_bf16 v[60:63], v[132:135], v[148:151], v[60:63]
	v_mfma_f32_16x16x32_bf16 v[56:59], v[140:143], v[148:151], v[56:59]
	v_mfma_f32_16x16x32_bf16 v[44:47], v[132:135], v[156:159], v[44:47]
	v_mfma_f32_16x16x32_bf16 v[40:43], v[140:143], v[156:159], v[40:43]
	v_mfma_f32_16x16x32_bf16 v[28:31], v[132:135], v[164:167], v[28:31]
	v_mfma_f32_16x16x32_bf16 v[24:27], v[140:143], v[164:167], v[24:27]
	v_mfma_f32_16x16x32_bf16 v[12:15], v[132:135], v[172:175], v[12:15]
	s_barrier
	v_mfma_f32_16x16x32_bf16 v[8:11], v[140:143], v[172:175], v[8:11]
	s_setprio 0
	s_add_u32 s14, s78, 0xb0080
	s_addc_u32 s15, s79, 0
	s_add_i32 s28, s29, s59
	v_lshl_add_u64 v[128:129], s[14:15], 0, v[178:179]
	s_mov_b32 m0, s28
	s_nop 0
	global_load_lds_dwordx4 v[128:129], off
	v_lshl_add_u64 v[128:129], s[14:15], 0, v[182:183]
	s_add_i32 m0, s28, 0x2000
	s_nop 0
	global_load_lds_dwordx4 v[128:129], off
	s_waitcnt vmcnt(6)
	s_barrier
	s_setprio 1
	v_mfma_f32_16x16x32_bf16 v[52:55], v[192:195], v[144:147], v[52:55]
	v_mfma_f32_16x16x32_bf16 v[48:51], v[200:203], v[144:147], v[48:51]
	v_mfma_f32_16x16x32_bf16 v[36:39], v[192:195], v[152:155], v[36:39]
	v_mfma_f32_16x16x32_bf16 v[32:35], v[200:203], v[152:155], v[32:35]
	v_mfma_f32_16x16x32_bf16 v[20:23], v[192:195], v[160:163], v[20:23]
	v_mfma_f32_16x16x32_bf16 v[16:19], v[200:203], v[160:163], v[16:19]
	v_mfma_f32_16x16x32_bf16 v[4:7], v[192:195], v[168:171], v[4:7]
	v_mfma_f32_16x16x32_bf16 v[0:3], v[200:203], v[168:171], v[0:3]
	v_mfma_f32_16x16x32_bf16 v[52:55], v[196:199], v[148:151], v[52:55]
	v_mfma_f32_16x16x32_bf16 v[48:51], v[212:215], v[148:151], v[48:51]
	v_mfma_f32_16x16x32_bf16 v[36:39], v[196:199], v[156:159], v[36:39]
	v_mfma_f32_16x16x32_bf16 v[32:35], v[212:215], v[156:159], v[32:35]
	v_mfma_f32_16x16x32_bf16 v[20:23], v[196:199], v[164:167], v[20:23]
	v_mfma_f32_16x16x32_bf16 v[16:19], v[212:215], v[164:167], v[16:19]
	v_mfma_f32_16x16x32_bf16 v[4:7], v[196:199], v[172:175], v[4:7]
	s_barrier
	v_mfma_f32_16x16x32_bf16 v[0:3], v[212:215], v[172:175], v[0:3]
	s_setprio 0
	s_add_i32 s97, s97, 2
	s_add_u32 s6, s6, 0x100
	s_addc_u32 s7, s7, 0
	s_cmp_gt_u32 s97, 41
	s_mov_b64 s[28:29], s[76:77]
	s_cbranch_scc0 .LBB0_186
	v_lshl_add_u32 v194, s96, 8, v204
	v_lshl_or_b32 v192, s95, 8, v206
	v_ashrrev_i32_e32 v193, 31, v192
	v_ashrrev_i32_e32 v195, 31, v194
	v_lshl_add_u64 v[196:197], v[192:193], 2, s[52:53]
	v_lshlrev_b64 v[128:129], 12, v[194:195]
	v_lshl_add_u64 v[128:129], v[196:197], 0, v[128:129]
	global_load_dwordx4 v[214:217], v[128:129], off
	global_load_dwordx4 v[218:221], v[128:129], off offset:16
	global_load_dwordx4 v[224:227], v[128:129], off offset:512
	global_load_dwordx4 v[228:231], v[128:129], off offset:528
	v_or_b32_e32 v202, 16, v194
	v_or_b32_e32 v200, 32, v194
	v_or_b32_e32 v198, 48, v194
	v_ashrrev_i32_e32 v203, 31, v202
	v_ashrrev_i32_e32 v201, 31, v200
	v_ashrrev_i32_e32 v199, 31, v198
	v_lshlrev_b64 v[128:129], 12, v[202:203]
	v_lshlrev_b64 v[130:131], 12, v[200:201]
	v_lshlrev_b64 v[132:133], 12, v[198:199]
	v_lshl_add_u64 v[128:129], v[196:197], 0, v[128:129]
	v_lshl_add_u64 v[130:131], v[196:197], 0, v[130:131]
	v_lshl_add_u64 v[132:133], v[196:197], 0, v[132:133]
	global_load_dwordx4 v[168:171], v[128:129], off offset:16
	global_load_dwordx4 v[172:175], v[128:129], off
	global_load_dwordx4 v[160:163], v[128:129], off offset:528
	global_load_dwordx4 v[164:167], v[128:129], off offset:512
	global_load_dwordx4 v[152:155], v[130:131], off offset:16
	global_load_dwordx4 v[156:159], v[130:131], off
	global_load_dwordx4 v[144:147], v[130:131], off offset:528
	global_load_dwordx4 v[148:151], v[130:131], off offset:512
	global_load_dwordx4 v[136:139], v[132:133], off offset:16
	global_load_dwordx4 v[140:143], v[132:133], off
	s_nop 0
	global_load_dwordx4 v[128:131], v[132:133], off offset:528
	s_nop 0
	global_load_dwordx4 v[132:135], v[132:133], off offset:512
	v_and_b32_e32 v212, 64, v210
	v_xor_b32_e32 v211, 16, v210
	v_add_u32_e32 v212, 64, v212
	v_xor_b32_e32 v213, 32, v210
	v_cmp_lt_i32_e32 vcc, v211, v212
	v_lshlrev_b64 v[232:233], 11, v[194:195]
	s_waitcnt vmcnt(0)
	v_pk_fma_f32 v[124:125], v[124:125], 0.5, v[214:215] op_sel_hi:[1,0,1]
	v_cndmask_b32_e32 v211, v210, v211, vcc
	v_cmp_lt_i32_e32 vcc, v213, v212
	v_pk_fma_f32 v[116:117], v[116:117], 0.5, v[224:225] op_sel_hi:[1,0,1]
	v_lshlrev_b32_e32 v212, 2, v211
	v_cndmask_b32_e32 v213, v210, v213, vcc
	v_lshlrev_b32_e32 v211, 2, v213
	v_pk_fma_f32 v[126:127], v[126:127], 0.5, v[216:217] op_sel_hi:[1,0,1]
	v_pk_fma_f32 v[216:217], v[112:113], 0.5, v[228:229] op_sel_hi:[1,0,1]
	v_cvt_pk_bf16_f32 v112, v124, v125
	v_mul_f32_e32 v125, v125, v125
	v_mul_f32_e32 v213, v117, v117
	v_pk_fma_f32 v[118:119], v[118:119], 0.5, v[226:227] op_sel_hi:[1,0,1]
	v_fmac_f32_e32 v125, v124, v124
	v_fmac_f32_e32 v213, v116, v116
	v_fmac_f32_e32 v125, v126, v126
	v_fmac_f32_e32 v213, v118, v118
	v_pk_fma_f32 v[120:121], v[120:121], 0.5, v[218:219] op_sel_hi:[1,0,1]
	v_fmac_f32_e32 v125, v127, v127
	v_fmac_f32_e32 v213, v119, v119
	v_fmac_f32_e32 v125, v120, v120
	v_fmac_f32_e32 v213, v216, v216
	v_pk_fma_f32 v[122:123], v[122:123], 0.5, v[220:221] op_sel_hi:[1,0,1]
	v_pk_fma_f32 v[214:215], v[114:115], 0.5, v[230:231] op_sel_hi:[1,0,1]
	v_fmac_f32_e32 v125, v121, v121
	v_fmac_f32_e32 v213, v217, v217
	v_fmac_f32_e32 v125, v122, v122
	v_fmac_f32_e32 v213, v214, v214
	v_fmac_f32_e32 v125, v123, v123
	v_fmac_f32_e32 v213, v215, v215
	v_cvt_pk_bf16_f32 v115, v122, v123
	v_add_f32_e32 v122, v125, v213
	ds_bpermute_b32 v123, v212, v122
	v_cvt_pk_bf16_f32 v114, v120, v121
	v_lshl_add_u64 v[120:121], s[56:57], 0, v[232:233]
	v_cvt_pk_bf16_f32 v113, v126, v127
	v_lshl_add_u64 v[120:121], v[192:193], 1, v[120:121]
	global_store_dwordx4 v[120:121], v[112:115], off
	s_waitcnt lgkmcnt(0)
	s_nop 0
	v_add_f32_e32 v112, v122, v123
	ds_bpermute_b32 v113, v211, v112
	v_cvt_pk_bf16_f32 v114, v116, v117
	v_cvt_pk_bf16_f32 v115, v118, v119
	v_cvt_pk_bf16_f32 v116, v216, v217
	v_cvt_pk_bf16_f32 v117, v214, v215
	global_store_dwordx4 v[120:121], v[114:117], off offset:256
	s_and_saveexec_b64 s[6:7], s[0:1]
	s_cbranch_execz .LBB0_189
	v_lshl_add_u64 v[114:115], v[194:195], 2, s[60:61]
	s_waitcnt lgkmcnt(0)
	v_add_f32_e32 v112, v112, v113
	global_atomic_add_f32 v[114:115], v112, off

; #define PG8_STAGE(bufoff, gbase, voff) do { _Pragma("unroll") for (int _i = 0; _i < 2; ++_i) \
;         __builtin_amdgcn_global_load_lds((const unsigned*)((const char*)(gbase) + (voff)[_i]), (LAS unsigned*)(lds + (bufoff) + ldsw + _i * 8192), 16, 0, 0); } while (0)
; #define PG8_LDA(dst, b, h) do { _Pragma("unroll") for (int m = 0; m < 4; ++m) _Pragma("unroll") for (int k = 0; k < 2; ++k) dst[m][k] = *(const LAS bf16x8*)(lds + PG8_SA(b, h) + aoff + m * 2048 + k * 1024); } while (0)
; #define PG8_LDB(dst, b, h) do { _Pragma("unroll") for (int n = 0; n < 2; ++n) _Pragma("unroll") for (int k = 0; k < 2; ++k) dst[n][k] = *(const LAS bf16x8*)(lds + PG8_SB(b, h) + boff + n * 2048 + k * 1024); } while (0)
; #define PG8_MMA(ai, bj, At, Bt) do { __builtin_amdgcn_s_setprio(1); _Pragma("unroll") for (int m = 0; m < 4; ++m) _Pragma("unroll") for (int n = 0; n < 2; ++n) _Pragma("unroll") for (int k = 0; k < 2; ++k) \
;         acc[ai][bj][m][n] = __builtin_amdgcn_mfma_f32_16x16x32_bf16(Bt[n][k], At[m][k], acc[ai][bj][m][n], 0, 0, 0); __builtin_amdgcn_s_setprio(0); } while (0)
; #define PG8_WAIT_L(n) asm volatile("s_waitcnt lgkmcnt(" #n ")" ::: "memory")
; #define PG8_BAR __builtin_amdgcn_s_barrier()
; #define PG8_SCHED __builtin_amdgcn_sched_barrier(0)
; #define PG8_STAGE(bufoff, gbase, voff) do { _Pragma("unroll") for (int _i = 0; _i < 2; ++_i) \
;         __builtin_amdgcn_global_load_lds((const unsigned*)((const char*)(gbase) + (voff)[_i]), (LAS unsigned*)(lds + (bufoff) + ldsw + _i * 8192), 16, 0, 0); } while (0)
; #define PG8_LDA(dst, b, h) do { _Pragma("unroll") for (int m = 0; m < 4; ++m) _Pragma("unroll") for (int k = 0; k < 2; ++k) dst[m][k] = *(const LAS bf16x8*)(lds + PG8_SA(b, h) + aoff + m * 2048 + k * 1024); } while (0)
; template <class Epi>
; DI void gemm_phase(LAS unsigned char* lds, const Gemm g, const StaticOrder S, const Epi E) {
;     ...
;             PG8_LDB(B0, 0, 0); PG8_SCHED; PG8_LDA(At, 0, 0); PG8_STAGE(PG8_SA(1, 1), a1 + hstep, voffA);
;             PG8_WAIT_L(8); PG8_BAR; PG8_WAIT_L(0); PG8_MMA(0, 0, At, B0); PG8_BAR; PG8_SCHED;
;             PG8_LDB(B1, 0, 1); PG8_STAGE(PG8_SB(0, 0), b2, voffB);
;             PG8_BAR; PG8_WAIT_L(0); PG8_MMA(0, 1, At, B1); PG8_BAR;
;             PG8_LDA(At, 0, 1); PG8_STAGE(PG8_SA(0, 0), a2, voffA);
;             PG8_BAR; PG8_WAIT_L(0); PG8_MMA(1, 0, At, B0); PG8_BAR; PG8_SCHED;
.LBB0_274:
	ds_read_b128 v[100:103], v227
	ds_read_b128 v[134:137], v227 offset:1024
	ds_read_b128 v[138:141], v227 offset:2048
	ds_read_b128 v[142:145], v227 offset:3072
	s_add_u32 s14, s8, 0xfffc0080
	s_addc_u32 s15, s9, -1
	s_cmp_eq_u32 s95, 12
	s_cselect_b32 s77, s1, s15
	s_cselect_b32 s76, s6, s14
	s_cselect_b32 s53, s7, s94
	s_cselect_b32 s52, s21, s23
	v_lshl_add_u64 v[104:105], s[8:9], 0, v[212:213]
	s_add_i32 m0, s78, 0xc000
	ds_read_b128 v[146:149], v228
	ds_read_b128 v[150:153], v228 offset:1024
	ds_read_b128 v[154:157], v228 offset:2048
	ds_read_b128 v[158:161], v228 offset:3072
	ds_read_b128 v[162:165], v228 offset:4096
	ds_read_b128 v[166:169], v228 offset:5120
	ds_read_b128 v[170:173], v228 offset:6144
	ds_read_b128 v[174:177], v228 offset:7168
	global_load_lds_dwordx4 v[104:105], off
	v_lshl_add_u64 v[104:105], s[8:9], 0, v[214:215]
	s_add_i32 m0, s78, 0xe000
	s_nop 0
	global_load_lds_dwordx4 v[104:105], off
	s_waitcnt lgkmcnt(8)
	s_barrier
	s_waitcnt lgkmcnt(0)
	s_setprio 1
	s_waitcnt lgkmcnt(0)
	v_mfma_f32_16x16x32_bf16 v[130:133], v[100:103], v[146:149], v[130:133]
	v_mfma_f32_16x16x32_bf16 v[126:129], v[138:141], v[146:149], v[126:129]
	v_mfma_f32_16x16x32_bf16 v[114:117], v[100:103], v[154:157], v[114:117]
	v_mfma_f32_16x16x32_bf16 v[110:113], v[138:141], v[154:157], v[110:113]
	v_mfma_f32_16x16x32_bf16 v[92:95], v[100:103], v[162:165], v[92:95]
	v_mfma_f32_16x16x32_bf16 v[88:91], v[138:141], v[162:165], v[88:91]
	v_mfma_f32_16x16x32_bf16 v[76:79], v[100:103], v[170:173], v[76:79]
	v_mfma_f32_16x16x32_bf16 v[72:75], v[138:141], v[170:173], v[72:75]
	v_mfma_f32_16x16x32_bf16 v[130:133], v[134:137], v[150:153], v[130:133]
	v_mfma_f32_16x16x32_bf16 v[126:129], v[142:145], v[150:153], v[126:129]
	v_mfma_f32_16x16x32_bf16 v[114:117], v[134:137], v[158:161], v[114:117]
	v_mfma_f32_16x16x32_bf16 v[110:113], v[142:145], v[158:161], v[110:113]
	v_mfma_f32_16x16x32_bf16 v[92:95], v[134:137], v[166:169], v[92:95]
	v_mfma_f32_16x16x32_bf16 v[88:91], v[142:145], v[166:169], v[88:91]
	v_mfma_f32_16x16x32_bf16 v[76:79], v[134:137], v[174:177], v[76:79]
	s_barrier
	v_mfma_f32_16x16x32_bf16 v[72:75], v[142:145], v[174:177], v[72:75]
	s_setprio 0
	s_add_i32 s14, s87, s59
	v_lshl_add_u64 v[194:195], s[52:53], 0, v[200:201]
	s_mov_b32 m0, s14
	ds_read_b128 v[178:181], v229
	ds_read_b128 v[182:185], v229 offset:1024
	ds_read_b128 v[186:189], v229 offset:2048
	ds_read_b128 v[190:193], v229 offset:3072
	global_load_lds_dwordx4 v[194:195], off
	v_lshl_add_u64 v[196:197], s[52:53], 0, v[204:205]
	s_add_i32 m0, s14, 0x2000
	s_nop 0
	global_load_lds_dwordx4 v[196:197], off
	s_barrier
	s_waitcnt lgkmcnt(0)
	s_setprio 1
	s_waitcnt lgkmcnt(0)
	v_mfma_f32_16x16x32_bf16 v[122:125], v[178:181], v[146:149], v[122:125]
	v_mfma_f32_16x16x32_bf16 v[118:121], v[186:189], v[146:149], v[118:121]
	v_mfma_f32_16x16x32_bf16 v[104:107], v[178:181], v[154:157], v[106:109]
	v_mfma_f32_16x16x32_bf16 v[96:99], v[186:189], v[154:157], v[96:99]
	v_mfma_f32_16x16x32_bf16 v[84:87], v[178:181], v[162:165], v[84:87]
	v_mfma_f32_16x16x32_bf16 v[80:83], v[186:189], v[162:165], v[80:83]
	v_mfma_f32_16x16x32_bf16 v[68:71], v[178:181], v[170:173], v[68:71]
	v_mfma_f32_16x16x32_bf16 v[64:67], v[186:189], v[170:173], v[64:67]
	v_mfma_f32_16x16x32_bf16 v[122:125], v[182:185], v[150:153], v[122:125]
	v_mfma_f32_16x16x32_bf16 v[118:121], v[190:193], v[150:153], v[118:121]
	v_mfma_f32_16x16x32_bf16 v[104:107], v[182:185], v[158:161], v[104:107]
	v_mfma_f32_16x16x32_bf16 v[96:99], v[190:193], v[158:161], v[96:99]
	v_mfma_f32_16x16x32_bf16 v[84:87], v[182:185], v[166:169], v[84:87]
	v_mfma_f32_16x16x32_bf16 v[80:83], v[190:193], v[166:169], v[80:83]
	v_mfma_f32_16x16x32_bf16 v[68:71], v[182:185], v[174:177], v[68:71]
	s_barrier
	v_mfma_f32_16x16x32_bf16 v[64:67], v[190:193], v[174:177], v[64:67]
	s_setprio 0
	s_mov_b32 m0, s78
	v_lshl_add_u64 v[220:221], s[76:77], 0, v[198:199]
	ds_read_b128 v[146:149], v228 offset:16384
	ds_read_b128 v[150:153], v228 offset:17408
	ds_read_b128 v[154:157], v228 offset:18432
	ds_read_b128 v[158:161], v228 offset:19456
	ds_read_b128 v[162:165], v228 offset:20480
	ds_read_b128 v[166:169], v228 offset:21504
	ds_read_b128 v[170:173], v228 offset:22528
	ds_read_b128 v[174:177], v228 offset:23552
	global_load_lds_dwordx4 v[220:221], off
	v_lshl_add_u64 v[232:233], s[76:77], 0, v[202:203]
	s_mov_b32 m0, s79
	s_nop 0
	global_load_lds_dwordx4 v[232:233], off
	s_barrier
	s_waitcnt lgkmcnt(0)
	s_setprio 1
	s_waitcnt lgkmcnt(0)
	v_mfma_f32_16x16x32_bf16 v[60:63], v[100:103], v[146:149], v[60:63]
	v_mfma_f32_16x16x32_bf16 v[56:59], v[138:141], v[146:149], v[56:59]
	v_mfma_f32_16x16x32_bf16 v[44:47], v[100:103], v[154:157], v[44:47]
	v_mfma_f32_16x16x32_bf16 v[40:43], v[138:141], v[154:157], v[40:43]
	v_mfma_f32_16x16x32_bf16 v[28:31], v[100:103], v[162:165], v[28:31]
	v_mfma_f32_16x16x32_bf16 v[24:27], v[138:141], v[162:165], v[24:27]
	v_mfma_f32_16x16x32_bf16 v[12:15], v[100:103], v[170:173], v[12:15]
	v_mfma_f32_16x16x32_bf16 v[8:11], v[138:141], v[170:173], v[8:11]
	v_mfma_f32_16x16x32_bf16 v[60:63], v[134:137], v[150:153], v[60:63]
	v_mfma_f32_16x16x32_bf16 v[56:59], v[142:145], v[150:153], v[56:59]
	v_mfma_f32_16x16x32_bf16 v[44:47], v[134:137], v[158:161], v[44:47]
	v_mfma_f32_16x16x32_bf16 v[40:43], v[142:145], v[158:161], v[40:43]
	v_mfma_f32_16x16x32_bf16 v[28:31], v[134:137], v[166:169], v[28:31]
	v_mfma_f32_16x16x32_bf16 v[24:27], v[142:145], v[166:169], v[24:27]
	v_mfma_f32_16x16x32_bf16 v[12:15], v[134:137], v[174:177], v[12:15]
	s_barrier
; #define PG8_STAGE(bufoff, gbase, voff) do { _Pragma("unroll") for (int _i = 0; _i < 2; ++_i) \
;         __builtin_amdgcn_global_load_lds((const unsigned*)((const char*)(gbase) + (voff)[_i]), (LAS unsigned*)(lds + (bufoff) + ldsw + _i * 8192), 16, 0, 0); } while (0)
; #define PG8_LDA(dst, b, h) do { _Pragma("unroll") for (int m = 0; m < 4; ++m) _Pragma("unroll") for (int k = 0; k < 2; ++k) dst[m][k] = *(const LAS bf16x8*)(lds + PG8_SA(b, h) + aoff + m * 2048 + k * 1024); } while (0)
; #define PG8_LDB(dst, b, h) do { _Pragma("unroll") for (int n = 0; n < 2; ++n) _Pragma("unroll") for (int k = 0; k < 2; ++k) dst[n][k] = *(const LAS bf16x8*)(lds + PG8_SB(b, h) + boff + n * 2048 + k * 1024); } while (0)
; #define PG8_MMA(ai, bj, At, Bt) do { __builtin_amdgcn_s_setprio(1); _Pragma("unroll") for (int m = 0; m < 4; ++m) _Pragma("unroll") for (int n = 0; n < 2; ++n) _Pragma("unroll") for (int k = 0; k < 2; ++k) \
;         acc[ai][bj][m][n] = __builtin_amdgcn_mfma_f32_16x16x32_bf16(Bt[n][k], At[m][k], acc[ai][bj][m][n], 0, 0, 0); __builtin_amdgcn_s_setprio(0); } while (0)
; #define PG8_WAIT_V(n) asm volatile("s_waitcnt vmcnt(" #n ")" ::: "memory")
; #define PG8_WAIT_L(n) asm volatile("s_waitcnt lgkmcnt(" #n ")" ::: "memory")
; #define PG8_BAR __builtin_amdgcn_s_barrier()
; #define PG8_SCHED __builtin_amdgcn_sched_barrier(0)
; #define PG8_STAGE(bufoff, gbase, voff) do { _Pragma("unroll") for (int _i = 0; _i < 2; ++_i) \
;         __builtin_amdgcn_global_load_lds((const unsigned*)((const char*)(gbase) + (voff)[_i]), (LAS unsigned*)(lds + (bufoff) + ldsw + _i * 8192), 16, 0, 0); } while (0)
; #define PG8_LDA(dst, b, h) do { _Pragma("unroll") for (int m = 0; m < 4; ++m) _Pragma("unroll") for (int k = 0; k < 2; ++k) dst[m][k] = *(const LAS bf16x8*)(lds + PG8_SA(b, h) + aoff + m * 2048 + k * 1024); } while (0)
; template <class Epi>
; DI void gemm_phase(LAS unsigned char* lds, const Gemm g, const StaticOrder S, const Epi E) {
;     ...
;             PG8_BAR; PG8_WAIT_L(0); PG8_MMA(1, 0, At, B0); PG8_BAR; PG8_SCHED;
;             PG8_STAGE(PG8_SB(0, 1), b2 + hstep, voffB);
;             PG8_WAIT_V(6); PG8_BAR; PG8_MMA(1, 1, At, B1); PG8_BAR;
;             PG8_LDB(B0, 1, 0); PG8_SCHED; PG8_LDA(At, 1, 0); PG8_STAGE(PG8_SA(0, 1), a2 + hstep, voffA);
;             PG8_WAIT_L(8); PG8_BAR; PG8_WAIT_L(0); PG8_MMA(0, 0, At, B0); PG8_BAR; PG8_SCHED;
	v_mfma_f32_16x16x32_bf16 v[8:11], v[142:145], v[174:177], v[8:11]
	s_setprio 0
	s_add_u32 s14, s52, 0x40000
	s_addc_u32 s15, s53, 0
	s_add_i32 s35, s90, s59
	v_lshl_add_u64 v[100:101], s[14:15], 0, v[200:201]
	s_mov_b32 m0, s35
	s_nop 0
	global_load_lds_dwordx4 v[100:101], off
	v_lshl_add_u64 v[100:101], s[14:15], 0, v[204:205]
	s_add_i32 m0, s35, 0x2000
	s_nop 0
	global_load_lds_dwordx4 v[100:101], off
	s_waitcnt vmcnt(6)
	s_barrier
	s_setprio 1
	v_mfma_f32_16x16x32_bf16 v[52:55], v[178:181], v[146:149], v[52:55]
	v_mfma_f32_16x16x32_bf16 v[48:51], v[186:189], v[146:149], v[48:51]
	v_mfma_f32_16x16x32_bf16 v[36:39], v[178:181], v[154:157], v[36:39]
	v_mfma_f32_16x16x32_bf16 v[32:35], v[186:189], v[154:157], v[32:35]
	v_mfma_f32_16x16x32_bf16 v[20:23], v[178:181], v[162:165], v[20:23]
	v_mfma_f32_16x16x32_bf16 v[16:19], v[186:189], v[162:165], v[16:19]
	v_mfma_f32_16x16x32_bf16 v[4:7], v[178:181], v[170:173], v[4:7]
	v_mfma_f32_16x16x32_bf16 v[0:3], v[186:189], v[170:173], v[0:3]
	v_mfma_f32_16x16x32_bf16 v[52:55], v[182:185], v[150:153], v[52:55]
	v_mfma_f32_16x16x32_bf16 v[48:51], v[190:193], v[150:153], v[48:51]
	v_mfma_f32_16x16x32_bf16 v[36:39], v[182:185], v[158:161], v[36:39]
	v_mfma_f32_16x16x32_bf16 v[32:35], v[190:193], v[158:161], v[32:35]
	v_mfma_f32_16x16x32_bf16 v[20:23], v[182:185], v[166:169], v[20:23]
	v_mfma_f32_16x16x32_bf16 v[16:19], v[190:193], v[166:169], v[16:19]
	v_mfma_f32_16x16x32_bf16 v[4:7], v[182:185], v[174:177], v[4:7]
	s_barrier
	v_mfma_f32_16x16x32_bf16 v[0:3], v[190:193], v[174:177], v[0:3]
	s_setprio 0
	s_add_i32 s35, 0, 0x18000
	v_add_u32_e32 v108, s35, v225
	ds_read_b128 v[100:103], v108
	ds_read_b128 v[134:137], v108 offset:1024
	ds_read_b128 v[138:141], v108 offset:2048
	ds_read_b128 v[142:145], v108 offset:3072
	s_add_u32 s14, s76, 0x40000
	s_addc_u32 s15, s77, 0
	s_mov_b32 m0, s80
	v_lshl_add_u64 v[108:109], s[14:15], 0, v[198:199]
	ds_read_b128 v[146:149], v228 offset:32768
	ds_read_b128 v[150:153], v228 offset:33792
	ds_read_b128 v[154:157], v228 offset:34816
	ds_read_b128 v[158:161], v228 offset:35840
	ds_read_b128 v[162:165], v228 offset:36864
	ds_read_b128 v[166:169], v228 offset:37888
	ds_read_b128 v[170:173], v228 offset:38912
	ds_read_b128 v[174:177], v228 offset:39936
	global_load_lds_dwordx4 v[108:109], off
	v_lshl_add_u64 v[108:109], s[14:15], 0, v[202:203]
	s_mov_b32 m0, s81
	s_nop 0
	global_load_lds_dwordx4 v[108:109], off
	s_waitcnt lgkmcnt(8)
	s_barrier
	s_waitcnt lgkmcnt(0)
	s_setprio 1
	s_waitcnt lgkmcnt(0)
	v_mfma_f32_16x16x32_bf16 v[130:133], v[100:103], v[146:149], v[130:133]
	v_mfma_f32_16x16x32_bf16 v[126:129], v[138:141], v[146:149], v[126:129]
	v_mfma_f32_16x16x32_bf16 v[114:117], v[100:103], v[154:157], v[114:117]
	v_mfma_f32_16x16x32_bf16 v[108:111], v[138:141], v[154:157], v[110:113]
	v_mfma_f32_16x16x32_bf16 v[92:95], v[100:103], v[162:165], v[92:95]
	v_mfma_f32_16x16x32_bf16 v[88:91], v[138:141], v[162:165], v[88:91]
	v_mfma_f32_16x16x32_bf16 v[76:79], v[100:103], v[170:173], v[76:79]
	v_mfma_f32_16x16x32_bf16 v[72:75], v[138:141], v[170:173], v[72:75]
	v_mfma_f32_16x16x32_bf16 v[130:133], v[134:137], v[150:153], v[130:133]
	v_mfma_f32_16x16x32_bf16 v[126:129], v[142:145], v[150:153], v[126:129]
	v_mfma_f32_16x16x32_bf16 v[114:117], v[134:137], v[158:161], v[114:117]
	v_mfma_f32_16x16x32_bf16 v[110:113], v[142:145], v[158:161], v[108:111]
	v_mfma_f32_16x16x32_bf16 v[92:95], v[134:137], v[166:169], v[92:95]
	v_mfma_f32_16x16x32_bf16 v[88:91], v[142:145], v[166:169], v[88:91]
	v_mfma_f32_16x16x32_bf16 v[76:79], v[134:137], v[174:177], v[76:79]
	s_barrier
	v_mfma_f32_16x16x32_bf16 v[72:75], v[142:145], v[174:177], v[72:75]
	s_setprio 0
	s_add_i32 s76, 0, 0x1c000
	v_add_u32_e32 v108, s76, v225
	s_add_i32 s14, s35, s59
	ds_read_b128 v[178:181], v108
	ds_read_b128 v[182:185], v108 offset:1024
	ds_read_b128 v[186:189], v108 offset:2048
	ds_read_b128 v[190:193], v108 offset:3072
	v_lshl_add_u64 v[108:109], v[194:195], 0, s[18:19]
	s_mov_b32 m0, s14
	s_nop 0
	global_load_lds_dwordx4 v[108:109], off
	v_lshl_add_u64 v[108:109], v[196:197], 0, s[18:19]
	s_add_i32 m0, s14, 0x2000
	s_nop 0
	global_load_lds_dwordx4 v[108:109], off
	s_barrier
	s_waitcnt lgkmcnt(0)
	s_setprio 1
	s_waitcnt lgkmcnt(0)
	v_mfma_f32_16x16x32_bf16 v[122:125], v[178:181], v[146:149], v[122:125]
	v_mfma_f32_16x16x32_bf16 v[118:121], v[186:189], v[146:149], v[118:121]
	v_mfma_f32_16x16x32_bf16 v[104:107], v[178:181], v[154:157], v[104:107]
	v_mfma_f32_16x16x32_bf16 v[96:99], v[186:189], v[154:157], v[96:99]
	v_mfma_f32_16x16x32_bf16 v[84:87], v[178:181], v[162:165], v[84:87]
	v_mfma_f32_16x16x32_bf16 v[80:83], v[186:189], v[162:165], v[80:83]
	v_mfma_f32_16x16x32_bf16 v[68:71], v[178:181], v[170:173], v[68:71]
	v_mfma_f32_16x16x32_bf16 v[64:67], v[186:189], v[170:173], v[64:67]
	v_mfma_f32_16x16x32_bf16 v[122:125], v[182:185], v[150:153], v[122:125]
	v_mfma_f32_16x16x32_bf16 v[118:121], v[190:193], v[150:153], v[118:121]
	v_mfma_f32_16x16x32_bf16 v[106:109], v[182:185], v[158:161], v[104:107]
	v_mfma_f32_16x16x32_bf16 v[96:99], v[190:193], v[158:161], v[96:99]
	v_mfma_f32_16x16x32_bf16 v[84:87], v[182:185], v[166:169], v[84:87]
	v_mfma_f32_16x16x32_bf16 v[80:83], v[190:193], v[166:169], v[80:83]
	v_mfma_f32_16x16x32_bf16 v[68:71], v[182:185], v[174:177], v[68:71]
	s_barrier
; #define PG8_STAGE(bufoff, gbase, voff) do { _Pragma("unroll") for (int _i = 0; _i < 2; ++_i) \
;         __builtin_amdgcn_global_load_lds((const unsigned*)((const char*)(gbase) + (voff)[_i]), (LAS unsigned*)(lds + (bufoff) + ldsw + _i * 8192), 16, 0, 0); } while (0)
; #define PG8_LDA(dst, b, h) do { _Pragma("unroll") for (int m = 0; m < 4; ++m) _Pragma("unroll") for (int k = 0; k < 2; ++k) dst[m][k] = *(const LAS bf16x8*)(lds + PG8_SA(b, h) + aoff + m * 2048 + k * 1024); } while (0)
; #define PG8_LDB(dst, b, h) do { _Pragma("unroll") for (int n = 0; n < 2; ++n) _Pragma("unroll") for (int k = 0; k < 2; ++k) dst[n][k] = *(const LAS bf16x8*)(lds + PG8_SB(b, h) + boff + n * 2048 + k * 1024); } while (0)
; #define PG8_MMA(ai, bj, At, Bt) do { __builtin_amdgcn_s_setprio(1); _Pragma("unroll") for (int m = 0; m < 4; ++m) _Pragma("unroll") for (int n = 0; n < 2; ++n) _Pragma("unroll") for (int k = 0; k < 2; ++k) \
;         acc[ai][bj][m][n] = __builtin_amdgcn_mfma_f32_16x16x32_bf16(Bt[n][k], At[m][k], acc[ai][bj][m][n], 0, 0, 0); __builtin_amdgcn_s_setprio(0); } while (0)
; #define PG8_WAIT_V(n) asm volatile("s_waitcnt vmcnt(" #n ")" ::: "memory")
; #define PG8_WAIT_L(n) asm volatile("s_waitcnt lgkmcnt(" #n ")" ::: "memory")
; #define PG8_BAR __builtin_amdgcn_s_barrier()
; #define PG8_SCHED __builtin_amdgcn_sched_barrier(0)
; #define PG8_STAGE(bufoff, gbase, voff) do { _Pragma("unroll") for (int _i = 0; _i < 2; ++_i) \
;         __builtin_amdgcn_global_load_lds((const unsigned*)((const char*)(gbase) + (voff)[_i]), (LAS unsigned*)(lds + (bufoff) + ldsw + _i * 8192), 16, 0, 0); } while (0)
; #define PG8_WAIT_V(n) asm volatile("s_waitcnt vmcnt(" #n ")" ::: "memory")
; #define PG8_WAIT_L(n) asm volatile("s_waitcnt lgkmcnt(" #n ")" ::: "memory")
; template <class Epi>
; DI void gemm_phase(LAS unsigned char* lds, const Gemm g, const StaticOrder S, const Epi E) {
;     ...
;             PG8_WAIT_L(8); PG8_BAR; PG8_WAIT_L(0); PG8_MMA(0, 0, At, B0); PG8_BAR; PG8_SCHED;
;             PG8_LDB(B1, 1, 1); PG8_STAGE(PG8_SB(1, 0), b3, voffB);
;             PG8_BAR; PG8_WAIT_L(0); PG8_MMA(0, 1, At, B1); PG8_BAR;
;             PG8_LDA(At, 1, 1); PG8_STAGE(PG8_SA(1, 0), a3, voffA);
;             PG8_BAR; PG8_WAIT_L(0); PG8_MMA(1, 0, At, B0); PG8_BAR; PG8_SCHED;
;             PG8_STAGE(PG8_SB(1, 1), b3 + hstep, voffB);
;             PG8_WAIT_V(6); PG8_BAR; PG8_MMA(1, 1, At, B1); PG8_BAR;
	v_mfma_f32_16x16x32_bf16 v[64:67], v[190:193], v[174:177], v[64:67]
	s_setprio 0
	s_mov_b32 m0, s83
	v_lshl_add_u64 v[104:105], v[220:221], 0, s[18:19]
	ds_read_b128 v[146:149], v228 offset:49152
	ds_read_b128 v[150:153], v228 offset:50176
	ds_read_b128 v[154:157], v228 offset:51200
	ds_read_b128 v[158:161], v228 offset:52224
	ds_read_b128 v[162:165], v228 offset:53248
	ds_read_b128 v[166:169], v228 offset:54272
	ds_read_b128 v[170:173], v228 offset:55296
	ds_read_b128 v[174:177], v228 offset:56320
	global_load_lds_dwordx4 v[104:105], off
	v_lshl_add_u64 v[104:105], v[232:233], 0, s[18:19]
	s_mov_b32 m0, s84
	s_nop 0
	global_load_lds_dwordx4 v[104:105], off
	s_barrier
	s_waitcnt lgkmcnt(0)
	s_setprio 1
	s_waitcnt lgkmcnt(0)
	v_mfma_f32_16x16x32_bf16 v[60:63], v[100:103], v[146:149], v[60:63]
	v_mfma_f32_16x16x32_bf16 v[56:59], v[138:141], v[146:149], v[56:59]
	v_mfma_f32_16x16x32_bf16 v[44:47], v[100:103], v[154:157], v[44:47]
	v_mfma_f32_16x16x32_bf16 v[40:43], v[138:141], v[154:157], v[40:43]
	v_mfma_f32_16x16x32_bf16 v[28:31], v[100:103], v[162:165], v[28:31]
	v_mfma_f32_16x16x32_bf16 v[24:27], v[138:141], v[162:165], v[24:27]
	v_mfma_f32_16x16x32_bf16 v[12:15], v[100:103], v[170:173], v[12:15]
	v_mfma_f32_16x16x32_bf16 v[8:11], v[138:141], v[170:173], v[8:11]
	v_mfma_f32_16x16x32_bf16 v[60:63], v[134:137], v[150:153], v[60:63]
	v_mfma_f32_16x16x32_bf16 v[56:59], v[142:145], v[150:153], v[56:59]
	v_mfma_f32_16x16x32_bf16 v[44:47], v[134:137], v[158:161], v[44:47]
	v_mfma_f32_16x16x32_bf16 v[40:43], v[142:145], v[158:161], v[40:43]
	v_mfma_f32_16x16x32_bf16 v[28:31], v[134:137], v[166:169], v[28:31]
	v_mfma_f32_16x16x32_bf16 v[24:27], v[142:145], v[166:169], v[24:27]
	v_mfma_f32_16x16x32_bf16 v[12:15], v[134:137], v[174:177], v[12:15]
	s_barrier
	v_mfma_f32_16x16x32_bf16 v[8:11], v[142:145], v[174:177], v[8:11]
	s_setprio 0
	s_add_u32 s14, s52, 0x40080
	s_addc_u32 s15, s53, 0
	s_add_i32 s35, s76, s59
	v_lshl_add_u64 v[100:101], s[14:15], 0, v[200:201]
	s_mov_b32 m0, s35
	s_nop 0
	global_load_lds_dwordx4 v[100:101], off
	v_lshl_add_u64 v[100:101], s[14:15], 0, v[204:205]
	s_add_i32 m0, s35, 0x2000
	s_nop 0
	global_load_lds_dwordx4 v[100:101], off
	s_waitcnt vmcnt(6)
	s_barrier
	s_setprio 1
	v_mfma_f32_16x16x32_bf16 v[52:55], v[178:181], v[146:149], v[52:55]
	v_mfma_f32_16x16x32_bf16 v[48:51], v[186:189], v[146:149], v[48:51]
	v_mfma_f32_16x16x32_bf16 v[36:39], v[178:181], v[154:157], v[36:39]
	v_mfma_f32_16x16x32_bf16 v[32:35], v[186:189], v[154:157], v[32:35]
	v_mfma_f32_16x16x32_bf16 v[20:23], v[178:181], v[162:165], v[20:23]
	v_mfma_f32_16x16x32_bf16 v[16:19], v[186:189], v[162:165], v[16:19]
	v_mfma_f32_16x16x32_bf16 v[4:7], v[178:181], v[170:173], v[4:7]
	v_mfma_f32_16x16x32_bf16 v[0:3], v[186:189], v[170:173], v[0:3]
	v_mfma_f32_16x16x32_bf16 v[52:55], v[182:185], v[150:153], v[52:55]
	v_mfma_f32_16x16x32_bf16 v[48:51], v[190:193], v[150:153], v[48:51]
	v_mfma_f32_16x16x32_bf16 v[36:39], v[182:185], v[158:161], v[36:39]
	v_mfma_f32_16x16x32_bf16 v[32:35], v[190:193], v[158:161], v[32:35]
	v_mfma_f32_16x16x32_bf16 v[20:23], v[182:185], v[166:169], v[20:23]
	v_mfma_f32_16x16x32_bf16 v[16:19], v[190:193], v[166:169], v[16:19]
	v_mfma_f32_16x16x32_bf16 v[4:7], v[182:185], v[174:177], v[4:7]
	s_barrier
	v_mfma_f32_16x16x32_bf16 v[0:3], v[190:193], v[174:177], v[0:3]
	s_setprio 0
	s_add_i32 s95, s95, 2
	s_add_u32 s8, s8, 0x100
	s_addc_u32 s9, s9, 0
	s_add_u32 s23, s23, 0x100
	s_addc_u32 s94, s94, 0
	s_cmp_gt_u32 s95, 13
	s_cbranch_scc0 .LBB0_274
;     DI void operator()(AccRef acc, const Unit& u, int wr, int wc, int fr, int fq) const {
;         const int X = u.pn >> 2, h = u.pn & 3, isk = wc >> 1, i0 = (wc & 1) * 32 + 8 * fq;
;         bf16_t* dst = (X ? qkoB : qkoA) + h * 256 + isk * 128 + i0;
;         const float qs0 = isk ? 1.0f : 0.08838834764831845f;
;         const int row0 = u.pm * 256 + wr * 64 + fr;
;         const RowScales rsc = load_rowscales(ss, row0);
; #pragma unroll
;         for (int ai = 0; ai < 2; ++ai) {
;             f32x4 cs[4][2], sn[4][2];
;             if (X == 0) {
; #pragma unroll
;                 for (int m = 0; m < 4; ++m) {
;                     const int pos = (row0 + ai * 128 + m * 16) & (SEQ - 1);
;                     cs[m][0] = *(const f32x4*)(cosT + pos * 64 + i0); cs[m][1] = *(const f32x4*)(cosT + pos * 64 + i0 + 4);
;                     sn[m][0] = *(const f32x4*)(sinT + pos * 64 + i0); sn[m][1] = *(const f32x4*)(sinT + pos * 64 + i0 + 4);
;                 }
;             } else {
; #pragma unroll
;                 for (int m = 0; m < 4; ++m) { cs[m][0] = cs[m][1] = (f32x4){1.f, 1.f, 1.f, 1.f}; sn[m][0] = sn[m][1] = (f32x4){0.f, 0.f, 0.f, 0.f}; }
;             }
	v_lshl_add_u32 v102, s0, 8, v224
	v_ashrrev_i32_e32 v103, 31, v102
	v_lshl_add_u64 v[134:135], v[102:103], 2, s[60:61]
	global_load_dword v237, v[134:135], off
	global_load_dword v236, v[134:135], off offset:64
	global_load_dword v105, v[134:135], off offset:128
	global_load_dword v101, v[134:135], off offset:192
	global_load_dword v231, v[134:135], off offset:512
	global_load_dword v232, v[134:135], off offset:576
	global_load_dword v233, v[134:135], off offset:640
	global_load_dword v234, v[134:135], off offset:704
	s_cmp_lt_u32 s93, 4
	s_cselect_b64 s[0:1], -1, 0
	s_cmp_gt_u32 s93, 3
	v_lshlrev_b32_e32 v235, 6, v102
	v_mov_b32_e32 v100, 1.0
	v_mov_b32_e32 v104, 0
	v_mov_b32_e32 v134, 0
	v_mov_b32_e32 v135, 0
	v_mov_b32_e32 v136, 0
	v_mov_b32_e32 v137, 0
	v_mov_b32_e32 v142, 0
	v_mov_b32_e32 v143, 0
	v_mov_b32_e32 v144, 0
	v_mov_b32_e32 v145, 0
	v_mov_b32_e32 v146, 0
	v_mov_b32_e32 v147, 0
	v_mov_b32_e32 v148, 0
	v_mov_b32_e32 v149, 0
	v_mov_b32_e32 v154, 0
	v_mov_b32_e32 v155, 0
	v_mov_b32_e32 v156, 0
	v_mov_b32_e32 v157, 0
	v_mov_b32_e32 v162, 0
	v_mov_b32_e32 v163, 0
	v_mov_b32_e32 v164, 0
	v_mov_b32_e32 v165, 0
	v_mov_b32_e32 v174, 0
	v_mov_b32_e32 v175, 0
	v_mov_b32_e32 v176, 0
	v_mov_b32_e32 v177, 0
	v_mov_b32_e32 v182, 0
	v_mov_b32_e32 v183, 0
	v_mov_b32_e32 v184, 0
	v_mov_b32_e32 v185, 0
	v_mov_b32_e32 v194, 0
	v_mov_b32_e32 v195, 0
	v_mov_b32_e32 v196, 0
	v_mov_b32_e32 v197, 0
	v_mov_b32_e32 v138, 1.0
	v_mov_b32_e32 v139, 1.0
	v_mov_b32_e32 v140, 1.0
	v_mov_b32_e32 v141, 1.0
	v_mov_b32_e32 v190, 1.0
	v_mov_b32_e32 v191, 1.0
	v_mov_b32_e32 v192, 1.0
	v_mov_b32_e32 v193, 1.0
	v_mov_b32_e32 v186, 1.0
	v_mov_b32_e32 v187, 1.0
	v_mov_b32_e32 v188, 1.0
	v_mov_b32_e32 v189, 1.0
	v_mov_b32_e32 v178, 1.0
	v_mov_b32_e32 v179, 1.0
	v_mov_b32_e32 v180, 1.0
	v_mov_b32_e32 v181, 1.0
	v_mov_b32_e32 v170, 1.0
	v_mov_b32_e32 v171, 1.0
	v_mov_b32_e32 v172, 1.0
	v_mov_b32_e32 v173, 1.0
	v_mov_b32_e32 v166, 1.0
	v_mov_b32_e32 v167, 1.0
	v_mov_b32_e32 v168, 1.0
	v_mov_b32_e32 v169, 1.0
	v_mov_b32_e32 v158, 1.0
	v_mov_b32_e32 v159, 1.0
	v_mov_b32_e32 v160, 1.0
	v_mov_b32_e32 v161, 1.0
	v_mov_b32_e32 v150, 1.0
	v_mov_b32_e32 v151, 1.0
	v_mov_b32_e32 v152, 1.0
	v_mov_b32_e32 v153, 1.0
	s_cbranch_scc1 .LBB0_277
	v_lshlrev_b32_e32 v134, 2, v235
	v_and_b32_e32 v134, 0x1fcf00, v134
	v_mov_b32_e32 v135, v207
	v_lshl_add_u64 v[136:137], v[208:209], 0, v[134:135]
	global_load_dwordx4 v[190:193], v[136:137], off
	global_load_dwordx4 v[186:189], v[136:137], off offset:16
	v_lshl_add_u64 v[136:137], v[210:211], 0, v[134:135]
	global_load_dwordx4 v[182:185], v[136:137], off offset:16
	global_load_dwordx4 v[194:197], v[136:137], off
	v_or_b32_e32 v136, 0x1000, v134
	v_mov_b32_e32 v137, v207
	v_lshl_add_u64 v[138:139], v[208:209], 0, v[136:137]
	v_lshl_add_u64 v[136:137], v[210:211], 0, v[136:137]
	global_load_dwordx4 v[178:181], v[138:139], off
	global_load_dwordx4 v[170:173], v[138:139], off offset:16
	global_load_dwordx4 v[162:165], v[136:137], off offset:16
	global_load_dwordx4 v[174:177], v[136:137], off
	v_or_b32_e32 v136, 0x2000, v134
	v_mov_b32_e32 v137, v207
	v_lshl_add_u64 v[138:139], v[208:209], 0, v[136:137]
	v_lshl_add_u64 v[136:137], v[210:211], 0, v[136:137]
	v_or_b32_e32 v134, 0x3000, v134
	global_load_dwordx4 v[166:169], v[138:139], off
	global_load_dwordx4 v[158:161], v[138:139], off offset:16
	global_load_dwordx4 v[146:149], v[136:137], off offset:16
	global_load_dwordx4 v[154:157], v[136:137], off
	v_lshl_add_u64 v[136:137], v[208:209], 0, v[134:135]
	v_lshl_add_u64 v[142:143], v[210:211], 0, v[134:135]
	global_load_dwordx4 v[138:141], v[136:137], off offset:16
	global_load_dwordx4 v[150:153], v[136:137], off
	s_nop 0
	global_load_dwordx4 v[134:137], v[142:143], off offset:16
	s_nop 0
	global_load_dwordx4 v[142:145], v[142:143], off

; #define PG8_STAGE(bufoff, gbase, voff) do { _Pragma("unroll") for (int _i = 0; _i < 2; ++_i) \
;         __builtin_amdgcn_global_load_lds((const unsigned*)((const char*)(gbase) + (voff)[_i]), (LAS unsigned*)(lds + (bufoff) + ldsw + _i * 8192), 16, 0, 0); } while (0)
; #define PG8_LDA(dst, b, h) do { _Pragma("unroll") for (int m = 0; m < 4; ++m) _Pragma("unroll") for (int k = 0; k < 2; ++k) dst[m][k] = *(const LAS bf16x8*)(lds + PG8_SA(b, h) + aoff + m * 2048 + k * 1024); } while (0)
; #define PG8_LDB(dst, b, h) do { _Pragma("unroll") for (int n = 0; n < 2; ++n) _Pragma("unroll") for (int k = 0; k < 2; ++k) dst[n][k] = *(const LAS bf16x8*)(lds + PG8_SB(b, h) + boff + n * 2048 + k * 1024); } while (0)
; #define PG8_MMA(ai, bj, At, Bt) do { __builtin_amdgcn_s_setprio(1); _Pragma("unroll") for (int m = 0; m < 4; ++m) _Pragma("unroll") for (int n = 0; n < 2; ++n) _Pragma("unroll") for (int k = 0; k < 2; ++k) \
;         acc[ai][bj][m][n] = __builtin_amdgcn_mfma_f32_16x16x32_bf16(Bt[n][k], At[m][k], acc[ai][bj][m][n], 0, 0, 0); __builtin_amdgcn_s_setprio(0); } while (0)
; #define PG8_WAIT_L(n) asm volatile("s_waitcnt lgkmcnt(" #n ")" ::: "memory")
; #define PG8_BAR __builtin_amdgcn_s_barrier()
; #define PG8_SCHED __builtin_amdgcn_sched_barrier(0)
; #define PG8_STAGE(bufoff, gbase, voff) do { _Pragma("unroll") for (int _i = 0; _i < 2; ++_i) \
;         __builtin_amdgcn_global_load_lds((const unsigned*)((const char*)(gbase) + (voff)[_i]), (LAS unsigned*)(lds + (bufoff) + ldsw + _i * 8192), 16, 0, 0); } while (0)
; #define PG8_LDA(dst, b, h) do { _Pragma("unroll") for (int m = 0; m < 4; ++m) _Pragma("unroll") for (int k = 0; k < 2; ++k) dst[m][k] = *(const LAS bf16x8*)(lds + PG8_SA(b, h) + aoff + m * 2048 + k * 1024); } while (0)
; template <class Epi>
; DI void gemm_phase(LAS unsigned char* lds, const Gemm g, const StaticOrder S, const Epi E) {
;     ...
;             PG8_LDB(B0, 0, 0); PG8_SCHED; PG8_LDA(At, 0, 0); PG8_STAGE(PG8_SA(1, 1), a1 + hstep, voffA);
;             PG8_WAIT_L(8); PG8_BAR; PG8_WAIT_L(0); PG8_MMA(0, 0, At, B0); PG8_BAR; PG8_SCHED;
;             PG8_LDB(B1, 0, 1); PG8_STAGE(PG8_SB(0, 0), b2, voffB);
;             PG8_BAR; PG8_WAIT_L(0); PG8_MMA(0, 1, At, B1); PG8_BAR;
;             PG8_LDA(At, 0, 1); PG8_STAGE(PG8_SA(0, 0), a2, voffA);
;             PG8_BAR; PG8_WAIT_L(0); PG8_MMA(1, 0, At, B0); PG8_BAR; PG8_SCHED;
.LBB0_298:
	ds_read_b128 v[128:131], v168
	ds_read_b128 v[132:135], v168 offset:1024
	ds_read_b128 v[154:157], v168 offset:2048
	ds_read_b128 v[158:161], v168 offset:3072
	s_add_u32 s5, s8, 0xfffc0080
	s_addc_u32 s14, s9, -1
	s_cmp_eq_u32 s4, 12
	s_cselect_b32 s81, s6, s14
	s_cselect_b32 s80, s7, s5
	s_cselect_b32 s79, s21, vcc_hi
	s_cselect_b32 s78, s23, vcc_lo
	v_lshl_add_u64 v[162:163], s[8:9], 0, v[146:147]
	s_add_i32 m0, s58, 0xc000
	ds_read_b128 v[172:175], v169
	ds_read_b128 v[176:179], v169 offset:1024
	ds_read_b128 v[180:183], v169 offset:2048
	ds_read_b128 v[184:187], v169 offset:3072
	ds_read_b128 v[188:191], v169 offset:4096
	ds_read_b128 v[192:195], v169 offset:5120
	ds_read_b128 v[196:199], v169 offset:6144
	ds_read_b128 v[200:203], v169 offset:7168
	global_load_lds_dwordx4 v[162:163], off
	v_lshl_add_u64 v[162:163], s[8:9], 0, v[148:149]
	s_add_i32 m0, s58, 0xe000
	s_nop 0
	global_load_lds_dwordx4 v[162:163], off
	s_waitcnt lgkmcnt(8)
	s_barrier
	s_waitcnt lgkmcnt(0)
	s_setprio 1
	s_waitcnt lgkmcnt(0)
	v_mfma_f32_16x16x32_bf16 v[124:127], v[128:131], v[172:175], v[124:127]
	v_mfma_f32_16x16x32_bf16 v[120:123], v[154:157], v[172:175], v[120:123]
	v_mfma_f32_16x16x32_bf16 v[112:115], v[128:131], v[180:183], v[112:115]
	v_mfma_f32_16x16x32_bf16 v[104:107], v[154:157], v[180:183], v[104:107]
	v_mfma_f32_16x16x32_bf16 v[96:99], v[128:131], v[188:191], v[96:99]
	v_mfma_f32_16x16x32_bf16 v[88:91], v[154:157], v[188:191], v[88:91]
	v_mfma_f32_16x16x32_bf16 v[80:83], v[128:131], v[196:199], v[80:83]
	v_mfma_f32_16x16x32_bf16 v[72:75], v[154:157], v[196:199], v[72:75]
	v_mfma_f32_16x16x32_bf16 v[124:127], v[132:135], v[176:179], v[124:127]
	v_mfma_f32_16x16x32_bf16 v[120:123], v[158:161], v[176:179], v[120:123]
	v_mfma_f32_16x16x32_bf16 v[112:115], v[132:135], v[184:187], v[112:115]
	v_mfma_f32_16x16x32_bf16 v[104:107], v[158:161], v[184:187], v[104:107]
	v_mfma_f32_16x16x32_bf16 v[96:99], v[132:135], v[192:195], v[96:99]
	v_mfma_f32_16x16x32_bf16 v[88:91], v[158:161], v[192:195], v[88:91]
	v_mfma_f32_16x16x32_bf16 v[80:83], v[132:135], v[200:203], v[80:83]
	s_barrier
	v_mfma_f32_16x16x32_bf16 v[72:75], v[158:161], v[200:203], v[72:75]
	s_setprio 0
	s_add_i32 s5, s94, s19
	v_lshl_add_u64 v[162:163], s[78:79], 0, v[138:139]
	s_mov_b32 m0, s5
	ds_read_b128 v[204:207], v170
	ds_read_b128 v[208:211], v170 offset:1024
	ds_read_b128 v[212:215], v170 offset:2048
	ds_read_b128 v[216:219], v170 offset:3072
	global_load_lds_dwordx4 v[162:163], off
	v_lshl_add_u64 v[220:221], s[78:79], 0, v[142:143]
	s_add_i32 m0, s5, 0x2000
	s_nop 0
	global_load_lds_dwordx4 v[220:221], off
	s_barrier
	s_waitcnt lgkmcnt(0)
	s_setprio 1
	s_waitcnt lgkmcnt(0)
	v_mfma_f32_16x16x32_bf16 v[116:119], v[204:207], v[172:175], v[116:119]
	v_mfma_f32_16x16x32_bf16 v[108:111], v[212:215], v[172:175], v[108:111]
	v_mfma_f32_16x16x32_bf16 v[100:103], v[204:207], v[180:183], v[100:103]
	v_mfma_f32_16x16x32_bf16 v[92:95], v[212:215], v[180:183], v[92:95]
	v_mfma_f32_16x16x32_bf16 v[84:87], v[204:207], v[188:191], v[84:87]
	v_mfma_f32_16x16x32_bf16 v[76:79], v[212:215], v[188:191], v[76:79]
	v_mfma_f32_16x16x32_bf16 v[68:71], v[204:207], v[196:199], v[68:71]
	v_mfma_f32_16x16x32_bf16 v[64:67], v[212:215], v[196:199], v[64:67]
	v_mfma_f32_16x16x32_bf16 v[116:119], v[208:211], v[176:179], v[116:119]
	v_mfma_f32_16x16x32_bf16 v[108:111], v[216:219], v[176:179], v[108:111]
	v_mfma_f32_16x16x32_bf16 v[100:103], v[208:211], v[184:187], v[100:103]
	v_mfma_f32_16x16x32_bf16 v[92:95], v[216:219], v[184:187], v[92:95]
	v_mfma_f32_16x16x32_bf16 v[84:87], v[208:211], v[192:195], v[84:87]
	v_mfma_f32_16x16x32_bf16 v[76:79], v[216:219], v[192:195], v[76:79]
	v_mfma_f32_16x16x32_bf16 v[68:71], v[208:211], v[200:203], v[68:71]
	s_barrier
	v_mfma_f32_16x16x32_bf16 v[64:67], v[216:219], v[200:203], v[64:67]
	s_setprio 0
	s_mov_b32 m0, s58
	v_lshl_add_u64 v[224:225], s[80:81], 0, v[136:137]
	ds_read_b128 v[172:175], v169 offset:16384
	ds_read_b128 v[176:179], v169 offset:17408
	ds_read_b128 v[180:183], v169 offset:18432
	ds_read_b128 v[184:187], v169 offset:19456
	ds_read_b128 v[188:191], v169 offset:20480
	ds_read_b128 v[192:195], v169 offset:21504
	ds_read_b128 v[196:199], v169 offset:22528
	ds_read_b128 v[200:203], v169 offset:23552
	global_load_lds_dwordx4 v[224:225], off
	v_lshl_add_u64 v[226:227], s[80:81], 0, v[140:141]
	s_mov_b32 m0, s59
	s_nop 0
	global_load_lds_dwordx4 v[226:227], off
	s_barrier
	s_waitcnt lgkmcnt(0)
	s_setprio 1
	s_waitcnt lgkmcnt(0)
	v_mfma_f32_16x16x32_bf16 v[60:63], v[128:131], v[172:175], v[60:63]
	v_mfma_f32_16x16x32_bf16 v[56:59], v[154:157], v[172:175], v[56:59]
	v_mfma_f32_16x16x32_bf16 v[48:51], v[128:131], v[180:183], v[48:51]
	v_mfma_f32_16x16x32_bf16 v[40:43], v[154:157], v[180:183], v[40:43]
	v_mfma_f32_16x16x32_bf16 v[32:35], v[128:131], v[188:191], v[32:35]
	v_mfma_f32_16x16x32_bf16 v[24:27], v[154:157], v[188:191], v[24:27]
	v_mfma_f32_16x16x32_bf16 v[16:19], v[128:131], v[196:199], v[16:19]
	v_mfma_f32_16x16x32_bf16 v[8:11], v[154:157], v[196:199], v[8:11]
	v_mfma_f32_16x16x32_bf16 v[60:63], v[132:135], v[176:179], v[60:63]
	v_mfma_f32_16x16x32_bf16 v[56:59], v[158:161], v[176:179], v[56:59]
	v_mfma_f32_16x16x32_bf16 v[48:51], v[132:135], v[184:187], v[48:51]
	v_mfma_f32_16x16x32_bf16 v[40:43], v[158:161], v[184:187], v[40:43]
	v_mfma_f32_16x16x32_bf16 v[32:35], v[132:135], v[192:195], v[32:35]
	v_mfma_f32_16x16x32_bf16 v[24:27], v[158:161], v[192:195], v[24:27]
	v_mfma_f32_16x16x32_bf16 v[16:19], v[132:135], v[200:203], v[16:19]
	s_barrier
; #define PG8_STAGE(bufoff, gbase, voff) do { _Pragma("unroll") for (int _i = 0; _i < 2; ++_i) \
;         __builtin_amdgcn_global_load_lds((const unsigned*)((const char*)(gbase) + (voff)[_i]), (LAS unsigned*)(lds + (bufoff) + ldsw + _i * 8192), 16, 0, 0); } while (0)
; #define PG8_LDA(dst, b, h) do { _Pragma("unroll") for (int m = 0; m < 4; ++m) _Pragma("unroll") for (int k = 0; k < 2; ++k) dst[m][k] = *(const LAS bf16x8*)(lds + PG8_SA(b, h) + aoff + m * 2048 + k * 1024); } while (0)
; #define PG8_LDB(dst, b, h) do { _Pragma("unroll") for (int n = 0; n < 2; ++n) _Pragma("unroll") for (int k = 0; k < 2; ++k) dst[n][k] = *(const LAS bf16x8*)(lds + PG8_SB(b, h) + boff + n * 2048 + k * 1024); } while (0)
; #define PG8_MMA(ai, bj, At, Bt) do { __builtin_amdgcn_s_setprio(1); _Pragma("unroll") for (int m = 0; m < 4; ++m) _Pragma("unroll") for (int n = 0; n < 2; ++n) _Pragma("unroll") for (int k = 0; k < 2; ++k) \
;         acc[ai][bj][m][n] = __builtin_amdgcn_mfma_f32_16x16x32_bf16(Bt[n][k], At[m][k], acc[ai][bj][m][n], 0, 0, 0); __builtin_amdgcn_s_setprio(0); } while (0)
; #define PG8_WAIT_V(n) asm volatile("s_waitcnt vmcnt(" #n ")" ::: "memory")
; #define PG8_WAIT_L(n) asm volatile("s_waitcnt lgkmcnt(" #n ")" ::: "memory")
; #define PG8_BAR __builtin_amdgcn_s_barrier()
; #define PG8_SCHED __builtin_amdgcn_sched_barrier(0)
; #define PG8_STAGE(bufoff, gbase, voff) do { _Pragma("unroll") for (int _i = 0; _i < 2; ++_i) \
;         __builtin_amdgcn_global_load_lds((const unsigned*)((const char*)(gbase) + (voff)[_i]), (LAS unsigned*)(lds + (bufoff) + ldsw + _i * 8192), 16, 0, 0); } while (0)
; #define PG8_LDA(dst, b, h) do { _Pragma("unroll") for (int m = 0; m < 4; ++m) _Pragma("unroll") for (int k = 0; k < 2; ++k) dst[m][k] = *(const LAS bf16x8*)(lds + PG8_SA(b, h) + aoff + m * 2048 + k * 1024); } while (0)
; template <class Epi>
; DI void gemm_phase(LAS unsigned char* lds, const Gemm g, const StaticOrder S, const Epi E) {
;     ...
;             PG8_BAR; PG8_WAIT_L(0); PG8_MMA(1, 0, At, B0); PG8_BAR; PG8_SCHED;
;             PG8_STAGE(PG8_SB(0, 1), b2 + hstep, voffB);
;             PG8_WAIT_V(6); PG8_BAR; PG8_MMA(1, 1, At, B1); PG8_BAR;
;             PG8_LDB(B0, 1, 0); PG8_SCHED; PG8_LDA(At, 1, 0); PG8_STAGE(PG8_SA(0, 1), a2 + hstep, voffA);
;             PG8_WAIT_L(8); PG8_BAR; PG8_WAIT_L(0); PG8_MMA(0, 0, At, B0); PG8_BAR; PG8_SCHED;
	v_mfma_f32_16x16x32_bf16 v[8:11], v[158:161], v[200:203], v[8:11]
	s_setprio 0
	s_add_u32 s14, s78, 0x40000
	s_addc_u32 s15, s79, 0
	s_add_i32 s5, s95, s19
	v_lshl_add_u64 v[128:129], s[14:15], 0, v[138:139]
	s_mov_b32 m0, s5
	s_nop 0
	global_load_lds_dwordx4 v[128:129], off
	v_lshl_add_u64 v[128:129], s[14:15], 0, v[142:143]
	s_add_i32 m0, s5, 0x2000
	s_nop 0
	global_load_lds_dwordx4 v[128:129], off
	s_waitcnt vmcnt(6)
	s_barrier
	s_setprio 1
	v_mfma_f32_16x16x32_bf16 v[52:55], v[204:207], v[172:175], v[52:55]
	v_mfma_f32_16x16x32_bf16 v[44:47], v[212:215], v[172:175], v[44:47]
	v_mfma_f32_16x16x32_bf16 v[36:39], v[204:207], v[180:183], v[36:39]
	v_mfma_f32_16x16x32_bf16 v[28:31], v[212:215], v[180:183], v[28:31]
	v_mfma_f32_16x16x32_bf16 v[20:23], v[204:207], v[188:191], v[20:23]
	v_mfma_f32_16x16x32_bf16 v[12:15], v[212:215], v[188:191], v[12:15]
	v_mfma_f32_16x16x32_bf16 v[4:7], v[204:207], v[196:199], v[4:7]
	v_mfma_f32_16x16x32_bf16 v[0:3], v[212:215], v[196:199], v[0:3]
	v_mfma_f32_16x16x32_bf16 v[52:55], v[208:211], v[176:179], v[52:55]
	v_mfma_f32_16x16x32_bf16 v[44:47], v[216:219], v[176:179], v[44:47]
	v_mfma_f32_16x16x32_bf16 v[36:39], v[208:211], v[184:187], v[36:39]
	v_mfma_f32_16x16x32_bf16 v[28:31], v[216:219], v[184:187], v[28:31]
	v_mfma_f32_16x16x32_bf16 v[20:23], v[208:211], v[192:195], v[20:23]
	v_mfma_f32_16x16x32_bf16 v[12:15], v[216:219], v[192:195], v[12:15]
	v_mfma_f32_16x16x32_bf16 v[4:7], v[208:211], v[200:203], v[4:7]
	s_barrier
	v_mfma_f32_16x16x32_bf16 v[0:3], v[216:219], v[200:203], v[0:3]
	s_setprio 0
	s_add_i32 s5, 0, 0x18000
	v_add_u32_e32 v158, s5, v165
	ds_read_b128 v[128:131], v158
	ds_read_b128 v[132:135], v158 offset:1024
	ds_read_b128 v[154:157], v158 offset:2048
	ds_read_b128 v[158:161], v158 offset:3072
	s_add_u32 s14, s80, 0x40000
	s_addc_u32 s15, s81, 0
	s_mov_b32 m0, s77
	v_lshl_add_u64 v[204:205], s[14:15], 0, v[136:137]
	ds_read_b128 v[172:175], v169 offset:32768
	ds_read_b128 v[176:179], v169 offset:33792
	ds_read_b128 v[180:183], v169 offset:34816
	ds_read_b128 v[184:187], v169 offset:35840
	ds_read_b128 v[188:191], v169 offset:36864
	ds_read_b128 v[192:195], v169 offset:37888
	ds_read_b128 v[196:199], v169 offset:38912
	ds_read_b128 v[200:203], v169 offset:39936
	global_load_lds_dwordx4 v[204:205], off
	v_lshl_add_u64 v[204:205], s[14:15], 0, v[140:141]
	s_mov_b32 m0, s82
	s_nop 0
	global_load_lds_dwordx4 v[204:205], off
	s_waitcnt lgkmcnt(8)
	s_barrier
	s_waitcnt lgkmcnt(0)
	s_setprio 1
	s_waitcnt lgkmcnt(0)
	v_mfma_f32_16x16x32_bf16 v[124:127], v[128:131], v[172:175], v[124:127]
	v_mfma_f32_16x16x32_bf16 v[120:123], v[154:157], v[172:175], v[120:123]
	v_mfma_f32_16x16x32_bf16 v[112:115], v[128:131], v[180:183], v[112:115]
	v_mfma_f32_16x16x32_bf16 v[104:107], v[154:157], v[180:183], v[104:107]
	v_mfma_f32_16x16x32_bf16 v[96:99], v[128:131], v[188:191], v[96:99]
	v_mfma_f32_16x16x32_bf16 v[88:91], v[154:157], v[188:191], v[88:91]
	v_mfma_f32_16x16x32_bf16 v[80:83], v[128:131], v[196:199], v[80:83]
	v_mfma_f32_16x16x32_bf16 v[72:75], v[154:157], v[196:199], v[72:75]
	v_mfma_f32_16x16x32_bf16 v[124:127], v[132:135], v[176:179], v[124:127]
	v_mfma_f32_16x16x32_bf16 v[120:123], v[158:161], v[176:179], v[120:123]
	v_mfma_f32_16x16x32_bf16 v[112:115], v[132:135], v[184:187], v[112:115]
	v_mfma_f32_16x16x32_bf16 v[104:107], v[158:161], v[184:187], v[104:107]
	v_mfma_f32_16x16x32_bf16 v[96:99], v[132:135], v[192:195], v[96:99]
	v_mfma_f32_16x16x32_bf16 v[88:91], v[158:161], v[192:195], v[88:91]
	v_mfma_f32_16x16x32_bf16 v[80:83], v[132:135], v[200:203], v[80:83]
	s_barrier
	v_mfma_f32_16x16x32_bf16 v[72:75], v[158:161], v[200:203], v[72:75]
	s_setprio 0
	s_add_i32 s35, 0, 0x1c000
	s_add_i32 s5, s5, s19
	v_add_u32_e32 v171, s35, v165
	v_lshl_add_u64 v[162:163], v[162:163], 0, s[10:11]
	s_mov_b32 m0, s5
	ds_read_b128 v[204:207], v171
	ds_read_b128 v[208:211], v171 offset:1024
	ds_read_b128 v[212:215], v171 offset:2048
	ds_read_b128 v[216:219], v171 offset:3072
	global_load_lds_dwordx4 v[162:163], off
	v_lshl_add_u64 v[162:163], v[220:221], 0, s[10:11]
	s_add_i32 m0, s5, 0x2000
	s_nop 0
	global_load_lds_dwordx4 v[162:163], off
	s_barrier
	s_waitcnt lgkmcnt(0)
	s_setprio 1
	s_waitcnt lgkmcnt(0)
	v_mfma_f32_16x16x32_bf16 v[116:119], v[204:207], v[172:175], v[116:119]
	v_mfma_f32_16x16x32_bf16 v[108:111], v[212:215], v[172:175], v[108:111]
	v_mfma_f32_16x16x32_bf16 v[100:103], v[204:207], v[180:183], v[100:103]
	v_mfma_f32_16x16x32_bf16 v[92:95], v[212:215], v[180:183], v[92:95]
	v_mfma_f32_16x16x32_bf16 v[84:87], v[204:207], v[188:191], v[84:87]
	v_mfma_f32_16x16x32_bf16 v[76:79], v[212:215], v[188:191], v[76:79]
	v_mfma_f32_16x16x32_bf16 v[68:71], v[204:207], v[196:199], v[68:71]
	v_mfma_f32_16x16x32_bf16 v[64:67], v[212:215], v[196:199], v[64:67]
	v_mfma_f32_16x16x32_bf16 v[116:119], v[208:211], v[176:179], v[116:119]
	v_mfma_f32_16x16x32_bf16 v[108:111], v[216:219], v[176:179], v[108:111]
	v_mfma_f32_16x16x32_bf16 v[100:103], v[208:211], v[184:187], v[100:103]
	v_mfma_f32_16x16x32_bf16 v[92:95], v[216:219], v[184:187], v[92:95]
	v_mfma_f32_16x16x32_bf16 v[84:87], v[208:211], v[192:195], v[84:87]
	v_mfma_f32_16x16x32_bf16 v[76:79], v[216:219], v[192:195], v[76:79]
	v_mfma_f32_16x16x32_bf16 v[68:71], v[208:211], v[200:203], v[68:71]
	s_barrier
	v_mfma_f32_16x16x32_bf16 v[64:67], v[216:219], v[200:203], v[64:67]
	s_setprio 0
	s_mov_b32 m0, s86
	v_lshl_add_u64 v[162:163], v[224:225], 0, s[10:11]
	ds_read_b128 v[172:175], v169 offset:49152
	ds_read_b128 v[176:179], v169 offset:50176
	ds_read_b128 v[180:183], v169 offset:51200
	ds_read_b128 v[184:187], v169 offset:52224
	ds_read_b128 v[188:191], v169 offset:53248
	ds_read_b128 v[192:195], v169 offset:54272
	ds_read_b128 v[196:199], v169 offset:55296
	ds_read_b128 v[200:203], v169 offset:56320
	global_load_lds_dwordx4 v[162:163], off
	v_lshl_add_u64 v[162:163], v[226:227], 0, s[10:11]
	s_mov_b32 m0, s87
	s_nop 0
	global_load_lds_dwordx4 v[162:163], off
	s_barrier
; #define PG8_STAGE(bufoff, gbase, voff) do { _Pragma("unroll") for (int _i = 0; _i < 2; ++_i) \
;         __builtin_amdgcn_global_load_lds((const unsigned*)((const char*)(gbase) + (voff)[_i]), (LAS unsigned*)(lds + (bufoff) + ldsw + _i * 8192), 16, 0, 0); } while (0)
; #define PG8_LDA(dst, b, h) do { _Pragma("unroll") for (int m = 0; m < 4; ++m) _Pragma("unroll") for (int k = 0; k < 2; ++k) dst[m][k] = *(const LAS bf16x8*)(lds + PG8_SA(b, h) + aoff + m * 2048 + k * 1024); } while (0)
; #define PG8_LDB(dst, b, h) do { _Pragma("unroll") for (int n = 0; n < 2; ++n) _Pragma("unroll") for (int k = 0; k < 2; ++k) dst[n][k] = *(const LAS bf16x8*)(lds + PG8_SB(b, h) + boff + n * 2048 + k * 1024); } while (0)
; #define PG8_MMA(ai, bj, At, Bt) do { __builtin_amdgcn_s_setprio(1); _Pragma("unroll") for (int m = 0; m < 4; ++m) _Pragma("unroll") for (int n = 0; n < 2; ++n) _Pragma("unroll") for (int k = 0; k < 2; ++k) \
;         acc[ai][bj][m][n] = __builtin_amdgcn_mfma_f32_16x16x32_bf16(Bt[n][k], At[m][k], acc[ai][bj][m][n], 0, 0, 0); __builtin_amdgcn_s_setprio(0); } while (0)
; #define PG8_WAIT_V(n) asm volatile("s_waitcnt vmcnt(" #n ")" ::: "memory")
; template <class Epi>
; DI void gemm_phase(LAS unsigned char* lds, const Gemm g, const StaticOrder S, const Epi E) {
;     ...
;             PG8_WAIT_L(8); PG8_BAR; PG8_WAIT_L(0); PG8_MMA(0, 0, At, B0); PG8_BAR; PG8_SCHED;
;             PG8_LDB(B1, 1, 1); PG8_STAGE(PG8_SB(1, 0), b3, voffB);
;             PG8_BAR; PG8_WAIT_L(0); PG8_MMA(0, 1, At, B1); PG8_BAR;
;             PG8_LDA(At, 1, 1); PG8_STAGE(PG8_SA(1, 0), a3, voffA);
;             PG8_BAR; PG8_WAIT_L(0); PG8_MMA(1, 0, At, B0); PG8_BAR; PG8_SCHED;
;             PG8_STAGE(PG8_SB(1, 1), b3 + hstep, voffB);
;             PG8_WAIT_V(6); PG8_BAR; PG8_MMA(1, 1, At, B1); PG8_BAR;
;     DI void operator()(AccRef acc, const Unit& u, int wr, int wc, int fr, int fq) const {
;         f32x4 ts[2][2];
; #pragma unroll
;         for (int bj = 0; bj < 2; ++bj) { const int tok = u.pn * 256 + bj * 128 + wc * 32 + 8 * fq; ts[bj][0] = *(const f32x4*)(ss + tok); ts[bj][1] = *(const f32x4*)(ss + tok + 4); }
; #pragma unroll
;         for (int bj = 0; bj < 2; ++bj)
; #pragma unroll
;             for (int n = 0; n < 2; ++n)
; #pragma unroll
;                 for (int e = 0; e < 4; ++e) ts[bj][n][e] = rsqrtf(ts[bj][n][e] * (1.0f / 1024.0f) + 1e-6f);
	s_waitcnt lgkmcnt(0)
	s_setprio 1
	s_waitcnt lgkmcnt(0)
	v_mfma_f32_16x16x32_bf16 v[60:63], v[128:131], v[172:175], v[60:63]
	v_mfma_f32_16x16x32_bf16 v[56:59], v[154:157], v[172:175], v[56:59]
	v_mfma_f32_16x16x32_bf16 v[48:51], v[128:131], v[180:183], v[48:51]
	v_mfma_f32_16x16x32_bf16 v[40:43], v[154:157], v[180:183], v[40:43]
	v_mfma_f32_16x16x32_bf16 v[32:35], v[128:131], v[188:191], v[32:35]
	v_mfma_f32_16x16x32_bf16 v[24:27], v[154:157], v[188:191], v[24:27]
	v_mfma_f32_16x16x32_bf16 v[16:19], v[128:131], v[196:199], v[16:19]
	v_mfma_f32_16x16x32_bf16 v[8:11], v[154:157], v[196:199], v[8:11]
	v_mfma_f32_16x16x32_bf16 v[60:63], v[132:135], v[176:179], v[60:63]
	v_mfma_f32_16x16x32_bf16 v[56:59], v[158:161], v[176:179], v[56:59]
	v_mfma_f32_16x16x32_bf16 v[48:51], v[132:135], v[184:187], v[48:51]
	v_mfma_f32_16x16x32_bf16 v[40:43], v[158:161], v[184:187], v[40:43]
	v_mfma_f32_16x16x32_bf16 v[32:35], v[132:135], v[192:195], v[32:35]
	v_mfma_f32_16x16x32_bf16 v[24:27], v[158:161], v[192:195], v[24:27]
	v_mfma_f32_16x16x32_bf16 v[16:19], v[132:135], v[200:203], v[16:19]
	s_barrier
	v_mfma_f32_16x16x32_bf16 v[8:11], v[158:161], v[200:203], v[8:11]
	s_setprio 0
	s_add_u32 s14, s78, 0x40080
	s_addc_u32 s15, s79, 0
	s_add_i32 s5, s35, s19
	v_lshl_add_u64 v[128:129], s[14:15], 0, v[138:139]
	s_mov_b32 m0, s5
	s_nop 0
	global_load_lds_dwordx4 v[128:129], off
	v_lshl_add_u64 v[128:129], s[14:15], 0, v[142:143]
	s_add_i32 m0, s5, 0x2000
	s_nop 0
	global_load_lds_dwordx4 v[128:129], off
	s_waitcnt vmcnt(6)
	s_barrier
	s_setprio 1
	v_mfma_f32_16x16x32_bf16 v[52:55], v[204:207], v[172:175], v[52:55]
	v_mfma_f32_16x16x32_bf16 v[44:47], v[212:215], v[172:175], v[44:47]
	v_mfma_f32_16x16x32_bf16 v[36:39], v[204:207], v[180:183], v[36:39]
	v_mfma_f32_16x16x32_bf16 v[28:31], v[212:215], v[180:183], v[28:31]
	v_mfma_f32_16x16x32_bf16 v[20:23], v[204:207], v[188:191], v[20:23]
	v_mfma_f32_16x16x32_bf16 v[12:15], v[212:215], v[188:191], v[12:15]
	v_mfma_f32_16x16x32_bf16 v[4:7], v[204:207], v[196:199], v[4:7]
	v_mfma_f32_16x16x32_bf16 v[0:3], v[212:215], v[196:199], v[0:3]
	v_mfma_f32_16x16x32_bf16 v[52:55], v[208:211], v[176:179], v[52:55]
	v_mfma_f32_16x16x32_bf16 v[44:47], v[216:219], v[176:179], v[44:47]
	v_mfma_f32_16x16x32_bf16 v[36:39], v[208:211], v[184:187], v[36:39]
	v_mfma_f32_16x16x32_bf16 v[28:31], v[216:219], v[184:187], v[28:31]
	v_mfma_f32_16x16x32_bf16 v[20:23], v[208:211], v[192:195], v[20:23]
	v_mfma_f32_16x16x32_bf16 v[12:15], v[216:219], v[192:195], v[12:15]
	v_mfma_f32_16x16x32_bf16 v[4:7], v[208:211], v[200:203], v[4:7]
	s_barrier
	v_mfma_f32_16x16x32_bf16 v[0:3], v[216:219], v[200:203], v[0:3]
	s_setprio 0
	s_add_i32 s4, s4, 2
	s_add_u32 s8, s8, 0x100
	s_addc_u32 s9, s9, 0
	s_add_u32 vcc_lo, vcc_lo, 0x100
	s_addc_u32 vcc_hi, vcc_hi, 0
	s_cmp_gt_u32 s4, 13
	s_cbranch_scc0 .LBB0_298
	s_lshl_b32 s4, s97, 8
	v_or_b32_e32 v128, s4, v166
	v_ashrrev_i32_e32 v129, 31, v128
	v_lshl_add_u64 v[132:133], v[128:129], 2, s[60:61]
	global_load_dwordx4 v[158:161], v[132:133], off offset:16
	global_load_dwordx4 v[154:157], v[132:133], off
	global_load_dwordx4 v[128:131], v[132:133], off offset:528
	s_nop 0
	global_load_dwordx4 v[132:135], v[132:133], off offset:512
	s_mov_b32 s6, 0x358637bd
	v_mov_b64_e32 v[162:163], s[6:7]
	s_lshl_b32 s6, s76, 8
	s_add_i32 s6, s6, s84
	s_lshr_b32 s5, s97, 3
	s_and_b32 s7, s5, 0x1fffc
	s_bfe_u32 s5, s6, 0x20008
	s_or_b32 s4, s4, s85
	s_or_b32 s5, s5, s7
	s_cmpk_lt_u32 s6, 0x400
	s_mov_b32 s97, s20
	s_mov_b32 s76, s22
	s_mov_b64 s[78:79], s[28:29]
	s_waitcnt vmcnt(0)
	v_pk_fma_f32 v[158:159], v[158:159], s[16:17], v[162:163] op_sel_hi:[1,0,0]
	v_pk_fma_f32 v[154:155], v[154:155], s[16:17], v[162:163] op_sel_hi:[1,0,0]
	v_pk_fma_f32 v[156:157], v[156:157], s[16:17], v[162:163] op_sel_hi:[1,0,0]
	v_mul_f32_e32 v171, 0x4b800000, v154
	v_cmp_gt_f32_e64 s[8:9], s96, v154
	v_cmp_gt_f32_e32 vcc, s96, v155
	v_pk_fma_f32 v[160:161], v[160:161], s[16:17], v[162:163] op_sel_hi:[1,0,0]
	v_cndmask_b32_e64 v154, v154, v171, s[8:9]
	v_mul_f32_e32 v171, 0x4b800000, v155
	v_cndmask_b32_e32 v155, v155, v171, vcc
	v_rsq_f32_e32 v154, v154
	v_rsq_f32_e32 v155, v155
	v_mul_f32_e32 v171, 0x4b800000, v156
	v_pk_fma_f32 v[132:133], v[132:133], s[16:17], v[162:163] op_sel_hi:[1,0,0]
	v_pk_fma_f32 v[134:135], v[134:135], s[16:17], v[162:163] op_sel_hi:[1,0,0]
	v_pk_mul_f32 v[172:173], v[154:155], s[18:19] op_sel_hi:[1,0]
	v_pk_fma_f32 v[128:129], v[128:129], s[16:17], v[162:163] op_sel_hi:[1,0,0]
	v_cndmask_b32_e64 v154, v154, v172, s[8:9]
	v_cmp_gt_f32_e64 s[8:9], s96, v156
	v_cndmask_b32_e32 v155, v155, v173, vcc
	v_cmp_gt_f32_e32 vcc, s96, v157
	v_cndmask_b32_e64 v156, v156, v171, s[8:9]
	v_mul_f32_e32 v171, 0x4b800000, v157
	v_cndmask_b32_e32 v157, v157, v171, vcc
	v_rsq_f32_e32 v156, v156
	v_rsq_f32_e32 v157, v157
	v_mul_f32_e32 v171, 0x4b800000, v158
	v_pk_fma_f32 v[130:131], v[130:131], s[16:17], v[162:163] op_sel_hi:[1,0,0]
	v_pk_mul_f32 v[124:125], v[124:125], v[154:155]
	v_pk_mul_f32 v[172:173], v[156:157], s[18:19] op_sel_hi:[1,0]
	v_mul_f32_e32 v162, 0x4b800000, v130
	v_cndmask_b32_e64 v156, v156, v172, s[8:9]
	v_cmp_gt_f32_e64 s[8:9], s96, v158
	v_cndmask_b32_e32 v157, v157, v173, vcc
	v_cmp_gt_f32_e32 vcc, s96, v159
	v_cndmask_b32_e64 v158, v158, v171, s[8:9]
	v_mul_f32_e32 v171, 0x4b800000, v159
	v_cndmask_b32_e32 v159, v159, v171, vcc
	v_rsq_f32_e32 v158, v158
	v_rsq_f32_e32 v159, v159
	v_mul_f32_e32 v171, 0x4b800000, v160
	v_pk_mul_f32 v[126:127], v[126:127], v[156:157]
	v_pk_mul_f32 v[112:113], v[112:113], v[154:155]
	v_pk_mul_f32 v[172:173], v[158:159], s[18:19] op_sel_hi:[1,0]
	v_pk_mul_f32 v[96:97], v[96:97], v[154:155]
; DI unsigned pk_bf16(float lo, float hi) { f32x2 v = {lo, hi}; return __builtin_bit_cast(unsigned, __builtin_convertvector(v, bf16v2)); }
;     DI void operator()(AccRef acc, const Unit& u, int wr, int wc, int fr, int fq) const {
;     ...
; #pragma unroll
;         for (int ai = 0; ai < 2; ++ai)
; #pragma unroll
;             for (int m = 0; m < 4; ++m) {
;                 const int R = u.pm * 256 + ai * 128 + wr * 64 + m * 16 + fr, X = R >> 10, hv = R & 1023;
; #pragma unroll
;                 for (int bj = 0; bj < 2; ++bj) {
;                     const int tok = u.pn * 256 + bj * 128 + wc * 32 + 8 * fq, b = tok >> 13, s = tok & (SEQ - 1);
;                     bf16_t* dst = (X ? vtB : vtA) + ((size_t)(((b * 4 + (hv >> 8)) * 128 + (s >> 6)) * 256 + (hv & 255))) * 64 + (s & 63);
;                     const f32x4 v0 = acc[ai][bj][m][0] * ts[bj][0], v1 = acc[ai][bj][m][1] * ts[bj][1];
;                     u32x4 w; w.x = pk_bf16(v0[0], v0[1]); w.y = pk_bf16(v0[2], v0[3]); w.z = pk_bf16(v1[0], v1[1]); w.w = pk_bf16(v1[2], v1[3]);
;                     *(u32x4*)dst = w;
;                 }
	v_cndmask_b32_e64 v158, v158, v172, s[8:9]
	v_cmp_gt_f32_e64 s[8:9], s96, v160
	v_cndmask_b32_e32 v159, v159, v173, vcc
	v_cmp_gt_f32_e32 vcc, s96, v161
	v_cndmask_b32_e64 v160, v160, v171, s[8:9]
	v_mul_f32_e32 v171, 0x4b800000, v161
	v_cndmask_b32_e32 v161, v161, v171, vcc
	v_rsq_f32_e32 v160, v160
	v_rsq_f32_e32 v161, v161
	v_mul_f32_e32 v171, 0x4b800000, v132
	v_pk_mul_f32 v[80:81], v[80:81], v[154:155]
	v_pk_mul_f32 v[62:63], v[62:63], v[156:157]
	v_pk_mul_f32 v[172:173], v[160:161], s[18:19] op_sel_hi:[1,0]
	v_pk_mul_f32 v[60:61], v[60:61], v[154:155]
	v_cndmask_b32_e64 v160, v160, v172, s[8:9]
	v_cmp_gt_f32_e64 s[8:9], s96, v132
	v_cndmask_b32_e32 v161, v161, v173, vcc
	v_cmp_gt_f32_e32 vcc, s96, v133
	v_cndmask_b32_e64 v132, v132, v171, s[8:9]
	v_mul_f32_e32 v171, 0x4b800000, v133
	v_cndmask_b32_e32 v133, v133, v171, vcc
	v_rsq_f32_e32 v132, v132
	v_rsq_f32_e32 v133, v133
	v_mul_f32_e32 v171, 0x4b800000, v134
	v_pk_mul_f32 v[48:49], v[48:49], v[154:155]
	v_pk_mul_f32 v[32:33], v[32:33], v[154:155]
	v_pk_mul_f32 v[172:173], v[132:133], s[18:19] op_sel_hi:[1,0]
	v_pk_mul_f32 v[16:17], v[16:17], v[154:155]
	v_cndmask_b32_e64 v132, v132, v172, s[8:9]
	v_cmp_gt_f32_e64 s[8:9], s96, v134
	v_cndmask_b32_e32 v133, v133, v173, vcc
	v_cmp_gt_f32_e32 vcc, s96, v135
	v_cndmask_b32_e64 v134, v134, v171, s[8:9]
	v_mul_f32_e32 v171, 0x4b800000, v135
	v_cndmask_b32_e32 v135, v135, v171, vcc
	v_rsq_f32_e32 v134, v134
	v_rsq_f32_e32 v135, v135
	v_mul_f32_e32 v171, 0x4b800000, v128
	v_pk_mul_f32 v[116:117], v[116:117], v[132:133]
	v_pk_mul_f32 v[100:101], v[100:101], v[132:133]
	v_pk_mul_f32 v[172:173], v[134:135], s[18:19] op_sel_hi:[1,0]
	v_pk_mul_f32 v[84:85], v[84:85], v[132:133]
	v_cndmask_b32_e64 v134, v134, v172, s[8:9]
	v_cmp_gt_f32_e64 s[8:9], s96, v128
	v_cndmask_b32_e32 v135, v135, v173, vcc
	v_cmp_gt_f32_e32 vcc, s96, v129
	v_cndmask_b32_e64 v128, v128, v171, s[8:9]
	v_mul_f32_e32 v171, 0x4b800000, v129
	v_cndmask_b32_e32 v129, v129, v171, vcc
	v_rsq_f32_e32 v128, v128
	v_rsq_f32_e32 v129, v129
	v_lshl_or_b32 v171, s5, 15, v167
	v_pk_mul_f32 v[118:119], v[118:119], v[134:135]
	v_pk_mul_f32 v[102:103], v[102:103], v[134:135]
	v_pk_mul_f32 v[172:173], v[128:129], s[18:19] op_sel_hi:[1,0]
	v_pk_mul_f32 v[86:87], v[86:87], v[134:135]
	v_cndmask_b32_e64 v128, v128, v172, s[8:9]
	v_cmp_gt_f32_e64 s[8:9], s96, v130
	v_cndmask_b32_e32 v129, v129, v173, vcc
	v_cmp_gt_f32_e32 vcc, s96, v131
	v_cndmask_b32_e64 v130, v130, v162, s[8:9]
	v_mul_f32_e32 v162, 0x4b800000, v131
	v_cndmask_b32_e32 v131, v131, v162, vcc
	v_rsq_f32_e32 v130, v130
	v_rsq_f32_e32 v131, v131
	v_pk_mul_f32 v[172:173], v[122:123], v[160:161]
	v_pk_mul_f32 v[122:123], v[120:121], v[158:159]
	v_cvt_pk_bf16_f32 v120, v124, v125
	v_pk_mul_f32 v[162:163], v[130:131], s[18:19] op_sel_hi:[1,0]
	v_cvt_pk_bf16_f32 v121, v126, v127
	v_cndmask_b32_e64 v130, v130, v162, s[8:9]
	s_cselect_b32 s9, s53, s91
	s_cselect_b32 s8, s52, s90
	s_lshl_b32 s4, s4, 2
	s_and_b32 s4, s4, 0x7d00
	v_or_b32_e32 v162, s4, v171
	v_cndmask_b32_e32 v131, v131, v163, vcc
	v_ashrrev_i32_e32 v163, 31, v162
	v_lshlrev_b64 v[162:163], 7, v[162:163]
	v_lshl_add_u64 v[162:163], s[8:9], 0, v[162:163]
	v_lshl_add_u64 v[162:163], v[162:163], 0, v[144:145]
	v_cvt_pk_bf16_f32 v122, v122, v123
	v_cvt_pk_bf16_f32 v123, v172, v173
	s_or_b32 s5, s4, 0x200
	global_store_dwordx4 v[162:163], v[120:123], off
	s_addk_i32 s6, 0x80
	v_pk_mul_f32 v[70:71], v[70:71], v[134:135]
	v_or_b32_e32 v120, s5, v171
	v_ashrrev_i32_e32 v121, 31, v120
	v_lshlrev_b64 v[120:121], 7, v[120:121]
	v_lshl_add_u64 v[120:121], s[8:9], 0, v[120:121]
	v_pk_mul_f32 v[122:123], v[110:111], v[130:131]
	v_pk_mul_f32 v[110:111], v[108:109], v[128:129]
	v_lshl_add_u64 v[120:121], v[120:121], 0, v[144:145]
	v_cvt_pk_bf16_f32 v108, v116, v117
	v_cvt_pk_bf16_f32 v109, v118, v119
	v_cvt_pk_bf16_f32 v110, v110, v111
	v_cvt_pk_bf16_f32 v111, v122, v123
	v_or_b32_e32 v116, 16, v171
	global_store_dwordx4 v[120:121], v[108:111], off
	v_pk_mul_f32 v[68:69], v[68:69], v[132:133]
	v_pk_mul_f32 v[54:55], v[54:55], v[134:135]
	v_or_b32_e32 v108, s4, v116
	v_ashrrev_i32_e32 v109, 31, v108
	v_lshlrev_b64 v[108:109], 7, v[108:109]
	v_lshl_add_u64 v[108:109], s[8:9], 0, v[108:109]
	v_pk_mul_f32 v[110:111], v[114:115], v[156:157]
	v_pk_mul_f32 v[114:115], v[106:107], v[160:161]
	v_pk_mul_f32 v[106:107], v[104:105], v[158:159]
	v_lshl_add_u64 v[108:109], v[108:109], 0, v[144:145]
	v_cvt_pk_bf16_f32 v104, v112, v113
	v_cvt_pk_bf16_f32 v105, v110, v111
	v_cvt_pk_bf16_f32 v106, v106, v107
	v_cvt_pk_bf16_f32 v107, v114, v115
	global_store_dwordx4 v[108:109], v[104:107], off
	v_pk_mul_f32 v[52:53], v[52:53], v[132:133]
	v_pk_mul_f32 v[38:39], v[38:39], v[134:135]
	v_or_b32_e32 v104, s5, v116
	v_ashrrev_i32_e32 v105, 31, v104
	v_lshlrev_b64 v[104:105], 7, v[104:105]
	v_lshl_add_u64 v[104:105], s[8:9], 0, v[104:105]
	v_pk_mul_f32 v[106:107], v[94:95], v[130:131]
	v_pk_mul_f32 v[94:95], v[92:93], v[128:129]
	v_lshl_add_u64 v[104:105], v[104:105], 0, v[144:145]
	v_cvt_pk_bf16_f32 v92, v100, v101
	v_cvt_pk_bf16_f32 v93, v102, v103
	v_cvt_pk_bf16_f32 v94, v94, v95
	v_cvt_pk_bf16_f32 v95, v106, v107
	v_or_b32_e32 v100, 32, v171
	global_store_dwordx4 v[104:105], v[92:95], off
	v_pk_mul_f32 v[36:37], v[36:37], v[132:133]
	v_pk_mul_f32 v[22:23], v[22:23], v[134:135]
	v_or_b32_e32 v92, s4, v100
	v_ashrrev_i32_e32 v93, 31, v92
	v_lshlrev_b64 v[92:93], 7, v[92:93]
	v_lshl_add_u64 v[92:93], s[8:9], 0, v[92:93]
	v_pk_mul_f32 v[94:95], v[98:99], v[156:157]
	v_pk_mul_f32 v[98:99], v[90:91], v[160:161]
	v_pk_mul_f32 v[90:91], v[88:89], v[158:159]
	v_lshl_add_u64 v[92:93], v[92:93], 0, v[144:145]
; DI unsigned pk_bf16(float lo, float hi) { f32x2 v = {lo, hi}; return __builtin_bit_cast(unsigned, __builtin_convertvector(v, bf16v2)); }
; #define PG8_WAIT_V(n) asm volatile("s_waitcnt vmcnt(" #n ")" ::: "memory")
; #define PG8_BAR __builtin_amdgcn_s_barrier()
; #define PG8_WAIT_V(n) asm volatile("s_waitcnt vmcnt(" #n ")" ::: "memory")
; #define PG8_BAR __builtin_amdgcn_s_barrier()
; template <class Epi>
; DI void gemm_phase(LAS unsigned char* lds, const Gemm g, const StaticOrder S, const Epi E) {
;     ...
;         E(acc, cur, wr, wc, fr, fq);
;         if (!has_next) break;
; #pragma unroll
;         for (int a = 0; a < 2; ++a)
; #pragma unroll
;             for (int b = 0; b < 2; ++b)
; #pragma unroll
;                 for (int m = 0; m < 4; ++m)
; #pragma unroll
;                     for (int n = 0; n < 2; ++n) acc[a][b][m][n] = (f32x4){0.f, 0.f, 0.f, 0.f};
;         cur = nxt; cA = nA; cB = nB; ++ui;
;     }
;     PG8_WAIT_V(0);
;     if (wr == 0) PG8_BAR;
;     PG8_BAR;
;     DI void operator()(AccRef acc, const Unit& u, int wr, int wc, int fr, int fq) const {
;     ...
; #pragma unroll
;         for (int ai = 0; ai < 2; ++ai)
; #pragma unroll
;             for (int m = 0; m < 4; ++m) {
;                 const int R = u.pm * 256 + ai * 128 + wr * 64 + m * 16 + fr, X = R >> 10, hv = R & 1023;
; #pragma unroll
;                 for (int bj = 0; bj < 2; ++bj) {
;                     const int tok = u.pn * 256 + bj * 128 + wc * 32 + 8 * fq, b = tok >> 13, s = tok & (SEQ - 1);
;                     bf16_t* dst = (X ? vtB : vtA) + ((size_t)(((b * 4 + (hv >> 8)) * 128 + (s >> 6)) * 256 + (hv & 255))) * 64 + (s & 63);
;                     const f32x4 v0 = acc[ai][bj][m][0] * ts[bj][0], v1 = acc[ai][bj][m][1] * ts[bj][1];
;                     u32x4 w; w.x = pk_bf16(v0[0], v0[1]); w.y = pk_bf16(v0[2], v0[3]); w.z = pk_bf16(v1[0], v1[1]); w.w = pk_bf16(v1[2], v1[3]);
;                     *(u32x4*)dst = w;
;                 }
	v_cvt_pk_bf16_f32 v88, v96, v97
	v_cvt_pk_bf16_f32 v89, v94, v95
	v_cvt_pk_bf16_f32 v90, v90, v91
	v_cvt_pk_bf16_f32 v91, v98, v99
	global_store_dwordx4 v[92:93], v[88:91], off
	v_pk_mul_f32 v[20:21], v[20:21], v[132:133]
	v_pk_mul_f32 v[6:7], v[6:7], v[134:135]
	v_or_b32_e32 v88, s5, v100
	v_ashrrev_i32_e32 v89, 31, v88
	v_lshlrev_b64 v[88:89], 7, v[88:89]
	v_lshl_add_u64 v[88:89], s[8:9], 0, v[88:89]
	v_pk_mul_f32 v[90:91], v[78:79], v[130:131]
	v_pk_mul_f32 v[78:79], v[76:77], v[128:129]
	v_lshl_add_u64 v[88:89], v[88:89], 0, v[144:145]
	v_cvt_pk_bf16_f32 v76, v84, v85
	v_cvt_pk_bf16_f32 v77, v86, v87
	v_cvt_pk_bf16_f32 v78, v78, v79
	v_cvt_pk_bf16_f32 v79, v90, v91
	v_or_b32_e32 v84, 48, v171
	global_store_dwordx4 v[88:89], v[76:79], off
	v_pk_mul_f32 v[4:5], v[4:5], v[132:133]
	s_nop 0
	v_or_b32_e32 v76, s4, v84
	v_ashrrev_i32_e32 v77, 31, v76
	v_lshlrev_b64 v[76:77], 7, v[76:77]
	v_lshl_add_u64 v[76:77], s[8:9], 0, v[76:77]
	v_pk_mul_f32 v[78:79], v[82:83], v[156:157]
	v_pk_mul_f32 v[82:83], v[74:75], v[160:161]
	v_pk_mul_f32 v[74:75], v[72:73], v[158:159]
	v_lshl_add_u64 v[76:77], v[76:77], 0, v[144:145]
	v_cvt_pk_bf16_f32 v72, v80, v81
	v_cvt_pk_bf16_f32 v73, v78, v79
	v_cvt_pk_bf16_f32 v74, v74, v75
	v_cvt_pk_bf16_f32 v75, v82, v83
	global_store_dwordx4 v[76:77], v[72:75], off
	s_nop 1
	v_or_b32_e32 v72, s5, v84
	v_ashrrev_i32_e32 v73, 31, v72
	v_lshlrev_b64 v[72:73], 7, v[72:73]
	v_lshl_add_u64 v[72:73], s[8:9], 0, v[72:73]
	s_bfe_u32 s8, s6, 0x20008
	s_or_b32 s7, s8, s7
	s_lshl_b32 s7, s7, 15
	s_and_b32 s8, s6, 0xc0
	v_pk_mul_f32 v[74:75], v[66:67], v[130:131]
	v_pk_mul_f32 v[66:67], v[64:65], v[128:129]
	s_or_b32 s7, s7, s8
	v_lshl_add_u64 v[72:73], v[72:73], 0, v[144:145]
	v_cvt_pk_bf16_f32 v64, v68, v69
	v_cvt_pk_bf16_f32 v65, v70, v71
	v_cvt_pk_bf16_f32 v66, v66, v67
	v_cvt_pk_bf16_f32 v67, v74, v75
	v_or_b32_e32 v68, s7, v164
	global_store_dwordx4 v[72:73], v[64:67], off
	s_cmpk_lt_u32 s6, 0x400
	s_cselect_b32 s9, s53, s91
	v_or_b32_e32 v64, s4, v68
	v_ashrrev_i32_e32 v65, 31, v64
	s_cselect_b32 s8, s52, s90
	v_lshlrev_b64 v[64:65], 7, v[64:65]
	v_lshl_add_u64 v[64:65], s[8:9], 0, v[64:65]
	v_pk_mul_f32 v[66:67], v[58:59], v[160:161]
	v_pk_mul_f32 v[58:59], v[56:57], v[158:159]
	v_lshl_add_u64 v[64:65], v[64:65], 0, v[144:145]
	v_cvt_pk_bf16_f32 v56, v60, v61
	v_cvt_pk_bf16_f32 v57, v62, v63
	v_cvt_pk_bf16_f32 v58, v58, v59
	v_cvt_pk_bf16_f32 v59, v66, v67
	global_store_dwordx4 v[64:65], v[56:59], off
	s_and_b64 vcc, exec, s[0:1]
	s_nop 0
	v_or_b32_e32 v56, s5, v68
	v_ashrrev_i32_e32 v57, 31, v56
	v_lshlrev_b64 v[56:57], 7, v[56:57]
	v_lshl_add_u64 v[56:57], s[8:9], 0, v[56:57]
	v_pk_mul_f32 v[58:59], v[46:47], v[130:131]
	v_pk_mul_f32 v[46:47], v[44:45], v[128:129]
	v_lshl_add_u64 v[56:57], v[56:57], 0, v[144:145]
	v_cvt_pk_bf16_f32 v44, v52, v53
	v_cvt_pk_bf16_f32 v45, v54, v55
	v_cvt_pk_bf16_f32 v46, v46, v47
	v_cvt_pk_bf16_f32 v47, v58, v59
	v_or_b32_e32 v52, 16, v68
	global_store_dwordx4 v[56:57], v[44:47], off
	s_nop 1
	v_or_b32_e32 v44, s4, v52
	v_ashrrev_i32_e32 v45, 31, v44
	v_lshlrev_b64 v[44:45], 7, v[44:45]
	v_lshl_add_u64 v[44:45], s[8:9], 0, v[44:45]
	v_pk_mul_f32 v[46:47], v[50:51], v[156:157]
	v_pk_mul_f32 v[50:51], v[42:43], v[160:161]
	v_pk_mul_f32 v[42:43], v[40:41], v[158:159]
	v_lshl_add_u64 v[44:45], v[44:45], 0, v[144:145]
	v_cvt_pk_bf16_f32 v40, v48, v49
	v_cvt_pk_bf16_f32 v41, v46, v47
	v_cvt_pk_bf16_f32 v42, v42, v43
	v_cvt_pk_bf16_f32 v43, v50, v51
	global_store_dwordx4 v[44:45], v[40:43], off
	s_nop 1
	v_or_b32_e32 v40, s5, v52
	v_ashrrev_i32_e32 v41, 31, v40
	v_lshlrev_b64 v[40:41], 7, v[40:41]
	v_lshl_add_u64 v[40:41], s[8:9], 0, v[40:41]
	v_pk_mul_f32 v[42:43], v[30:31], v[130:131]
	v_pk_mul_f32 v[30:31], v[28:29], v[128:129]
	v_lshl_add_u64 v[40:41], v[40:41], 0, v[144:145]
	v_cvt_pk_bf16_f32 v28, v36, v37
	v_cvt_pk_bf16_f32 v29, v38, v39
	v_cvt_pk_bf16_f32 v30, v30, v31
	v_cvt_pk_bf16_f32 v31, v42, v43
	v_or_b32_e32 v36, 32, v68
	global_store_dwordx4 v[40:41], v[28:31], off
	s_nop 1
	v_or_b32_e32 v28, s4, v36
	v_ashrrev_i32_e32 v29, 31, v28
	v_lshlrev_b64 v[28:29], 7, v[28:29]
	v_lshl_add_u64 v[28:29], s[8:9], 0, v[28:29]
	v_pk_mul_f32 v[30:31], v[34:35], v[156:157]
	v_pk_mul_f32 v[34:35], v[26:27], v[160:161]
	v_pk_mul_f32 v[26:27], v[24:25], v[158:159]
	v_lshl_add_u64 v[28:29], v[28:29], 0, v[144:145]
	v_cvt_pk_bf16_f32 v24, v32, v33
	v_cvt_pk_bf16_f32 v25, v30, v31
	v_cvt_pk_bf16_f32 v26, v26, v27
	v_cvt_pk_bf16_f32 v27, v34, v35
	global_store_dwordx4 v[28:29], v[24:27], off
	s_nop 1
	v_or_b32_e32 v24, s5, v36
	v_ashrrev_i32_e32 v25, 31, v24
	v_lshlrev_b64 v[24:25], 7, v[24:25]
	v_lshl_add_u64 v[24:25], s[8:9], 0, v[24:25]
	v_pk_mul_f32 v[26:27], v[14:15], v[130:131]
	v_pk_mul_f32 v[14:15], v[12:13], v[128:129]
	v_lshl_add_u64 v[24:25], v[24:25], 0, v[144:145]
	v_cvt_pk_bf16_f32 v12, v20, v21
	v_cvt_pk_bf16_f32 v13, v22, v23
	v_cvt_pk_bf16_f32 v14, v14, v15
	v_cvt_pk_bf16_f32 v15, v26, v27
	v_or_b32_e32 v20, 48, v68
	global_store_dwordx4 v[24:25], v[12:15], off
	s_nop 1
	v_or_b32_e32 v12, s4, v20
	v_ashrrev_i32_e32 v13, 31, v12
	v_lshlrev_b64 v[12:13], 7, v[12:13]
	v_lshl_add_u64 v[12:13], s[8:9], 0, v[12:13]
	v_pk_mul_f32 v[14:15], v[18:19], v[156:157]
	v_pk_mul_f32 v[18:19], v[10:11], v[160:161]
	v_pk_mul_f32 v[10:11], v[8:9], v[158:159]
	v_lshl_add_u64 v[12:13], v[12:13], 0, v[144:145]
	v_cvt_pk_bf16_f32 v8, v16, v17
	v_cvt_pk_bf16_f32 v9, v14, v15
	v_cvt_pk_bf16_f32 v10, v10, v11
	v_cvt_pk_bf16_f32 v11, v18, v19
	global_store_dwordx4 v[12:13], v[8:11], off
	s_nop 1
	v_or_b32_e32 v8, s5, v20
	v_ashrrev_i32_e32 v9, 31, v8
	v_lshlrev_b64 v[8:9], 7, v[8:9]
	v_lshl_add_u64 v[8:9], s[8:9], 0, v[8:9]
	v_pk_mul_f32 v[10:11], v[2:3], v[130:131]
	v_pk_mul_f32 v[2:3], v[0:1], v[128:129]
	v_lshl_add_u64 v[8:9], v[8:9], 0, v[144:145]
	v_cvt_pk_bf16_f32 v0, v4, v5
	v_cvt_pk_bf16_f32 v1, v6, v7
	v_cvt_pk_bf16_f32 v2, v2, v3
	v_cvt_pk_bf16_f32 v3, v10, v11
	s_mov_b64 s[8:9], s[24:25]
	global_store_dwordx4 v[8:9], v[0:3], off
	s_cbranch_vccz .LBB0_291
	s_waitcnt vmcnt(0)
	s_cmpk_gt_u32 s17, 0xff
	s_cbranch_scc1 .LBB0_302
	s_barrier

; #define PG8_STAGE(bufoff, gbase, voff) do { _Pragma("unroll") for (int _i = 0; _i < 2; ++_i) \
;         __builtin_amdgcn_global_load_lds((const unsigned*)((const char*)(gbase) + (voff)[_i]), (LAS unsigned*)(lds + (bufoff) + ldsw + _i * 8192), 16, 0, 0); } while (0)
; #define PG8_LDA(dst, b, h) do { _Pragma("unroll") for (int m = 0; m < 4; ++m) _Pragma("unroll") for (int k = 0; k < 2; ++k) dst[m][k] = *(const LAS bf16x8*)(lds + PG8_SA(b, h) + aoff + m * 2048 + k * 1024); } while (0)
; #define PG8_LDB(dst, b, h) do { _Pragma("unroll") for (int n = 0; n < 2; ++n) _Pragma("unroll") for (int k = 0; k < 2; ++k) dst[n][k] = *(const LAS bf16x8*)(lds + PG8_SB(b, h) + boff + n * 2048 + k * 1024); } while (0)
; #define PG8_WAIT_V(n) asm volatile("s_waitcnt vmcnt(" #n ")" ::: "memory")
; #define PG8_WAIT_L(n) asm volatile("s_waitcnt lgkmcnt(" #n ")" ::: "memory")
; #define PG8_BAR __builtin_amdgcn_s_barrier()
; #define PG8_SCHED __builtin_amdgcn_sched_barrier(0)
; template <class Epi0, class Epi1>
; DI void gemm_phase_dual(LAS unsigned char* lds, const Gemm g, const Gemm g1, const StaticOrder S, const Epi0 E0, const Epi1 E1) {
;     ...
;             PG8_LDB(B0, 0, 0); PG8_SCHED; PG8_LDA(At, 0, 0); PG8_STAGE(PG8_SA(1, 1), a1 + hstep, voffA);
;             PG8_WAIT_L(8); PG8_BAR; PG8_WAIT_L(0); PG8_MMA(0, 0, At, B0); PG8_BAR; PG8_SCHED;
;             PG8_LDB(B1, 0, 1); PG8_STAGE(PG8_SB(0, 0), b2, voffB);
;             PG8_BAR; PG8_WAIT_L(0); PG8_MMA(0, 1, At, B1); PG8_BAR;
;             PG8_LDA(At, 0, 1); PG8_STAGE(PG8_SA(0, 0), a2, voffA);
;             PG8_BAR; PG8_WAIT_L(0); PG8_MMA(1, 0, At, B0); PG8_BAR; PG8_SCHED;
;             PG8_STAGE(PG8_SB(0, 1), b2 + hstep, voffB);
;             PG8_WAIT_V(6); PG8_BAR; PG8_MMA(1, 1, At, B1); PG8_BAR;
;             PG8_LDB(B0, 1, 0); PG8_SCHED; PG8_LDA(At, 1, 0); PG8_STAGE(PG8_SA(0, 1), a2 + hstep, voffA);
;             PG8_WAIT_L(8); PG8_BAR; PG8_WAIT_L(0); PG8_MMA(0, 0, At, B0); PG8_BAR; PG8_SCHED;
;             PG8_LDB(B1, 1, 1); PG8_STAGE(PG8_SB(1, 0), b3, voffB);
;             PG8_BAR; PG8_WAIT_L(0); PG8_MMA(0, 1, At, B1); PG8_BAR;
;             PG8_LDA(At, 1, 1); PG8_STAGE(PG8_SA(1, 0), a3, voffA);
;             PG8_BAR; PG8_WAIT_L(0); PG8_MMA(1, 0, At, B0); PG8_BAR; PG8_SCHED;
;             PG8_STAGE(PG8_SB(1, 1), b3 + hstep, voffB);
;             PG8_WAIT_V(6); PG8_BAR; PG8_MMA(1, 1, At, B1); PG8_BAR;
.LBB0_632:
	ds_read_b128 v[128:131], v181
	ds_read_b128 v[132:135], v181 offset:1024
	ds_read_b128 v[136:139], v181 offset:2048
	ds_read_b128 v[140:143], v181 offset:3072
	s_add_u32 s12, s10, 0xfffc0080
	s_addc_u32 s13, s11, -1
	s_cmp_eq_u32 s19, 12
	s_cselect_b32 s15, s1, s13
	s_cselect_b32 s14, s6, s12
	s_cselect_b32 s13, s7, s18
	s_cselect_b32 s12, s16, s17
	v_lshl_add_u64 v[190:191], s[10:11], 0, v[168:169]
	s_add_i32 m0, s49, 0xc000
	ds_read_b128 v[144:147], v183
	ds_read_b128 v[148:151], v183 offset:1024
	ds_read_b128 v[152:155], v183 offset:2048
	ds_read_b128 v[184:187], v183 offset:3072
	ds_read_b128 v[194:197], v183 offset:4096
	ds_read_b128 v[198:201], v183 offset:5120
	ds_read_b128 v[202:205], v183 offset:6144
	ds_read_b128 v[206:209], v183 offset:7168
	global_load_lds_dwordx4 v[190:191], off
	v_lshl_add_u64 v[190:191], s[10:11], 0, v[170:171]
	s_add_i32 m0, s49, 0xe000
	s_nop 0
	global_load_lds_dwordx4 v[190:191], off
	s_waitcnt lgkmcnt(8)
	s_barrier
	s_waitcnt lgkmcnt(0)
	s_setprio 1
	s_waitcnt lgkmcnt(0)
	v_mfma_f32_16x16x32_bf16 v[124:127], v[128:131], v[144:147], v[124:127]
	v_mfma_f32_16x16x32_bf16 v[120:123], v[136:139], v[144:147], v[120:123]
	v_mfma_f32_16x16x32_bf16 v[108:111], v[128:131], v[152:155], v[108:111]
	v_mfma_f32_16x16x32_bf16 v[104:107], v[136:139], v[152:155], v[104:107]
	v_mfma_f32_16x16x32_bf16 v[92:95], v[128:131], v[194:197], v[92:95]
	v_mfma_f32_16x16x32_bf16 v[88:91], v[136:139], v[194:197], v[88:91]
	v_mfma_f32_16x16x32_bf16 v[76:79], v[128:131], v[202:205], v[76:79]
	v_mfma_f32_16x16x32_bf16 v[72:75], v[136:139], v[202:205], v[72:75]
	v_mfma_f32_16x16x32_bf16 v[124:127], v[132:135], v[148:151], v[124:127]
	v_mfma_f32_16x16x32_bf16 v[120:123], v[140:143], v[148:151], v[120:123]
	v_mfma_f32_16x16x32_bf16 v[108:111], v[132:135], v[184:187], v[108:111]
	v_mfma_f32_16x16x32_bf16 v[104:107], v[140:143], v[184:187], v[104:107]
	v_mfma_f32_16x16x32_bf16 v[92:95], v[132:135], v[198:201], v[92:95]
	v_mfma_f32_16x16x32_bf16 v[88:91], v[140:143], v[198:201], v[88:91]
	v_mfma_f32_16x16x32_bf16 v[76:79], v[132:135], v[206:209], v[76:79]
	s_barrier
	v_mfma_f32_16x16x32_bf16 v[72:75], v[140:143], v[206:209], v[72:75]
	s_setprio 0
	s_add_i32 s41, s78, s48
	v_lshl_add_u64 v[190:191], s[12:13], 0, v[158:159]
	s_mov_b32 m0, s41
	ds_read_b128 v[210:213], v189
	ds_read_b128 v[214:217], v189 offset:1024
	ds_read_b128 v[218:221], v189 offset:2048
	ds_read_b128 v[224:227], v189 offset:3072
	global_load_lds_dwordx4 v[190:191], off
	v_lshl_add_u64 v[228:229], s[12:13], 0, v[162:163]
	s_add_i32 m0, s41, 0x2000
	s_nop 0
	global_load_lds_dwordx4 v[228:229], off
	s_barrier
	s_waitcnt lgkmcnt(0)
	s_setprio 1
	s_waitcnt lgkmcnt(0)
	v_mfma_f32_16x16x32_bf16 v[116:119], v[210:213], v[144:147], v[116:119]
	v_mfma_f32_16x16x32_bf16 v[112:115], v[218:221], v[144:147], v[112:115]
	v_mfma_f32_16x16x32_bf16 v[100:103], v[210:213], v[152:155], v[100:103]
	v_mfma_f32_16x16x32_bf16 v[96:99], v[218:221], v[152:155], v[96:99]
	v_mfma_f32_16x16x32_bf16 v[84:87], v[210:213], v[194:197], v[84:87]
	v_mfma_f32_16x16x32_bf16 v[80:83], v[218:221], v[194:197], v[80:83]
	v_mfma_f32_16x16x32_bf16 v[68:71], v[210:213], v[202:205], v[68:71]
	v_mfma_f32_16x16x32_bf16 v[64:67], v[218:221], v[202:205], v[64:67]
	v_mfma_f32_16x16x32_bf16 v[116:119], v[214:217], v[148:151], v[116:119]
	v_mfma_f32_16x16x32_bf16 v[112:115], v[224:227], v[148:151], v[112:115]
	v_mfma_f32_16x16x32_bf16 v[100:103], v[214:217], v[184:187], v[100:103]
	v_mfma_f32_16x16x32_bf16 v[96:99], v[224:227], v[184:187], v[96:99]
	v_mfma_f32_16x16x32_bf16 v[84:87], v[214:217], v[198:201], v[84:87]
	v_mfma_f32_16x16x32_bf16 v[80:83], v[224:227], v[198:201], v[80:83]
	v_mfma_f32_16x16x32_bf16 v[68:71], v[214:217], v[206:209], v[68:71]
	s_barrier
	v_mfma_f32_16x16x32_bf16 v[64:67], v[224:227], v[206:209], v[64:67]
	s_setprio 0
	s_mov_b32 m0, s49
	v_lshl_add_u64 v[230:231], s[14:15], 0, v[156:157]
	ds_read_b128 v[144:147], v183 offset:16384
	ds_read_b128 v[148:151], v183 offset:17408
	ds_read_b128 v[152:155], v183 offset:18432
	ds_read_b128 v[184:187], v183 offset:19456
	ds_read_b128 v[194:197], v183 offset:20480
	ds_read_b128 v[198:201], v183 offset:21504
	ds_read_b128 v[202:205], v183 offset:22528
	ds_read_b128 v[206:209], v183 offset:23552
	global_load_lds_dwordx4 v[230:231], off
	v_lshl_add_u64 v[232:233], s[14:15], 0, v[160:161]
	s_mov_b32 m0, s50
	s_nop 0
	global_load_lds_dwordx4 v[232:233], off
	s_barrier
	s_waitcnt lgkmcnt(0)
	s_setprio 1
	s_waitcnt lgkmcnt(0)
	v_mfma_f32_16x16x32_bf16 v[60:63], v[128:131], v[144:147], v[60:63]
	v_mfma_f32_16x16x32_bf16 v[56:59], v[136:139], v[144:147], v[56:59]
	v_mfma_f32_16x16x32_bf16 v[44:47], v[128:131], v[152:155], v[44:47]
	v_mfma_f32_16x16x32_bf16 v[40:43], v[136:139], v[152:155], v[40:43]
	v_mfma_f32_16x16x32_bf16 v[28:31], v[128:131], v[194:197], v[28:31]
	v_mfma_f32_16x16x32_bf16 v[24:27], v[136:139], v[194:197], v[24:27]
	v_mfma_f32_16x16x32_bf16 v[12:15], v[128:131], v[202:205], v[12:15]
	v_mfma_f32_16x16x32_bf16 v[8:11], v[136:139], v[202:205], v[8:11]
	v_mfma_f32_16x16x32_bf16 v[60:63], v[132:135], v[148:151], v[60:63]
	v_mfma_f32_16x16x32_bf16 v[56:59], v[140:143], v[148:151], v[56:59]
	v_mfma_f32_16x16x32_bf16 v[44:47], v[132:135], v[184:187], v[44:47]
	v_mfma_f32_16x16x32_bf16 v[40:43], v[140:143], v[184:187], v[40:43]
	v_mfma_f32_16x16x32_bf16 v[28:31], v[132:135], v[198:201], v[28:31]
	v_mfma_f32_16x16x32_bf16 v[24:27], v[140:143], v[198:201], v[24:27]
	v_mfma_f32_16x16x32_bf16 v[12:15], v[132:135], v[206:209], v[12:15]
	s_barrier
; #define PG8_STAGE(bufoff, gbase, voff) do { _Pragma("unroll") for (int _i = 0; _i < 2; ++_i) \
;         __builtin_amdgcn_global_load_lds((const unsigned*)((const char*)(gbase) + (voff)[_i]), (LAS unsigned*)(lds + (bufoff) + ldsw + _i * 8192), 16, 0, 0); } while (0)
; #define PG8_LDA(dst, b, h) do { _Pragma("unroll") for (int m = 0; m < 4; ++m) _Pragma("unroll") for (int k = 0; k < 2; ++k) dst[m][k] = *(const LAS bf16x8*)(lds + PG8_SA(b, h) + aoff + m * 2048 + k * 1024); } while (0)
; #define PG8_LDB(dst, b, h) do { _Pragma("unroll") for (int n = 0; n < 2; ++n) _Pragma("unroll") for (int k = 0; k < 2; ++k) dst[n][k] = *(const LAS bf16x8*)(lds + PG8_SB(b, h) + boff + n * 2048 + k * 1024); } while (0)
; #define PG8_WAIT_V(n) asm volatile("s_waitcnt vmcnt(" #n ")" ::: "memory")
; #define PG8_WAIT_L(n) asm volatile("s_waitcnt lgkmcnt(" #n ")" ::: "memory")
; #define PG8_BAR __builtin_amdgcn_s_barrier()
; #define PG8_SCHED __builtin_amdgcn_sched_barrier(0)
; template <class Epi0, class Epi1>
; DI void gemm_phase_dual(LAS unsigned char* lds, const Gemm g, const Gemm g1, const StaticOrder S, const Epi0 E0, const Epi1 E1) {
;     ...
;             PG8_LDB(B0, 0, 0); PG8_SCHED; PG8_LDA(At, 0, 0); PG8_STAGE(PG8_SA(1, 1), a1 + hstep, voffA);
;             PG8_WAIT_L(8); PG8_BAR; PG8_WAIT_L(0); PG8_MMA(0, 0, At, B0); PG8_BAR; PG8_SCHED;
;             PG8_LDB(B1, 0, 1); PG8_STAGE(PG8_SB(0, 0), b2, voffB);
;             PG8_BAR; PG8_WAIT_L(0); PG8_MMA(0, 1, At, B1); PG8_BAR;
;             PG8_LDA(At, 0, 1); PG8_STAGE(PG8_SA(0, 0), a2, voffA);
;             PG8_BAR; PG8_WAIT_L(0); PG8_MMA(1, 0, At, B0); PG8_BAR; PG8_SCHED;
;             PG8_STAGE(PG8_SB(0, 1), b2 + hstep, voffB);
;             PG8_WAIT_V(6); PG8_BAR; PG8_MMA(1, 1, At, B1); PG8_BAR;
;             PG8_LDB(B0, 1, 0); PG8_SCHED; PG8_LDA(At, 1, 0); PG8_STAGE(PG8_SA(0, 1), a2 + hstep, voffA);
;             PG8_WAIT_L(8); PG8_BAR; PG8_WAIT_L(0); PG8_MMA(0, 0, At, B0); PG8_BAR; PG8_SCHED;
;             PG8_LDB(B1, 1, 1); PG8_STAGE(PG8_SB(1, 0), b3, voffB);
;             PG8_BAR; PG8_WAIT_L(0); PG8_MMA(0, 1, At, B1); PG8_BAR;
;             PG8_LDA(At, 1, 1); PG8_STAGE(PG8_SA(1, 0), a3, voffA);
;             PG8_BAR; PG8_WAIT_L(0); PG8_MMA(1, 0, At, B0); PG8_BAR; PG8_SCHED;
;             PG8_STAGE(PG8_SB(1, 1), b3 + hstep, voffB);
;             PG8_WAIT_V(6); PG8_BAR; PG8_MMA(1, 1, At, B1); PG8_BAR;
	v_mfma_f32_16x16x32_bf16 v[8:11], v[140:143], v[206:209], v[8:11]
	s_setprio 0
	s_add_u32 s90, s12, 0x40000
	s_addc_u32 s91, s13, 0
	s_add_i32 s41, s79, s48
	v_lshl_add_u64 v[128:129], s[90:91], 0, v[158:159]
	s_mov_b32 m0, s41
	s_nop 0
	global_load_lds_dwordx4 v[128:129], off
	v_lshl_add_u64 v[128:129], s[90:91], 0, v[162:163]
	s_add_i32 m0, s41, 0x2000
	s_nop 0
	global_load_lds_dwordx4 v[128:129], off
	s_waitcnt vmcnt(6)
	s_barrier
	s_setprio 1
	v_mfma_f32_16x16x32_bf16 v[52:55], v[210:213], v[144:147], v[52:55]
	v_mfma_f32_16x16x32_bf16 v[48:51], v[218:221], v[144:147], v[48:51]
	v_mfma_f32_16x16x32_bf16 v[36:39], v[210:213], v[152:155], v[36:39]
	v_mfma_f32_16x16x32_bf16 v[32:35], v[218:221], v[152:155], v[32:35]
	v_mfma_f32_16x16x32_bf16 v[20:23], v[210:213], v[194:197], v[20:23]
	v_mfma_f32_16x16x32_bf16 v[16:19], v[218:221], v[194:197], v[16:19]
	v_mfma_f32_16x16x32_bf16 v[4:7], v[210:213], v[202:205], v[4:7]
	v_mfma_f32_16x16x32_bf16 v[0:3], v[218:221], v[202:205], v[0:3]
	v_mfma_f32_16x16x32_bf16 v[52:55], v[214:217], v[148:151], v[52:55]
	v_mfma_f32_16x16x32_bf16 v[48:51], v[224:227], v[148:151], v[48:51]
	v_mfma_f32_16x16x32_bf16 v[36:39], v[214:217], v[184:187], v[36:39]
	v_mfma_f32_16x16x32_bf16 v[32:35], v[224:227], v[184:187], v[32:35]
	v_mfma_f32_16x16x32_bf16 v[20:23], v[214:217], v[198:201], v[20:23]
	v_mfma_f32_16x16x32_bf16 v[16:19], v[224:227], v[198:201], v[16:19]
	v_mfma_f32_16x16x32_bf16 v[4:7], v[214:217], v[206:209], v[4:7]
	s_barrier
	v_mfma_f32_16x16x32_bf16 v[0:3], v[224:227], v[206:209], v[0:3]
	s_setprio 0
	s_add_i32 s41, 0, 0x18000
	v_add_u32_e32 v140, s41, v179
	ds_read_b128 v[128:131], v140
	ds_read_b128 v[132:135], v140 offset:1024
	ds_read_b128 v[136:139], v140 offset:2048
	ds_read_b128 v[140:143], v140 offset:3072
	s_add_u32 s14, s14, 0x40000
	s_addc_u32 s15, s15, 0
	s_mov_b32 m0, s51
	v_lshl_add_u64 v[210:211], s[14:15], 0, v[156:157]
	ds_read_b128 v[144:147], v183 offset:32768
	ds_read_b128 v[148:151], v183 offset:33792
	ds_read_b128 v[152:155], v183 offset:34816
	ds_read_b128 v[184:187], v183 offset:35840
	ds_read_b128 v[194:197], v183 offset:36864
	ds_read_b128 v[198:201], v183 offset:37888
	ds_read_b128 v[202:205], v183 offset:38912
	ds_read_b128 v[206:209], v183 offset:39936
	global_load_lds_dwordx4 v[210:211], off
	v_lshl_add_u64 v[210:211], s[14:15], 0, v[160:161]
	s_mov_b32 m0, s58
	s_nop 0
	global_load_lds_dwordx4 v[210:211], off
	s_waitcnt lgkmcnt(8)
	s_barrier
	s_waitcnt lgkmcnt(0)
	s_setprio 1
	s_waitcnt lgkmcnt(0)
	v_mfma_f32_16x16x32_bf16 v[124:127], v[128:131], v[144:147], v[124:127]
	v_mfma_f32_16x16x32_bf16 v[120:123], v[136:139], v[144:147], v[120:123]
	v_mfma_f32_16x16x32_bf16 v[108:111], v[128:131], v[152:155], v[108:111]
	v_mfma_f32_16x16x32_bf16 v[104:107], v[136:139], v[152:155], v[104:107]
	v_mfma_f32_16x16x32_bf16 v[92:95], v[128:131], v[194:197], v[92:95]
	v_mfma_f32_16x16x32_bf16 v[88:91], v[136:139], v[194:197], v[88:91]
	v_mfma_f32_16x16x32_bf16 v[76:79], v[128:131], v[202:205], v[76:79]
	v_mfma_f32_16x16x32_bf16 v[72:75], v[136:139], v[202:205], v[72:75]
	v_mfma_f32_16x16x32_bf16 v[124:127], v[132:135], v[148:151], v[124:127]
	v_mfma_f32_16x16x32_bf16 v[120:123], v[140:143], v[148:151], v[120:123]
	v_mfma_f32_16x16x32_bf16 v[108:111], v[132:135], v[184:187], v[108:111]
	v_mfma_f32_16x16x32_bf16 v[104:107], v[140:143], v[184:187], v[104:107]
	v_mfma_f32_16x16x32_bf16 v[92:95], v[132:135], v[198:201], v[92:95]
	v_mfma_f32_16x16x32_bf16 v[88:91], v[140:143], v[198:201], v[88:91]
	v_mfma_f32_16x16x32_bf16 v[76:79], v[132:135], v[206:209], v[76:79]
	s_barrier
	v_mfma_f32_16x16x32_bf16 v[72:75], v[140:143], v[206:209], v[72:75]
	s_setprio 0
	s_add_i32 s14, 0, 0x1c000
	s_add_i32 s15, s41, s48
	v_add_u32_e32 v176, s14, v179
	v_lshl_add_u64 v[190:191], v[190:191], 0, s[22:23]
	s_mov_b32 m0, s15
	ds_read_b128 v[210:213], v176
	ds_read_b128 v[214:217], v176 offset:1024
	ds_read_b128 v[218:221], v176 offset:2048
	ds_read_b128 v[224:227], v176 offset:3072
	global_load_lds_dwordx4 v[190:191], off
	v_lshl_add_u64 v[190:191], v[228:229], 0, s[22:23]
	s_add_i32 m0, s15, 0x2000
	s_nop 0
	global_load_lds_dwordx4 v[190:191], off
	s_barrier
	s_waitcnt lgkmcnt(0)
	s_setprio 1
	s_waitcnt lgkmcnt(0)
	v_mfma_f32_16x16x32_bf16 v[116:119], v[210:213], v[144:147], v[116:119]
	v_mfma_f32_16x16x32_bf16 v[112:115], v[218:221], v[144:147], v[112:115]
	v_mfma_f32_16x16x32_bf16 v[100:103], v[210:213], v[152:155], v[100:103]
	v_mfma_f32_16x16x32_bf16 v[96:99], v[218:221], v[152:155], v[96:99]
	v_mfma_f32_16x16x32_bf16 v[84:87], v[210:213], v[194:197], v[84:87]
	v_mfma_f32_16x16x32_bf16 v[80:83], v[218:221], v[194:197], v[80:83]
	v_mfma_f32_16x16x32_bf16 v[68:71], v[210:213], v[202:205], v[68:71]
	v_mfma_f32_16x16x32_bf16 v[64:67], v[218:221], v[202:205], v[64:67]
	v_mfma_f32_16x16x32_bf16 v[116:119], v[214:217], v[148:151], v[116:119]
	v_mfma_f32_16x16x32_bf16 v[112:115], v[224:227], v[148:151], v[112:115]
	v_mfma_f32_16x16x32_bf16 v[100:103], v[214:217], v[184:187], v[100:103]
	v_mfma_f32_16x16x32_bf16 v[96:99], v[224:227], v[184:187], v[96:99]
	v_mfma_f32_16x16x32_bf16 v[84:87], v[214:217], v[198:201], v[84:87]
	v_mfma_f32_16x16x32_bf16 v[80:83], v[224:227], v[198:201], v[80:83]
	v_mfma_f32_16x16x32_bf16 v[68:71], v[214:217], v[206:209], v[68:71]
	s_barrier
	v_mfma_f32_16x16x32_bf16 v[64:67], v[224:227], v[206:209], v[64:67]
	s_setprio 0
	s_mov_b32 m0, s76
	v_lshl_add_u64 v[190:191], v[230:231], 0, s[22:23]
	ds_read_b128 v[144:147], v183 offset:49152
	ds_read_b128 v[148:151], v183 offset:50176
	ds_read_b128 v[152:155], v183 offset:51200
	ds_read_b128 v[184:187], v183 offset:52224
	ds_read_b128 v[194:197], v183 offset:53248
	ds_read_b128 v[198:201], v183 offset:54272
	ds_read_b128 v[202:205], v183 offset:55296
	ds_read_b128 v[206:209], v183 offset:56320
	global_load_lds_dwordx4 v[190:191], off
	v_lshl_add_u64 v[190:191], v[232:233], 0, s[22:23]
	s_mov_b32 m0, s77
	s_nop 0
	global_load_lds_dwordx4 v[190:191], off
	s_barrier
; #define PG8_STAGE(bufoff, gbase, voff) do { _Pragma("unroll") for (int _i = 0; _i < 2; ++_i) \
;         __builtin_amdgcn_global_load_lds((const unsigned*)((const char*)(gbase) + (voff)[_i]), (LAS unsigned*)(lds + (bufoff) + ldsw + _i * 8192), 16, 0, 0); } while (0)
; #define PG8_LDA(dst, b, h) do { _Pragma("unroll") for (int m = 0; m < 4; ++m) _Pragma("unroll") for (int k = 0; k < 2; ++k) dst[m][k] = *(const LAS bf16x8*)(lds + PG8_SA(b, h) + aoff + m * 2048 + k * 1024); } while (0)
; #define PG8_LDB(dst, b, h) do { _Pragma("unroll") for (int n = 0; n < 2; ++n) _Pragma("unroll") for (int k = 0; k < 2; ++k) dst[n][k] = *(const LAS bf16x8*)(lds + PG8_SB(b, h) + boff + n * 2048 + k * 1024); } while (0)
; #define PG8_WAIT_V(n) asm volatile("s_waitcnt vmcnt(" #n ")" ::: "memory")
; #define PG8_WAIT_L(n) asm volatile("s_waitcnt lgkmcnt(" #n ")" ::: "memory")
; #define PG8_BAR __builtin_amdgcn_s_barrier()
; #define PG8_SCHED __builtin_amdgcn_sched_barrier(0)
; template <class Epi0, class Epi1>
; DI void gemm_phase_dual(LAS unsigned char* lds, const Gemm g, const Gemm g1, const StaticOrder S, const Epi0 E0, const Epi1 E1) {
;     ...
;             PG8_WAIT_L(8); PG8_BAR; PG8_WAIT_L(0); PG8_MMA(0, 0, At, B0); PG8_BAR; PG8_SCHED;
;             PG8_LDB(B1, 1, 1); PG8_STAGE(PG8_SB(1, 0), b3, voffB);
;             PG8_BAR; PG8_WAIT_L(0); PG8_MMA(0, 1, At, B1); PG8_BAR;
;             PG8_LDA(At, 1, 1); PG8_STAGE(PG8_SA(1, 0), a3, voffA);
;             PG8_BAR; PG8_WAIT_L(0); PG8_MMA(1, 0, At, B0); PG8_BAR; PG8_SCHED;
;             PG8_STAGE(PG8_SB(1, 1), b3 + hstep, voffB);
;             PG8_WAIT_V(6); PG8_BAR; PG8_MMA(1, 1, At, B1); PG8_BAR;
;         }
;         if (ui & 1) E1(acc, cur, wr, wc, fr, fq); else E0(acc, cur, wr, wc, fr, fq);
;     DI void operator()(AccRef acc, const Unit& u, int wr, int wc, int fr, int fq) const {
;         const int row0 = u.pm * 256 + wr * 64 + fr;
;         bf16_t* Gp = gab + (size_t)(u.pm * 8 + u.pn) * 65536 + (wr * 64 + fr) * 256 + wc * 32 + 8 * fq;
;         const RowScales rsc = load_rowscales(ss, row0);
; #pragma unroll
;         for (int ai = 0; ai < 2; ++ai)
; #pragma unroll
;             for (int m = 0; m < 4; ++m)
; #pragma unroll
;                 for (int bj = 0; bj < 2; ++bj) {
;                     const float rs = rsc.r[ai][m];
;                     const f32x4 r0 = acc[ai][bj][m][0] * rs, r1 = acc[ai][bj][m][1] * rs;
	s_waitcnt lgkmcnt(0)
	s_setprio 1
	s_waitcnt lgkmcnt(0)
	v_mfma_f32_16x16x32_bf16 v[60:63], v[128:131], v[144:147], v[60:63]
	v_mfma_f32_16x16x32_bf16 v[56:59], v[136:139], v[144:147], v[56:59]
	v_mfma_f32_16x16x32_bf16 v[44:47], v[128:131], v[152:155], v[44:47]
	v_mfma_f32_16x16x32_bf16 v[40:43], v[136:139], v[152:155], v[40:43]
	v_mfma_f32_16x16x32_bf16 v[28:31], v[128:131], v[194:197], v[28:31]
	v_mfma_f32_16x16x32_bf16 v[24:27], v[136:139], v[194:197], v[24:27]
	v_mfma_f32_16x16x32_bf16 v[12:15], v[128:131], v[202:205], v[12:15]
	v_mfma_f32_16x16x32_bf16 v[8:11], v[136:139], v[202:205], v[8:11]
	v_mfma_f32_16x16x32_bf16 v[60:63], v[132:135], v[148:151], v[60:63]
	v_mfma_f32_16x16x32_bf16 v[56:59], v[140:143], v[148:151], v[56:59]
	v_mfma_f32_16x16x32_bf16 v[44:47], v[132:135], v[184:187], v[44:47]
	v_mfma_f32_16x16x32_bf16 v[40:43], v[140:143], v[184:187], v[40:43]
	v_mfma_f32_16x16x32_bf16 v[28:31], v[132:135], v[198:201], v[28:31]
	v_mfma_f32_16x16x32_bf16 v[24:27], v[140:143], v[198:201], v[24:27]
	v_mfma_f32_16x16x32_bf16 v[12:15], v[132:135], v[206:209], v[12:15]
	s_barrier
	v_mfma_f32_16x16x32_bf16 v[8:11], v[140:143], v[206:209], v[8:11]
	s_setprio 0
	s_add_u32 s12, s12, 0x40080
	s_addc_u32 s13, s13, 0
	s_add_i32 s14, s14, s48
	v_lshl_add_u64 v[128:129], s[12:13], 0, v[158:159]
	s_mov_b32 m0, s14
	s_nop 0
	global_load_lds_dwordx4 v[128:129], off
	v_lshl_add_u64 v[128:129], s[12:13], 0, v[162:163]
	s_add_i32 m0, s14, 0x2000
	s_nop 0
	global_load_lds_dwordx4 v[128:129], off
	s_waitcnt vmcnt(6)
	s_barrier
	s_setprio 1
	v_mfma_f32_16x16x32_bf16 v[52:55], v[210:213], v[144:147], v[52:55]
	v_mfma_f32_16x16x32_bf16 v[48:51], v[218:221], v[144:147], v[48:51]
	v_mfma_f32_16x16x32_bf16 v[36:39], v[210:213], v[152:155], v[36:39]
	v_mfma_f32_16x16x32_bf16 v[32:35], v[218:221], v[152:155], v[32:35]
	v_mfma_f32_16x16x32_bf16 v[20:23], v[210:213], v[194:197], v[20:23]
	v_mfma_f32_16x16x32_bf16 v[16:19], v[218:221], v[194:197], v[16:19]
	v_mfma_f32_16x16x32_bf16 v[4:7], v[210:213], v[202:205], v[4:7]
	v_mfma_f32_16x16x32_bf16 v[0:3], v[218:221], v[202:205], v[0:3]
	v_mfma_f32_16x16x32_bf16 v[52:55], v[214:217], v[148:151], v[52:55]
	v_mfma_f32_16x16x32_bf16 v[48:51], v[224:227], v[148:151], v[48:51]
	v_mfma_f32_16x16x32_bf16 v[36:39], v[214:217], v[184:187], v[36:39]
	v_mfma_f32_16x16x32_bf16 v[32:35], v[224:227], v[184:187], v[32:35]
	v_mfma_f32_16x16x32_bf16 v[20:23], v[214:217], v[198:201], v[20:23]
	v_mfma_f32_16x16x32_bf16 v[16:19], v[224:227], v[198:201], v[16:19]
	v_mfma_f32_16x16x32_bf16 v[4:7], v[214:217], v[206:209], v[4:7]
	s_barrier
	v_mfma_f32_16x16x32_bf16 v[0:3], v[224:227], v[206:209], v[0:3]
	s_setprio 0
	s_add_i32 s19, s19, 2
	s_add_u32 s10, s10, 0x100
	s_addc_u32 s11, s11, 0
	s_add_u32 s17, s17, 0x100
	s_addc_u32 s18, s18, 0
	s_cmp_gt_u32 s19, 13
	s_cbranch_scc0 .LBB0_632
	v_lshl_add_u32 v128, s0, 8, v177
	s_mov_b64 s[6:7], -1
	s_and_b64 vcc, exec, s[8:9]
	v_ashrrev_i32_e32 v129, 31, v128
	s_cbranch_vccz .LBB0_635
	v_lshl_add_u64 v[130:131], v[128:129], 2, s[60:61]
	global_load_dword v132, v[130:131], off
	global_load_dword v133, v[130:131], off offset:64
	global_load_dword v134, v[130:131], off offset:128
	global_load_dword v135, v[130:131], off offset:192
	global_load_dword v136, v[130:131], off offset:512
	global_load_dword v137, v[130:131], off offset:576
	global_load_dword v138, v[130:131], off offset:640
	global_load_dword v139, v[130:131], off offset:704
	s_lshl_b32 s0, s0, 3
	s_add_i32 s0, s0, s87
	s_ashr_i32 s1, s0, 31
	s_lshl_b64 s[0:1], s[0:1], 17
	v_lshl_add_u64 v[130:131], v[166:167], 0, s[0:1]
	s_mov_b64 s[6:7], 0
	s_waitcnt vmcnt(0)
	v_fmamk_f32 v132, v132, 0x3a800000, v193
	v_mul_f32_e32 v140, 0x4b800000, v132
	v_cmp_gt_f32_e32 vcc, s80, v132
	v_fmamk_f32 v134, v134, 0x3a800000, v193
	v_fmamk_f32 v136, v136, 0x3a800000, v193
	v_fmamk_f32 v137, v137, 0x3a800000, v193
	v_fmamk_f32 v138, v138, 0x3a800000, v193
	v_fmamk_f32 v139, v139, 0x3a800000, v193
	v_mul_f32_e32 v144, 0x4b800000, v136
	v_mul_f32_e32 v145, 0x4b800000, v137
	v_cndmask_b32_e32 v132, v132, v140, vcc
	v_cmp_gt_f32_e64 s[12:13], s80, v136
	v_cmp_gt_f32_e64 s[14:15], s80, v137
	v_fmamk_f32 v133, v133, 0x3a800000, v193
	v_fmamk_f32 v135, v135, 0x3a800000, v193
	v_mul_f32_e32 v142, 0x4b800000, v134
	v_mul_f32_e32 v146, 0x4b800000, v138
	v_mul_f32_e32 v147, 0x4b800000, v139
	v_cmp_gt_f32_e64 s[8:9], s80, v134
	v_cndmask_b32_e64 v136, v136, v144, s[12:13]
	v_cndmask_b32_e64 v137, v137, v145, s[14:15]
	v_cmp_gt_f32_e64 s[16:17], s80, v138
	v_cmp_gt_f32_e64 s[18:19], s80, v139
	v_rsq_f32_e32 v132, v132
	v_mul_f32_e32 v141, 0x4b800000, v133
	v_mul_f32_e32 v143, 0x4b800000, v135
	v_cmp_gt_f32_e64 s[0:1], s80, v133
	v_cndmask_b32_e64 v134, v134, v142, s[8:9]
	v_cmp_gt_f32_e64 s[10:11], s80, v135
	v_cndmask_b32_e64 v138, v138, v146, s[16:17]
	v_cndmask_b32_e64 v139, v139, v147, s[18:19]
	v_rsq_f32_e32 v136, v136
	v_rsq_f32_e32 v137, v137
	v_cndmask_b32_e64 v133, v133, v141, s[0:1]
	v_cndmask_b32_e64 v135, v135, v143, s[10:11]
	v_rsq_f32_e32 v134, v134
	v_rsq_f32_e32 v141, v138
	v_rsq_f32_e32 v139, v139
	v_rsq_f32_e32 v133, v133
	v_rsq_f32_e32 v135, v135
	v_mul_f32_e32 v138, 0x45800000, v132
	v_mul_f32_e32 v144, 0x45800000, v136
	v_mul_f32_e32 v145, 0x45800000, v137
	v_cndmask_b32_e32 v148, v132, v138, vcc
	v_mul_f32_e32 v142, 0x45800000, v134
	v_mul_f32_e32 v146, 0x45800000, v141
	v_mul_f32_e32 v147, 0x45800000, v139
	v_cndmask_b32_e64 v138, v136, v144, s[12:13]
	v_cndmask_b32_e64 v136, v137, v145, s[14:15]
	v_pk_mul_f32 v[144:145], v[126:127], v[148:149] op_sel_hi:[1,0]
	v_pk_mul_f32 v[152:153], v[122:123], v[148:149] op_sel_hi:[1,0]
; DI unsigned pk_bf16(float lo, float hi) { f32x2 v = {lo, hi}; return __builtin_bit_cast(unsigned, __builtin_convertvector(v, bf16v2)); }
; DI float fast_sigmoid(float x) { return __builtin_amdgcn_rcpf(1.0f + __expf(-x)); }
;     DI void operator()(AccRef acc, const Unit& u, int wr, int wc, int fr, int fq) const {
;     ...
; #pragma unroll
;         for (int ai = 0; ai < 2; ++ai)
; #pragma unroll
;             for (int m = 0; m < 4; ++m)
; #pragma unroll
;                 for (int bj = 0; bj < 2; ++bj) {
;                     const float rs = rsc.r[ai][m];
;                     const f32x4 r0 = acc[ai][bj][m][0] * rs, r1 = acc[ai][bj][m][1] * rs;
;                     u32x4 w;
;                     w.x = pk_bf16(fast_sigmoid(r0[0]), fast_sigmoid(r0[1])); w.y = pk_bf16(fast_sigmoid(r0[2]), fast_sigmoid(r0[3]));
;                     w.z = pk_bf16(fast_sigmoid(r1[0]), fast_sigmoid(r1[1])); w.w = pk_bf16(fast_sigmoid(r1[2]), fast_sigmoid(r1[3]));
;                     *(u32x4*)(Gp + (ai * 128 + m * 16) * 256 + bj * 128) = w;
;                 }
	v_mul_f32_e32 v140, 0x45800000, v133
	v_mul_f32_e32 v143, 0x45800000, v135
	v_cndmask_b32_e64 v142, v134, v142, s[8:9]
	v_cndmask_b32_e64 v134, v141, v146, s[16:17]
	v_cndmask_b32_e64 v132, v139, v147, s[18:19]
	v_pk_mul_f32 v[146:147], v[124:125], v[148:149] op_sel_hi:[1,0]
	v_pk_mul_f32 v[154:155], v[120:121], v[148:149] op_sel_hi:[1,0]
	v_mul_f32_e32 v137, 0xbfb8aa3b, v144
	v_mul_f32_e32 v144, 0xbfb8aa3b, v152
	v_cndmask_b32_e64 v150, v133, v140, s[0:1]
	v_cndmask_b32_e64 v140, v135, v143, s[10:11]
	v_mul_f32_e32 v133, 0xbfb8aa3b, v146
	v_mul_f32_e32 v135, 0xbfb8aa3b, v147
	v_mul_f32_e32 v139, 0xbfb8aa3b, v145
	v_mul_f32_e32 v141, 0xbfb8aa3b, v154
	v_mul_f32_e32 v143, 0xbfb8aa3b, v155
	v_exp_f32_e32 v144, v144
	v_mul_f32_e32 v145, 0xbfb8aa3b, v153
	v_exp_f32_e32 v133, v133
	v_exp_f32_e32 v135, v135
	v_exp_f32_e32 v137, v137
	v_exp_f32_e32 v139, v139
	v_exp_f32_e32 v141, v141
	v_exp_f32_e32 v143, v143
	v_exp_f32_e32 v145, v145
	v_add_f32_e32 v144, 1.0, v144
	v_add_f32_e32 v133, 1.0, v133
	v_add_f32_e32 v135, 1.0, v135
	v_add_f32_e32 v137, 1.0, v137
	v_add_f32_e32 v139, 1.0, v139
	v_add_f32_e32 v141, 1.0, v141
	v_add_f32_e32 v143, 1.0, v143
	v_rcp_f32_e32 v147, v144
	v_add_f32_e32 v144, 1.0, v145
	v_rcp_f32_e32 v133, v133
	v_rcp_f32_e32 v135, v135
	v_rcp_f32_e32 v137, v137
	v_rcp_f32_e32 v139, v139
	v_rcp_f32_e32 v141, v141
	v_rcp_f32_e32 v143, v143
	v_rcp_f32_e32 v149, v144
	v_cvt_pk_bf16_f32 v144, v133, v135
	v_cvt_pk_bf16_f32 v145, v137, v139
	v_cvt_pk_bf16_f32 v146, v141, v143
	v_cvt_pk_bf16_f32 v147, v147, v149
	global_store_dwordx4 v[130:131], v[144:147], off
	v_pk_mul_f32 v[152:153], v[114:115], v[148:149] op_sel_hi:[1,0]
	s_nop 0
	v_pk_mul_f32 v[144:145], v[118:119], v[148:149] op_sel_hi:[1,0]
	v_pk_mul_f32 v[146:147], v[116:117], v[148:149] op_sel_hi:[1,0]
	v_mul_f32_e32 v137, 0xbfb8aa3b, v144
	v_mul_f32_e32 v133, 0xbfb8aa3b, v146
	v_mul_f32_e32 v135, 0xbfb8aa3b, v147
	v_pk_mul_f32 v[146:147], v[112:113], v[148:149] op_sel_hi:[1,0]
	v_mul_f32_e32 v144, 0xbfb8aa3b, v152
	v_mul_f32_e32 v139, 0xbfb8aa3b, v145
	v_mul_f32_e32 v141, 0xbfb8aa3b, v146
	v_mul_f32_e32 v143, 0xbfb8aa3b, v147
	v_exp_f32_e32 v144, v144
	v_mul_f32_e32 v145, 0xbfb8aa3b, v153
	v_exp_f32_e32 v133, v133
	v_exp_f32_e32 v135, v135
	v_exp_f32_e32 v137, v137
	v_exp_f32_e32 v139, v139
	v_exp_f32_e32 v141, v141
	v_exp_f32_e32 v143, v143
	v_exp_f32_e32 v145, v145
	v_add_f32_e32 v144, 1.0, v144
	v_add_f32_e32 v133, 1.0, v133
	v_add_f32_e32 v135, 1.0, v135
	v_add_f32_e32 v137, 1.0, v137
	v_add_f32_e32 v139, 1.0, v139
	v_add_f32_e32 v141, 1.0, v141
	v_add_f32_e32 v143, 1.0, v143
	v_rcp_f32_e32 v147, v144
	v_add_f32_e32 v144, 1.0, v145
	v_rcp_f32_e32 v133, v133
	v_rcp_f32_e32 v135, v135
	v_rcp_f32_e32 v137, v137
	v_rcp_f32_e32 v139, v139
	v_rcp_f32_e32 v141, v141
	v_rcp_f32_e32 v143, v143
	v_rcp_f32_e32 v148, v144
	v_cvt_pk_bf16_f32 v144, v133, v135
	v_cvt_pk_bf16_f32 v145, v137, v139
	v_cvt_pk_bf16_f32 v146, v141, v143
	v_cvt_pk_bf16_f32 v147, v147, v148
	global_store_dwordx4 v[130:131], v[144:147], off offset:256
	v_pk_mul_f32 v[148:149], v[106:107], v[150:151] op_sel_hi:[1,0]
	v_pk_mul_f32 v[152:153], v[98:99], v[150:151] op_sel_hi:[1,0]
	v_pk_mul_f32 v[144:145], v[110:111], v[150:151] op_sel_hi:[1,0]
	v_pk_mul_f32 v[146:147], v[108:109], v[150:151] op_sel_hi:[1,0]
	v_mul_f32_e32 v137, 0xbfb8aa3b, v144
	v_mul_f32_e32 v144, 0xbfb8aa3b, v148
	v_mul_f32_e32 v133, 0xbfb8aa3b, v146
	v_mul_f32_e32 v135, 0xbfb8aa3b, v147
	v_pk_mul_f32 v[146:147], v[104:105], v[150:151] op_sel_hi:[1,0]
	v_mul_f32_e32 v139, 0xbfb8aa3b, v145
	v_exp_f32_e32 v144, v144
	v_mul_f32_e32 v145, 0xbfb8aa3b, v149
	v_mul_f32_e32 v141, 0xbfb8aa3b, v146
	v_mul_f32_e32 v143, 0xbfb8aa3b, v147
	v_exp_f32_e32 v145, v145
	v_exp_f32_e32 v133, v133
	v_exp_f32_e32 v135, v135
	v_exp_f32_e32 v137, v137
	v_exp_f32_e32 v139, v139
	v_exp_f32_e32 v141, v141
	v_exp_f32_e32 v143, v143
	v_add_f32_e32 v144, 1.0, v144
	v_rcp_f32_e32 v147, v144
	v_add_f32_e32 v144, 1.0, v145
	v_add_f32_e32 v133, 1.0, v133
	v_add_f32_e32 v135, 1.0, v135
	v_add_f32_e32 v137, 1.0, v137
	v_add_f32_e32 v139, 1.0, v139
	v_add_f32_e32 v141, 1.0, v141
	v_add_f32_e32 v143, 1.0, v143
	v_rcp_f32_e32 v148, v144
	v_rcp_f32_e32 v133, v133
	v_rcp_f32_e32 v135, v135
	v_rcp_f32_e32 v137, v137
	v_rcp_f32_e32 v139, v139
	v_rcp_f32_e32 v141, v141
	v_rcp_f32_e32 v143, v143
	v_cvt_pk_bf16_f32 v147, v147, v148
	v_add_co_u32_e32 v148, vcc, s59, v130
	v_cvt_pk_bf16_f32 v144, v133, v135
	v_cvt_pk_bf16_f32 v145, v137, v139
	v_cvt_pk_bf16_f32 v146, v141, v143
	v_addc_co_u32_e32 v149, vcc, 0, v131, vcc
	global_store_dwordx4 v[148:149], v[144:147], off
	s_nop 1
	v_pk_mul_f32 v[144:145], v[102:103], v[150:151] op_sel_hi:[1,0]
	v_pk_mul_f32 v[146:147], v[100:101], v[150:151] op_sel_hi:[1,0]
	v_mul_f32_e32 v137, 0xbfb8aa3b, v144
	v_mul_f32_e32 v133, 0xbfb8aa3b, v146
	v_mul_f32_e32 v135, 0xbfb8aa3b, v147
	v_pk_mul_f32 v[146:147], v[96:97], v[150:151] op_sel_hi:[1,0]
	v_mul_f32_e32 v144, 0xbfb8aa3b, v152
	v_mul_f32_e32 v139, 0xbfb8aa3b, v145
	v_mul_f32_e32 v141, 0xbfb8aa3b, v146
	v_mul_f32_e32 v143, 0xbfb8aa3b, v147
	v_exp_f32_e32 v144, v144
	v_mul_f32_e32 v145, 0xbfb8aa3b, v153
	v_exp_f32_e32 v133, v133
	v_exp_f32_e32 v135, v135
	v_exp_f32_e32 v137, v137
	v_exp_f32_e32 v139, v139
	v_exp_f32_e32 v141, v141
	v_exp_f32_e32 v143, v143
	v_exp_f32_e32 v145, v145
	v_add_f32_e32 v144, 1.0, v144
	v_add_f32_e32 v133, 1.0, v133
	v_add_f32_e32 v135, 1.0, v135
	v_add_f32_e32 v137, 1.0, v137
	v_add_f32_e32 v139, 1.0, v139
	v_add_f32_e32 v141, 1.0, v141
	v_add_f32_e32 v143, 1.0, v143
	v_rcp_f32_e32 v147, v144
	v_add_f32_e32 v144, 1.0, v145
	v_rcp_f32_e32 v133, v133
	v_rcp_f32_e32 v135, v135
; DI unsigned pk_bf16(float lo, float hi) { f32x2 v = {lo, hi}; return __builtin_bit_cast(unsigned, __builtin_convertvector(v, bf16v2)); }
; DI float fast_sigmoid(float x) { return __builtin_amdgcn_rcpf(1.0f + __expf(-x)); }
;     DI void operator()(AccRef acc, const Unit& u, int wr, int wc, int fr, int fq) const {
;     ...
; #pragma unroll
;         for (int ai = 0; ai < 2; ++ai)
; #pragma unroll
;             for (int m = 0; m < 4; ++m)
; #pragma unroll
;                 for (int bj = 0; bj < 2; ++bj) {
;                     const float rs = rsc.r[ai][m];
;                     const f32x4 r0 = acc[ai][bj][m][0] * rs, r1 = acc[ai][bj][m][1] * rs;
;                     u32x4 w;
;                     w.x = pk_bf16(fast_sigmoid(r0[0]), fast_sigmoid(r0[1])); w.y = pk_bf16(fast_sigmoid(r0[2]), fast_sigmoid(r0[3]));
;                     w.z = pk_bf16(fast_sigmoid(r1[0]), fast_sigmoid(r1[1])); w.w = pk_bf16(fast_sigmoid(r1[2]), fast_sigmoid(r1[3]));
;                     *(u32x4*)(Gp + (ai * 128 + m * 16) * 256 + bj * 128) = w;
;                 }
	v_rcp_f32_e32 v137, v137
	v_rcp_f32_e32 v139, v139
	v_rcp_f32_e32 v141, v141
	v_rcp_f32_e32 v143, v143
	v_rcp_f32_e32 v150, v144
	v_cvt_pk_bf16_f32 v144, v133, v135
	v_cvt_pk_bf16_f32 v145, v137, v139
	v_cvt_pk_bf16_f32 v146, v141, v143
	v_cvt_pk_bf16_f32 v147, v147, v150
	global_store_dwordx4 v[148:149], v[144:147], off offset:256
	v_pk_mul_f32 v[148:149], v[90:91], v[142:143] op_sel_hi:[1,0]
	s_nop 0
	v_pk_mul_f32 v[144:145], v[94:95], v[142:143] op_sel_hi:[1,0]
	v_pk_mul_f32 v[146:147], v[92:93], v[142:143] op_sel_hi:[1,0]
	v_mul_f32_e32 v137, 0xbfb8aa3b, v144
	v_mul_f32_e32 v144, 0xbfb8aa3b, v148
	v_mul_f32_e32 v133, 0xbfb8aa3b, v146
	v_mul_f32_e32 v135, 0xbfb8aa3b, v147
	v_pk_mul_f32 v[146:147], v[88:89], v[142:143] op_sel_hi:[1,0]
	v_mul_f32_e32 v139, 0xbfb8aa3b, v145
	v_exp_f32_e32 v144, v144
	v_mul_f32_e32 v145, 0xbfb8aa3b, v149
	v_mul_f32_e32 v141, 0xbfb8aa3b, v146
	v_mul_f32_e32 v143, 0xbfb8aa3b, v147
	v_exp_f32_e32 v145, v145
	v_exp_f32_e32 v133, v133
	v_exp_f32_e32 v135, v135
	v_exp_f32_e32 v137, v137
	v_exp_f32_e32 v139, v139
	v_exp_f32_e32 v141, v141
	v_exp_f32_e32 v143, v143
	v_add_f32_e32 v144, 1.0, v144
	v_rcp_f32_e32 v147, v144
	v_add_f32_e32 v144, 1.0, v145
	v_add_f32_e32 v133, 1.0, v133
	v_add_f32_e32 v135, 1.0, v135
	v_add_f32_e32 v137, 1.0, v137
	v_add_f32_e32 v139, 1.0, v139
	v_add_f32_e32 v141, 1.0, v141
	v_add_f32_e32 v143, 1.0, v143
	v_rcp_f32_e32 v148, v144
	v_rcp_f32_e32 v133, v133
	v_rcp_f32_e32 v135, v135
	v_rcp_f32_e32 v137, v137
	v_rcp_f32_e32 v139, v139
	v_rcp_f32_e32 v141, v141
	v_rcp_f32_e32 v143, v143
	v_cvt_pk_bf16_f32 v147, v147, v148
	v_add_co_u32_e32 v148, vcc, s66, v130
	v_cvt_pk_bf16_f32 v144, v133, v135
	v_cvt_pk_bf16_f32 v145, v137, v139
	v_cvt_pk_bf16_f32 v146, v141, v143
	v_addc_co_u32_e32 v149, vcc, 0, v131, vcc
	global_store_dwordx4 v[148:149], v[144:147], off
	v_pk_mul_f32 v[150:151], v[82:83], v[142:143] op_sel_hi:[1,0]
	s_nop 0
	v_pk_mul_f32 v[144:145], v[86:87], v[142:143] op_sel_hi:[1,0]
	v_pk_mul_f32 v[146:147], v[84:85], v[142:143] op_sel_hi:[1,0]
	v_pk_mul_f32 v[142:143], v[80:81], v[142:143] op_sel_hi:[1,0]
	v_mul_f32_e32 v133, 0xbfb8aa3b, v146
	v_mul_f32_e32 v141, 0xbfb8aa3b, v142
	v_mul_f32_e32 v142, 0xbfb8aa3b, v143
	v_exp_f32_e32 v142, v142
	v_mul_f32_e32 v143, 0xbfb8aa3b, v150
	v_mul_f32_e32 v135, 0xbfb8aa3b, v147
	v_mul_f32_e32 v137, 0xbfb8aa3b, v144
	v_mul_f32_e32 v139, 0xbfb8aa3b, v145
	v_exp_f32_e32 v143, v143
	v_mul_f32_e32 v144, 0xbfb8aa3b, v151
	v_exp_f32_e32 v133, v133
	v_exp_f32_e32 v135, v135
	v_exp_f32_e32 v137, v137
	v_exp_f32_e32 v139, v139
	v_exp_f32_e32 v141, v141
	v_exp_f32_e32 v144, v144
	v_add_f32_e32 v142, 1.0, v142
	v_rcp_f32_e32 v145, v142
	v_add_f32_e32 v142, 1.0, v143
	v_add_f32_e32 v133, 1.0, v133
	v_add_f32_e32 v135, 1.0, v135
	v_add_f32_e32 v137, 1.0, v137
	v_add_f32_e32 v139, 1.0, v139
	v_add_f32_e32 v141, 1.0, v141
	v_rcp_f32_e32 v146, v142
	v_add_f32_e32 v142, 1.0, v144
	v_rcp_f32_e32 v133, v133
	v_rcp_f32_e32 v135, v135
	v_rcp_f32_e32 v137, v137
	v_rcp_f32_e32 v139, v139
	v_rcp_f32_e32 v141, v141
	v_rcp_f32_e32 v147, v142
	v_cvt_pk_bf16_f32 v142, v133, v135
	v_cvt_pk_bf16_f32 v143, v137, v139
	v_cvt_pk_bf16_f32 v144, v141, v145
	v_cvt_pk_bf16_f32 v145, v146, v147
	global_store_dwordx4 v[148:149], v[142:145], off offset:256
	v_pk_mul_f32 v[146:147], v[74:75], v[140:141] op_sel_hi:[1,0]
	s_nop 0
	v_pk_mul_f32 v[144:145], v[76:77], v[140:141] op_sel_hi:[1,0]
	v_pk_mul_f32 v[142:143], v[78:79], v[140:141] op_sel_hi:[1,0]
	v_mul_f32_e32 v133, 0xbfb8aa3b, v144
	v_mul_f32_e32 v135, 0xbfb8aa3b, v145
	v_pk_mul_f32 v[144:145], v[72:73], v[140:141] op_sel_hi:[1,0]
	v_mul_f32_e32 v137, 0xbfb8aa3b, v142
	v_mul_f32_e32 v142, 0xbfb8aa3b, v145
	v_mul_f32_e32 v139, 0xbfb8aa3b, v143
	v_exp_f32_e32 v142, v142
	v_mul_f32_e32 v143, 0xbfb8aa3b, v146
	v_mul_f32_e32 v141, 0xbfb8aa3b, v144
	v_exp_f32_e32 v143, v143
	v_mul_f32_e32 v144, 0xbfb8aa3b, v147
	v_exp_f32_e32 v141, v141
	v_exp_f32_e32 v144, v144
	v_exp_f32_e32 v133, v133
	v_exp_f32_e32 v135, v135
	v_exp_f32_e32 v137, v137
	v_exp_f32_e32 v139, v139
	v_add_f32_e32 v142, 1.0, v142
	v_rcp_f32_e32 v145, v142
	v_add_f32_e32 v142, 1.0, v143
	v_add_f32_e32 v141, 1.0, v141
	v_rcp_f32_e32 v146, v142
	v_add_f32_e32 v142, 1.0, v144
	v_add_f32_e32 v133, 1.0, v133
	v_add_f32_e32 v135, 1.0, v135
	v_add_f32_e32 v137, 1.0, v137
	v_add_f32_e32 v139, 1.0, v139
	v_rcp_f32_e32 v141, v141
	v_rcp_f32_e32 v147, v142
	v_rcp_f32_e32 v133, v133
	v_rcp_f32_e32 v135, v135
	v_rcp_f32_e32 v137, v137
	v_rcp_f32_e32 v139, v139
	v_cvt_pk_bf16_f32 v144, v141, v145
	v_cvt_pk_bf16_f32 v145, v146, v147
	v_add_co_u32_e32 v146, vcc, s67, v130
	v_cvt_pk_bf16_f32 v142, v133, v135
	v_cvt_pk_bf16_f32 v143, v137, v139
	v_addc_co_u32_e32 v147, vcc, 0, v131, vcc
	global_store_dwordx4 v[146:147], v[142:145], off
	v_pk_mul_f32 v[148:149], v[66:67], v[140:141] op_sel_hi:[1,0]
	s_nop 0
	v_pk_mul_f32 v[142:143], v[70:71], v[140:141] op_sel_hi:[1,0]
	v_pk_mul_f32 v[144:145], v[68:69], v[140:141] op_sel_hi:[1,0]
	v_pk_mul_f32 v[140:141], v[64:65], v[140:141] op_sel_hi:[1,0]
	v_mul_f32_e32 v137, 0xbfb8aa3b, v142
	v_mul_f32_e32 v140, 0xbfb8aa3b, v140
	v_exp_f32_e32 v140, v140
	v_mul_f32_e32 v141, 0xbfb8aa3b, v141
	v_exp_f32_e32 v141, v141
	v_mul_f32_e32 v133, 0xbfb8aa3b, v144
	v_add_f32_e32 v140, 1.0, v140
	v_rcp_f32_e32 v142, v140
	v_add_f32_e32 v140, 1.0, v141
	v_mul_f32_e32 v141, 0xbfb8aa3b, v148
	v_mul_f32_e32 v135, 0xbfb8aa3b, v145
	v_mul_f32_e32 v139, 0xbfb8aa3b, v143
	v_exp_f32_e32 v141, v141
	v_mul_f32_e32 v143, 0xbfb8aa3b, v149
	v_exp_f32_e32 v133, v133
	v_exp_f32_e32 v135, v135
	v_exp_f32_e32 v137, v137
	v_exp_f32_e32 v139, v139
	v_exp_f32_e32 v143, v143
; DI unsigned pk_bf16(float lo, float hi) { f32x2 v = {lo, hi}; return __builtin_bit_cast(unsigned, __builtin_convertvector(v, bf16v2)); }
; DI float fast_sigmoid(float x) { return __builtin_amdgcn_rcpf(1.0f + __expf(-x)); }
;     DI void operator()(AccRef acc, const Unit& u, int wr, int wc, int fr, int fq) const {
;     ...
; #pragma unroll
;         for (int ai = 0; ai < 2; ++ai)
; #pragma unroll
;             for (int m = 0; m < 4; ++m)
; #pragma unroll
;                 for (int bj = 0; bj < 2; ++bj) {
;                     const float rs = rsc.r[ai][m];
;                     const f32x4 r0 = acc[ai][bj][m][0] * rs, r1 = acc[ai][bj][m][1] * rs;
;                     u32x4 w;
;                     w.x = pk_bf16(fast_sigmoid(r0[0]), fast_sigmoid(r0[1])); w.y = pk_bf16(fast_sigmoid(r0[2]), fast_sigmoid(r0[3]));
;                     w.z = pk_bf16(fast_sigmoid(r1[0]), fast_sigmoid(r1[1])); w.w = pk_bf16(fast_sigmoid(r1[2]), fast_sigmoid(r1[3]));
;                     *(u32x4*)(Gp + (ai * 128 + m * 16) * 256 + bj * 128) = w;
;                 }
	v_rcp_f32_e32 v144, v140
	v_add_f32_e32 v140, 1.0, v141
	v_add_f32_e32 v133, 1.0, v133
	v_add_f32_e32 v135, 1.0, v135
	v_add_f32_e32 v137, 1.0, v137
	v_add_f32_e32 v139, 1.0, v139
	v_rcp_f32_e32 v145, v140
	v_add_f32_e32 v140, 1.0, v143
	v_rcp_f32_e32 v133, v133
	v_rcp_f32_e32 v135, v135
	v_rcp_f32_e32 v137, v137
	v_rcp_f32_e32 v139, v139
	v_rcp_f32_e32 v143, v140
	v_cvt_pk_bf16_f32 v140, v133, v135
	v_cvt_pk_bf16_f32 v142, v142, v144
	v_cvt_pk_bf16_f32 v141, v137, v139
	v_cvt_pk_bf16_f32 v143, v145, v143
	global_store_dwordx4 v[146:147], v[140:143], off offset:256
	v_pk_mul_f32 v[144:145], v[58:59], v[138:139] op_sel_hi:[1,0]
	s_nop 0
	v_pk_mul_f32 v[142:143], v[60:61], v[138:139] op_sel_hi:[1,0]
	v_pk_mul_f32 v[140:141], v[62:63], v[138:139] op_sel_hi:[1,0]
	v_mul_f32_e32 v133, 0xbfb8aa3b, v142
	v_mul_f32_e32 v135, 0xbfb8aa3b, v143
	v_pk_mul_f32 v[142:143], v[56:57], v[138:139] op_sel_hi:[1,0]
	v_mul_f32_e32 v137, 0xbfb8aa3b, v140
	v_mul_f32_e32 v140, 0xbfb8aa3b, v142
	v_mul_f32_e32 v139, 0xbfb8aa3b, v141
	v_exp_f32_e32 v140, v140
	v_mul_f32_e32 v141, 0xbfb8aa3b, v143
	v_exp_f32_e32 v141, v141
	v_mul_f32_e32 v143, 0xbfb8aa3b, v145
	v_add_f32_e32 v140, 1.0, v140
	v_rcp_f32_e32 v142, v140
	v_add_f32_e32 v140, 1.0, v141
	v_mul_f32_e32 v141, 0xbfb8aa3b, v144
	v_exp_f32_e32 v141, v141
	v_exp_f32_e32 v133, v133
	v_exp_f32_e32 v135, v135
	v_exp_f32_e32 v137, v137
	v_exp_f32_e32 v139, v139
	v_exp_f32_e32 v143, v143
	v_rcp_f32_e32 v144, v140
	v_add_f32_e32 v140, 1.0, v141
	v_add_f32_e32 v133, 1.0, v133
	v_add_f32_e32 v135, 1.0, v135
	v_add_f32_e32 v137, 1.0, v137
	v_add_f32_e32 v139, 1.0, v139
	v_rcp_f32_e32 v145, v140
	v_add_f32_e32 v140, 1.0, v143
	v_rcp_f32_e32 v133, v133
	v_rcp_f32_e32 v135, v135
	v_rcp_f32_e32 v137, v137
	v_rcp_f32_e32 v139, v139
	v_rcp_f32_e32 v143, v140
	v_cvt_pk_bf16_f32 v142, v142, v144
	v_add_co_u32_e32 v144, vcc, s62, v130
	v_cvt_pk_bf16_f32 v140, v133, v135
	v_cvt_pk_bf16_f32 v141, v137, v139
	v_cvt_pk_bf16_f32 v143, v145, v143
	v_addc_co_u32_e32 v145, vcc, 0, v131, vcc
	global_store_dwordx4 v[144:145], v[140:143], off
	v_pk_mul_f32 v[146:147], v[50:51], v[138:139] op_sel_hi:[1,0]
	s_nop 0
	v_pk_mul_f32 v[140:141], v[54:55], v[138:139] op_sel_hi:[1,0]
	v_pk_mul_f32 v[142:143], v[52:53], v[138:139] op_sel_hi:[1,0]
	v_pk_mul_f32 v[138:139], v[48:49], v[138:139] op_sel_hi:[1,0]
	v_mul_f32_e32 v137, 0xbfb8aa3b, v140
	v_mul_f32_e32 v138, 0xbfb8aa3b, v138
	v_exp_f32_e32 v138, v138
	v_mul_f32_e32 v139, 0xbfb8aa3b, v139
	v_exp_f32_e32 v139, v139
	v_mul_f32_e32 v140, 0xbfb8aa3b, v141
	v_add_f32_e32 v138, 1.0, v138
	v_rcp_f32_e32 v141, v138
	v_add_f32_e32 v138, 1.0, v139
	v_mul_f32_e32 v139, 0xbfb8aa3b, v146
	v_mul_f32_e32 v133, 0xbfb8aa3b, v142
	v_mul_f32_e32 v135, 0xbfb8aa3b, v143
	v_exp_f32_e32 v139, v139
	v_mul_f32_e32 v142, 0xbfb8aa3b, v147
	v_exp_f32_e32 v133, v133
	v_exp_f32_e32 v135, v135
	v_exp_f32_e32 v137, v137
	v_exp_f32_e32 v140, v140
	v_exp_f32_e32 v142, v142
	v_rcp_f32_e32 v143, v138
	v_add_f32_e32 v138, 1.0, v139
	v_add_f32_e32 v133, 1.0, v133
	v_add_f32_e32 v135, 1.0, v135
	v_add_f32_e32 v137, 1.0, v137
	v_add_f32_e32 v140, 1.0, v140
	v_rcp_f32_e32 v146, v138
	v_add_f32_e32 v138, 1.0, v142
	v_rcp_f32_e32 v133, v133
	v_rcp_f32_e32 v135, v135
	v_rcp_f32_e32 v137, v137
	v_rcp_f32_e32 v140, v140
	v_rcp_f32_e32 v142, v138
	v_cvt_pk_bf16_f32 v138, v133, v135
	v_cvt_pk_bf16_f32 v139, v137, v140
	v_cvt_pk_bf16_f32 v140, v141, v143
	v_cvt_pk_bf16_f32 v141, v146, v142
	global_store_dwordx4 v[144:145], v[138:141], off offset:256
	v_pk_mul_f32 v[142:143], v[42:43], v[136:137] op_sel_hi:[1,0]
	s_nop 0
	v_pk_mul_f32 v[138:139], v[46:47], v[136:137] op_sel_hi:[1,0]
	v_pk_mul_f32 v[140:141], v[44:45], v[136:137] op_sel_hi:[1,0]
	s_nop 0
	v_mul_f32_e32 v133, 0xbfb8aa3b, v140
	v_mul_f32_e32 v135, 0xbfb8aa3b, v141
	v_pk_mul_f32 v[140:141], v[40:41], v[136:137] op_sel_hi:[1,0]
	v_mul_f32_e32 v137, 0xbfb8aa3b, v138
	v_mul_f32_e32 v138, 0xbfb8aa3b, v139
	v_exp_f32_e32 v138, v138
	v_mul_f32_e32 v139, 0xbfb8aa3b, v140
	v_exp_f32_e32 v139, v139
	v_mul_f32_e32 v140, 0xbfb8aa3b, v141
	v_exp_f32_e32 v140, v140
	v_add_f32_e32 v138, 1.0, v138
	v_rcp_f32_e32 v141, v138
	v_add_f32_e32 v138, 1.0, v139
	v_mul_f32_e32 v139, 0xbfb8aa3b, v142
	v_rcp_f32_e32 v144, v138
	v_add_f32_e32 v138, 1.0, v140
	v_exp_f32_e32 v139, v139
	v_mul_f32_e32 v140, 0xbfb8aa3b, v143
	v_exp_f32_e32 v133, v133
	v_exp_f32_e32 v135, v135
	v_exp_f32_e32 v137, v137
	v_exp_f32_e32 v140, v140
	v_rcp_f32_e32 v142, v138
	v_add_f32_e32 v138, 1.0, v139
	v_add_f32_e32 v133, 1.0, v133
	v_add_f32_e32 v135, 1.0, v135
	v_add_f32_e32 v137, 1.0, v137
	v_rcp_f32_e32 v143, v138
	v_add_f32_e32 v138, 1.0, v140
	v_rcp_f32_e32 v133, v133
	v_rcp_f32_e32 v135, v135
	v_rcp_f32_e32 v137, v137
	v_rcp_f32_e32 v145, v138
	v_cvt_pk_bf16_f32 v140, v144, v142
	v_add_co_u32_e32 v142, vcc, s63, v130
	v_cvt_pk_bf16_f32 v138, v133, v135
	v_cvt_pk_bf16_f32 v139, v137, v141
	v_cvt_pk_bf16_f32 v141, v143, v145
	v_addc_co_u32_e32 v143, vcc, 0, v131, vcc
	global_store_dwordx4 v[142:143], v[138:141], off
	v_pk_mul_f32 v[144:145], v[34:35], v[136:137] op_sel_hi:[1,0]
	s_nop 0
	v_pk_mul_f32 v[138:139], v[38:39], v[136:137] op_sel_hi:[1,0]
	v_pk_mul_f32 v[140:141], v[36:37], v[136:137] op_sel_hi:[1,0]
	v_pk_mul_f32 v[136:137], v[32:33], v[136:137] op_sel_hi:[1,0]
	v_mul_f32_e32 v133, 0xbfb8aa3b, v140
	v_mul_f32_e32 v136, 0xbfb8aa3b, v136
	v_exp_f32_e32 v136, v136
	v_mul_f32_e32 v137, 0xbfb8aa3b, v137
	v_exp_f32_e32 v137, v137
	v_mul_f32_e32 v135, 0xbfb8aa3b, v141
	v_add_f32_e32 v136, 1.0, v136
	v_rcp_f32_e32 v140, v136
	v_add_f32_e32 v136, 1.0, v137
	v_mul_f32_e32 v137, 0xbfb8aa3b, v144
	v_mul_f32_e32 v138, 0xbfb8aa3b, v138
; DI unsigned pk_bf16(float lo, float hi) { f32x2 v = {lo, hi}; return __builtin_bit_cast(unsigned, __builtin_convertvector(v, bf16v2)); }
; DI float fast_sigmoid(float x) { return __builtin_amdgcn_rcpf(1.0f + __expf(-x)); }
;     DI void operator()(AccRef acc, const Unit& u, int wr, int wc, int fr, int fq) const {
;     ...
; #pragma unroll
;         for (int ai = 0; ai < 2; ++ai)
; #pragma unroll
;             for (int m = 0; m < 4; ++m)
; #pragma unroll
;                 for (int bj = 0; bj < 2; ++bj) {
;                     const float rs = rsc.r[ai][m];
;                     const f32x4 r0 = acc[ai][bj][m][0] * rs, r1 = acc[ai][bj][m][1] * rs;
;                     u32x4 w;
;                     w.x = pk_bf16(fast_sigmoid(r0[0]), fast_sigmoid(r0[1])); w.y = pk_bf16(fast_sigmoid(r0[2]), fast_sigmoid(r0[3]));
;                     w.z = pk_bf16(fast_sigmoid(r1[0]), fast_sigmoid(r1[1])); w.w = pk_bf16(fast_sigmoid(r1[2]), fast_sigmoid(r1[3]));
;                     *(u32x4*)(Gp + (ai * 128 + m * 16) * 256 + bj * 128) = w;
;                 }
	v_mul_f32_e32 v139, 0xbfb8aa3b, v139
	v_exp_f32_e32 v137, v137
	v_mul_f32_e32 v141, 0xbfb8aa3b, v145
	v_exp_f32_e32 v133, v133
	v_exp_f32_e32 v135, v135
	v_exp_f32_e32 v138, v138
	v_exp_f32_e32 v139, v139
	v_exp_f32_e32 v141, v141
	v_rcp_f32_e32 v144, v136
	v_add_f32_e32 v136, 1.0, v137
	v_add_f32_e32 v133, 1.0, v133
	v_add_f32_e32 v135, 1.0, v135
	v_add_f32_e32 v138, 1.0, v138
	v_add_f32_e32 v139, 1.0, v139
	v_rcp_f32_e32 v145, v136
	v_add_f32_e32 v136, 1.0, v141
	v_rcp_f32_e32 v133, v133
	v_rcp_f32_e32 v135, v135
	v_rcp_f32_e32 v138, v138
	v_rcp_f32_e32 v139, v139
	v_rcp_f32_e32 v141, v136
	v_cvt_pk_bf16_f32 v136, v133, v135
	v_cvt_pk_bf16_f32 v137, v138, v139
	v_cvt_pk_bf16_f32 v138, v140, v144
	v_cvt_pk_bf16_f32 v139, v145, v141
	global_store_dwordx4 v[142:143], v[136:139], off offset:256
	v_pk_mul_f32 v[140:141], v[26:27], v[134:135] op_sel_hi:[1,0]
	s_nop 0
	v_pk_mul_f32 v[136:137], v[30:31], v[134:135] op_sel_hi:[1,0]
	v_pk_mul_f32 v[138:139], v[28:29], v[134:135] op_sel_hi:[1,0]
	v_mul_f32_e32 v136, 0xbfb8aa3b, v136
	v_mul_f32_e32 v135, 0xbfb8aa3b, v139
	v_exp_f32_e32 v135, v135
	v_exp_f32_e32 v136, v136
	v_mul_f32_e32 v137, 0xbfb8aa3b, v137
	v_exp_f32_e32 v137, v137
	v_mul_f32_e32 v133, 0xbfb8aa3b, v138
	v_pk_mul_f32 v[138:139], v[24:25], v[134:135] op_sel_hi:[1,0]
	v_add_f32_e32 v136, 1.0, v136
	v_rcp_f32_e32 v142, v136
	v_add_f32_e32 v136, 1.0, v137
	v_mul_f32_e32 v137, 0xbfb8aa3b, v138
	v_exp_f32_e32 v137, v137
	v_mul_f32_e32 v138, 0xbfb8aa3b, v139
	v_exp_f32_e32 v138, v138
	v_rcp_f32_e32 v139, v136
	v_add_f32_e32 v136, 1.0, v137
	v_mul_f32_e32 v137, 0xbfb8aa3b, v140
	v_rcp_f32_e32 v143, v136
	v_add_f32_e32 v136, 1.0, v138
	v_exp_f32_e32 v137, v137
	v_mul_f32_e32 v138, 0xbfb8aa3b, v141
	v_exp_f32_e32 v133, v133
	v_exp_f32_e32 v138, v138
	v_rcp_f32_e32 v140, v136
	v_add_f32_e32 v136, 1.0, v137
	v_add_f32_e32 v133, 1.0, v133
	v_add_f32_e32 v135, 1.0, v135
	v_rcp_f32_e32 v141, v136
	v_add_f32_e32 v136, 1.0, v138
	v_rcp_f32_e32 v133, v133
	v_rcp_f32_e32 v135, v135
	v_rcp_f32_e32 v144, v136
	v_cvt_pk_bf16_f32 v138, v143, v140
	v_add_co_u32_e32 v140, vcc, s64, v130
	v_cvt_pk_bf16_f32 v136, v133, v135
	v_cvt_pk_bf16_f32 v137, v142, v139
	v_cvt_pk_bf16_f32 v139, v141, v144
	v_addc_co_u32_e32 v141, vcc, 0, v131, vcc
	global_store_dwordx4 v[140:141], v[136:139], off
	v_pk_mul_f32 v[142:143], v[18:19], v[134:135] op_sel_hi:[1,0]
	s_nop 0
	v_pk_mul_f32 v[138:139], v[20:21], v[134:135] op_sel_hi:[1,0]
	v_pk_mul_f32 v[136:137], v[22:23], v[134:135] op_sel_hi:[1,0]
	v_mul_f32_e32 v135, 0xbfb8aa3b, v139
	v_mul_f32_e32 v133, 0xbfb8aa3b, v138
	v_exp_f32_e32 v138, v135
	v_pk_mul_f32 v[134:135], v[16:17], v[134:135] op_sel_hi:[1,0]
	v_mul_f32_e32 v136, 0xbfb8aa3b, v136
	v_mul_f32_e32 v134, 0xbfb8aa3b, v134
	v_exp_f32_e32 v134, v134
	v_mul_f32_e32 v135, 0xbfb8aa3b, v135
	v_exp_f32_e32 v135, v135
	v_mul_f32_e32 v137, 0xbfb8aa3b, v137
	v_add_f32_e32 v134, 1.0, v134
	v_rcp_f32_e32 v139, v134
	v_add_f32_e32 v134, 1.0, v135
	v_mul_f32_e32 v135, 0xbfb8aa3b, v142
	v_exp_f32_e32 v135, v135
	v_mul_f32_e32 v142, 0xbfb8aa3b, v143
	v_exp_f32_e32 v133, v133
	v_exp_f32_e32 v136, v136
	v_exp_f32_e32 v137, v137
	v_exp_f32_e32 v142, v142
	v_rcp_f32_e32 v143, v134
	v_add_f32_e32 v134, 1.0, v135
	v_add_f32_e32 v133, 1.0, v133
	v_add_f32_e32 v138, 1.0, v138
	v_add_f32_e32 v136, 1.0, v136
	v_add_f32_e32 v137, 1.0, v137
	v_rcp_f32_e32 v144, v134
	v_add_f32_e32 v134, 1.0, v142
	v_rcp_f32_e32 v133, v133
	v_rcp_f32_e32 v138, v138
	v_rcp_f32_e32 v136, v136
	v_rcp_f32_e32 v137, v137
	v_rcp_f32_e32 v142, v134
	v_cvt_pk_bf16_f32 v134, v133, v138
	v_cvt_pk_bf16_f32 v135, v136, v137
	v_cvt_pk_bf16_f32 v136, v139, v143
	v_cvt_pk_bf16_f32 v137, v144, v142
	global_store_dwordx4 v[140:141], v[134:137], off offset:256
	v_pk_mul_f32 v[138:139], v[10:11], v[132:133] op_sel_hi:[1,0]
	s_nop 0
	v_pk_mul_f32 v[134:135], v[14:15], v[132:133] op_sel_hi:[1,0]
	v_pk_mul_f32 v[136:137], v[12:13], v[132:133] op_sel_hi:[1,0]
	v_mul_f32_e32 v134, 0xbfb8aa3b, v134
	v_mul_f32_e32 v133, 0xbfb8aa3b, v136
	v_exp_f32_e32 v133, v133
	v_exp_f32_e32 v134, v134
	v_mul_f32_e32 v135, 0xbfb8aa3b, v135
	v_exp_f32_e32 v135, v135
	v_mul_f32_e32 v136, 0xbfb8aa3b, v137
	v_exp_f32_e32 v140, v136
	v_pk_mul_f32 v[136:137], v[8:9], v[132:133] op_sel_hi:[1,0]
	v_add_f32_e32 v134, 1.0, v134
	v_rcp_f32_e32 v141, v134
	v_add_f32_e32 v134, 1.0, v135
	v_mul_f32_e32 v135, 0xbfb8aa3b, v136
	v_exp_f32_e32 v135, v135
	v_mul_f32_e32 v136, 0xbfb8aa3b, v137
	v_exp_f32_e32 v136, v136
	v_rcp_f32_e32 v137, v134
	v_add_f32_e32 v134, 1.0, v135
	v_mul_f32_e32 v135, 0xbfb8aa3b, v138
	v_rcp_f32_e32 v142, v134
	v_add_f32_e32 v134, 1.0, v136
	v_exp_f32_e32 v135, v135
	v_mul_f32_e32 v136, 0xbfb8aa3b, v139
	v_exp_f32_e32 v136, v136
	v_rcp_f32_e32 v138, v134
	v_add_f32_e32 v134, 1.0, v135
	v_add_f32_e32 v133, 1.0, v133
	v_rcp_f32_e32 v139, v134
	v_add_f32_e32 v134, 1.0, v136
	v_rcp_f32_e32 v133, v133
	v_rcp_f32_e32 v143, v134
	v_add_f32_e32 v140, 1.0, v140
	v_rcp_f32_e32 v140, v140
	v_cvt_pk_bf16_f32 v136, v142, v138
	v_add_co_u32_e32 v138, vcc, s65, v130
	v_cvt_pk_bf16_f32 v135, v141, v137
	v_cvt_pk_bf16_f32 v137, v139, v143
	v_addc_co_u32_e32 v139, vcc, 0, v131, vcc
	v_pk_mul_f32 v[130:131], v[6:7], v[132:133] op_sel_hi:[1,0]
	v_cvt_pk_bf16_f32 v134, v133, v140
	v_mul_f32_e32 v130, 0xbfb8aa3b, v130
	v_exp_f32_e32 v130, v130
	v_mul_f32_e32 v131, 0xbfb8aa3b, v131
	global_store_dwordx4 v[138:139], v[134:137], off
	v_exp_f32_e32 v131, v131
	v_add_f32_e32 v130, 1.0, v130
	v_pk_mul_f32 v[134:135], v[4:5], v[132:133] op_sel_hi:[1,0]
	v_pk_mul_f32 v[136:137], v[2:3], v[132:133] op_sel_hi:[1,0]
	v_mul_f32_e32 v133, 0xbfb8aa3b, v134
	v_exp_f32_e32 v134, v133
	v_mul_f32_e32 v133, 0xbfb8aa3b, v135
	v_exp_f32_e32 v135, v133
	v_pk_mul_f32 v[132:133], v[0:1], v[132:133] op_sel_hi:[1,0]
	v_rcp_f32_e32 v140, v130
	v_add_f32_e32 v130, 1.0, v131
	v_mul_f32_e32 v131, 0xbfb8aa3b, v132
	v_exp_f32_e32 v131, v131
	v_mul_f32_e32 v132, 0xbfb8aa3b, v133
	v_exp_f32_e32 v132, v132
	v_rcp_f32_e32 v133, v130
	v_add_f32_e32 v130, 1.0, v131
	v_mul_f32_e32 v131, 0xbfb8aa3b, v136
	v_rcp_f32_e32 v141, v130
	v_add_f32_e32 v130, 1.0, v132
	v_exp_f32_e32 v131, v131
	v_mul_f32_e32 v132, 0xbfb8aa3b, v137
	v_exp_f32_e32 v132, v132
	v_rcp_f32_e32 v136, v130
	v_add_f32_e32 v130, 1.0, v131
	v_add_f32_e32 v134, 1.0, v134
	v_add_f32_e32 v135, 1.0, v135
	v_rcp_f32_e32 v137, v130
	v_add_f32_e32 v130, 1.0, v132
	v_rcp_f32_e32 v134, v134
	v_rcp_f32_e32 v135, v135
	v_rcp_f32_e32 v142, v130
	v_cvt_pk_bf16_f32 v131, v140, v133
	v_cvt_pk_bf16_f32 v132, v141, v136
	v_cvt_pk_bf16_f32 v130, v134, v135
	v_cvt_pk_bf16_f32 v133, v137, v142
	global_store_dwordx4 v[138:139], v[130:133], off offset:256

; #define PG8_STAGE(bufoff, gbase, voff) do { _Pragma("unroll") for (int _i = 0; _i < 2; ++_i) \
;         __builtin_amdgcn_global_load_lds((const unsigned*)((const char*)(gbase) + (voff)[_i]), (LAS unsigned*)(lds + (bufoff) + ldsw + _i * 8192), 16, 0, 0); } while (0)
; #define PG8_LDA(dst, b, h) do { _Pragma("unroll") for (int m = 0; m < 4; ++m) _Pragma("unroll") for (int k = 0; k < 2; ++k) dst[m][k] = *(const LAS bf16x8*)(lds + PG8_SA(b, h) + aoff + m * 2048 + k * 1024); } while (0)
; #define PG8_LDB(dst, b, h) do { _Pragma("unroll") for (int n = 0; n < 2; ++n) _Pragma("unroll") for (int k = 0; k < 2; ++k) dst[n][k] = *(const LAS bf16x8*)(lds + PG8_SB(b, h) + boff + n * 2048 + k * 1024); } while (0)
; #define PG8_WAIT_V(n) asm volatile("s_waitcnt vmcnt(" #n ")" ::: "memory")
; #define PG8_WAIT_L(n) asm volatile("s_waitcnt lgkmcnt(" #n ")" ::: "memory")
; #define PG8_BAR __builtin_amdgcn_s_barrier()
; #define PG8_SCHED __builtin_amdgcn_sched_barrier(0)
; template <class Epi0, class Epi1>
; DI void gemm_phase_dual(LAS unsigned char* lds, const Gemm g, const Gemm g1, const StaticOrder S, const Epi0 E0, const Epi1 E1) {
;     ...
;             PG8_LDB(B0, 0, 0); PG8_SCHED; PG8_LDA(At, 0, 0); PG8_STAGE(PG8_SA(1, 1), a1 + hstep, voffA);
;             PG8_WAIT_L(8); PG8_BAR; PG8_WAIT_L(0); PG8_MMA(0, 0, At, B0); PG8_BAR; PG8_SCHED;
;             PG8_LDB(B1, 0, 1); PG8_STAGE(PG8_SB(0, 0), b2, voffB);
;             PG8_BAR; PG8_WAIT_L(0); PG8_MMA(0, 1, At, B1); PG8_BAR;
;             PG8_LDA(At, 0, 1); PG8_STAGE(PG8_SA(0, 0), a2, voffA);
;             PG8_BAR; PG8_WAIT_L(0); PG8_MMA(1, 0, At, B0); PG8_BAR; PG8_SCHED;
;             PG8_STAGE(PG8_SB(0, 1), b2 + hstep, voffB);
;             PG8_WAIT_V(6); PG8_BAR; PG8_MMA(1, 1, At, B1); PG8_BAR;
;             PG8_LDB(B0, 1, 0); PG8_SCHED; PG8_LDA(At, 1, 0); PG8_STAGE(PG8_SA(0, 1), a2 + hstep, voffA);
;             PG8_WAIT_L(8); PG8_BAR; PG8_WAIT_L(0); PG8_MMA(0, 0, At, B0); PG8_BAR; PG8_SCHED;
;             PG8_LDB(B1, 1, 1); PG8_STAGE(PG8_SB(1, 0), b3, voffB);
;             PG8_BAR; PG8_WAIT_L(0); PG8_MMA(0, 1, At, B1); PG8_BAR;
;             PG8_LDA(At, 1, 1); PG8_STAGE(PG8_SA(1, 0), a3, voffA);
;             PG8_BAR; PG8_WAIT_L(0); PG8_MMA(1, 0, At, B0); PG8_BAR; PG8_SCHED;
;             PG8_STAGE(PG8_SB(1, 1), b3 + hstep, voffB);
;             PG8_WAIT_V(6); PG8_BAR; PG8_MMA(1, 1, At, B1); PG8_BAR;
.LBB0_708:
	ds_read_b128 v[156:159], v179
	ds_read_b128 v[160:163], v179 offset:1024
	ds_read_b128 v[164:167], v179 offset:2048
	ds_read_b128 v[168:171], v179 offset:3072
	s_add_u32 s40, s38, 0xfffc0080
	s_addc_u32 s41, s39, -1
	s_cmp_eq_u32 s69, 12
	s_cselect_b32 s43, s6, s41
	s_cselect_b32 s42, s7, s40
	s_cselect_b32 s41, s17, s68
	s_cselect_b32 s40, s19, s67
	v_lshl_add_u64 v[210:211], s[38:39], 0, v[148:149]
	s_add_i32 m0, s25, 0xc000
	ds_read_b128 v[172:175], v180
	ds_read_b128 v[182:185], v180 offset:1024
	ds_read_b128 v[186:189], v180 offset:2048
	ds_read_b128 v[190:193], v180 offset:3072
	ds_read_b128 v[194:197], v180 offset:4096
	ds_read_b128 v[198:201], v180 offset:5120
	ds_read_b128 v[202:205], v180 offset:6144
	ds_read_b128 v[206:209], v180 offset:7168
	global_load_lds_dwordx4 v[210:211], off
	v_lshl_add_u64 v[210:211], s[38:39], 0, v[150:151]
	s_add_i32 m0, s25, 0xe000
	s_nop 0
	global_load_lds_dwordx4 v[210:211], off
	s_waitcnt lgkmcnt(8)
	s_barrier
	s_waitcnt lgkmcnt(0)
	s_setprio 1
	s_waitcnt lgkmcnt(0)
	v_mfma_f32_16x16x32_bf16 v[124:127], v[156:159], v[172:175], v[124:127]
	v_mfma_f32_16x16x32_bf16 v[120:123], v[164:167], v[172:175], v[120:123]
	v_mfma_f32_16x16x32_bf16 v[108:111], v[156:159], v[186:189], v[108:111]
	v_mfma_f32_16x16x32_bf16 v[104:107], v[164:167], v[186:189], v[104:107]
	v_mfma_f32_16x16x32_bf16 v[92:95], v[156:159], v[194:197], v[92:95]
	v_mfma_f32_16x16x32_bf16 v[88:91], v[164:167], v[194:197], v[88:91]
	v_mfma_f32_16x16x32_bf16 v[84:87], v[156:159], v[202:205], v[84:87]
	v_mfma_f32_16x16x32_bf16 v[80:83], v[164:167], v[202:205], v[80:83]
	v_mfma_f32_16x16x32_bf16 v[124:127], v[160:163], v[182:185], v[124:127]
	v_mfma_f32_16x16x32_bf16 v[120:123], v[168:171], v[182:185], v[120:123]
	v_mfma_f32_16x16x32_bf16 v[108:111], v[160:163], v[190:193], v[108:111]
	v_mfma_f32_16x16x32_bf16 v[104:107], v[168:171], v[190:193], v[104:107]
	v_mfma_f32_16x16x32_bf16 v[92:95], v[160:163], v[198:201], v[92:95]
	v_mfma_f32_16x16x32_bf16 v[88:91], v[168:171], v[198:201], v[88:91]
	v_mfma_f32_16x16x32_bf16 v[84:87], v[160:163], v[206:209], v[84:87]
	s_barrier
	v_mfma_f32_16x16x32_bf16 v[80:83], v[168:171], v[206:209], v[80:83]
	s_setprio 0
	s_add_i32 s76, s52, s44
	v_lshl_add_u64 v[228:229], s[40:41], 0, v[130:131]
	s_mov_b32 m0, s76
	ds_read_b128 v[210:213], v181
	ds_read_b128 v[214:217], v181 offset:1024
	ds_read_b128 v[218:221], v181 offset:2048
	ds_read_b128 v[224:227], v181 offset:3072
	global_load_lds_dwordx4 v[228:229], off
	v_lshl_add_u64 v[230:231], s[40:41], 0, v[134:135]
	s_add_i32 m0, s76, 0x2000
	s_nop 0
	global_load_lds_dwordx4 v[230:231], off
	s_barrier
	s_waitcnt lgkmcnt(0)
	s_setprio 1
	s_waitcnt lgkmcnt(0)
	v_mfma_f32_16x16x32_bf16 v[116:119], v[210:213], v[172:175], v[116:119]
	v_mfma_f32_16x16x32_bf16 v[112:115], v[218:221], v[172:175], v[112:115]
	v_mfma_f32_16x16x32_bf16 v[100:103], v[210:213], v[186:189], v[100:103]
	v_mfma_f32_16x16x32_bf16 v[96:99], v[218:221], v[186:189], v[96:99]
	v_mfma_f32_16x16x32_bf16 v[76:79], v[210:213], v[194:197], v[76:79]
	v_mfma_f32_16x16x32_bf16 v[72:75], v[218:221], v[194:197], v[72:75]
	v_mfma_f32_16x16x32_bf16 v[68:71], v[210:213], v[202:205], v[68:71]
	v_mfma_f32_16x16x32_bf16 v[64:67], v[218:221], v[202:205], v[64:67]
	v_mfma_f32_16x16x32_bf16 v[116:119], v[214:217], v[182:185], v[116:119]
	v_mfma_f32_16x16x32_bf16 v[112:115], v[224:227], v[182:185], v[112:115]
	v_mfma_f32_16x16x32_bf16 v[100:103], v[214:217], v[190:193], v[100:103]
	v_mfma_f32_16x16x32_bf16 v[96:99], v[224:227], v[190:193], v[96:99]
	v_mfma_f32_16x16x32_bf16 v[76:79], v[214:217], v[198:201], v[76:79]
	v_mfma_f32_16x16x32_bf16 v[72:75], v[224:227], v[198:201], v[72:75]
	v_mfma_f32_16x16x32_bf16 v[68:71], v[214:217], v[206:209], v[68:71]
	s_barrier
	v_mfma_f32_16x16x32_bf16 v[64:67], v[224:227], v[206:209], v[64:67]
	s_setprio 0
	s_mov_b32 m0, s25
	v_lshl_add_u64 v[232:233], s[42:43], 0, v[128:129]
	ds_read_b128 v[172:175], v180 offset:16384
	ds_read_b128 v[182:185], v180 offset:17408
	ds_read_b128 v[186:189], v180 offset:18432
	ds_read_b128 v[190:193], v180 offset:19456
	ds_read_b128 v[194:197], v180 offset:20480
	ds_read_b128 v[198:201], v180 offset:21504
	ds_read_b128 v[202:205], v180 offset:22528
	ds_read_b128 v[206:209], v180 offset:23552
	global_load_lds_dwordx4 v[232:233], off
	v_lshl_add_u64 v[234:235], s[42:43], 0, v[132:133]
	s_mov_b32 m0, s45
	s_nop 0
	global_load_lds_dwordx4 v[234:235], off
	s_barrier
	s_waitcnt lgkmcnt(0)
	s_setprio 1
	s_waitcnt lgkmcnt(0)
	v_mfma_f32_16x16x32_bf16 v[60:63], v[156:159], v[172:175], v[60:63]
	v_mfma_f32_16x16x32_bf16 v[56:59], v[164:167], v[172:175], v[56:59]
	v_mfma_f32_16x16x32_bf16 v[52:55], v[156:159], v[186:189], v[52:55]
	v_mfma_f32_16x16x32_bf16 v[48:51], v[164:167], v[186:189], v[48:51]
	v_mfma_f32_16x16x32_bf16 v[28:31], v[156:159], v[194:197], v[28:31]
	v_mfma_f32_16x16x32_bf16 v[24:27], v[164:167], v[194:197], v[24:27]
	v_mfma_f32_16x16x32_bf16 v[20:23], v[156:159], v[202:205], v[20:23]
	v_mfma_f32_16x16x32_bf16 v[16:19], v[164:167], v[202:205], v[16:19]
	v_mfma_f32_16x16x32_bf16 v[60:63], v[160:163], v[182:185], v[60:63]
	v_mfma_f32_16x16x32_bf16 v[56:59], v[168:171], v[182:185], v[56:59]
	v_mfma_f32_16x16x32_bf16 v[52:55], v[160:163], v[190:193], v[52:55]
	v_mfma_f32_16x16x32_bf16 v[48:51], v[168:171], v[190:193], v[48:51]
	v_mfma_f32_16x16x32_bf16 v[28:31], v[160:163], v[198:201], v[28:31]
	v_mfma_f32_16x16x32_bf16 v[24:27], v[168:171], v[198:201], v[24:27]
	v_mfma_f32_16x16x32_bf16 v[20:23], v[160:163], v[206:209], v[20:23]
	s_barrier
; #define PG8_STAGE(bufoff, gbase, voff) do { _Pragma("unroll") for (int _i = 0; _i < 2; ++_i) \
;         __builtin_amdgcn_global_load_lds((const unsigned*)((const char*)(gbase) + (voff)[_i]), (LAS unsigned*)(lds + (bufoff) + ldsw + _i * 8192), 16, 0, 0); } while (0)
; #define PG8_LDA(dst, b, h) do { _Pragma("unroll") for (int m = 0; m < 4; ++m) _Pragma("unroll") for (int k = 0; k < 2; ++k) dst[m][k] = *(const LAS bf16x8*)(lds + PG8_SA(b, h) + aoff + m * 2048 + k * 1024); } while (0)
; #define PG8_LDB(dst, b, h) do { _Pragma("unroll") for (int n = 0; n < 2; ++n) _Pragma("unroll") for (int k = 0; k < 2; ++k) dst[n][k] = *(const LAS bf16x8*)(lds + PG8_SB(b, h) + boff + n * 2048 + k * 1024); } while (0)
; #define PG8_WAIT_V(n) asm volatile("s_waitcnt vmcnt(" #n ")" ::: "memory")
; #define PG8_WAIT_L(n) asm volatile("s_waitcnt lgkmcnt(" #n ")" ::: "memory")
; #define PG8_BAR __builtin_amdgcn_s_barrier()
; #define PG8_SCHED __builtin_amdgcn_sched_barrier(0)
; template <class Epi0, class Epi1>
; DI void gemm_phase_dual(LAS unsigned char* lds, const Gemm g, const Gemm g1, const StaticOrder S, const Epi0 E0, const Epi1 E1) {
;     ...
;             PG8_LDB(B0, 0, 0); PG8_SCHED; PG8_LDA(At, 0, 0); PG8_STAGE(PG8_SA(1, 1), a1 + hstep, voffA);
;             PG8_WAIT_L(8); PG8_BAR; PG8_WAIT_L(0); PG8_MMA(0, 0, At, B0); PG8_BAR; PG8_SCHED;
;             PG8_LDB(B1, 0, 1); PG8_STAGE(PG8_SB(0, 0), b2, voffB);
;             PG8_BAR; PG8_WAIT_L(0); PG8_MMA(0, 1, At, B1); PG8_BAR;
;             PG8_LDA(At, 0, 1); PG8_STAGE(PG8_SA(0, 0), a2, voffA);
;             PG8_BAR; PG8_WAIT_L(0); PG8_MMA(1, 0, At, B0); PG8_BAR; PG8_SCHED;
;             PG8_STAGE(PG8_SB(0, 1), b2 + hstep, voffB);
;             PG8_WAIT_V(6); PG8_BAR; PG8_MMA(1, 1, At, B1); PG8_BAR;
;             PG8_LDB(B0, 1, 0); PG8_SCHED; PG8_LDA(At, 1, 0); PG8_STAGE(PG8_SA(0, 1), a2 + hstep, voffA);
;             PG8_WAIT_L(8); PG8_BAR; PG8_WAIT_L(0); PG8_MMA(0, 0, At, B0); PG8_BAR; PG8_SCHED;
;             PG8_LDB(B1, 1, 1); PG8_STAGE(PG8_SB(1, 0), b3, voffB);
;             PG8_BAR; PG8_WAIT_L(0); PG8_MMA(0, 1, At, B1); PG8_BAR;
;             PG8_LDA(At, 1, 1); PG8_STAGE(PG8_SA(1, 0), a3, voffA);
;             PG8_BAR; PG8_WAIT_L(0); PG8_MMA(1, 0, At, B0); PG8_BAR; PG8_SCHED;
;             PG8_STAGE(PG8_SB(1, 1), b3 + hstep, voffB);
;             PG8_WAIT_V(6); PG8_BAR; PG8_MMA(1, 1, At, B1); PG8_BAR;
	v_mfma_f32_16x16x32_bf16 v[16:19], v[168:171], v[206:209], v[16:19]
	s_setprio 0
	s_add_u32 s76, s40, 0x40000
	s_addc_u32 s77, s41, 0
	s_add_i32 s78, s53, s44
	v_lshl_add_u64 v[156:157], s[76:77], 0, v[130:131]
	s_mov_b32 m0, s78
	s_nop 0
	global_load_lds_dwordx4 v[156:157], off
	v_lshl_add_u64 v[156:157], s[76:77], 0, v[134:135]
	s_add_i32 m0, s78, 0x2000
	s_nop 0
	global_load_lds_dwordx4 v[156:157], off
	s_waitcnt vmcnt(6)
	s_barrier
	s_setprio 1
	v_mfma_f32_16x16x32_bf16 v[44:47], v[210:213], v[172:175], v[44:47]
	v_mfma_f32_16x16x32_bf16 v[40:43], v[218:221], v[172:175], v[40:43]
	v_mfma_f32_16x16x32_bf16 v[36:39], v[210:213], v[186:189], v[36:39]
	v_mfma_f32_16x16x32_bf16 v[32:35], v[218:221], v[186:189], v[32:35]
	v_mfma_f32_16x16x32_bf16 v[12:15], v[210:213], v[194:197], v[12:15]
	v_mfma_f32_16x16x32_bf16 v[8:11], v[218:221], v[194:197], v[8:11]
	v_mfma_f32_16x16x32_bf16 v[4:7], v[210:213], v[202:205], v[4:7]
	v_mfma_f32_16x16x32_bf16 v[0:3], v[218:221], v[202:205], v[0:3]
	v_mfma_f32_16x16x32_bf16 v[44:47], v[214:217], v[182:185], v[44:47]
	v_mfma_f32_16x16x32_bf16 v[40:43], v[224:227], v[182:185], v[40:43]
	v_mfma_f32_16x16x32_bf16 v[36:39], v[214:217], v[190:193], v[36:39]
	v_mfma_f32_16x16x32_bf16 v[32:35], v[224:227], v[190:193], v[32:35]
	v_mfma_f32_16x16x32_bf16 v[12:15], v[214:217], v[198:201], v[12:15]
	v_mfma_f32_16x16x32_bf16 v[8:11], v[224:227], v[198:201], v[8:11]
	v_mfma_f32_16x16x32_bf16 v[4:7], v[214:217], v[206:209], v[4:7]
	s_barrier
	v_mfma_f32_16x16x32_bf16 v[0:3], v[224:227], v[206:209], v[0:3]
	s_setprio 0
	s_add_i32 s76, 0, 0x18000
	v_add_u32_e32 v168, s76, v177
	ds_read_b128 v[156:159], v168
	ds_read_b128 v[160:163], v168 offset:1024
	ds_read_b128 v[164:167], v168 offset:2048
	ds_read_b128 v[168:171], v168 offset:3072
	s_add_u32 s42, s42, 0x40000
	s_addc_u32 s43, s43, 0
	s_mov_b32 m0, s46
	v_lshl_add_u64 v[210:211], s[42:43], 0, v[128:129]
	ds_read_b128 v[172:175], v180 offset:32768
	ds_read_b128 v[182:185], v180 offset:33792
	ds_read_b128 v[186:189], v180 offset:34816
	ds_read_b128 v[190:193], v180 offset:35840
	ds_read_b128 v[194:197], v180 offset:36864
	ds_read_b128 v[198:201], v180 offset:37888
	ds_read_b128 v[202:205], v180 offset:38912
	ds_read_b128 v[206:209], v180 offset:39936
	global_load_lds_dwordx4 v[210:211], off
	v_lshl_add_u64 v[210:211], s[42:43], 0, v[132:133]
	s_mov_b32 m0, s47
	s_nop 0
	global_load_lds_dwordx4 v[210:211], off
	s_waitcnt lgkmcnt(8)
	s_barrier
	s_waitcnt lgkmcnt(0)
	s_setprio 1
	s_waitcnt lgkmcnt(0)
	v_mfma_f32_16x16x32_bf16 v[124:127], v[156:159], v[172:175], v[124:127]
	v_mfma_f32_16x16x32_bf16 v[120:123], v[164:167], v[172:175], v[120:123]
	v_mfma_f32_16x16x32_bf16 v[108:111], v[156:159], v[186:189], v[108:111]
	v_mfma_f32_16x16x32_bf16 v[104:107], v[164:167], v[186:189], v[104:107]
	v_mfma_f32_16x16x32_bf16 v[92:95], v[156:159], v[194:197], v[92:95]
	v_mfma_f32_16x16x32_bf16 v[88:91], v[164:167], v[194:197], v[88:91]
	v_mfma_f32_16x16x32_bf16 v[84:87], v[156:159], v[202:205], v[84:87]
	v_mfma_f32_16x16x32_bf16 v[80:83], v[164:167], v[202:205], v[80:83]
	v_mfma_f32_16x16x32_bf16 v[124:127], v[160:163], v[182:185], v[124:127]
	v_mfma_f32_16x16x32_bf16 v[120:123], v[168:171], v[182:185], v[120:123]
	v_mfma_f32_16x16x32_bf16 v[108:111], v[160:163], v[190:193], v[108:111]
	v_mfma_f32_16x16x32_bf16 v[104:107], v[168:171], v[190:193], v[104:107]
	v_mfma_f32_16x16x32_bf16 v[92:95], v[160:163], v[198:201], v[92:95]
	v_mfma_f32_16x16x32_bf16 v[88:91], v[168:171], v[198:201], v[88:91]
	v_mfma_f32_16x16x32_bf16 v[84:87], v[160:163], v[206:209], v[84:87]
	s_barrier
	v_mfma_f32_16x16x32_bf16 v[80:83], v[168:171], v[206:209], v[80:83]
	s_setprio 0
	s_add_i32 s42, 0, 0x1c000
	s_add_i32 s43, s76, s44
	v_add_u32_e32 v224, s42, v177
	v_lshl_add_u64 v[228:229], v[228:229], 0, s[8:9]
	s_mov_b32 m0, s43
	ds_read_b128 v[210:213], v224
	ds_read_b128 v[214:217], v224 offset:1024
	ds_read_b128 v[218:221], v224 offset:2048
	ds_read_b128 v[224:227], v224 offset:3072
	global_load_lds_dwordx4 v[228:229], off
	v_lshl_add_u64 v[228:229], v[230:231], 0, s[8:9]
	s_add_i32 m0, s43, 0x2000
	s_nop 0
	global_load_lds_dwordx4 v[228:229], off
	s_barrier
	s_waitcnt lgkmcnt(0)
	s_setprio 1
	s_waitcnt lgkmcnt(0)
	v_mfma_f32_16x16x32_bf16 v[116:119], v[210:213], v[172:175], v[116:119]
	v_mfma_f32_16x16x32_bf16 v[112:115], v[218:221], v[172:175], v[112:115]
	v_mfma_f32_16x16x32_bf16 v[100:103], v[210:213], v[186:189], v[100:103]
	v_mfma_f32_16x16x32_bf16 v[96:99], v[218:221], v[186:189], v[96:99]
	v_mfma_f32_16x16x32_bf16 v[76:79], v[210:213], v[194:197], v[76:79]
	v_mfma_f32_16x16x32_bf16 v[72:75], v[218:221], v[194:197], v[72:75]
	v_mfma_f32_16x16x32_bf16 v[68:71], v[210:213], v[202:205], v[68:71]
	v_mfma_f32_16x16x32_bf16 v[64:67], v[218:221], v[202:205], v[64:67]
	v_mfma_f32_16x16x32_bf16 v[116:119], v[214:217], v[182:185], v[116:119]
	v_mfma_f32_16x16x32_bf16 v[112:115], v[224:227], v[182:185], v[112:115]
	v_mfma_f32_16x16x32_bf16 v[100:103], v[214:217], v[190:193], v[100:103]
	v_mfma_f32_16x16x32_bf16 v[96:99], v[224:227], v[190:193], v[96:99]
	v_mfma_f32_16x16x32_bf16 v[76:79], v[214:217], v[198:201], v[76:79]
	v_mfma_f32_16x16x32_bf16 v[72:75], v[224:227], v[198:201], v[72:75]
	v_mfma_f32_16x16x32_bf16 v[68:71], v[214:217], v[206:209], v[68:71]
	s_barrier
	v_mfma_f32_16x16x32_bf16 v[64:67], v[224:227], v[206:209], v[64:67]
	s_setprio 0
	s_mov_b32 m0, s59
	v_lshl_add_u64 v[228:229], v[232:233], 0, s[8:9]
	ds_read_b128 v[172:175], v180 offset:49152
	ds_read_b128 v[182:185], v180 offset:50176
	ds_read_b128 v[186:189], v180 offset:51200
	ds_read_b128 v[190:193], v180 offset:52224
	ds_read_b128 v[194:197], v180 offset:53248
	ds_read_b128 v[198:201], v180 offset:54272
	ds_read_b128 v[202:205], v180 offset:55296
	ds_read_b128 v[206:209], v180 offset:56320
	global_load_lds_dwordx4 v[228:229], off
	v_lshl_add_u64 v[228:229], v[234:235], 0, s[8:9]
	s_mov_b32 m0, s60
	s_nop 0
	global_load_lds_dwordx4 v[228:229], off
	s_barrier
; #define PG8_STAGE(bufoff, gbase, voff) do { _Pragma("unroll") for (int _i = 0; _i < 2; ++_i) \
;         __builtin_amdgcn_global_load_lds((const unsigned*)((const char*)(gbase) + (voff)[_i]), (LAS unsigned*)(lds + (bufoff) + ldsw + _i * 8192), 16, 0, 0); } while (0)
; #define PG8_LDA(dst, b, h) do { _Pragma("unroll") for (int m = 0; m < 4; ++m) _Pragma("unroll") for (int k = 0; k < 2; ++k) dst[m][k] = *(const LAS bf16x8*)(lds + PG8_SA(b, h) + aoff + m * 2048 + k * 1024); } while (0)
; #define PG8_WAIT_V(n) asm volatile("s_waitcnt vmcnt(" #n ")" ::: "memory")
; #define PG8_WAIT_L(n) asm volatile("s_waitcnt lgkmcnt(" #n ")" ::: "memory")
; #define PG8_BAR __builtin_amdgcn_s_barrier()
; #define PG8_SCHED __builtin_amdgcn_sched_barrier(0)
; #define PG8_WAIT_V(n) asm volatile("s_waitcnt vmcnt(" #n ")" ::: "memory")
; template <class Epi0, class Epi1>
; DI void gemm_phase_dual(LAS unsigned char* lds, const Gemm g, const Gemm g1, const StaticOrder S, const Epi0 E0, const Epi1 E1) {
;     ...
;             PG8_BAR; PG8_WAIT_L(0); PG8_MMA(0, 1, At, B1); PG8_BAR;
;             PG8_LDA(At, 1, 1); PG8_STAGE(PG8_SA(1, 0), a3, voffA);
;             PG8_BAR; PG8_WAIT_L(0); PG8_MMA(1, 0, At, B0); PG8_BAR; PG8_SCHED;
;             PG8_STAGE(PG8_SB(1, 1), b3 + hstep, voffB);
;             PG8_WAIT_V(6); PG8_BAR; PG8_MMA(1, 1, At, B1); PG8_BAR;
;         }
;         if (ui & 1) E1(acc, cur, wr, wc, fr, fq); else E0(acc, cur, wr, wc, fr, fq);
;     DI void operator()(AccRef acc, const Unit& u, int wr, int wc, int fr, int fq) const {
;         const int row0 = u.pm * 256 + wr * 64 + fr, col0 = u.pn * 256 + wc * 32 + 8 * fq;
; #pragma unroll
;         for (int ai = 0; ai < 2; ++ai)
; #pragma unroll
;             for (int mh = 0; mh < 2; ++mh) {
;                 u32x4 gv[2][2], mv[2][2];
; #pragma unroll
;                 for (int mm = 0; mm < 2; ++mm)
; #pragma unroll
;                     for (int bj = 0; bj < 2; ++bj) {
;                         const size_t row = (size_t)(row0 + ai * 128 + (mh * 2 + mm) * 16); const int col = col0 + bj * 128;
;                         gv[mm][bj] = *(const u32x4*)(gab + (size_t)(u.pm * 8 + SECOND * 4 + u.pn) * 65536 + (wr * 64 + fr + ai * 128 + (mh * 2 + mm) * 16) * 256 + wc * 32 + 8 * fq + bj * 128);
;                         if (SECOND) mv[mm][bj] = *(const u32x4*)(mrg + row * 1024 + col);
;                     }
	s_waitcnt lgkmcnt(0)
	s_setprio 1
	s_waitcnt lgkmcnt(0)
	v_mfma_f32_16x16x32_bf16 v[60:63], v[156:159], v[172:175], v[60:63]
	v_mfma_f32_16x16x32_bf16 v[56:59], v[164:167], v[172:175], v[56:59]
	v_mfma_f32_16x16x32_bf16 v[52:55], v[156:159], v[186:189], v[52:55]
	v_mfma_f32_16x16x32_bf16 v[48:51], v[164:167], v[186:189], v[48:51]
	v_mfma_f32_16x16x32_bf16 v[28:31], v[156:159], v[194:197], v[28:31]
	v_mfma_f32_16x16x32_bf16 v[24:27], v[164:167], v[194:197], v[24:27]
	v_mfma_f32_16x16x32_bf16 v[20:23], v[156:159], v[202:205], v[20:23]
	v_mfma_f32_16x16x32_bf16 v[16:19], v[164:167], v[202:205], v[16:19]
	v_mfma_f32_16x16x32_bf16 v[60:63], v[160:163], v[182:185], v[60:63]
	v_mfma_f32_16x16x32_bf16 v[56:59], v[168:171], v[182:185], v[56:59]
	v_mfma_f32_16x16x32_bf16 v[52:55], v[160:163], v[190:193], v[52:55]
	v_mfma_f32_16x16x32_bf16 v[48:51], v[168:171], v[190:193], v[48:51]
	v_mfma_f32_16x16x32_bf16 v[28:31], v[160:163], v[198:201], v[28:31]
	v_mfma_f32_16x16x32_bf16 v[24:27], v[168:171], v[198:201], v[24:27]
	v_mfma_f32_16x16x32_bf16 v[20:23], v[160:163], v[206:209], v[20:23]
	s_barrier
	v_mfma_f32_16x16x32_bf16 v[16:19], v[168:171], v[206:209], v[16:19]
	s_setprio 0
	s_add_u32 s40, s40, 0x40080
	s_addc_u32 s41, s41, 0
	s_add_i32 s42, s42, s44
	v_lshl_add_u64 v[156:157], s[40:41], 0, v[130:131]
	s_mov_b32 m0, s42
	s_nop 0
	global_load_lds_dwordx4 v[156:157], off
	v_lshl_add_u64 v[156:157], s[40:41], 0, v[134:135]
	s_add_i32 m0, s42, 0x2000
	s_nop 0
	global_load_lds_dwordx4 v[156:157], off
	s_waitcnt vmcnt(6)
	s_barrier
	s_setprio 1
	v_mfma_f32_16x16x32_bf16 v[44:47], v[210:213], v[172:175], v[44:47]
	v_mfma_f32_16x16x32_bf16 v[40:43], v[218:221], v[172:175], v[40:43]
	v_mfma_f32_16x16x32_bf16 v[36:39], v[210:213], v[186:189], v[36:39]
	v_mfma_f32_16x16x32_bf16 v[32:35], v[218:221], v[186:189], v[32:35]
	v_mfma_f32_16x16x32_bf16 v[12:15], v[210:213], v[194:197], v[12:15]
	v_mfma_f32_16x16x32_bf16 v[8:11], v[218:221], v[194:197], v[8:11]
	v_mfma_f32_16x16x32_bf16 v[4:7], v[210:213], v[202:205], v[4:7]
	v_mfma_f32_16x16x32_bf16 v[0:3], v[218:221], v[202:205], v[0:3]
	v_mfma_f32_16x16x32_bf16 v[44:47], v[214:217], v[182:185], v[44:47]
	v_mfma_f32_16x16x32_bf16 v[40:43], v[224:227], v[182:185], v[40:43]
	v_mfma_f32_16x16x32_bf16 v[36:39], v[214:217], v[190:193], v[36:39]
	v_mfma_f32_16x16x32_bf16 v[32:35], v[224:227], v[190:193], v[32:35]
	v_mfma_f32_16x16x32_bf16 v[12:15], v[214:217], v[198:201], v[12:15]
	v_mfma_f32_16x16x32_bf16 v[8:11], v[224:227], v[198:201], v[8:11]
	v_mfma_f32_16x16x32_bf16 v[4:7], v[214:217], v[206:209], v[4:7]
	s_barrier
	v_mfma_f32_16x16x32_bf16 v[0:3], v[224:227], v[206:209], v[0:3]
	s_setprio 0
	s_add_i32 s69, s69, 2
	s_add_u32 s38, s38, 0x100
	s_addc_u32 s39, s39, 0
	s_add_u32 s67, s67, 0x100
	s_addc_u32 s68, s68, 0
	s_cmp_gt_u32 s69, 13
	s_cbranch_scc0 .LBB0_708
	v_lshl_add_u32 v164, s24, 8, v176
	s_lshl_b32 s17, s66, 8
	v_or_b32_e32 v162, s17, v178
	v_or_b32_e32 v160, 16, v164
	s_mov_b64 s[6:7], -1
	s_and_b64 vcc, exec, s[28:29]
	v_ashrrev_i32_e32 v165, 31, v164
	v_ashrrev_i32_e32 v163, 31, v162
	v_ashrrev_i32_e32 v161, 31, v160
	v_or_b32_e32 v158, 32, v164
	v_or_b32_e32 v156, 48, v164
	s_cbranch_vccz .LBB0_711
	s_lshl_b32 s6, s24, 3
	s_add_i32 s6, s66, s6
	s_add_i32 s6, s6, 4
	v_lshlrev_b64 v[168:169], 11, v[160:161]
	s_ashr_i32 s7, s6, 31
	v_lshlrev_b64 v[166:167], 11, v[164:165]
	v_lshlrev_b64 v[170:171], 1, v[162:163]
	v_lshl_add_u64 v[168:169], s[36:37], 0, v[168:169]
	s_lshl_b64 s[6:7], s[6:7], 17
	v_lshl_add_u64 v[166:167], s[36:37], 0, v[166:167]
	v_lshl_add_u64 v[174:175], v[168:169], 0, v[170:171]
	v_lshl_add_u64 v[168:169], v[136:137], 0, s[6:7]
	v_lshl_add_u64 v[166:167], v[166:167], 0, v[170:171]
	v_lshl_add_u64 v[172:173], v[138:139], 1, v[168:169]
	global_load_dwordx4 v[182:185], v[166:167], off
	global_load_dwordx4 v[186:189], v[166:167], off offset:256
	global_load_dwordx4 v[190:193], v[174:175], off
	global_load_dwordx4 v[194:197], v[172:173], off
	global_load_dwordx4 v[198:201], v[172:173], off offset:256
	v_add_co_u32_e32 v206, vcc, s48, v172
	v_ashrrev_i32_e32 v159, 31, v158
	s_nop 0
	v_addc_co_u32_e32 v207, vcc, 0, v173, vcc
	global_load_dwordx4 v[202:205], v[206:207], off
	s_nop 0
	global_load_dwordx4 v[206:209], v[206:207], off offset:256
	s_nop 0
	global_load_dwordx4 v[210:213], v[174:175], off offset:256
	v_ashrrev_i32_e32 v157, 31, v156
	s_mov_b64 s[6:7], 0
	s_waitcnt vmcnt(0)
; DI unsigned pk_bf16(float lo, float hi) { f32x2 v = {lo, hi}; return __builtin_bit_cast(unsigned, __builtin_convertvector(v, bf16v2)); }
; DI float bf_lo(unsigned w) { return __uint_as_float(w << 16); }
; DI float bf_hi(unsigned w) { return __uint_as_float(w & 0xffff0000u); }
;     DI void operator()(AccRef acc, const Unit& u, int wr, int wc, int fr, int fq) const {
;     ...
;                 u32x4 gv[2][2], mv[2][2];
; #pragma unroll
;                 for (int mm = 0; mm < 2; ++mm)
; #pragma unroll
;                     for (int bj = 0; bj < 2; ++bj) {
;                         const size_t row = (size_t)(row0 + ai * 128 + (mh * 2 + mm) * 16); const int col = col0 + bj * 128;
;                         gv[mm][bj] = *(const u32x4*)(gab + (size_t)(u.pm * 8 + SECOND * 4 + u.pn) * 65536 + (wr * 64 + fr + ai * 128 + (mh * 2 + mm) * 16) * 256 + wc * 32 + 8 * fq + bj * 128);
;                         if (SECOND) mv[mm][bj] = *(const u32x4*)(mrg + row * 1024 + col);
;                     }
; #pragma unroll
;                 for (int mm = 0; mm < 2; ++mm)
; #pragma unroll
;                     for (int bj = 0; bj < 2; ++bj) {
;                         const int m = mh * 2 + mm;
;                         const size_t row = (size_t)(row0 + ai * 128 + m * 16); const int col = col0 + bj * 128;
;                         const u32x4 gt = gv[mm][bj];
;                         const f32x4 r0 = acc[ai][bj][m][0], r1 = acc[ai][bj][m][1];
;                         float v[8] = {bf_lo(gt.x) * r0[0], bf_hi(gt.x) * r0[1], bf_lo(gt.y) * r0[2], bf_hi(gt.y) * r0[3], bf_lo(gt.z) * r1[0], bf_hi(gt.z) * r1[1], bf_lo(gt.w) * r1[2], bf_hi(gt.w) * r1[3]};
;                         if (SECOND) { const u32x4 o = mv[mm][bj]; v[0] += bf_lo(o.x); v[1] += bf_hi(o.x); v[2] += bf_lo(o.y); v[3] += bf_hi(o.y); v[4] += bf_lo(o.z); v[5] += bf_hi(o.z); v[6] += bf_lo(o.w); v[7] += bf_hi(o.w); }
;                         u32x4 w; w.x = pk_bf16(v[0], v[1]); w.y = pk_bf16(v[2], v[3]); w.z = pk_bf16(v[4], v[5]); w.w = pk_bf16(v[6], v[7]);
;                         *(u32x4*)(mrg + row * 1024 + col) = w;
;                     }
	v_lshlrev_b32_e32 v214, 16, v182
	v_and_b32_e32 v215, 0xffff0000, v182
	v_lshlrev_b32_e32 v182, 16, v183
	v_and_b32_e32 v183, 0xffff0000, v183
	v_lshlrev_b32_e32 v216, 16, v184
	v_and_b32_e32 v217, 0xffff0000, v184
	v_lshlrev_b32_e32 v184, 16, v185
	v_and_b32_e32 v185, 0xffff0000, v185
	v_lshlrev_b32_e32 v228, 16, v194
	v_and_b32_e32 v229, 0xffff0000, v194
	v_lshlrev_b32_e32 v194, 16, v195
	v_and_b32_e32 v195, 0xffff0000, v195
	v_lshlrev_b32_e32 v230, 16, v196
	v_and_b32_e32 v231, 0xffff0000, v196
	v_lshlrev_b32_e32 v196, 16, v197
	v_and_b32_e32 v197, 0xffff0000, v197
	v_lshlrev_b32_e32 v218, 16, v186
	v_and_b32_e32 v219, 0xffff0000, v186
	v_lshlrev_b32_e32 v186, 16, v187
	v_and_b32_e32 v187, 0xffff0000, v187
	v_lshlrev_b32_e32 v220, 16, v188
	v_and_b32_e32 v221, 0xffff0000, v188
	v_lshlrev_b32_e32 v188, 16, v189
	v_and_b32_e32 v189, 0xffff0000, v189
	v_lshlrev_b32_e32 v232, 16, v198
	v_and_b32_e32 v233, 0xffff0000, v198
	v_lshlrev_b32_e32 v198, 16, v199
	v_and_b32_e32 v199, 0xffff0000, v199
	v_lshlrev_b32_e32 v234, 16, v200
	v_and_b32_e32 v235, 0xffff0000, v200
	v_lshlrev_b32_e32 v200, 16, v201
	v_and_b32_e32 v201, 0xffff0000, v201
	v_pk_fma_f32 v[214:215], v[124:125], v[228:229], v[214:215]
	v_pk_fma_f32 v[194:195], v[126:127], v[194:195], v[182:183]
	v_pk_fma_f32 v[216:217], v[120:121], v[230:231], v[216:217]
	v_pk_fma_f32 v[196:197], v[122:123], v[196:197], v[184:185]
	v_pk_fma_f32 v[218:219], v[116:117], v[232:233], v[218:219]
	v_pk_fma_f32 v[198:199], v[118:119], v[198:199], v[186:187]
	v_pk_fma_f32 v[220:221], v[112:113], v[234:235], v[220:221]
	v_pk_fma_f32 v[200:201], v[114:115], v[200:201], v[188:189]
	v_cvt_pk_bf16_f32 v182, v214, v215
	v_cvt_pk_bf16_f32 v183, v194, v195
	v_cvt_pk_bf16_f32 v184, v216, v217
	v_cvt_pk_bf16_f32 v185, v196, v197
	v_lshlrev_b32_e32 v224, 16, v190
	v_and_b32_e32 v225, 0xffff0000, v190
	v_lshlrev_b32_e32 v190, 16, v191
	v_and_b32_e32 v191, 0xffff0000, v191
	v_lshlrev_b32_e32 v226, 16, v192
	v_and_b32_e32 v227, 0xffff0000, v192
	v_lshlrev_b32_e32 v228, 16, v202
	v_and_b32_e32 v229, 0xffff0000, v202
	v_lshlrev_b32_e32 v202, 16, v203
	v_and_b32_e32 v203, 0xffff0000, v203
	v_lshlrev_b32_e32 v230, 16, v204
	v_and_b32_e32 v231, 0xffff0000, v204
	v_cvt_pk_bf16_f32 v186, v218, v219
	v_cvt_pk_bf16_f32 v187, v198, v199
	v_cvt_pk_bf16_f32 v188, v220, v221
	v_cvt_pk_bf16_f32 v189, v200, v201
	global_store_dwordx4 v[166:167], v[182:185], off
	global_store_dwordx4 v[166:167], v[186:189], off offset:256
	v_pk_fma_f32 v[194:195], v[108:109], v[228:229], v[224:225]
	v_lshlrev_b32_e32 v182, 16, v205
	v_and_b32_e32 v183, 0xffff0000, v205
	v_lshlrev_b32_e32 v184, 16, v193
	v_and_b32_e32 v185, 0xffff0000, v193
	v_pk_fma_f32 v[190:191], v[110:111], v[202:203], v[190:191]
	v_pk_fma_f32 v[196:197], v[104:105], v[230:231], v[226:227]
	v_pk_fma_f32 v[186:187], v[106:107], v[182:183], v[184:185]
	v_cvt_pk_bf16_f32 v182, v194, v195
	v_cvt_pk_bf16_f32 v183, v190, v191
	v_cvt_pk_bf16_f32 v184, v196, v197
	v_cvt_pk_bf16_f32 v185, v186, v187
	global_store_dwordx4 v[174:175], v[182:185], off
	v_lshlrev_b32_e32 v186, 16, v211
	v_and_b32_e32 v187, 0xffff0000, v211
	v_lshlrev_b32_e32 v182, 16, v206
	v_and_b32_e32 v183, 0xffff0000, v206
	v_lshlrev_b32_e32 v184, 16, v210
	v_and_b32_e32 v185, 0xffff0000, v210
	v_pk_fma_f32 v[182:183], v[100:101], v[182:183], v[184:185]
	v_lshlrev_b32_e32 v184, 16, v207
	v_and_b32_e32 v185, 0xffff0000, v207
	v_pk_fma_f32 v[184:185], v[102:103], v[184:185], v[186:187]
	v_lshlrev_b32_e32 v186, 16, v208
	v_and_b32_e32 v187, 0xffff0000, v208
	v_lshlrev_b32_e32 v188, 16, v212
	v_and_b32_e32 v189, 0xffff0000, v212
	v_pk_fma_f32 v[190:191], v[96:97], v[186:187], v[188:189]
	v_lshlrev_b32_e32 v186, 16, v209
	v_and_b32_e32 v187, 0xffff0000, v209
	v_lshlrev_b32_e32 v188, 16, v213
	v_and_b32_e32 v189, 0xffff0000, v213
	v_cvt_pk_bf16_f32 v182, v182, v183
	v_cvt_pk_bf16_f32 v183, v184, v185
	v_lshlrev_b64 v[184:185], 11, v[158:159]
	v_pk_fma_f32 v[192:193], v[98:99], v[186:187], v[188:189]
	v_lshl_add_u64 v[184:185], s[36:37], 0, v[184:185]
	v_lshl_add_u64 v[210:211], v[184:185], 0, v[170:171]
	v_cvt_pk_bf16_f32 v184, v190, v191
	v_cvt_pk_bf16_f32 v185, v192, v193
	global_load_dwordx4 v[186:189], v[210:211], off
	s_waitcnt vmcnt(0)
	v_lshlrev_b32_e32 v214, 16, v188
	global_store_dwordx4 v[174:175], v[182:185], off offset:256
	v_add_co_u32_e32 v174, vcc, s49, v172
	v_and_b32_e32 v215, 0xffff0000, v188
	s_nop 0
	v_addc_co_u32_e32 v175, vcc, 0, v173, vcc
	global_load_dwordx4 v[182:185], v[174:175], off
	global_load_dwordx4 v[190:193], v[174:175], off offset:256
	global_load_dwordx4 v[194:197], v[210:211], off offset:256
	v_add_co_u32_e32 v202, vcc, s50, v172
	v_lshlrev_b64 v[174:175], 11, v[156:157]
	s_nop 0
	v_addc_co_u32_e32 v203, vcc, 0, v173, vcc
	v_lshl_add_u64 v[198:199], s[36:37], 0, v[174:175]
	global_load_dwordx4 v[172:175], v[202:203], off
	v_lshl_add_u64 v[212:213], v[198:199], 0, v[170:171]
	global_load_dwordx4 v[198:201], v[212:213], off
	s_nop 0
	global_load_dwordx4 v[202:205], v[202:203], off offset:256
	s_nop 0
	global_load_dwordx4 v[206:209], v[212:213], off offset:256
	v_lshlrev_b32_e32 v170, 16, v186
	v_and_b32_e32 v171, 0xffff0000, v186
	v_lshlrev_b32_e32 v186, 16, v187
	v_and_b32_e32 v187, 0xffff0000, v187
	v_lshlrev_b32_e32 v188, 16, v189
	v_and_b32_e32 v189, 0xffff0000, v189
	s_waitcnt vmcnt(0)
; DI unsigned pk_bf16(float lo, float hi) { f32x2 v = {lo, hi}; return __builtin_bit_cast(unsigned, __builtin_convertvector(v, bf16v2)); }
; DI float bf_lo(unsigned w) { return __uint_as_float(w << 16); }
; DI float bf_hi(unsigned w) { return __uint_as_float(w & 0xffff0000u); }
;     DI void operator()(AccRef acc, const Unit& u, int wr, int wc, int fr, int fq) const {
;     ...
;                 u32x4 gv[2][2], mv[2][2];
; #pragma unroll
;                 for (int mm = 0; mm < 2; ++mm)
; #pragma unroll
;                     for (int bj = 0; bj < 2; ++bj) {
;                         const size_t row = (size_t)(row0 + ai * 128 + (mh * 2 + mm) * 16); const int col = col0 + bj * 128;
;                         gv[mm][bj] = *(const u32x4*)(gab + (size_t)(u.pm * 8 + SECOND * 4 + u.pn) * 65536 + (wr * 64 + fr + ai * 128 + (mh * 2 + mm) * 16) * 256 + wc * 32 + 8 * fq + bj * 128);
;                         if (SECOND) mv[mm][bj] = *(const u32x4*)(mrg + row * 1024 + col);
;                     }
; #pragma unroll
;                 for (int mm = 0; mm < 2; ++mm)
; #pragma unroll
;                     for (int bj = 0; bj < 2; ++bj) {
;                         const int m = mh * 2 + mm;
;                         const size_t row = (size_t)(row0 + ai * 128 + m * 16); const int col = col0 + bj * 128;
;                         const u32x4 gt = gv[mm][bj];
;                         const f32x4 r0 = acc[ai][bj][m][0], r1 = acc[ai][bj][m][1];
;                         float v[8] = {bf_lo(gt.x) * r0[0], bf_hi(gt.x) * r0[1], bf_lo(gt.y) * r0[2], bf_hi(gt.y) * r0[3], bf_lo(gt.z) * r1[0], bf_hi(gt.z) * r1[1], bf_lo(gt.w) * r1[2], bf_hi(gt.w) * r1[3]};
;                         if (SECOND) { const u32x4 o = mv[mm][bj]; v[0] += bf_lo(o.x); v[1] += bf_hi(o.x); v[2] += bf_lo(o.y); v[3] += bf_hi(o.y); v[4] += bf_lo(o.z); v[5] += bf_hi(o.z); v[6] += bf_lo(o.w); v[7] += bf_hi(o.w); }
;                         u32x4 w; w.x = pk_bf16(v[0], v[1]); w.y = pk_bf16(v[2], v[3]); w.z = pk_bf16(v[4], v[5]); w.w = pk_bf16(v[6], v[7]);
;                         *(u32x4*)(mrg + row * 1024 + col) = w;
;                     }
	v_lshlrev_b32_e32 v216, 16, v182
	v_and_b32_e32 v217, 0xffff0000, v182
	v_lshlrev_b32_e32 v182, 16, v183
	v_and_b32_e32 v183, 0xffff0000, v183
	v_lshlrev_b32_e32 v218, 16, v184
	v_and_b32_e32 v219, 0xffff0000, v184
	v_lshlrev_b32_e32 v184, 16, v185
	v_and_b32_e32 v185, 0xffff0000, v185
	v_pk_fma_f32 v[170:171], v[92:93], v[216:217], v[170:171]
	v_pk_fma_f32 v[186:187], v[94:95], v[182:183], v[186:187]
	v_pk_fma_f32 v[214:215], v[88:89], v[218:219], v[214:215]
	v_pk_fma_f32 v[188:189], v[90:91], v[184:185], v[188:189]
	v_cvt_pk_bf16_f32 v182, v170, v171
	v_cvt_pk_bf16_f32 v183, v186, v187
	v_cvt_pk_bf16_f32 v184, v214, v215
	v_cvt_pk_bf16_f32 v185, v188, v189
	global_store_dwordx4 v[210:211], v[182:185], off
	v_lshlrev_b32_e32 v186, 16, v196
	v_and_b32_e32 v187, 0xffff0000, v196
	v_lshlrev_b32_e32 v182, 16, v191
	v_and_b32_e32 v183, 0xffff0000, v191
	v_lshlrev_b32_e32 v184, 16, v195
	v_and_b32_e32 v185, 0xffff0000, v195
	v_pk_fma_f32 v[184:185], v[78:79], v[182:183], v[184:185]
	v_lshlrev_b32_e32 v182, 16, v192
	v_and_b32_e32 v183, 0xffff0000, v192
	v_lshlrev_b32_e32 v220, 16, v190
	v_and_b32_e32 v221, 0xffff0000, v190
	v_lshlrev_b32_e32 v170, 16, v194
	v_and_b32_e32 v171, 0xffff0000, v194
	v_pk_fma_f32 v[186:187], v[72:73], v[182:183], v[186:187]
	v_lshlrev_b32_e32 v182, 16, v193
	v_and_b32_e32 v183, 0xffff0000, v193
	v_lshlrev_b32_e32 v188, 16, v197
	v_and_b32_e32 v189, 0xffff0000, v197
	v_pk_fma_f32 v[170:171], v[76:77], v[220:221], v[170:171]
	v_pk_fma_f32 v[188:189], v[74:75], v[182:183], v[188:189]
	v_cvt_pk_bf16_f32 v182, v170, v171
	v_cvt_pk_bf16_f32 v183, v184, v185
	v_cvt_pk_bf16_f32 v184, v186, v187
	v_cvt_pk_bf16_f32 v185, v188, v189
	global_store_dwordx4 v[210:211], v[182:185], off offset:256
	v_lshlrev_b32_e32 v170, 16, v172
	v_and_b32_e32 v171, 0xffff0000, v172
	v_lshlrev_b32_e32 v182, 16, v198
	v_and_b32_e32 v183, 0xffff0000, v198
	v_pk_fma_f32 v[170:171], v[84:85], v[170:171], v[182:183]
	v_lshlrev_b32_e32 v172, 16, v173
	v_and_b32_e32 v173, 0xffff0000, v173
	v_lshlrev_b32_e32 v182, 16, v199
	v_and_b32_e32 v183, 0xffff0000, v199
	v_pk_fma_f32 v[172:173], v[86:87], v[172:173], v[182:183]
	v_lshlrev_b32_e32 v182, 16, v174
	v_and_b32_e32 v183, 0xffff0000, v174
	v_lshlrev_b32_e32 v184, 16, v200
	v_and_b32_e32 v185, 0xffff0000, v200
	v_pk_fma_f32 v[182:183], v[80:81], v[182:183], v[184:185]
	v_lshlrev_b32_e32 v174, 16, v175
	v_and_b32_e32 v175, 0xffff0000, v175
	v_lshlrev_b32_e32 v184, 16, v201
	v_and_b32_e32 v185, 0xffff0000, v201
	v_pk_fma_f32 v[174:175], v[82:83], v[174:175], v[184:185]
	v_cvt_pk_bf16_f32 v170, v170, v171
	v_cvt_pk_bf16_f32 v171, v172, v173
	v_cvt_pk_bf16_f32 v172, v182, v183
	v_cvt_pk_bf16_f32 v173, v174, v175
	global_store_dwordx4 v[212:213], v[170:173], off
	v_lshlrev_b32_e32 v174, 16, v207
	v_and_b32_e32 v175, 0xffff0000, v207
	v_lshlrev_b32_e32 v170, 16, v202
	v_and_b32_e32 v171, 0xffff0000, v202
	v_lshlrev_b32_e32 v172, 16, v206
	v_and_b32_e32 v173, 0xffff0000, v206
	v_pk_fma_f32 v[170:171], v[68:69], v[170:171], v[172:173]
	v_lshlrev_b32_e32 v172, 16, v203
	v_and_b32_e32 v173, 0xffff0000, v203
	v_pk_fma_f32 v[172:173], v[70:71], v[172:173], v[174:175]
	v_lshlrev_b32_e32 v174, 16, v204
	v_and_b32_e32 v175, 0xffff0000, v204
	v_lshlrev_b32_e32 v182, 16, v208
	v_and_b32_e32 v183, 0xffff0000, v208
	v_pk_fma_f32 v[174:175], v[64:65], v[174:175], v[182:183]
	v_lshlrev_b32_e32 v182, 16, v205
	v_and_b32_e32 v183, 0xffff0000, v205
	v_lshlrev_b32_e32 v184, 16, v209
	v_and_b32_e32 v185, 0xffff0000, v209
	v_pk_fma_f32 v[182:183], v[66:67], v[182:183], v[184:185]
	v_cvt_pk_bf16_f32 v170, v170, v171
	v_cvt_pk_bf16_f32 v171, v172, v173
	v_cvt_pk_bf16_f32 v172, v174, v175
	v_cvt_pk_bf16_f32 v173, v182, v183
	global_store_dwordx4 v[212:213], v[170:173], off offset:256
	v_lshl_add_u64 v[174:175], v[140:141], 1, v[168:169]
	v_add_co_u32_e32 v210, vcc, s61, v166
	global_load_dwordx4 v[170:173], v[174:175], off
	s_nop 0
	v_addc_co_u32_e32 v211, vcc, 0, v167, vcc
	global_load_dwordx4 v[182:185], v[210:211], off
	global_load_dwordx4 v[186:189], v[174:175], off offset:256
	v_lshl_add_u64 v[174:175], v[166:167], 0, s[0:1]
	global_load_dwordx4 v[190:193], v[174:175], off offset:256
	v_lshl_add_u64 v[202:203], v[142:143], 1, v[168:169]
	v_add_co_u32_e32 v212, vcc, s62, v166
	global_load_dwordx4 v[194:197], v[202:203], off
	s_nop 0
	v_addc_co_u32_e32 v213, vcc, 0, v167, vcc
	global_load_dwordx4 v[198:201], v[212:213], off
	s_nop 0
	global_load_dwordx4 v[202:205], v[202:203], off offset:256
	v_lshl_add_u64 v[214:215], v[166:167], 0, s[10:11]
	global_load_dwordx4 v[206:209], v[214:215], off offset:256
	s_waitcnt vmcnt(0)
; DI unsigned pk_bf16(float lo, float hi) { f32x2 v = {lo, hi}; return __builtin_bit_cast(unsigned, __builtin_convertvector(v, bf16v2)); }
; DI float bf_lo(unsigned w) { return __uint_as_float(w << 16); }
; DI float bf_hi(unsigned w) { return __uint_as_float(w & 0xffff0000u); }
;     DI void operator()(AccRef acc, const Unit& u, int wr, int wc, int fr, int fq) const {
;     ...
;                 u32x4 gv[2][2], mv[2][2];
; #pragma unroll
;                 for (int mm = 0; mm < 2; ++mm)
; #pragma unroll
;                     for (int bj = 0; bj < 2; ++bj) {
;                         const size_t row = (size_t)(row0 + ai * 128 + (mh * 2 + mm) * 16); const int col = col0 + bj * 128;
;                         gv[mm][bj] = *(const u32x4*)(gab + (size_t)(u.pm * 8 + SECOND * 4 + u.pn) * 65536 + (wr * 64 + fr + ai * 128 + (mh * 2 + mm) * 16) * 256 + wc * 32 + 8 * fq + bj * 128);
;                         if (SECOND) mv[mm][bj] = *(const u32x4*)(mrg + row * 1024 + col);
;                     }
; #pragma unroll
;                 for (int mm = 0; mm < 2; ++mm)
; #pragma unroll
;                     for (int bj = 0; bj < 2; ++bj) {
;                         const int m = mh * 2 + mm;
;                         const size_t row = (size_t)(row0 + ai * 128 + m * 16); const int col = col0 + bj * 128;
;                         const u32x4 gt = gv[mm][bj];
;                         const f32x4 r0 = acc[ai][bj][m][0], r1 = acc[ai][bj][m][1];
;                         float v[8] = {bf_lo(gt.x) * r0[0], bf_hi(gt.x) * r0[1], bf_lo(gt.y) * r0[2], bf_hi(gt.y) * r0[3], bf_lo(gt.z) * r1[0], bf_hi(gt.z) * r1[1], bf_lo(gt.w) * r1[2], bf_hi(gt.w) * r1[3]};
;                         if (SECOND) { const u32x4 o = mv[mm][bj]; v[0] += bf_lo(o.x); v[1] += bf_hi(o.x); v[2] += bf_lo(o.y); v[3] += bf_hi(o.y); v[4] += bf_lo(o.z); v[5] += bf_hi(o.z); v[6] += bf_lo(o.w); v[7] += bf_hi(o.w); }
;                         u32x4 w; w.x = pk_bf16(v[0], v[1]); w.y = pk_bf16(v[2], v[3]); w.z = pk_bf16(v[4], v[5]); w.w = pk_bf16(v[6], v[7]);
;                         *(u32x4*)(mrg + row * 1024 + col) = w;
;                     }
	v_lshlrev_b32_e32 v216, 16, v170
	v_and_b32_e32 v217, 0xffff0000, v170
	v_lshlrev_b32_e32 v218, 16, v182
	v_and_b32_e32 v219, 0xffff0000, v182
	v_lshlrev_b32_e32 v170, 16, v171
	v_and_b32_e32 v171, 0xffff0000, v171
	v_lshlrev_b32_e32 v182, 16, v183
	v_and_b32_e32 v183, 0xffff0000, v183
	v_pk_fma_f32 v[216:217], v[60:61], v[216:217], v[218:219]
	v_pk_fma_f32 v[182:183], v[62:63], v[170:171], v[182:183]
	v_lshlrev_b32_e32 v170, 16, v172
	v_and_b32_e32 v171, 0xffff0000, v172
	v_lshlrev_b32_e32 v218, 16, v184
	v_and_b32_e32 v219, 0xffff0000, v184
	v_pk_fma_f32 v[218:219], v[56:57], v[170:171], v[218:219]
	v_lshlrev_b32_e32 v170, 16, v173
	v_and_b32_e32 v171, 0xffff0000, v173
	v_lshlrev_b32_e32 v172, 16, v185
	v_and_b32_e32 v173, 0xffff0000, v185
	v_pk_fma_f32 v[184:185], v[58:59], v[170:171], v[172:173]
	v_cvt_pk_bf16_f32 v170, v216, v217
	v_cvt_pk_bf16_f32 v171, v182, v183
	v_cvt_pk_bf16_f32 v172, v218, v219
	v_cvt_pk_bf16_f32 v173, v184, v185
	global_store_dwordx4 v[210:211], v[170:173], off
	v_lshlrev_b32_e32 v182, 16, v191
	v_and_b32_e32 v183, 0xffff0000, v191
	v_lshlrev_b32_e32 v170, 16, v186
	v_and_b32_e32 v171, 0xffff0000, v186
	v_lshlrev_b32_e32 v172, 16, v190
	v_and_b32_e32 v173, 0xffff0000, v190
	v_pk_fma_f32 v[170:171], v[44:45], v[170:171], v[172:173]
	v_lshlrev_b32_e32 v172, 16, v187
	v_and_b32_e32 v173, 0xffff0000, v187
	v_pk_fma_f32 v[172:173], v[46:47], v[172:173], v[182:183]
	v_lshlrev_b32_e32 v182, 16, v188
	v_and_b32_e32 v183, 0xffff0000, v188
	v_lshlrev_b32_e32 v184, 16, v192
	v_and_b32_e32 v185, 0xffff0000, v192
	v_pk_fma_f32 v[182:183], v[40:41], v[182:183], v[184:185]
	v_lshlrev_b32_e32 v184, 16, v189
	v_and_b32_e32 v185, 0xffff0000, v189
	v_lshlrev_b32_e32 v186, 16, v193
	v_and_b32_e32 v187, 0xffff0000, v193
	v_pk_fma_f32 v[184:185], v[42:43], v[184:185], v[186:187]
	v_cvt_pk_bf16_f32 v170, v170, v171
	v_cvt_pk_bf16_f32 v171, v172, v173
	v_cvt_pk_bf16_f32 v172, v182, v183
	v_cvt_pk_bf16_f32 v173, v184, v185
	global_store_dwordx4 v[174:175], v[170:173], off offset:256
	v_lshlrev_b32_e32 v174, 16, v199
	v_and_b32_e32 v175, 0xffff0000, v199
	v_lshlrev_b32_e32 v170, 16, v194
	v_and_b32_e32 v171, 0xffff0000, v194
	v_lshlrev_b32_e32 v172, 16, v198
	v_and_b32_e32 v173, 0xffff0000, v198
	v_pk_fma_f32 v[170:171], v[52:53], v[170:171], v[172:173]
	v_lshlrev_b32_e32 v172, 16, v195
	v_and_b32_e32 v173, 0xffff0000, v195
	v_pk_fma_f32 v[172:173], v[54:55], v[172:173], v[174:175]
	v_lshlrev_b32_e32 v174, 16, v196
	v_and_b32_e32 v175, 0xffff0000, v196
	v_lshlrev_b32_e32 v182, 16, v200
	v_and_b32_e32 v183, 0xffff0000, v200
	v_pk_fma_f32 v[174:175], v[48:49], v[174:175], v[182:183]
	v_lshlrev_b32_e32 v182, 16, v197
	v_and_b32_e32 v183, 0xffff0000, v197
	v_lshlrev_b32_e32 v184, 16, v201
	v_and_b32_e32 v185, 0xffff0000, v201
	v_pk_fma_f32 v[182:183], v[50:51], v[182:183], v[184:185]
	v_cvt_pk_bf16_f32 v170, v170, v171
	v_cvt_pk_bf16_f32 v171, v172, v173
	v_cvt_pk_bf16_f32 v172, v174, v175
	v_cvt_pk_bf16_f32 v173, v182, v183
	global_store_dwordx4 v[212:213], v[170:173], off
	v_lshlrev_b32_e32 v174, 16, v207
	v_and_b32_e32 v175, 0xffff0000, v207
	v_lshlrev_b32_e32 v170, 16, v202
	v_and_b32_e32 v171, 0xffff0000, v202
	v_lshlrev_b32_e32 v172, 16, v206
	v_and_b32_e32 v173, 0xffff0000, v206
	v_pk_fma_f32 v[170:171], v[36:37], v[170:171], v[172:173]
	v_lshlrev_b32_e32 v172, 16, v203
	v_and_b32_e32 v173, 0xffff0000, v203
	v_pk_fma_f32 v[172:173], v[38:39], v[172:173], v[174:175]
	v_lshlrev_b32_e32 v174, 16, v204
	v_and_b32_e32 v175, 0xffff0000, v204
	v_lshlrev_b32_e32 v182, 16, v208
	v_and_b32_e32 v183, 0xffff0000, v208
	v_pk_fma_f32 v[174:175], v[32:33], v[174:175], v[182:183]
	v_lshlrev_b32_e32 v182, 16, v205
	v_and_b32_e32 v183, 0xffff0000, v205
	v_lshlrev_b32_e32 v184, 16, v209
	v_and_b32_e32 v185, 0xffff0000, v209
	v_pk_fma_f32 v[182:183], v[34:35], v[182:183], v[184:185]
	v_cvt_pk_bf16_f32 v170, v170, v171
	v_cvt_pk_bf16_f32 v171, v172, v173
	v_cvt_pk_bf16_f32 v172, v174, v175
	v_cvt_pk_bf16_f32 v173, v182, v183
	global_store_dwordx4 v[214:215], v[170:173], off offset:256
	v_lshl_add_u64 v[174:175], v[144:145], 1, v[168:169]
	v_add_co_u32_e32 v206, vcc, s63, v166
	global_load_dwordx4 v[170:173], v[174:175], off
	s_nop 0
	v_addc_co_u32_e32 v207, vcc, 0, v167, vcc
	global_load_dwordx4 v[182:185], v[206:207], off
	global_load_dwordx4 v[186:189], v[174:175], off offset:256
	v_lshl_add_u64 v[174:175], v[166:167], 0, s[12:13]
	global_load_dwordx4 v[190:193], v[174:175], off offset:256
	v_lshl_add_u64 v[168:169], v[146:147], 1, v[168:169]
	v_add_co_u32_e32 v208, vcc, s64, v166
	global_load_dwordx4 v[194:197], v[168:169], off
	s_nop 0
	v_addc_co_u32_e32 v209, vcc, 0, v167, vcc
	global_load_dwordx4 v[198:201], v[208:209], off
	global_load_dwordx4 v[202:205], v[168:169], off offset:256
	v_lshl_add_u64 v[210:211], v[166:167], 0, s[14:15]
	global_load_dwordx4 v[166:169], v[210:211], off offset:256
	s_waitcnt vmcnt(0)
; DI unsigned pk_bf16(float lo, float hi) { f32x2 v = {lo, hi}; return __builtin_bit_cast(unsigned, __builtin_convertvector(v, bf16v2)); }
; DI float bf_lo(unsigned w) { return __uint_as_float(w << 16); }
; DI float bf_hi(unsigned w) { return __uint_as_float(w & 0xffff0000u); }
;     DI void operator()(AccRef acc, const Unit& u, int wr, int wc, int fr, int fq) const {
;     ...
;                 u32x4 gv[2][2], mv[2][2];
; #pragma unroll
;                 for (int mm = 0; mm < 2; ++mm)
; #pragma unroll
;                     for (int bj = 0; bj < 2; ++bj) {
;                         const size_t row = (size_t)(row0 + ai * 128 + (mh * 2 + mm) * 16); const int col = col0 + bj * 128;
;                         gv[mm][bj] = *(const u32x4*)(gab + (size_t)(u.pm * 8 + SECOND * 4 + u.pn) * 65536 + (wr * 64 + fr + ai * 128 + (mh * 2 + mm) * 16) * 256 + wc * 32 + 8 * fq + bj * 128);
;                         if (SECOND) mv[mm][bj] = *(const u32x4*)(mrg + row * 1024 + col);
;                     }
; #pragma unroll
;                 for (int mm = 0; mm < 2; ++mm)
; #pragma unroll
;                     for (int bj = 0; bj < 2; ++bj) {
;                         const int m = mh * 2 + mm;
;                         const size_t row = (size_t)(row0 + ai * 128 + m * 16); const int col = col0 + bj * 128;
;                         const u32x4 gt = gv[mm][bj];
;                         const f32x4 r0 = acc[ai][bj][m][0], r1 = acc[ai][bj][m][1];
;                         float v[8] = {bf_lo(gt.x) * r0[0], bf_hi(gt.x) * r0[1], bf_lo(gt.y) * r0[2], bf_hi(gt.y) * r0[3], bf_lo(gt.z) * r1[0], bf_hi(gt.z) * r1[1], bf_lo(gt.w) * r1[2], bf_hi(gt.w) * r1[3]};
;                         if (SECOND) { const u32x4 o = mv[mm][bj]; v[0] += bf_lo(o.x); v[1] += bf_hi(o.x); v[2] += bf_lo(o.y); v[3] += bf_hi(o.y); v[4] += bf_lo(o.z); v[5] += bf_hi(o.z); v[6] += bf_lo(o.w); v[7] += bf_hi(o.w); }
;                         u32x4 w; w.x = pk_bf16(v[0], v[1]); w.y = pk_bf16(v[2], v[3]); w.z = pk_bf16(v[4], v[5]); w.w = pk_bf16(v[6], v[7]);
;                         *(u32x4*)(mrg + row * 1024 + col) = w;
;                     }
	v_lshlrev_b32_e32 v212, 16, v170
	v_and_b32_e32 v213, 0xffff0000, v170
	v_lshlrev_b32_e32 v214, 16, v182
	v_and_b32_e32 v215, 0xffff0000, v182
	v_lshlrev_b32_e32 v170, 16, v171
	v_and_b32_e32 v171, 0xffff0000, v171
	v_lshlrev_b32_e32 v182, 16, v183
	v_and_b32_e32 v183, 0xffff0000, v183
	v_pk_fma_f32 v[212:213], v[28:29], v[212:213], v[214:215]
	v_pk_fma_f32 v[182:183], v[30:31], v[170:171], v[182:183]
	v_lshlrev_b32_e32 v170, 16, v172
	v_and_b32_e32 v171, 0xffff0000, v172
	v_lshlrev_b32_e32 v214, 16, v184
	v_and_b32_e32 v215, 0xffff0000, v184
	v_pk_fma_f32 v[214:215], v[24:25], v[170:171], v[214:215]
	v_lshlrev_b32_e32 v170, 16, v173
	v_and_b32_e32 v171, 0xffff0000, v173
	v_lshlrev_b32_e32 v172, 16, v185
	v_and_b32_e32 v173, 0xffff0000, v185
	v_pk_fma_f32 v[184:185], v[26:27], v[170:171], v[172:173]
	v_cvt_pk_bf16_f32 v170, v212, v213
	v_cvt_pk_bf16_f32 v171, v182, v183
	v_cvt_pk_bf16_f32 v172, v214, v215
	v_cvt_pk_bf16_f32 v173, v184, v185
	global_store_dwordx4 v[206:207], v[170:173], off
	v_lshlrev_b32_e32 v182, 16, v191
	v_and_b32_e32 v183, 0xffff0000, v191
	v_lshlrev_b32_e32 v170, 16, v186
	v_and_b32_e32 v171, 0xffff0000, v186
	v_lshlrev_b32_e32 v172, 16, v190
	v_and_b32_e32 v173, 0xffff0000, v190
	v_pk_fma_f32 v[170:171], v[12:13], v[170:171], v[172:173]
	v_lshlrev_b32_e32 v172, 16, v187
	v_and_b32_e32 v173, 0xffff0000, v187
	v_pk_fma_f32 v[172:173], v[14:15], v[172:173], v[182:183]
	v_lshlrev_b32_e32 v182, 16, v188
	v_and_b32_e32 v183, 0xffff0000, v188
	v_lshlrev_b32_e32 v184, 16, v192
	v_and_b32_e32 v185, 0xffff0000, v192
	v_pk_fma_f32 v[182:183], v[8:9], v[182:183], v[184:185]
	v_lshlrev_b32_e32 v184, 16, v189
	v_and_b32_e32 v185, 0xffff0000, v189
	v_lshlrev_b32_e32 v186, 16, v193
	v_and_b32_e32 v187, 0xffff0000, v193
	v_pk_fma_f32 v[184:185], v[10:11], v[184:185], v[186:187]
	v_cvt_pk_bf16_f32 v170, v170, v171
	v_cvt_pk_bf16_f32 v171, v172, v173
	v_cvt_pk_bf16_f32 v172, v182, v183
	v_cvt_pk_bf16_f32 v173, v184, v185
	global_store_dwordx4 v[174:175], v[170:173], off offset:256
	v_lshlrev_b32_e32 v174, 16, v199
	v_and_b32_e32 v175, 0xffff0000, v199
	v_lshlrev_b32_e32 v170, 16, v194
	v_and_b32_e32 v171, 0xffff0000, v194
	v_lshlrev_b32_e32 v172, 16, v198
	v_and_b32_e32 v173, 0xffff0000, v198
	v_pk_fma_f32 v[170:171], v[20:21], v[170:171], v[172:173]
	v_lshlrev_b32_e32 v172, 16, v195
	v_and_b32_e32 v173, 0xffff0000, v195
	v_pk_fma_f32 v[172:173], v[22:23], v[172:173], v[174:175]
	v_lshlrev_b32_e32 v174, 16, v196
	v_and_b32_e32 v175, 0xffff0000, v196
	v_lshlrev_b32_e32 v182, 16, v200
	v_and_b32_e32 v183, 0xffff0000, v200
	v_pk_fma_f32 v[174:175], v[16:17], v[174:175], v[182:183]
	v_lshlrev_b32_e32 v182, 16, v197
	v_and_b32_e32 v183, 0xffff0000, v197
	v_lshlrev_b32_e32 v184, 16, v201
	v_and_b32_e32 v185, 0xffff0000, v201
	v_pk_fma_f32 v[182:183], v[18:19], v[182:183], v[184:185]
	v_cvt_pk_bf16_f32 v170, v170, v171
	v_cvt_pk_bf16_f32 v171, v172, v173
	v_cvt_pk_bf16_f32 v172, v174, v175
	v_cvt_pk_bf16_f32 v173, v182, v183
	global_store_dwordx4 v[208:209], v[170:173], off
	v_lshlrev_b32_e32 v174, 16, v168
	v_and_b32_e32 v175, 0xffff0000, v168
	v_lshlrev_b32_e32 v170, 16, v202
	v_and_b32_e32 v171, 0xffff0000, v202
	v_lshlrev_b32_e32 v172, 16, v166
	v_and_b32_e32 v173, 0xffff0000, v166
	v_pk_fma_f32 v[170:171], v[4:5], v[170:171], v[172:173]
	v_lshlrev_b32_e32 v172, 16, v203
	v_and_b32_e32 v173, 0xffff0000, v203
	v_lshlrev_b32_e32 v166, 16, v167
	v_and_b32_e32 v167, 0xffff0000, v167
	v_pk_fma_f32 v[172:173], v[6:7], v[172:173], v[166:167]
	v_lshlrev_b32_e32 v166, 16, v204
	v_and_b32_e32 v167, 0xffff0000, v204
	v_pk_fma_f32 v[174:175], v[0:1], v[166:167], v[174:175]
	v_lshlrev_b32_e32 v166, 16, v205
	v_and_b32_e32 v167, 0xffff0000, v205
	v_lshlrev_b32_e32 v168, 16, v169
	v_and_b32_e32 v169, 0xffff0000, v169
	v_pk_fma_f32 v[182:183], v[2:3], v[166:167], v[168:169]
	v_cvt_pk_bf16_f32 v166, v170, v171
	v_cvt_pk_bf16_f32 v167, v172, v173
	v_cvt_pk_bf16_f32 v168, v174, v175
	v_cvt_pk_bf16_f32 v169, v182, v183
	global_store_dwordx4 v[210:211], v[166:169], off offset:256

; #define PG8_STAGE(bufoff, gbase, voff) do { _Pragma("unroll") for (int _i = 0; _i < 2; ++_i) \
;         __builtin_amdgcn_global_load_lds((const unsigned*)((const char*)(gbase) + (voff)[_i]), (LAS unsigned*)(lds + (bufoff) + ldsw + _i * 8192), 16, 0, 0); } while (0)
; #define PG8_LDA(dst, b, h) do { _Pragma("unroll") for (int m = 0; m < 4; ++m) _Pragma("unroll") for (int k = 0; k < 2; ++k) dst[m][k] = *(const LAS bf16x8*)(lds + PG8_SA(b, h) + aoff + m * 2048 + k * 1024); } while (0)
; #define PG8_LDB(dst, b, h) do { _Pragma("unroll") for (int n = 0; n < 2; ++n) _Pragma("unroll") for (int k = 0; k < 2; ++k) dst[n][k] = *(const LAS bf16x8*)(lds + PG8_SB(b, h) + boff + n * 2048 + k * 1024); } while (0)
; #define PG8_WAIT_V(n) asm volatile("s_waitcnt vmcnt(" #n ")" ::: "memory")
; #define PG8_WAIT_L(n) asm volatile("s_waitcnt lgkmcnt(" #n ")" ::: "memory")
; #define PG8_BAR __builtin_amdgcn_s_barrier()
; #define PG8_SCHED __builtin_amdgcn_sched_barrier(0)
; #define PG8_BAR __builtin_amdgcn_s_barrier()
; template <class Epi>
; DI void gemm_phase(LAS unsigned char* lds, const Gemm g, const StaticOrder S, const Epi E) {
;     ...
;             PG8_LDB(B0, 0, 0); PG8_SCHED; PG8_LDA(At, 0, 0); PG8_STAGE(PG8_SA(1, 1), a1 + hstep, voffA);
;             PG8_WAIT_L(8); PG8_BAR; PG8_WAIT_L(0); PG8_MMA(0, 0, At, B0); PG8_BAR; PG8_SCHED;
;             PG8_LDB(B1, 0, 1); PG8_STAGE(PG8_SB(0, 0), b2, voffB);
;             PG8_BAR; PG8_WAIT_L(0); PG8_MMA(0, 1, At, B1); PG8_BAR;
;             PG8_LDA(At, 0, 1); PG8_STAGE(PG8_SA(0, 0), a2, voffA);
;             PG8_BAR; PG8_WAIT_L(0); PG8_MMA(1, 0, At, B0); PG8_BAR; PG8_SCHED;
;             PG8_STAGE(PG8_SB(0, 1), b2 + hstep, voffB);
;             PG8_WAIT_V(6); PG8_BAR; PG8_MMA(1, 1, At, B1); PG8_BAR;
;             PG8_LDB(B0, 1, 0); PG8_SCHED; PG8_LDA(At, 1, 0); PG8_STAGE(PG8_SA(0, 1), a2 + hstep, voffA);
;             PG8_WAIT_L(8); PG8_BAR; PG8_WAIT_L(0); PG8_MMA(0, 0, At, B0); PG8_BAR; PG8_SCHED;
;             PG8_LDB(B1, 1, 1); PG8_STAGE(PG8_SB(1, 0), b3, voffB);
;             PG8_BAR; PG8_WAIT_L(0); PG8_MMA(0, 1, At, B1); PG8_BAR;
;             PG8_LDA(At, 1, 1); PG8_STAGE(PG8_SA(1, 0), a3, voffA);
;             PG8_BAR; PG8_WAIT_L(0); PG8_MMA(1, 0, At, B0); PG8_BAR; PG8_SCHED;
;             PG8_STAGE(PG8_SB(1, 1), b3 + hstep, voffB);
;             PG8_WAIT_V(6); PG8_BAR; PG8_MMA(1, 1, At, B1); PG8_BAR;
.LBB0_786:
	ds_read_b128 v[128:131], v187
	ds_read_b128 v[132:135], v187 offset:1024
	ds_read_b128 v[136:139], v187 offset:2048
	ds_read_b128 v[140:143], v187 offset:3072
	s_add_u32 s28, s24, 0xfffc0080
	s_addc_u32 s29, s25, -1
	s_cmp_eq_u32 s52, 12
	s_cselect_b32 s39, s6, s29
	s_cselect_b32 s38, s7, s28
	s_cselect_b32 s29, s11, s51
	s_cselect_b32 s28, s13, s50
	v_lshl_add_u64 v[200:201], s[24:25], 0, v[160:161]
	s_add_i32 m0, s19, 0xc000
	ds_read_b128 v[144:147], v188
	ds_read_b128 v[148:151], v188 offset:1024
	ds_read_b128 v[168:171], v188 offset:2048
	ds_read_b128 v[172:175], v188 offset:3072
	ds_read_b128 v[176:179], v188 offset:4096
	ds_read_b128 v[180:183], v188 offset:5120
	ds_read_b128 v[192:195], v188 offset:6144
	ds_read_b128 v[196:199], v188 offset:7168
	global_load_lds_dwordx4 v[200:201], off
	v_lshl_add_u64 v[200:201], s[24:25], 0, v[162:163]
	s_add_i32 m0, s19, 0xe000
	s_nop 0
	global_load_lds_dwordx4 v[200:201], off
	s_waitcnt lgkmcnt(8)
	s_barrier
	s_waitcnt lgkmcnt(0)
	s_setprio 1
	s_waitcnt lgkmcnt(0)
	v_mfma_f32_16x16x32_bf16 v[124:127], v[128:131], v[144:147], v[124:127]
	v_mfma_f32_16x16x32_bf16 v[120:123], v[136:139], v[144:147], v[120:123]
	v_mfma_f32_16x16x32_bf16 v[108:111], v[128:131], v[168:171], v[108:111]
	v_mfma_f32_16x16x32_bf16 v[104:107], v[136:139], v[168:171], v[104:107]
	v_mfma_f32_16x16x32_bf16 v[92:95], v[128:131], v[176:179], v[92:95]
	v_mfma_f32_16x16x32_bf16 v[88:91], v[136:139], v[176:179], v[88:91]
	v_mfma_f32_16x16x32_bf16 v[76:79], v[128:131], v[192:195], v[76:79]
	v_mfma_f32_16x16x32_bf16 v[72:75], v[136:139], v[192:195], v[72:75]
	v_mfma_f32_16x16x32_bf16 v[124:127], v[132:135], v[148:151], v[124:127]
	v_mfma_f32_16x16x32_bf16 v[120:123], v[140:143], v[148:151], v[120:123]
	v_mfma_f32_16x16x32_bf16 v[108:111], v[132:135], v[172:175], v[108:111]
	v_mfma_f32_16x16x32_bf16 v[104:107], v[140:143], v[172:175], v[104:107]
	v_mfma_f32_16x16x32_bf16 v[92:95], v[132:135], v[180:183], v[92:95]
	v_mfma_f32_16x16x32_bf16 v[88:91], v[140:143], v[180:183], v[88:91]
	v_mfma_f32_16x16x32_bf16 v[76:79], v[132:135], v[196:199], v[76:79]
	s_barrier
	v_mfma_f32_16x16x32_bf16 v[72:75], v[140:143], v[196:199], v[72:75]
	s_setprio 0
	s_add_i32 s53, s48, s40
	v_lshl_add_u64 v[216:217], s[28:29], 0, v[154:155]
	s_mov_b32 m0, s53
	ds_read_b128 v[200:203], v189
	ds_read_b128 v[204:207], v189 offset:1024
	ds_read_b128 v[208:211], v189 offset:2048
	ds_read_b128 v[212:215], v189 offset:3072
	global_load_lds_dwordx4 v[216:217], off
	v_lshl_add_u64 v[218:219], s[28:29], 0, v[158:159]
	s_add_i32 m0, s53, 0x2000
	s_nop 0
	global_load_lds_dwordx4 v[218:219], off
	s_barrier
	s_waitcnt lgkmcnt(0)
	s_setprio 1
	s_waitcnt lgkmcnt(0)
	v_mfma_f32_16x16x32_bf16 v[116:119], v[200:203], v[144:147], v[116:119]
	v_mfma_f32_16x16x32_bf16 v[112:115], v[208:211], v[144:147], v[112:115]
	v_mfma_f32_16x16x32_bf16 v[100:103], v[200:203], v[168:171], v[100:103]
	v_mfma_f32_16x16x32_bf16 v[96:99], v[208:211], v[168:171], v[96:99]
	v_mfma_f32_16x16x32_bf16 v[84:87], v[200:203], v[176:179], v[84:87]
	v_mfma_f32_16x16x32_bf16 v[80:83], v[208:211], v[176:179], v[80:83]
	v_mfma_f32_16x16x32_bf16 v[68:71], v[200:203], v[192:195], v[68:71]
	v_mfma_f32_16x16x32_bf16 v[64:67], v[208:211], v[192:195], v[64:67]
	v_mfma_f32_16x16x32_bf16 v[116:119], v[204:207], v[148:151], v[116:119]
	v_mfma_f32_16x16x32_bf16 v[112:115], v[212:215], v[148:151], v[112:115]
	v_mfma_f32_16x16x32_bf16 v[100:103], v[204:207], v[172:175], v[100:103]
	v_mfma_f32_16x16x32_bf16 v[96:99], v[212:215], v[172:175], v[96:99]
	v_mfma_f32_16x16x32_bf16 v[84:87], v[204:207], v[180:183], v[84:87]
	v_mfma_f32_16x16x32_bf16 v[80:83], v[212:215], v[180:183], v[80:83]
	v_mfma_f32_16x16x32_bf16 v[68:71], v[204:207], v[196:199], v[68:71]
	s_barrier
	v_mfma_f32_16x16x32_bf16 v[64:67], v[212:215], v[196:199], v[64:67]
	s_setprio 0
	s_mov_b32 m0, s19
	v_lshl_add_u64 v[220:221], s[38:39], 0, v[152:153]
	ds_read_b128 v[144:147], v188 offset:16384
	ds_read_b128 v[148:151], v188 offset:17408
	ds_read_b128 v[168:171], v188 offset:18432
	ds_read_b128 v[172:175], v188 offset:19456
	ds_read_b128 v[176:179], v188 offset:20480
	ds_read_b128 v[180:183], v188 offset:21504
	ds_read_b128 v[192:195], v188 offset:22528
	ds_read_b128 v[196:199], v188 offset:23552
	global_load_lds_dwordx4 v[220:221], off
	v_lshl_add_u64 v[224:225], s[38:39], 0, v[156:157]
	s_mov_b32 m0, s23
	s_nop 0
	global_load_lds_dwordx4 v[224:225], off
	s_barrier
	s_waitcnt lgkmcnt(0)
	s_setprio 1
	s_waitcnt lgkmcnt(0)
	v_mfma_f32_16x16x32_bf16 v[60:63], v[128:131], v[144:147], v[60:63]
	v_mfma_f32_16x16x32_bf16 v[56:59], v[136:139], v[144:147], v[56:59]
	v_mfma_f32_16x16x32_bf16 v[44:47], v[128:131], v[168:171], v[44:47]
	v_mfma_f32_16x16x32_bf16 v[40:43], v[136:139], v[168:171], v[40:43]
	v_mfma_f32_16x16x32_bf16 v[28:31], v[128:131], v[176:179], v[28:31]
	v_mfma_f32_16x16x32_bf16 v[24:27], v[136:139], v[176:179], v[24:27]
	v_mfma_f32_16x16x32_bf16 v[12:15], v[128:131], v[192:195], v[12:15]
	v_mfma_f32_16x16x32_bf16 v[8:11], v[136:139], v[192:195], v[8:11]
	v_mfma_f32_16x16x32_bf16 v[60:63], v[132:135], v[148:151], v[60:63]
	v_mfma_f32_16x16x32_bf16 v[56:59], v[140:143], v[148:151], v[56:59]
	v_mfma_f32_16x16x32_bf16 v[44:47], v[132:135], v[172:175], v[44:47]
	v_mfma_f32_16x16x32_bf16 v[40:43], v[140:143], v[172:175], v[40:43]
	v_mfma_f32_16x16x32_bf16 v[28:31], v[132:135], v[180:183], v[28:31]
	v_mfma_f32_16x16x32_bf16 v[24:27], v[140:143], v[180:183], v[24:27]
	v_mfma_f32_16x16x32_bf16 v[12:15], v[132:135], v[196:199], v[12:15]
	s_barrier
; #define PG8_STAGE(bufoff, gbase, voff) do { _Pragma("unroll") for (int _i = 0; _i < 2; ++_i) \
;         __builtin_amdgcn_global_load_lds((const unsigned*)((const char*)(gbase) + (voff)[_i]), (LAS unsigned*)(lds + (bufoff) + ldsw + _i * 8192), 16, 0, 0); } while (0)
; #define PG8_LDA(dst, b, h) do { _Pragma("unroll") for (int m = 0; m < 4; ++m) _Pragma("unroll") for (int k = 0; k < 2; ++k) dst[m][k] = *(const LAS bf16x8*)(lds + PG8_SA(b, h) + aoff + m * 2048 + k * 1024); } while (0)
; #define PG8_LDB(dst, b, h) do { _Pragma("unroll") for (int n = 0; n < 2; ++n) _Pragma("unroll") for (int k = 0; k < 2; ++k) dst[n][k] = *(const LAS bf16x8*)(lds + PG8_SB(b, h) + boff + n * 2048 + k * 1024); } while (0)
; #define PG8_WAIT_V(n) asm volatile("s_waitcnt vmcnt(" #n ")" ::: "memory")
; #define PG8_WAIT_L(n) asm volatile("s_waitcnt lgkmcnt(" #n ")" ::: "memory")
; #define PG8_BAR __builtin_amdgcn_s_barrier()
; #define PG8_SCHED __builtin_amdgcn_sched_barrier(0)
; #define PG8_BAR __builtin_amdgcn_s_barrier()
; template <class Epi>
; DI void gemm_phase(LAS unsigned char* lds, const Gemm g, const StaticOrder S, const Epi E) {
;     ...
;             PG8_LDB(B0, 0, 0); PG8_SCHED; PG8_LDA(At, 0, 0); PG8_STAGE(PG8_SA(1, 1), a1 + hstep, voffA);
;             PG8_WAIT_L(8); PG8_BAR; PG8_WAIT_L(0); PG8_MMA(0, 0, At, B0); PG8_BAR; PG8_SCHED;
;             PG8_LDB(B1, 0, 1); PG8_STAGE(PG8_SB(0, 0), b2, voffB);
;             PG8_BAR; PG8_WAIT_L(0); PG8_MMA(0, 1, At, B1); PG8_BAR;
;             PG8_LDA(At, 0, 1); PG8_STAGE(PG8_SA(0, 0), a2, voffA);
;             PG8_BAR; PG8_WAIT_L(0); PG8_MMA(1, 0, At, B0); PG8_BAR; PG8_SCHED;
;             PG8_STAGE(PG8_SB(0, 1), b2 + hstep, voffB);
;             PG8_WAIT_V(6); PG8_BAR; PG8_MMA(1, 1, At, B1); PG8_BAR;
;             PG8_LDB(B0, 1, 0); PG8_SCHED; PG8_LDA(At, 1, 0); PG8_STAGE(PG8_SA(0, 1), a2 + hstep, voffA);
;             PG8_WAIT_L(8); PG8_BAR; PG8_WAIT_L(0); PG8_MMA(0, 0, At, B0); PG8_BAR; PG8_SCHED;
;             PG8_LDB(B1, 1, 1); PG8_STAGE(PG8_SB(1, 0), b3, voffB);
;             PG8_BAR; PG8_WAIT_L(0); PG8_MMA(0, 1, At, B1); PG8_BAR;
;             PG8_LDA(At, 1, 1); PG8_STAGE(PG8_SA(1, 0), a3, voffA);
;             PG8_BAR; PG8_WAIT_L(0); PG8_MMA(1, 0, At, B0); PG8_BAR; PG8_SCHED;
;             PG8_STAGE(PG8_SB(1, 1), b3 + hstep, voffB);
;             PG8_WAIT_V(6); PG8_BAR; PG8_MMA(1, 1, At, B1); PG8_BAR;
	v_mfma_f32_16x16x32_bf16 v[8:11], v[140:143], v[196:199], v[8:11]
	s_setprio 0
	s_add_u32 s58, s28, 0x40000
	s_addc_u32 s59, s29, 0
	s_add_i32 s53, s49, s40
	v_lshl_add_u64 v[128:129], s[58:59], 0, v[154:155]
	s_mov_b32 m0, s53
	s_nop 0
	global_load_lds_dwordx4 v[128:129], off
	v_lshl_add_u64 v[128:129], s[58:59], 0, v[158:159]
	s_add_i32 m0, s53, 0x2000
	s_nop 0
	global_load_lds_dwordx4 v[128:129], off
	s_waitcnt vmcnt(6)
	s_barrier
	s_setprio 1
	v_mfma_f32_16x16x32_bf16 v[52:55], v[200:203], v[144:147], v[52:55]
	v_mfma_f32_16x16x32_bf16 v[48:51], v[208:211], v[144:147], v[48:51]
	v_mfma_f32_16x16x32_bf16 v[36:39], v[200:203], v[168:171], v[36:39]
	v_mfma_f32_16x16x32_bf16 v[32:35], v[208:211], v[168:171], v[32:35]
	v_mfma_f32_16x16x32_bf16 v[20:23], v[200:203], v[176:179], v[20:23]
	v_mfma_f32_16x16x32_bf16 v[16:19], v[208:211], v[176:179], v[16:19]
	v_mfma_f32_16x16x32_bf16 v[4:7], v[200:203], v[192:195], v[4:7]
	v_mfma_f32_16x16x32_bf16 v[0:3], v[208:211], v[192:195], v[0:3]
	v_mfma_f32_16x16x32_bf16 v[52:55], v[204:207], v[148:151], v[52:55]
	v_mfma_f32_16x16x32_bf16 v[48:51], v[212:215], v[148:151], v[48:51]
	v_mfma_f32_16x16x32_bf16 v[36:39], v[204:207], v[172:175], v[36:39]
	v_mfma_f32_16x16x32_bf16 v[32:35], v[212:215], v[172:175], v[32:35]
	v_mfma_f32_16x16x32_bf16 v[20:23], v[204:207], v[180:183], v[20:23]
	v_mfma_f32_16x16x32_bf16 v[16:19], v[212:215], v[180:183], v[16:19]
	v_mfma_f32_16x16x32_bf16 v[4:7], v[204:207], v[196:199], v[4:7]
	s_barrier
	v_mfma_f32_16x16x32_bf16 v[0:3], v[212:215], v[196:199], v[0:3]
	s_setprio 0
	s_add_i32 s53, 0, 0x18000
	v_add_u32_e32 v140, s53, v185
	ds_read_b128 v[128:131], v140
	ds_read_b128 v[132:135], v140 offset:1024
	ds_read_b128 v[136:139], v140 offset:2048
	ds_read_b128 v[140:143], v140 offset:3072
	s_add_u32 s38, s38, 0x40000
	s_addc_u32 s39, s39, 0
	s_mov_b32 m0, s41
	v_lshl_add_u64 v[200:201], s[38:39], 0, v[152:153]
	ds_read_b128 v[144:147], v188 offset:32768
	ds_read_b128 v[148:151], v188 offset:33792
	ds_read_b128 v[168:171], v188 offset:34816
	ds_read_b128 v[172:175], v188 offset:35840
	ds_read_b128 v[176:179], v188 offset:36864
	ds_read_b128 v[180:183], v188 offset:37888
	ds_read_b128 v[192:195], v188 offset:38912
	ds_read_b128 v[196:199], v188 offset:39936
	global_load_lds_dwordx4 v[200:201], off
	v_lshl_add_u64 v[200:201], s[38:39], 0, v[156:157]
	s_mov_b32 m0, s42
	s_nop 0
	global_load_lds_dwordx4 v[200:201], off
	s_waitcnt lgkmcnt(8)
	s_barrier
	s_waitcnt lgkmcnt(0)
	s_setprio 1
	s_waitcnt lgkmcnt(0)
	v_mfma_f32_16x16x32_bf16 v[124:127], v[128:131], v[144:147], v[124:127]
	v_mfma_f32_16x16x32_bf16 v[120:123], v[136:139], v[144:147], v[120:123]
	v_mfma_f32_16x16x32_bf16 v[108:111], v[128:131], v[168:171], v[108:111]
	v_mfma_f32_16x16x32_bf16 v[104:107], v[136:139], v[168:171], v[104:107]
	v_mfma_f32_16x16x32_bf16 v[92:95], v[128:131], v[176:179], v[92:95]
	v_mfma_f32_16x16x32_bf16 v[88:91], v[136:139], v[176:179], v[88:91]
	v_mfma_f32_16x16x32_bf16 v[76:79], v[128:131], v[192:195], v[76:79]
	v_mfma_f32_16x16x32_bf16 v[72:75], v[136:139], v[192:195], v[72:75]
	v_mfma_f32_16x16x32_bf16 v[124:127], v[132:135], v[148:151], v[124:127]
	v_mfma_f32_16x16x32_bf16 v[120:123], v[140:143], v[148:151], v[120:123]
	v_mfma_f32_16x16x32_bf16 v[108:111], v[132:135], v[172:175], v[108:111]
	v_mfma_f32_16x16x32_bf16 v[104:107], v[140:143], v[172:175], v[104:107]
	v_mfma_f32_16x16x32_bf16 v[92:95], v[132:135], v[180:183], v[92:95]
	v_mfma_f32_16x16x32_bf16 v[88:91], v[140:143], v[180:183], v[88:91]
	v_mfma_f32_16x16x32_bf16 v[76:79], v[132:135], v[196:199], v[76:79]
	s_barrier
	v_mfma_f32_16x16x32_bf16 v[72:75], v[140:143], v[196:199], v[72:75]
	s_setprio 0
	s_add_i32 s38, 0, 0x1c000
	s_add_i32 s39, s53, s40
	v_add_u32_e32 v191, s38, v185
	v_lshl_add_u64 v[216:217], v[216:217], 0, s[8:9]
	s_mov_b32 m0, s39
	ds_read_b128 v[200:203], v191
	ds_read_b128 v[204:207], v191 offset:1024
	ds_read_b128 v[208:211], v191 offset:2048
	ds_read_b128 v[212:215], v191 offset:3072
	global_load_lds_dwordx4 v[216:217], off
	v_lshl_add_u64 v[216:217], v[218:219], 0, s[8:9]
	s_add_i32 m0, s39, 0x2000
	s_nop 0
	global_load_lds_dwordx4 v[216:217], off
	s_barrier
	s_waitcnt lgkmcnt(0)
	s_setprio 1
	s_waitcnt lgkmcnt(0)
	v_mfma_f32_16x16x32_bf16 v[116:119], v[200:203], v[144:147], v[116:119]
	v_mfma_f32_16x16x32_bf16 v[112:115], v[208:211], v[144:147], v[112:115]
	v_mfma_f32_16x16x32_bf16 v[100:103], v[200:203], v[168:171], v[100:103]
	v_mfma_f32_16x16x32_bf16 v[96:99], v[208:211], v[168:171], v[96:99]
	v_mfma_f32_16x16x32_bf16 v[84:87], v[200:203], v[176:179], v[84:87]
	v_mfma_f32_16x16x32_bf16 v[80:83], v[208:211], v[176:179], v[80:83]
	v_mfma_f32_16x16x32_bf16 v[68:71], v[200:203], v[192:195], v[68:71]
	v_mfma_f32_16x16x32_bf16 v[64:67], v[208:211], v[192:195], v[64:67]
	v_mfma_f32_16x16x32_bf16 v[116:119], v[204:207], v[148:151], v[116:119]
	v_mfma_f32_16x16x32_bf16 v[112:115], v[212:215], v[148:151], v[112:115]
	v_mfma_f32_16x16x32_bf16 v[100:103], v[204:207], v[172:175], v[100:103]
	v_mfma_f32_16x16x32_bf16 v[96:99], v[212:215], v[172:175], v[96:99]
	v_mfma_f32_16x16x32_bf16 v[84:87], v[204:207], v[180:183], v[84:87]
	v_mfma_f32_16x16x32_bf16 v[80:83], v[212:215], v[180:183], v[80:83]
	v_mfma_f32_16x16x32_bf16 v[68:71], v[204:207], v[196:199], v[68:71]
	s_barrier
	v_mfma_f32_16x16x32_bf16 v[64:67], v[212:215], v[196:199], v[64:67]
	s_setprio 0
	s_mov_b32 m0, s44
	v_lshl_add_u64 v[216:217], v[220:221], 0, s[8:9]
	ds_read_b128 v[144:147], v188 offset:49152
	ds_read_b128 v[148:151], v188 offset:50176
	ds_read_b128 v[168:171], v188 offset:51200
	ds_read_b128 v[172:175], v188 offset:52224
	ds_read_b128 v[176:179], v188 offset:53248
	ds_read_b128 v[180:183], v188 offset:54272
	ds_read_b128 v[192:195], v188 offset:55296
	ds_read_b128 v[196:199], v188 offset:56320
	global_load_lds_dwordx4 v[216:217], off
	v_lshl_add_u64 v[216:217], v[224:225], 0, s[8:9]
	s_mov_b32 m0, s45
	s_nop 0
	global_load_lds_dwordx4 v[216:217], off
	s_barrier
; DI unsigned pk_bf16(float lo, float hi) { f32x2 v = {lo, hi}; return __builtin_bit_cast(unsigned, __builtin_convertvector(v, bf16v2)); }
; DI f32x4 bf_lo4(u32x4 w) { f32x4 r; r[0] = bf_lo(w.x); r[1] = bf_hi(w.x); r[2] = bf_lo(w.y); r[3] = bf_hi(w.y); return r; }
; template <class Epi>
; DI void gemm_phase(LAS unsigned char* lds, const Gemm g, const StaticOrder S, const Epi E) {
;     ...
;             PG8_BAR; PG8_WAIT_L(0); PG8_MMA(0, 1, At, B1); PG8_BAR;
;             PG8_LDA(At, 1, 1); PG8_STAGE(PG8_SA(1, 0), a3, voffA);
;             PG8_BAR; PG8_WAIT_L(0); PG8_MMA(1, 0, At, B0); PG8_BAR; PG8_SCHED;
;             PG8_STAGE(PG8_SB(1, 1), b3 + hstep, voffB);
;             PG8_WAIT_V(6); PG8_BAR; PG8_MMA(1, 1, At, B1); PG8_BAR;
;         }
;         E(acc, cur, wr, wc, fr, fq);
;     DI void operator()(AccRef acc, const Unit& u, int wr, int wc, int fr, int fq) const {
;     ...
; #pragma unroll
;         for (int ai = 0; ai < 2; ++ai) {
;             f32x4 bv[4][2][2];
; #pragma unroll
;             for (int m = 0; m < 4; ++m)
; #pragma unroll
;                 for (int bj = 0; bj < 2; ++bj) {
;                     const size_t o = (size_t)(row0 + ai * 128 + m * 16) * DM + col0 + bj * 128;
;                     if (BASEF32) { bv[m][bj][0] = *(const f32x4*)(basef + o); bv[m][bj][1] = *(const f32x4*)(basef + o + 4); }
;                     else { const u32x4 h = *(const u32x4*)(xnb + o); bv[m][bj][0] = bf_lo4(h); bv[m][bj][1] = bf_hi4(h); }
;                 }
; #pragma unroll
;             for (int m = 0; m < 4; ++m) {
;                 const int row = row0 + ai * 128 + m * 16;
;                 float q = 0.f;
; #pragma unroll
;                 for (int bj = 0; bj < 2; ++bj) {
;                     const size_t o = (size_t)row * DM + col0 + bj * 128;
;                     const f32x4 r0 = bv[m][bj][0] + scale * acc[ai][bj][m][0], r1 = bv[m][bj][1] + scale * acc[ai][bj][m][1];
;                     u32x4 w; w.x = pk_bf16(r0[0], r0[1]); w.y = pk_bf16(r0[2], r0[3]); w.z = pk_bf16(r1[0], r1[1]); w.w = pk_bf16(r1[2], r1[3]);
;                     *(u32x4*)(xnb + o) = w;
;                     if (STATS) q += r0[0] * r0[0] + r0[1] * r0[1] + r0[2] * r0[2] + r0[3] * r0[3] + r1[0] * r1[0] + r1[1] * r1[1] + r1[2] * r1[2] + r1[3] * r1[3];
;                 }
;                 if (STATS) { q += __shfl_xor(q, 16); q += __shfl_xor(q, 32); if (fq == 0) atomicAdd(ss + row, q); }
	s_waitcnt lgkmcnt(0)
	s_setprio 1
	s_waitcnt lgkmcnt(0)
	v_mfma_f32_16x16x32_bf16 v[60:63], v[128:131], v[144:147], v[60:63]
	v_mfma_f32_16x16x32_bf16 v[56:59], v[136:139], v[144:147], v[56:59]
	v_mfma_f32_16x16x32_bf16 v[44:47], v[128:131], v[168:171], v[44:47]
	v_mfma_f32_16x16x32_bf16 v[40:43], v[136:139], v[168:171], v[40:43]
	v_mfma_f32_16x16x32_bf16 v[28:31], v[128:131], v[176:179], v[28:31]
	v_mfma_f32_16x16x32_bf16 v[24:27], v[136:139], v[176:179], v[24:27]
	v_mfma_f32_16x16x32_bf16 v[12:15], v[128:131], v[192:195], v[12:15]
	v_mfma_f32_16x16x32_bf16 v[8:11], v[136:139], v[192:195], v[8:11]
	v_mfma_f32_16x16x32_bf16 v[60:63], v[132:135], v[148:151], v[60:63]
	v_mfma_f32_16x16x32_bf16 v[56:59], v[140:143], v[148:151], v[56:59]
	v_mfma_f32_16x16x32_bf16 v[44:47], v[132:135], v[172:175], v[44:47]
	v_mfma_f32_16x16x32_bf16 v[40:43], v[140:143], v[172:175], v[40:43]
	v_mfma_f32_16x16x32_bf16 v[28:31], v[132:135], v[180:183], v[28:31]
	v_mfma_f32_16x16x32_bf16 v[24:27], v[140:143], v[180:183], v[24:27]
	v_mfma_f32_16x16x32_bf16 v[12:15], v[132:135], v[196:199], v[12:15]
	s_barrier
	v_mfma_f32_16x16x32_bf16 v[8:11], v[140:143], v[196:199], v[8:11]
	s_setprio 0
	s_add_u32 s28, s28, 0x40080
	s_addc_u32 s29, s29, 0
	s_add_i32 s38, s38, s40
	v_lshl_add_u64 v[128:129], s[28:29], 0, v[154:155]
	s_mov_b32 m0, s38
	s_nop 0
	global_load_lds_dwordx4 v[128:129], off
	v_lshl_add_u64 v[128:129], s[28:29], 0, v[158:159]
	s_add_i32 m0, s38, 0x2000
	s_nop 0
	global_load_lds_dwordx4 v[128:129], off
	s_waitcnt vmcnt(6)
	s_barrier
	s_setprio 1
	v_mfma_f32_16x16x32_bf16 v[52:55], v[200:203], v[144:147], v[52:55]
	v_mfma_f32_16x16x32_bf16 v[48:51], v[208:211], v[144:147], v[48:51]
	v_mfma_f32_16x16x32_bf16 v[36:39], v[200:203], v[168:171], v[36:39]
	v_mfma_f32_16x16x32_bf16 v[32:35], v[208:211], v[168:171], v[32:35]
	v_mfma_f32_16x16x32_bf16 v[20:23], v[200:203], v[176:179], v[20:23]
	v_mfma_f32_16x16x32_bf16 v[16:19], v[208:211], v[176:179], v[16:19]
	v_mfma_f32_16x16x32_bf16 v[4:7], v[200:203], v[192:195], v[4:7]
	v_mfma_f32_16x16x32_bf16 v[0:3], v[208:211], v[192:195], v[0:3]
	v_mfma_f32_16x16x32_bf16 v[52:55], v[204:207], v[148:151], v[52:55]
	v_mfma_f32_16x16x32_bf16 v[48:51], v[212:215], v[148:151], v[48:51]
	v_mfma_f32_16x16x32_bf16 v[36:39], v[204:207], v[172:175], v[36:39]
	v_mfma_f32_16x16x32_bf16 v[32:35], v[212:215], v[172:175], v[32:35]
	v_mfma_f32_16x16x32_bf16 v[20:23], v[204:207], v[180:183], v[20:23]
	v_mfma_f32_16x16x32_bf16 v[16:19], v[212:215], v[180:183], v[16:19]
	v_mfma_f32_16x16x32_bf16 v[4:7], v[204:207], v[196:199], v[4:7]
	s_barrier
	v_mfma_f32_16x16x32_bf16 v[0:3], v[212:215], v[196:199], v[0:3]
	s_setprio 0
	s_add_i32 s52, s52, 2
	s_add_u32 s24, s24, 0x100
	s_addc_u32 s25, s25, 0
	s_add_u32 s50, s50, 0x100
	s_addc_u32 s51, s51, 0
	s_cmp_gt_u32 s52, 13
	s_cbranch_scc0 .LBB0_786
	v_lshl_add_u32 v170, s18, 8, v184
	v_lshl_or_b32 v128, s22, 8, v186
	v_ashrrev_i32_e32 v129, 31, v128
	v_ashrrev_i32_e32 v171, 31, v170
	v_lshl_add_u64 v[168:169], v[128:129], 1, s[56:57]
	v_lshlrev_b64 v[128:129], 11, v[170:171]
	v_lshl_add_u64 v[202:203], v[168:169], 0, v[128:129]
	global_load_dwordx4 v[194:197], v[202:203], off
	global_load_dwordx4 v[198:201], v[202:203], off offset:256
	v_or_b32_e32 v180, 16, v170
	v_or_b32_e32 v176, 32, v170
	v_or_b32_e32 v172, 48, v170
	v_ashrrev_i32_e32 v181, 31, v180
	v_ashrrev_i32_e32 v177, 31, v176
	v_ashrrev_i32_e32 v173, 31, v172
	v_lshlrev_b64 v[128:129], 11, v[180:181]
	v_lshlrev_b64 v[130:131], 11, v[176:177]
	v_lshlrev_b64 v[132:133], 11, v[172:173]
	v_lshl_add_u64 v[182:183], v[168:169], 0, v[128:129]
	v_lshl_add_u64 v[178:179], v[168:169], 0, v[130:131]
	v_lshl_add_u64 v[174:175], v[168:169], 0, v[132:133]
	global_load_dwordx4 v[148:151], v[182:183], off
	global_load_dwordx4 v[144:147], v[182:183], off offset:256
	global_load_dwordx4 v[140:143], v[178:179], off
	global_load_dwordx4 v[136:139], v[178:179], off offset:256
	global_load_dwordx4 v[132:135], v[174:175], off
	global_load_dwordx4 v[128:131], v[174:175], off offset:256
	v_and_b32_e32 v192, 64, v190
	v_xor_b32_e32 v191, 16, v190
	v_add_u32_e32 v192, 64, v192
	v_cmp_lt_i32_e32 vcc, v191, v192
	v_xor_b32_e32 v193, 32, v190
	s_waitcnt vmcnt(0)
	v_lshlrev_b32_e32 v204, 16, v194
	v_and_b32_e32 v205, 0xffff0000, v194
	v_lshlrev_b32_e32 v208, 16, v198
	v_and_b32_e32 v209, 0xffff0000, v198
	v_lshlrev_b32_e32 v194, 16, v195
	v_and_b32_e32 v195, 0xffff0000, v195
	v_lshlrev_b32_e32 v210, 16, v200
	v_and_b32_e32 v211, 0xffff0000, v200
	v_lshlrev_b32_e32 v200, 16, v201
	v_and_b32_e32 v201, 0xffff0000, v201
	v_pk_add_f32 v[124:125], v[124:125], v[204:205]
	v_pk_add_f32 v[116:117], v[116:117], v[208:209]
	v_lshlrev_b32_e32 v198, 16, v199
	v_and_b32_e32 v199, 0xffff0000, v199
	v_pk_add_f32 v[126:127], v[126:127], v[194:195]
	v_pk_add_f32 v[194:195], v[114:115], v[200:201]
	v_mul_f32_e32 v114, v125, v125
	v_mul_f32_e32 v115, v117, v117
	v_pk_add_f32 v[118:119], v[118:119], v[198:199]
	v_fmac_f32_e32 v114, v124, v124
	v_fmac_f32_e32 v115, v116, v116
	v_lshlrev_b32_e32 v206, 16, v196
	v_and_b32_e32 v207, 0xffff0000, v196
	v_lshlrev_b32_e32 v196, 16, v197
	v_and_b32_e32 v197, 0xffff0000, v197
	v_fmac_f32_e32 v114, v126, v126
	v_fmac_f32_e32 v115, v118, v118
	v_pk_add_f32 v[122:123], v[122:123], v[196:197]
	v_pk_add_f32 v[120:121], v[120:121], v[206:207]
	v_pk_add_f32 v[196:197], v[112:113], v[210:211]
	v_fmac_f32_e32 v114, v127, v127
	v_fmac_f32_e32 v115, v119, v119
	v_fmac_f32_e32 v114, v120, v120
	v_fmac_f32_e32 v115, v196, v196
	v_fmac_f32_e32 v114, v121, v121
	v_fmac_f32_e32 v115, v197, v197
	v_fmac_f32_e32 v114, v122, v122
	v_fmac_f32_e32 v115, v194, v194
	v_cndmask_b32_e32 v191, v190, v191, vcc
	v_fmac_f32_e32 v114, v123, v123
	v_fmac_f32_e32 v115, v195, v195
	v_cmp_lt_i32_e32 vcc, v193, v192
	v_lshlrev_b32_e32 v192, 2, v191
	v_cvt_pk_bf16_f32 v112, v124, v125
	v_add_f32_e32 v124, v114, v115
	ds_bpermute_b32 v125, v192, v124
	v_cndmask_b32_e32 v193, v190, v193, vcc
	v_cvt_pk_bf16_f32 v113, v126, v127
	v_cvt_pk_bf16_f32 v114, v120, v121
	v_cvt_pk_bf16_f32 v115, v122, v123
	v_lshlrev_b32_e32 v191, 2, v193
	global_store_dwordx4 v[202:203], v[112:115], off
	s_waitcnt lgkmcnt(0)
	s_nop 0
	v_add_f32_e32 v112, v124, v125
	ds_bpermute_b32 v113, v191, v112
	v_cvt_pk_bf16_f32 v114, v116, v117
	v_cvt_pk_bf16_f32 v115, v118, v119
	v_cvt_pk_bf16_f32 v116, v196, v197
	v_cvt_pk_bf16_f32 v117, v194, v195
	global_store_dwordx4 v[202:203], v[114:117], off offset:256
	s_and_saveexec_b64 s[6:7], s[0:1]
	s_cbranch_execz .LBB0_789
	s_waitcnt lgkmcnt(0)
	v_add_f32_e32 v114, v112, v113
	v_lshl_add_u64 v[112:113], v[170:171], 2, s[20:21]
	global_atomic_add_f32 v[112:113], v114, off

; #define PG8_STAGE(bufoff, gbase, voff) do { _Pragma("unroll") for (int _i = 0; _i < 2; ++_i) \
;         __builtin_amdgcn_global_load_lds((const unsigned*)((const char*)(gbase) + (voff)[_i]), (LAS unsigned*)(lds + (bufoff) + ldsw + _i * 8192), 16, 0, 0); } while (0)
; #define PG8_LDA(dst, b, h) do { _Pragma("unroll") for (int m = 0; m < 4; ++m) _Pragma("unroll") for (int k = 0; k < 2; ++k) dst[m][k] = *(const LAS bf16x8*)(lds + PG8_SA(b, h) + aoff + m * 2048 + k * 1024); } while (0)
; #define PG8_LDB(dst, b, h) do { _Pragma("unroll") for (int n = 0; n < 2; ++n) _Pragma("unroll") for (int k = 0; k < 2; ++k) dst[n][k] = *(const LAS bf16x8*)(lds + PG8_SB(b, h) + boff + n * 2048 + k * 1024); } while (0)
; #define PG8_WAIT_V(n) asm volatile("s_waitcnt vmcnt(" #n ")" ::: "memory")
; #define PG8_WAIT_L(n) asm volatile("s_waitcnt lgkmcnt(" #n ")" ::: "memory")
; #define PG8_BAR __builtin_amdgcn_s_barrier()
; #define PG8_SCHED __builtin_amdgcn_sched_barrier(0)
; #define PG8_BAR __builtin_amdgcn_s_barrier()
; template <class Epi>
; DI void gemm_phase(LAS unsigned char* lds, const Gemm g, const StaticOrder S, const Epi E) {
;     ...
;             PG8_LDB(B0, 0, 0); PG8_SCHED; PG8_LDA(At, 0, 0); PG8_STAGE(PG8_SA(1, 1), a1 + hstep, voffA);
;             PG8_WAIT_L(8); PG8_BAR; PG8_WAIT_L(0); PG8_MMA(0, 0, At, B0); PG8_BAR; PG8_SCHED;
;             PG8_LDB(B1, 0, 1); PG8_STAGE(PG8_SB(0, 0), b2, voffB);
;             PG8_BAR; PG8_WAIT_L(0); PG8_MMA(0, 1, At, B1); PG8_BAR;
;             PG8_LDA(At, 0, 1); PG8_STAGE(PG8_SA(0, 0), a2, voffA);
;             PG8_BAR; PG8_WAIT_L(0); PG8_MMA(1, 0, At, B0); PG8_BAR; PG8_SCHED;
;             PG8_STAGE(PG8_SB(0, 1), b2 + hstep, voffB);
;             PG8_WAIT_V(6); PG8_BAR; PG8_MMA(1, 1, At, B1); PG8_BAR;
;             PG8_LDB(B0, 1, 0); PG8_SCHED; PG8_LDA(At, 1, 0); PG8_STAGE(PG8_SA(0, 1), a2 + hstep, voffA);
;             PG8_WAIT_L(8); PG8_BAR; PG8_WAIT_L(0); PG8_MMA(0, 0, At, B0); PG8_BAR; PG8_SCHED;
;             PG8_LDB(B1, 1, 1); PG8_STAGE(PG8_SB(1, 0), b3, voffB);
;             PG8_BAR; PG8_WAIT_L(0); PG8_MMA(0, 1, At, B1); PG8_BAR;
;             PG8_LDA(At, 1, 1); PG8_STAGE(PG8_SA(1, 0), a3, voffA);
;             PG8_BAR; PG8_WAIT_L(0); PG8_MMA(1, 0, At, B0); PG8_BAR; PG8_SCHED;
;             PG8_STAGE(PG8_SB(1, 1), b3 + hstep, voffB);
;             PG8_WAIT_V(6); PG8_BAR; PG8_MMA(1, 1, At, B1); PG8_BAR;
.LBB0_865:
	ds_read_b128 v[144:147], v155
	ds_read_b128 v[160:163], v155 offset:1024
	ds_read_b128 v[164:167], v155 offset:2048
	ds_read_b128 v[168:171], v155 offset:3072
	s_add_u32 s10, s8, 0xfffc0080
	s_addc_u32 s11, s9, -1
	s_cmp_eq_u32 s25, 12
	s_cselect_b32 s13, s14, s11
	s_cselect_b32 s12, s15, s10
	s_cselect_b32 s11, s16, s19
	s_cselect_b32 s10, s17, s18
	v_lshl_add_u64 v[204:205], s[8:9], 0, v[136:137]
	s_add_i32 m0, s40, 0xc000
	ds_read_b128 v[172:175], v157
	ds_read_b128 v[176:179], v157 offset:1024
	ds_read_b128 v[180:183], v157 offset:2048
	ds_read_b128 v[184:187], v157 offset:3072
	ds_read_b128 v[188:191], v157 offset:4096
	ds_read_b128 v[192:195], v157 offset:5120
	ds_read_b128 v[196:199], v157 offset:6144
	ds_read_b128 v[200:203], v157 offset:7168
	global_load_lds_dwordx4 v[204:205], off
	v_lshl_add_u64 v[204:205], s[8:9], 0, v[138:139]
	s_add_i32 m0, s40, 0xe000
	s_nop 0
	global_load_lds_dwordx4 v[204:205], off
	s_waitcnt lgkmcnt(8)
	s_barrier
	s_waitcnt lgkmcnt(0)
	s_setprio 1
	s_waitcnt lgkmcnt(0)
	v_mfma_f32_16x16x32_bf16 v[124:127], v[144:147], v[172:175], v[124:127]
	v_mfma_f32_16x16x32_bf16 v[120:123], v[164:167], v[172:175], v[120:123]
	v_mfma_f32_16x16x32_bf16 v[108:111], v[144:147], v[180:183], v[108:111]
	v_mfma_f32_16x16x32_bf16 v[104:107], v[164:167], v[180:183], v[104:107]
	v_mfma_f32_16x16x32_bf16 v[92:95], v[144:147], v[188:191], v[92:95]
	v_mfma_f32_16x16x32_bf16 v[88:91], v[164:167], v[188:191], v[88:91]
	v_mfma_f32_16x16x32_bf16 v[76:79], v[144:147], v[196:199], v[76:79]
	v_mfma_f32_16x16x32_bf16 v[72:75], v[164:167], v[196:199], v[72:75]
	v_mfma_f32_16x16x32_bf16 v[124:127], v[160:163], v[176:179], v[124:127]
	v_mfma_f32_16x16x32_bf16 v[120:123], v[168:171], v[176:179], v[120:123]
	v_mfma_f32_16x16x32_bf16 v[108:111], v[160:163], v[184:187], v[108:111]
	v_mfma_f32_16x16x32_bf16 v[104:107], v[168:171], v[184:187], v[104:107]
	v_mfma_f32_16x16x32_bf16 v[92:95], v[160:163], v[192:195], v[92:95]
	v_mfma_f32_16x16x32_bf16 v[88:91], v[168:171], v[192:195], v[88:91]
	v_mfma_f32_16x16x32_bf16 v[76:79], v[160:163], v[200:203], v[76:79]
	s_barrier
	v_mfma_f32_16x16x32_bf16 v[72:75], v[168:171], v[200:203], v[72:75]
	s_setprio 0
	s_add_i32 s29, s49, s34
	v_lshl_add_u64 v[220:221], s[10:11], 0, v[132:133]
	s_mov_b32 m0, s29
	ds_read_b128 v[204:207], v158
	ds_read_b128 v[208:211], v158 offset:1024
	ds_read_b128 v[212:215], v158 offset:2048
	ds_read_b128 v[216:219], v158 offset:3072
	global_load_lds_dwordx4 v[220:221], off
	v_lshl_add_u64 v[224:225], s[10:11], 0, v[128:129]
	s_add_i32 m0, s29, 0x2000
	s_nop 0
	global_load_lds_dwordx4 v[224:225], off
	s_barrier
	s_waitcnt lgkmcnt(0)
	s_setprio 1
	s_waitcnt lgkmcnt(0)
	v_mfma_f32_16x16x32_bf16 v[116:119], v[204:207], v[172:175], v[116:119]
	v_mfma_f32_16x16x32_bf16 v[112:115], v[212:215], v[172:175], v[112:115]
	v_mfma_f32_16x16x32_bf16 v[100:103], v[204:207], v[180:183], v[100:103]
	v_mfma_f32_16x16x32_bf16 v[96:99], v[212:215], v[180:183], v[96:99]
	v_mfma_f32_16x16x32_bf16 v[84:87], v[204:207], v[188:191], v[84:87]
	v_mfma_f32_16x16x32_bf16 v[80:83], v[212:215], v[188:191], v[80:83]
	v_mfma_f32_16x16x32_bf16 v[68:71], v[204:207], v[196:199], v[68:71]
	v_mfma_f32_16x16x32_bf16 v[64:67], v[212:215], v[196:199], v[64:67]
	v_mfma_f32_16x16x32_bf16 v[116:119], v[208:211], v[176:179], v[116:119]
	v_mfma_f32_16x16x32_bf16 v[112:115], v[216:219], v[176:179], v[112:115]
	v_mfma_f32_16x16x32_bf16 v[100:103], v[208:211], v[184:187], v[100:103]
	v_mfma_f32_16x16x32_bf16 v[96:99], v[216:219], v[184:187], v[96:99]
	v_mfma_f32_16x16x32_bf16 v[84:87], v[208:211], v[192:195], v[84:87]
	v_mfma_f32_16x16x32_bf16 v[80:83], v[216:219], v[192:195], v[80:83]
	v_mfma_f32_16x16x32_bf16 v[68:71], v[208:211], v[200:203], v[68:71]
	s_barrier
	v_mfma_f32_16x16x32_bf16 v[64:67], v[216:219], v[200:203], v[64:67]
	s_setprio 0
	s_mov_b32 m0, s40
	v_lshl_add_u64 v[226:227], s[12:13], 0, v[134:135]
	ds_read_b128 v[172:175], v157 offset:16384
	ds_read_b128 v[176:179], v157 offset:17408
	ds_read_b128 v[180:183], v157 offset:18432
	ds_read_b128 v[184:187], v157 offset:19456
	ds_read_b128 v[188:191], v157 offset:20480
	ds_read_b128 v[192:195], v157 offset:21504
	ds_read_b128 v[196:199], v157 offset:22528
	ds_read_b128 v[200:203], v157 offset:23552
	global_load_lds_dwordx4 v[226:227], off
	v_lshl_add_u64 v[228:229], s[12:13], 0, v[130:131]
	s_mov_b32 m0, s41
	s_nop 0
	global_load_lds_dwordx4 v[228:229], off
	s_barrier
	s_waitcnt lgkmcnt(0)
	s_setprio 1
	s_waitcnt lgkmcnt(0)
	v_mfma_f32_16x16x32_bf16 v[60:63], v[144:147], v[172:175], v[60:63]
	v_mfma_f32_16x16x32_bf16 v[56:59], v[164:167], v[172:175], v[56:59]
	v_mfma_f32_16x16x32_bf16 v[44:47], v[144:147], v[180:183], v[44:47]
	v_mfma_f32_16x16x32_bf16 v[40:43], v[164:167], v[180:183], v[40:43]
	v_mfma_f32_16x16x32_bf16 v[28:31], v[144:147], v[188:191], v[28:31]
	v_mfma_f32_16x16x32_bf16 v[24:27], v[164:167], v[188:191], v[24:27]
	v_mfma_f32_16x16x32_bf16 v[12:15], v[144:147], v[196:199], v[12:15]
	v_mfma_f32_16x16x32_bf16 v[8:11], v[164:167], v[196:199], v[8:11]
	v_mfma_f32_16x16x32_bf16 v[60:63], v[160:163], v[176:179], v[60:63]
	v_mfma_f32_16x16x32_bf16 v[56:59], v[168:171], v[176:179], v[56:59]
	v_mfma_f32_16x16x32_bf16 v[44:47], v[160:163], v[184:187], v[44:47]
	v_mfma_f32_16x16x32_bf16 v[40:43], v[168:171], v[184:187], v[40:43]
	v_mfma_f32_16x16x32_bf16 v[28:31], v[160:163], v[192:195], v[28:31]
	v_mfma_f32_16x16x32_bf16 v[24:27], v[168:171], v[192:195], v[24:27]
	v_mfma_f32_16x16x32_bf16 v[12:15], v[160:163], v[200:203], v[12:15]
	s_barrier
; #define PG8_STAGE(bufoff, gbase, voff) do { _Pragma("unroll") for (int _i = 0; _i < 2; ++_i) \
;         __builtin_amdgcn_global_load_lds((const unsigned*)((const char*)(gbase) + (voff)[_i]), (LAS unsigned*)(lds + (bufoff) + ldsw + _i * 8192), 16, 0, 0); } while (0)
; #define PG8_LDA(dst, b, h) do { _Pragma("unroll") for (int m = 0; m < 4; ++m) _Pragma("unroll") for (int k = 0; k < 2; ++k) dst[m][k] = *(const LAS bf16x8*)(lds + PG8_SA(b, h) + aoff + m * 2048 + k * 1024); } while (0)
; #define PG8_LDB(dst, b, h) do { _Pragma("unroll") for (int n = 0; n < 2; ++n) _Pragma("unroll") for (int k = 0; k < 2; ++k) dst[n][k] = *(const LAS bf16x8*)(lds + PG8_SB(b, h) + boff + n * 2048 + k * 1024); } while (0)
; #define PG8_WAIT_V(n) asm volatile("s_waitcnt vmcnt(" #n ")" ::: "memory")
; #define PG8_WAIT_L(n) asm volatile("s_waitcnt lgkmcnt(" #n ")" ::: "memory")
; #define PG8_BAR __builtin_amdgcn_s_barrier()
; #define PG8_SCHED __builtin_amdgcn_sched_barrier(0)
; #define PG8_BAR __builtin_amdgcn_s_barrier()
; template <class Epi>
; DI void gemm_phase(LAS unsigned char* lds, const Gemm g, const StaticOrder S, const Epi E) {
;     ...
;             PG8_LDB(B0, 0, 0); PG8_SCHED; PG8_LDA(At, 0, 0); PG8_STAGE(PG8_SA(1, 1), a1 + hstep, voffA);
;             PG8_WAIT_L(8); PG8_BAR; PG8_WAIT_L(0); PG8_MMA(0, 0, At, B0); PG8_BAR; PG8_SCHED;
;             PG8_LDB(B1, 0, 1); PG8_STAGE(PG8_SB(0, 0), b2, voffB);
;             PG8_BAR; PG8_WAIT_L(0); PG8_MMA(0, 1, At, B1); PG8_BAR;
;             PG8_LDA(At, 0, 1); PG8_STAGE(PG8_SA(0, 0), a2, voffA);
;             PG8_BAR; PG8_WAIT_L(0); PG8_MMA(1, 0, At, B0); PG8_BAR; PG8_SCHED;
;             PG8_STAGE(PG8_SB(0, 1), b2 + hstep, voffB);
;             PG8_WAIT_V(6); PG8_BAR; PG8_MMA(1, 1, At, B1); PG8_BAR;
;             PG8_LDB(B0, 1, 0); PG8_SCHED; PG8_LDA(At, 1, 0); PG8_STAGE(PG8_SA(0, 1), a2 + hstep, voffA);
;             PG8_WAIT_L(8); PG8_BAR; PG8_WAIT_L(0); PG8_MMA(0, 0, At, B0); PG8_BAR; PG8_SCHED;
;             PG8_LDB(B1, 1, 1); PG8_STAGE(PG8_SB(1, 0), b3, voffB);
;             PG8_BAR; PG8_WAIT_L(0); PG8_MMA(0, 1, At, B1); PG8_BAR;
;             PG8_LDA(At, 1, 1); PG8_STAGE(PG8_SA(1, 0), a3, voffA);
;             PG8_BAR; PG8_WAIT_L(0); PG8_MMA(1, 0, At, B0); PG8_BAR; PG8_SCHED;
;             PG8_STAGE(PG8_SB(1, 1), b3 + hstep, voffB);
;             PG8_WAIT_V(6); PG8_BAR; PG8_MMA(1, 1, At, B1); PG8_BAR;
	v_mfma_f32_16x16x32_bf16 v[8:11], v[168:171], v[200:203], v[8:11]
	s_setprio 0
	s_add_u32 s58, s10, 0x40000
	s_addc_u32 s59, s11, 0
	s_add_i32 s29, s50, s34
	v_lshl_add_u64 v[144:145], s[58:59], 0, v[132:133]
	s_mov_b32 m0, s29
	s_nop 0
	global_load_lds_dwordx4 v[144:145], off
	v_lshl_add_u64 v[144:145], s[58:59], 0, v[128:129]
	s_add_i32 m0, s29, 0x2000
	s_nop 0
	global_load_lds_dwordx4 v[144:145], off
	s_waitcnt vmcnt(6)
	s_barrier
	s_setprio 1
	v_mfma_f32_16x16x32_bf16 v[52:55], v[204:207], v[172:175], v[52:55]
	v_mfma_f32_16x16x32_bf16 v[48:51], v[212:215], v[172:175], v[48:51]
	v_mfma_f32_16x16x32_bf16 v[36:39], v[204:207], v[180:183], v[36:39]
	v_mfma_f32_16x16x32_bf16 v[32:35], v[212:215], v[180:183], v[32:35]
	v_mfma_f32_16x16x32_bf16 v[20:23], v[204:207], v[188:191], v[20:23]
	v_mfma_f32_16x16x32_bf16 v[16:19], v[212:215], v[188:191], v[16:19]
	v_mfma_f32_16x16x32_bf16 v[4:7], v[204:207], v[196:199], v[4:7]
	v_mfma_f32_16x16x32_bf16 v[0:3], v[212:215], v[196:199], v[0:3]
	v_mfma_f32_16x16x32_bf16 v[52:55], v[208:211], v[176:179], v[52:55]
	v_mfma_f32_16x16x32_bf16 v[48:51], v[216:219], v[176:179], v[48:51]
	v_mfma_f32_16x16x32_bf16 v[36:39], v[208:211], v[184:187], v[36:39]
	v_mfma_f32_16x16x32_bf16 v[32:35], v[216:219], v[184:187], v[32:35]
	v_mfma_f32_16x16x32_bf16 v[20:23], v[208:211], v[192:195], v[20:23]
	v_mfma_f32_16x16x32_bf16 v[16:19], v[216:219], v[192:195], v[16:19]
	v_mfma_f32_16x16x32_bf16 v[4:7], v[208:211], v[200:203], v[4:7]
	s_barrier
	v_mfma_f32_16x16x32_bf16 v[0:3], v[216:219], v[200:203], v[0:3]
	s_setprio 0
	s_add_i32 s29, 0, 0x18000
	v_add_u32_e32 v148, s29, v151
	ds_read_b128 v[144:147], v148
	ds_read_b128 v[160:163], v148 offset:1024
	ds_read_b128 v[164:167], v148 offset:2048
	ds_read_b128 v[168:171], v148 offset:3072
	s_add_u32 s12, s12, 0x40000
	s_addc_u32 s13, s13, 0
	s_mov_b32 m0, s42
	v_lshl_add_u64 v[204:205], s[12:13], 0, v[134:135]
	ds_read_b128 v[172:175], v157 offset:32768
	ds_read_b128 v[176:179], v157 offset:33792
	ds_read_b128 v[180:183], v157 offset:34816
	ds_read_b128 v[184:187], v157 offset:35840
	ds_read_b128 v[188:191], v157 offset:36864
	ds_read_b128 v[192:195], v157 offset:37888
	ds_read_b128 v[196:199], v157 offset:38912
	ds_read_b128 v[200:203], v157 offset:39936
	global_load_lds_dwordx4 v[204:205], off
	v_lshl_add_u64 v[204:205], s[12:13], 0, v[130:131]
	s_mov_b32 m0, s43
	s_nop 0
	global_load_lds_dwordx4 v[204:205], off
	s_waitcnt lgkmcnt(8)
	s_barrier
	s_waitcnt lgkmcnt(0)
	s_setprio 1
	s_waitcnt lgkmcnt(0)
	v_mfma_f32_16x16x32_bf16 v[124:127], v[144:147], v[172:175], v[124:127]
	v_mfma_f32_16x16x32_bf16 v[120:123], v[164:167], v[172:175], v[120:123]
	v_mfma_f32_16x16x32_bf16 v[108:111], v[144:147], v[180:183], v[108:111]
	v_mfma_f32_16x16x32_bf16 v[104:107], v[164:167], v[180:183], v[104:107]
	v_mfma_f32_16x16x32_bf16 v[92:95], v[144:147], v[188:191], v[92:95]
	v_mfma_f32_16x16x32_bf16 v[88:91], v[164:167], v[188:191], v[88:91]
	v_mfma_f32_16x16x32_bf16 v[76:79], v[144:147], v[196:199], v[76:79]
	v_mfma_f32_16x16x32_bf16 v[72:75], v[164:167], v[196:199], v[72:75]
	v_mfma_f32_16x16x32_bf16 v[124:127], v[160:163], v[176:179], v[124:127]
	v_mfma_f32_16x16x32_bf16 v[120:123], v[168:171], v[176:179], v[120:123]
	v_mfma_f32_16x16x32_bf16 v[108:111], v[160:163], v[184:187], v[108:111]
	v_mfma_f32_16x16x32_bf16 v[104:107], v[168:171], v[184:187], v[104:107]
	v_mfma_f32_16x16x32_bf16 v[92:95], v[160:163], v[192:195], v[92:95]
	v_mfma_f32_16x16x32_bf16 v[88:91], v[168:171], v[192:195], v[88:91]
	v_mfma_f32_16x16x32_bf16 v[76:79], v[160:163], v[200:203], v[76:79]
	s_barrier
	v_mfma_f32_16x16x32_bf16 v[72:75], v[168:171], v[200:203], v[72:75]
	s_setprio 0
	s_add_i32 s12, 0, 0x1c000
	s_add_i32 s13, s29, s34
	v_add_u32_e32 v148, s12, v151
	v_lshl_add_u64 v[220:221], v[220:221], 0, s[22:23]
	s_mov_b32 m0, s13
	ds_read_b128 v[204:207], v148
	ds_read_b128 v[208:211], v148 offset:1024
	ds_read_b128 v[212:215], v148 offset:2048
	ds_read_b128 v[216:219], v148 offset:3072
	global_load_lds_dwordx4 v[220:221], off
	v_lshl_add_u64 v[220:221], v[224:225], 0, s[22:23]
	s_add_i32 m0, s13, 0x2000
	s_nop 0
	global_load_lds_dwordx4 v[220:221], off
	s_barrier
	s_waitcnt lgkmcnt(0)
	s_setprio 1
	s_waitcnt lgkmcnt(0)
	v_mfma_f32_16x16x32_bf16 v[116:119], v[204:207], v[172:175], v[116:119]
	v_mfma_f32_16x16x32_bf16 v[112:115], v[212:215], v[172:175], v[112:115]
	v_mfma_f32_16x16x32_bf16 v[100:103], v[204:207], v[180:183], v[100:103]
	v_mfma_f32_16x16x32_bf16 v[96:99], v[212:215], v[180:183], v[96:99]
	v_mfma_f32_16x16x32_bf16 v[84:87], v[204:207], v[188:191], v[84:87]
	v_mfma_f32_16x16x32_bf16 v[80:83], v[212:215], v[188:191], v[80:83]
	v_mfma_f32_16x16x32_bf16 v[68:71], v[204:207], v[196:199], v[68:71]
	v_mfma_f32_16x16x32_bf16 v[64:67], v[212:215], v[196:199], v[64:67]
	v_mfma_f32_16x16x32_bf16 v[116:119], v[208:211], v[176:179], v[116:119]
	v_mfma_f32_16x16x32_bf16 v[112:115], v[216:219], v[176:179], v[112:115]
	v_mfma_f32_16x16x32_bf16 v[100:103], v[208:211], v[184:187], v[100:103]
	v_mfma_f32_16x16x32_bf16 v[96:99], v[216:219], v[184:187], v[96:99]
	v_mfma_f32_16x16x32_bf16 v[84:87], v[208:211], v[192:195], v[84:87]
	v_mfma_f32_16x16x32_bf16 v[80:83], v[216:219], v[192:195], v[80:83]
	v_mfma_f32_16x16x32_bf16 v[68:71], v[208:211], v[200:203], v[68:71]
	s_barrier
	v_mfma_f32_16x16x32_bf16 v[64:67], v[216:219], v[200:203], v[64:67]
	s_setprio 0
	s_mov_b32 m0, s45
	v_lshl_add_u64 v[220:221], v[226:227], 0, s[22:23]
	ds_read_b128 v[172:175], v157 offset:49152
	ds_read_b128 v[176:179], v157 offset:50176
	ds_read_b128 v[180:183], v157 offset:51200
	ds_read_b128 v[184:187], v157 offset:52224
	ds_read_b128 v[188:191], v157 offset:53248
	ds_read_b128 v[192:195], v157 offset:54272
	ds_read_b128 v[196:199], v157 offset:55296
	ds_read_b128 v[200:203], v157 offset:56320
	global_load_lds_dwordx4 v[220:221], off
	v_lshl_add_u64 v[220:221], v[228:229], 0, s[22:23]
	s_mov_b32 m0, s46
	s_nop 0
	global_load_lds_dwordx4 v[220:221], off
	s_barrier
; #define PG8_STAGE(bufoff, gbase, voff) do { _Pragma("unroll") for (int _i = 0; _i < 2; ++_i) \
;         __builtin_amdgcn_global_load_lds((const unsigned*)((const char*)(gbase) + (voff)[_i]), (LAS unsigned*)(lds + (bufoff) + ldsw + _i * 8192), 16, 0, 0); } while (0)
; #define PG8_LDA(dst, b, h) do { _Pragma("unroll") for (int m = 0; m < 4; ++m) _Pragma("unroll") for (int k = 0; k < 2; ++k) dst[m][k] = *(const LAS bf16x8*)(lds + PG8_SA(b, h) + aoff + m * 2048 + k * 1024); } while (0)
; #define PG8_MMA(ai, bj, At, Bt) do { __builtin_amdgcn_s_setprio(1); _Pragma("unroll") for (int m = 0; m < 4; ++m) _Pragma("unroll") for (int n = 0; n < 2; ++n) _Pragma("unroll") for (int k = 0; k < 2; ++k) \
;         acc[ai][bj][m][n] = __builtin_amdgcn_mfma_f32_16x16x32_bf16(Bt[n][k], At[m][k], acc[ai][bj][m][n], 0, 0, 0); __builtin_amdgcn_s_setprio(0); } while (0)
; #define PG8_WAIT_V(n) asm volatile("s_waitcnt vmcnt(" #n ")" ::: "memory")
; #define PG8_WAIT_L(n) asm volatile("s_waitcnt lgkmcnt(" #n ")" ::: "memory")
; #define PG8_BAR __builtin_amdgcn_s_barrier()
; #define PG8_SCHED __builtin_amdgcn_sched_barrier(0)
; #define PG8_WAIT_V(n) asm volatile("s_waitcnt vmcnt(" #n ")" ::: "memory")
; #define PG8_BAR __builtin_amdgcn_s_barrier()
; template <class Epi>
; DI void gemm_phase(LAS unsigned char* lds, const Gemm g, const StaticOrder S, const Epi E) {
;     ...
;             PG8_BAR; PG8_WAIT_L(0); PG8_MMA(0, 1, At, B1); PG8_BAR;
;             PG8_LDA(At, 1, 1); PG8_STAGE(PG8_SA(1, 0), a3, voffA);
;             PG8_BAR; PG8_WAIT_L(0); PG8_MMA(1, 0, At, B0); PG8_BAR; PG8_SCHED;
;             PG8_STAGE(PG8_SB(1, 1), b3 + hstep, voffB);
;             PG8_WAIT_V(6); PG8_BAR; PG8_MMA(1, 1, At, B1); PG8_BAR;
;         }
;         E(acc, cur, wr, wc, fr, fq);
;     DI void operator()(AccRef acc, const Unit& u, int wr, int wc, int fr, int fq) const {
;         const int row0 = u.pm * 256 + wr * 64 + fr, col = u.pn * 128 + wc * 32 + 8 * fq;
;         RowScales rsc; if (RS) rsc = load_rowscales(ss, row0);
; #pragma unroll
;         for (int ai = 0; ai < 2; ++ai)
; #pragma unroll
;             for (int m = 0; m < 4; ++m) {
;                 const int row = row0 + ai * 128 + m * 16;
;                 const float r = RS ? rsc.r[ai][m] : 1.0f;
;                 const f32x4 a0 = acc[ai][0][m][0] * r, a1 = acc[ai][0][m][1] * r, b0 = acc[ai][1][m][0] * r, b1 = acc[ai][1][m][1] * r;
	s_waitcnt lgkmcnt(0)
	s_setprio 1
	s_waitcnt lgkmcnt(0)
	v_mfma_f32_16x16x32_bf16 v[60:63], v[144:147], v[172:175], v[60:63]
	v_mfma_f32_16x16x32_bf16 v[56:59], v[164:167], v[172:175], v[56:59]
	v_mfma_f32_16x16x32_bf16 v[44:47], v[144:147], v[180:183], v[44:47]
	v_mfma_f32_16x16x32_bf16 v[40:43], v[164:167], v[180:183], v[40:43]
	v_mfma_f32_16x16x32_bf16 v[28:31], v[144:147], v[188:191], v[28:31]
	v_mfma_f32_16x16x32_bf16 v[24:27], v[164:167], v[188:191], v[24:27]
	v_mfma_f32_16x16x32_bf16 v[12:15], v[144:147], v[196:199], v[12:15]
	v_mfma_f32_16x16x32_bf16 v[8:11], v[164:167], v[196:199], v[8:11]
	v_mfma_f32_16x16x32_bf16 v[60:63], v[160:163], v[176:179], v[60:63]
	v_mfma_f32_16x16x32_bf16 v[56:59], v[168:171], v[176:179], v[56:59]
	v_mfma_f32_16x16x32_bf16 v[44:47], v[160:163], v[184:187], v[44:47]
	v_mfma_f32_16x16x32_bf16 v[40:43], v[168:171], v[184:187], v[40:43]
	v_mfma_f32_16x16x32_bf16 v[28:31], v[160:163], v[192:195], v[28:31]
	v_mfma_f32_16x16x32_bf16 v[24:27], v[168:171], v[192:195], v[24:27]
	v_mfma_f32_16x16x32_bf16 v[12:15], v[160:163], v[200:203], v[12:15]
	s_barrier
	v_mfma_f32_16x16x32_bf16 v[8:11], v[168:171], v[200:203], v[8:11]
	s_setprio 0
	s_add_u32 s10, s10, 0x40080
	s_addc_u32 s11, s11, 0
	s_add_i32 s12, s12, s34
	v_lshl_add_u64 v[144:145], s[10:11], 0, v[132:133]
	s_mov_b32 m0, s12
	s_nop 0
	global_load_lds_dwordx4 v[144:145], off
	v_lshl_add_u64 v[144:145], s[10:11], 0, v[128:129]
	s_add_i32 m0, s12, 0x2000
	s_nop 0
	global_load_lds_dwordx4 v[144:145], off
	s_waitcnt vmcnt(6)
	s_barrier
	s_setprio 1
	v_mfma_f32_16x16x32_bf16 v[52:55], v[204:207], v[172:175], v[52:55]
	v_mfma_f32_16x16x32_bf16 v[48:51], v[212:215], v[172:175], v[48:51]
	v_mfma_f32_16x16x32_bf16 v[36:39], v[204:207], v[180:183], v[36:39]
	v_mfma_f32_16x16x32_bf16 v[32:35], v[212:215], v[180:183], v[32:35]
	v_mfma_f32_16x16x32_bf16 v[20:23], v[204:207], v[188:191], v[20:23]
	v_mfma_f32_16x16x32_bf16 v[16:19], v[212:215], v[188:191], v[16:19]
	v_mfma_f32_16x16x32_bf16 v[4:7], v[204:207], v[196:199], v[4:7]
	v_mfma_f32_16x16x32_bf16 v[0:3], v[212:215], v[196:199], v[0:3]
	v_mfma_f32_16x16x32_bf16 v[52:55], v[208:211], v[176:179], v[52:55]
	v_mfma_f32_16x16x32_bf16 v[48:51], v[216:219], v[176:179], v[48:51]
	v_mfma_f32_16x16x32_bf16 v[36:39], v[208:211], v[184:187], v[36:39]
	v_mfma_f32_16x16x32_bf16 v[32:35], v[216:219], v[184:187], v[32:35]
	v_mfma_f32_16x16x32_bf16 v[20:23], v[208:211], v[192:195], v[20:23]
	v_mfma_f32_16x16x32_bf16 v[16:19], v[216:219], v[192:195], v[16:19]
	v_mfma_f32_16x16x32_bf16 v[4:7], v[208:211], v[200:203], v[4:7]
	s_barrier
	v_mfma_f32_16x16x32_bf16 v[0:3], v[216:219], v[200:203], v[0:3]
	s_setprio 0
	s_add_i32 s25, s25, 2
	s_add_u32 s8, s8, 0x100
	s_addc_u32 s9, s9, 0
	s_add_u32 s18, s18, 0x100
	s_addc_u32 s19, s19, 0
	s_cmp_gt_u32 s25, 13
	s_cbranch_scc0 .LBB0_865
	v_lshl_add_u32 v146, s4, 8, v149
	v_ashrrev_i32_e32 v147, 31, v146
	v_lshl_add_u64 v[144:145], v[146:147], 2, s[20:21]
	global_load_dword v147, v[144:145], off
	global_load_dword v148, v[144:145], off offset:64
	global_load_dword v150, v[144:145], off offset:128
	global_load_dword v152, v[144:145], off offset:192
	global_load_dword v154, v[144:145], off offset:512
	global_load_dword v156, v[144:145], off offset:576
	global_load_dword v160, v[144:145], off offset:640
	global_load_dword v161, v[144:145], off offset:704
	v_lshl_or_b32 v144, s5, 7, v153
	v_ashrrev_i32_e32 v145, 31, v144
	v_lshl_add_u64 v[144:145], v[144:145], 1, s[54:55]
	s_waitcnt vmcnt(0)
	v_fmamk_f32 v147, v147, 0x3a800000, v159
	v_mul_f32_e32 v162, 0x4b800000, v147
	v_cmp_gt_f32_e32 vcc, s51, v147
	v_fmamk_f32 v152, v152, 0x3a800000, v159
	v_fmamk_f32 v154, v154, 0x3a800000, v159
	v_cndmask_b32_e32 v147, v147, v162, vcc
	v_mul_f32_e32 v165, 0x4b800000, v152
	v_fmamk_f32 v161, v161, 0x3a800000, v159
	v_mul_f32_e32 v166, 0x4b800000, v154
	v_mul_f32_e32 v169, 0x4b800000, v161
	v_cmp_gt_f32_e64 s[10:11], s51, v152
	v_cmp_gt_f32_e64 s[12:13], s51, v154
	v_cmp_gt_f32_e64 s[18:19], s51, v161
	v_rsq_f32_e32 v147, v147
	v_fmamk_f32 v156, v156, 0x3a800000, v159
	v_cndmask_b32_e64 v152, v152, v165, s[10:11]
	v_cndmask_b32_e64 v154, v154, v166, s[12:13]
	v_cndmask_b32_e64 v161, v161, v169, s[18:19]
	v_fmamk_f32 v148, v148, 0x3a800000, v159
	v_fmamk_f32 v160, v160, 0x3a800000, v159
	v_mul_f32_e32 v167, 0x4b800000, v156
	v_cmp_gt_f32_e64 s[14:15], s51, v156
	v_rsq_f32_e32 v152, v152
	v_rsq_f32_e32 v154, v154
	v_rsq_f32_e32 v161, v161
	v_mul_f32_e32 v163, 0x4b800000, v148
	v_mul_f32_e32 v168, 0x4b800000, v160
	v_cmp_gt_f32_e64 s[4:5], s51, v148
	v_cndmask_b32_e64 v156, v156, v167, s[14:15]
	v_cmp_gt_f32_e64 s[16:17], s51, v160
	v_fmamk_f32 v150, v150, 0x3a800000, v159
	v_cndmask_b32_e64 v148, v148, v163, s[4:5]
	v_cndmask_b32_e64 v160, v160, v168, s[16:17]
	v_rsq_f32_e32 v163, v156
	v_mul_f32_e32 v156, 0x45800000, v147
	v_mul_f32_e32 v164, 0x4b800000, v150
	v_cmp_gt_f32_e64 s[8:9], s51, v150
	v_rsq_f32_e32 v165, v160
	v_cndmask_b32_e32 v160, v147, v156, vcc
	v_cndmask_b32_e64 v150, v150, v164, s[8:9]
	v_rsq_f32_e32 v148, v148
	v_mul_f32_e32 v166, 0x45800000, v152
	v_mul_f32_e32 v167, 0x45800000, v154
	v_pk_mul_f32 v[126:127], v[126:127], v[160:161] op_sel_hi:[1,0]
	v_pk_mul_f32 v[124:125], v[124:125], v[160:161] op_sel_hi:[1,0]
	v_rsq_f32_e32 v150, v150
	v_cndmask_b32_e64 v156, v152, v166, s[10:11]
	v_cndmask_b32_e64 v154, v154, v167, s[12:13]
	v_pk_mul_f32 v[122:123], v[122:123], v[160:161] op_sel_hi:[1,0]
	v_pk_mul_f32 v[120:121], v[120:121], v[160:161] op_sel_hi:[1,0]
	v_pk_mul_f32 v[118:119], v[118:119], v[160:161] op_sel_hi:[1,0]
	v_pk_mul_f32 v[116:117], v[116:117], v[160:161] op_sel_hi:[1,0]
; DI unsigned pk_bf16(float lo, float hi) { f32x2 v = {lo, hi}; return __builtin_bit_cast(unsigned, __builtin_convertvector(v, bf16v2)); }
; DI float fast_silu(float x) { return x * fast_sigmoid(x); }
;     DI void operator()(AccRef acc, const Unit& u, int wr, int wc, int fr, int fq) const {
;     ...
;             for (int m = 0; m < 4; ++m) {
;                 const int row = row0 + ai * 128 + m * 16;
;                 const float r = RS ? rsc.r[ai][m] : 1.0f;
;                 const f32x4 a0 = acc[ai][0][m][0] * r, a1 = acc[ai][0][m][1] * r, b0 = acc[ai][1][m][0] * r, b1 = acc[ai][1][m][1] * r;
;                 u32x4 w;
;                 w.x = pk_bf16(fast_silu(a0[0]) * b0[0], fast_silu(a0[1]) * b0[1]); w.y = pk_bf16(fast_silu(a0[2]) * b0[2], fast_silu(a0[3]) * b0[3]);
;                 w.z = pk_bf16(fast_silu(a1[0]) * b1[0], fast_silu(a1[1]) * b1[1]); w.w = pk_bf16(fast_silu(a1[2]) * b1[2], fast_silu(a1[3]) * b1[3]);
;                 *(u32x4*)(G + (size_t)row * DFF + col) = w;
	v_pk_mul_f32 v[166:167], v[114:115], v[160:161] op_sel_hi:[1,0]
	v_pk_mul_f32 v[114:115], v[112:113], v[160:161] op_sel_hi:[1,0]
	v_mul_f32_e32 v112, 0xbfb8aa3b, v124
	v_mul_f32_e32 v113, 0xbfb8aa3b, v125
	v_mul_f32_e32 v147, 0xbfb8aa3b, v126
	v_mul_f32_e32 v160, 0xbfb8aa3b, v127
	v_exp_f32_e32 v112, v112
	v_exp_f32_e32 v113, v113
	v_exp_f32_e32 v147, v147
	v_exp_f32_e32 v160, v160
	v_mul_f32_e32 v162, 0x45800000, v148
	v_mul_f32_e32 v170, 0x45800000, v161
	v_mul_f32_e32 v164, 0x45800000, v150
	v_mul_f32_e32 v169, 0x45800000, v165
	v_cndmask_b32_e64 v162, v148, v162, s[4:5]
	v_cndmask_b32_e64 v148, v161, v170, s[18:19]
	v_mul_f32_e32 v161, 0xbfb8aa3b, v120
	v_cndmask_b32_e64 v164, v150, v164, s[8:9]
	v_cndmask_b32_e64 v150, v165, v169, s[16:17]
	v_exp_f32_e32 v165, v161
	v_add_f32_e32 v112, 1.0, v112
	v_add_f32_e32 v113, 1.0, v113
	v_add_f32_e32 v147, 1.0, v147
	v_add_f32_e32 v161, 1.0, v160
	v_rcp_f32_e32 v112, v112
	v_rcp_f32_e32 v113, v113
	v_rcp_f32_e32 v160, v147
	v_rcp_f32_e32 v161, v161
	v_mul_f32_e32 v168, 0x45800000, v163
	v_pk_mul_f32 v[112:113], v[124:125], v[112:113]
	v_cndmask_b32_e64 v152, v163, v168, s[14:15]
	v_pk_mul_f32 v[124:125], v[126:127], v[160:161]
	v_mul_f32_e32 v163, 0xbfb8aa3b, v121
	v_pk_mul_f32 v[112:113], v[116:117], v[112:113]
	v_pk_mul_f32 v[116:117], v[118:119], v[124:125]
	v_exp_f32_e32 v163, v163
	v_cvt_pk_bf16_f32 v112, v112, v113
	v_cvt_pk_bf16_f32 v113, v116, v117
	v_mul_f32_e32 v117, 0xbfb8aa3b, v122
	v_mul_f32_e32 v118, 0xbfb8aa3b, v123
	v_exp_f32_e32 v117, v117
	v_exp_f32_e32 v118, v118
	v_add_f32_e32 v116, 1.0, v163
	v_add_f32_e32 v147, 1.0, v165
	v_rcp_f32_e32 v169, v116
	v_add_f32_e32 v116, 1.0, v117
	v_add_f32_e32 v117, 1.0, v118
	v_rcp_f32_e32 v168, v147
	v_rcp_f32_e32 v116, v116
	v_rcp_f32_e32 v117, v117
	v_pk_mul_f32 v[108:109], v[108:109], v[162:163] op_sel_hi:[1,0]
	v_pk_mul_f32 v[118:119], v[120:121], v[168:169]
	v_pk_mul_f32 v[110:111], v[110:111], v[162:163] op_sel_hi:[1,0]
	v_pk_mul_f32 v[116:117], v[122:123], v[116:117]
	v_pk_mul_f32 v[114:115], v[114:115], v[118:119]
	v_pk_mul_f32 v[116:117], v[166:167], v[116:117]
	v_cvt_pk_bf16_f32 v114, v114, v115
	v_cvt_pk_bf16_f32 v115, v116, v117
	v_mad_i64_i32 v[116:117], s[4:5], v146, s52, v[144:145]
	global_store_dwordx4 v[116:117], v[112:115], off
	v_pk_mul_f32 v[100:101], v[100:101], v[162:163] op_sel_hi:[1,0]
	v_pk_mul_f32 v[104:105], v[104:105], v[162:163] op_sel_hi:[1,0]
	v_pk_mul_f32 v[112:113], v[98:99], v[162:163] op_sel_hi:[1,0]
	v_mul_f32_e32 v98, 0xbfb8aa3b, v108
	v_exp_f32_e32 v114, v98
	v_mul_f32_e32 v98, 0xbfb8aa3b, v109
	v_exp_f32_e32 v115, v98
	v_pk_mul_f32 v[98:99], v[96:97], v[162:163] op_sel_hi:[1,0]
	v_add_f32_e32 v96, 1.0, v114
	v_mul_f32_e32 v114, 0xbfb8aa3b, v110
	v_add_f32_e32 v97, 1.0, v115
	v_mul_f32_e32 v115, 0xbfb8aa3b, v111
	v_exp_f32_e32 v114, v114
	v_exp_f32_e32 v115, v115
	v_rcp_f32_e32 v96, v96
	v_rcp_f32_e32 v97, v97
	v_add_f32_e32 v114, 1.0, v114
	v_add_f32_e32 v115, 1.0, v115
	v_rcp_f32_e32 v114, v114
	v_rcp_f32_e32 v115, v115
	v_pk_mul_f32 v[96:97], v[108:109], v[96:97]
	v_pk_mul_f32 v[102:103], v[102:103], v[162:163] op_sel_hi:[1,0]
	v_pk_mul_f32 v[96:97], v[100:101], v[96:97]
	v_pk_mul_f32 v[100:101], v[110:111], v[114:115]
	v_cvt_pk_bf16_f32 v96, v96, v97
	v_mul_f32_e32 v97, 0xbfb8aa3b, v104
	v_pk_mul_f32 v[100:101], v[102:103], v[100:101]
	v_exp_f32_e32 v102, v97
	v_mul_f32_e32 v97, 0xbfb8aa3b, v105
	v_exp_f32_e32 v103, v97
	v_pk_mul_f32 v[106:107], v[106:107], v[162:163] op_sel_hi:[1,0]
	v_cvt_pk_bf16_f32 v97, v100, v101
	v_add_f32_e32 v100, 1.0, v102
	v_add_f32_e32 v101, 1.0, v103
	v_mul_f32_e32 v102, 0xbfb8aa3b, v106
	v_mul_f32_e32 v103, 0xbfb8aa3b, v107
	v_exp_f32_e32 v102, v102
	v_exp_f32_e32 v103, v103
	v_rcp_f32_e32 v100, v100
	v_rcp_f32_e32 v101, v101
	v_add_f32_e32 v102, 1.0, v102
	v_add_f32_e32 v103, 1.0, v103
	v_rcp_f32_e32 v102, v102
	v_rcp_f32_e32 v103, v103
	v_pk_mul_f32 v[100:101], v[104:105], v[100:101]
	v_or_b32_e32 v116, 16, v146
	v_pk_mul_f32 v[98:99], v[98:99], v[100:101]
	v_pk_mul_f32 v[100:101], v[106:107], v[102:103]
	v_cvt_pk_bf16_f32 v98, v98, v99
	v_pk_mul_f32 v[100:101], v[112:113], v[100:101]
	v_pk_mul_f32 v[92:93], v[92:93], v[164:165] op_sel_hi:[1,0]
	v_cvt_pk_bf16_f32 v99, v100, v101
	v_mad_i64_i32 v[100:101], s[4:5], v116, s52, v[144:145]
	global_store_dwordx4 v[100:101], v[96:99], off
	v_pk_mul_f32 v[94:95], v[94:95], v[164:165] op_sel_hi:[1,0]
	v_pk_mul_f32 v[84:85], v[84:85], v[164:165] op_sel_hi:[1,0]
	v_pk_mul_f32 v[96:97], v[82:83], v[164:165] op_sel_hi:[1,0]
	v_mul_f32_e32 v82, 0xbfb8aa3b, v92
	v_exp_f32_e32 v98, v82
	v_mul_f32_e32 v82, 0xbfb8aa3b, v93
	v_exp_f32_e32 v99, v82
	v_pk_mul_f32 v[82:83], v[80:81], v[164:165] op_sel_hi:[1,0]
	v_add_f32_e32 v80, 1.0, v98
	v_mul_f32_e32 v98, 0xbfb8aa3b, v94
	v_add_f32_e32 v81, 1.0, v99
	v_mul_f32_e32 v99, 0xbfb8aa3b, v95
	v_exp_f32_e32 v98, v98
	v_exp_f32_e32 v99, v99
	v_rcp_f32_e32 v80, v80
	v_rcp_f32_e32 v81, v81
	v_add_f32_e32 v98, 1.0, v98
	v_add_f32_e32 v99, 1.0, v99
	v_rcp_f32_e32 v98, v98
	v_rcp_f32_e32 v99, v99
	v_pk_mul_f32 v[80:81], v[92:93], v[80:81]
	v_pk_mul_f32 v[88:89], v[88:89], v[164:165] op_sel_hi:[1,0]
	v_pk_mul_f32 v[80:81], v[84:85], v[80:81]
	v_pk_mul_f32 v[86:87], v[86:87], v[164:165] op_sel_hi:[1,0]
	v_cvt_pk_bf16_f32 v80, v80, v81
	v_pk_mul_f32 v[84:85], v[94:95], v[98:99]
	v_mul_f32_e32 v81, 0xbfb8aa3b, v88
	v_pk_mul_f32 v[84:85], v[86:87], v[84:85]
	v_exp_f32_e32 v86, v81
	v_mul_f32_e32 v81, 0xbfb8aa3b, v89
	v_exp_f32_e32 v87, v81
	v_pk_mul_f32 v[90:91], v[90:91], v[164:165] op_sel_hi:[1,0]
	v_cvt_pk_bf16_f32 v81, v84, v85
	v_add_f32_e32 v84, 1.0, v86
	v_add_f32_e32 v85, 1.0, v87
; DI unsigned pk_bf16(float lo, float hi) { f32x2 v = {lo, hi}; return __builtin_bit_cast(unsigned, __builtin_convertvector(v, bf16v2)); }
; DI float fast_silu(float x) { return x * fast_sigmoid(x); }
;     DI void operator()(AccRef acc, const Unit& u, int wr, int wc, int fr, int fq) const {
;     ...
;             for (int m = 0; m < 4; ++m) {
;                 const int row = row0 + ai * 128 + m * 16;
;                 const float r = RS ? rsc.r[ai][m] : 1.0f;
;                 const f32x4 a0 = acc[ai][0][m][0] * r, a1 = acc[ai][0][m][1] * r, b0 = acc[ai][1][m][0] * r, b1 = acc[ai][1][m][1] * r;
;                 u32x4 w;
;                 w.x = pk_bf16(fast_silu(a0[0]) * b0[0], fast_silu(a0[1]) * b0[1]); w.y = pk_bf16(fast_silu(a0[2]) * b0[2], fast_silu(a0[3]) * b0[3]);
;                 w.z = pk_bf16(fast_silu(a1[0]) * b1[0], fast_silu(a1[1]) * b1[1]); w.w = pk_bf16(fast_silu(a1[2]) * b1[2], fast_silu(a1[3]) * b1[3]);
;                 *(u32x4*)(G + (size_t)row * DFF + col) = w;
	v_mul_f32_e32 v86, 0xbfb8aa3b, v90
	v_mul_f32_e32 v87, 0xbfb8aa3b, v91
	v_exp_f32_e32 v86, v86
	v_exp_f32_e32 v87, v87
	v_rcp_f32_e32 v84, v84
	v_rcp_f32_e32 v85, v85
	v_add_f32_e32 v86, 1.0, v86
	v_add_f32_e32 v87, 1.0, v87
	v_rcp_f32_e32 v86, v86
	v_rcp_f32_e32 v87, v87
	v_pk_mul_f32 v[84:85], v[88:89], v[84:85]
	v_or_b32_e32 v100, 32, v146
	v_pk_mul_f32 v[82:83], v[82:83], v[84:85]
	v_pk_mul_f32 v[84:85], v[90:91], v[86:87]
	v_cvt_pk_bf16_f32 v82, v82, v83
	v_pk_mul_f32 v[84:85], v[96:97], v[84:85]
	v_pk_mul_f32 v[76:77], v[76:77], v[156:157] op_sel_hi:[1,0]
	v_cvt_pk_bf16_f32 v83, v84, v85
	v_mad_i64_i32 v[84:85], s[4:5], v100, s52, v[144:145]
	global_store_dwordx4 v[84:85], v[80:83], off
	v_pk_mul_f32 v[78:79], v[78:79], v[156:157] op_sel_hi:[1,0]
	v_pk_mul_f32 v[68:69], v[68:69], v[156:157] op_sel_hi:[1,0]
	v_pk_mul_f32 v[80:81], v[66:67], v[156:157] op_sel_hi:[1,0]
	v_mul_f32_e32 v66, 0xbfb8aa3b, v76
	v_exp_f32_e32 v82, v66
	v_mul_f32_e32 v66, 0xbfb8aa3b, v77
	v_exp_f32_e32 v83, v66
	v_pk_mul_f32 v[66:67], v[64:65], v[156:157] op_sel_hi:[1,0]
	v_add_f32_e32 v64, 1.0, v82
	v_mul_f32_e32 v82, 0xbfb8aa3b, v78
	v_add_f32_e32 v65, 1.0, v83
	v_mul_f32_e32 v83, 0xbfb8aa3b, v79
	v_exp_f32_e32 v82, v82
	v_exp_f32_e32 v83, v83
	v_rcp_f32_e32 v64, v64
	v_rcp_f32_e32 v65, v65
	v_add_f32_e32 v82, 1.0, v82
	v_add_f32_e32 v83, 1.0, v83
	v_rcp_f32_e32 v82, v82
	v_rcp_f32_e32 v83, v83
	v_pk_mul_f32 v[64:65], v[76:77], v[64:65]
	v_pk_mul_f32 v[72:73], v[72:73], v[156:157] op_sel_hi:[1,0]
	v_pk_mul_f32 v[64:65], v[68:69], v[64:65]
	v_pk_mul_f32 v[70:71], v[70:71], v[156:157] op_sel_hi:[1,0]
	v_cvt_pk_bf16_f32 v64, v64, v65
	v_pk_mul_f32 v[68:69], v[78:79], v[82:83]
	v_mul_f32_e32 v65, 0xbfb8aa3b, v72
	v_pk_mul_f32 v[68:69], v[70:71], v[68:69]
	v_exp_f32_e32 v70, v65
	v_mul_f32_e32 v65, 0xbfb8aa3b, v73
	v_exp_f32_e32 v71, v65
	v_pk_mul_f32 v[74:75], v[74:75], v[156:157] op_sel_hi:[1,0]
	v_cvt_pk_bf16_f32 v65, v68, v69
	v_add_f32_e32 v68, 1.0, v70
	v_add_f32_e32 v69, 1.0, v71
	v_mul_f32_e32 v70, 0xbfb8aa3b, v74
	v_mul_f32_e32 v71, 0xbfb8aa3b, v75
	v_exp_f32_e32 v70, v70
	v_exp_f32_e32 v71, v71
	v_rcp_f32_e32 v68, v68
	v_rcp_f32_e32 v69, v69
	v_add_f32_e32 v70, 1.0, v70
	v_add_f32_e32 v71, 1.0, v71
	v_rcp_f32_e32 v70, v70
	v_rcp_f32_e32 v71, v71
	v_pk_mul_f32 v[68:69], v[72:73], v[68:69]
	v_or_b32_e32 v84, 48, v146
	v_pk_mul_f32 v[66:67], v[66:67], v[68:69]
	v_pk_mul_f32 v[68:69], v[74:75], v[70:71]
	v_cvt_pk_bf16_f32 v66, v66, v67
	v_pk_mul_f32 v[68:69], v[80:81], v[68:69]
	v_pk_mul_f32 v[60:61], v[60:61], v[154:155] op_sel_hi:[1,0]
	v_cvt_pk_bf16_f32 v67, v68, v69
	v_mad_i64_i32 v[68:69], s[4:5], v84, s52, v[144:145]
	global_store_dwordx4 v[68:69], v[64:67], off
	v_pk_mul_f32 v[62:63], v[62:63], v[154:155] op_sel_hi:[1,0]
	v_pk_mul_f32 v[52:53], v[52:53], v[154:155] op_sel_hi:[1,0]
	v_pk_mul_f32 v[64:65], v[50:51], v[154:155] op_sel_hi:[1,0]
	v_mul_f32_e32 v50, 0xbfb8aa3b, v60
	v_exp_f32_e32 v66, v50
	v_mul_f32_e32 v50, 0xbfb8aa3b, v61
	v_exp_f32_e32 v67, v50
	v_pk_mul_f32 v[50:51], v[48:49], v[154:155] op_sel_hi:[1,0]
	v_add_f32_e32 v48, 1.0, v66
	v_mul_f32_e32 v66, 0xbfb8aa3b, v62
	v_add_f32_e32 v49, 1.0, v67
	v_mul_f32_e32 v67, 0xbfb8aa3b, v63
	v_exp_f32_e32 v66, v66
	v_exp_f32_e32 v67, v67
	v_rcp_f32_e32 v48, v48
	v_rcp_f32_e32 v49, v49
	v_add_f32_e32 v66, 1.0, v66
	v_add_f32_e32 v67, 1.0, v67
	v_rcp_f32_e32 v66, v66
	v_rcp_f32_e32 v67, v67
	v_pk_mul_f32 v[48:49], v[60:61], v[48:49]
	v_pk_mul_f32 v[56:57], v[56:57], v[154:155] op_sel_hi:[1,0]
	v_pk_mul_f32 v[48:49], v[52:53], v[48:49]
	v_pk_mul_f32 v[54:55], v[54:55], v[154:155] op_sel_hi:[1,0]
	v_cvt_pk_bf16_f32 v48, v48, v49
	v_pk_mul_f32 v[52:53], v[62:63], v[66:67]
	v_mul_f32_e32 v49, 0xbfb8aa3b, v56
	v_pk_mul_f32 v[52:53], v[54:55], v[52:53]
	v_exp_f32_e32 v54, v49
	v_mul_f32_e32 v49, 0xbfb8aa3b, v57
	v_exp_f32_e32 v55, v49
	v_pk_mul_f32 v[58:59], v[58:59], v[154:155] op_sel_hi:[1,0]
	v_cvt_pk_bf16_f32 v49, v52, v53
	v_add_f32_e32 v52, 1.0, v54
	v_add_f32_e32 v53, 1.0, v55
	v_mul_f32_e32 v54, 0xbfb8aa3b, v58
	v_mul_f32_e32 v55, 0xbfb8aa3b, v59
	v_exp_f32_e32 v54, v54
	v_exp_f32_e32 v55, v55
	v_rcp_f32_e32 v52, v52
	v_rcp_f32_e32 v53, v53
	v_add_f32_e32 v54, 1.0, v54
	v_add_f32_e32 v55, 1.0, v55
	v_rcp_f32_e32 v54, v54
	v_rcp_f32_e32 v55, v55
	v_pk_mul_f32 v[52:53], v[56:57], v[52:53]
	v_add_u32_e32 v68, 0x80, v146
	v_pk_mul_f32 v[50:51], v[50:51], v[52:53]
	v_pk_mul_f32 v[52:53], v[58:59], v[54:55]
	v_cvt_pk_bf16_f32 v50, v50, v51
	v_pk_mul_f32 v[52:53], v[64:65], v[52:53]
	v_pk_mul_f32 v[44:45], v[44:45], v[152:153] op_sel_hi:[1,0]
	v_cvt_pk_bf16_f32 v51, v52, v53
	v_mad_i64_i32 v[52:53], s[4:5], v68, s52, v[144:145]
	global_store_dwordx4 v[52:53], v[48:51], off
	v_pk_mul_f32 v[46:47], v[46:47], v[152:153] op_sel_hi:[1,0]
	v_pk_mul_f32 v[36:37], v[36:37], v[152:153] op_sel_hi:[1,0]
	v_pk_mul_f32 v[48:49], v[34:35], v[152:153] op_sel_hi:[1,0]
	v_mul_f32_e32 v34, 0xbfb8aa3b, v44
	v_exp_f32_e32 v50, v34
	v_mul_f32_e32 v34, 0xbfb8aa3b, v45
	v_exp_f32_e32 v51, v34
	v_pk_mul_f32 v[34:35], v[32:33], v[152:153] op_sel_hi:[1,0]
	v_add_f32_e32 v32, 1.0, v50
	v_mul_f32_e32 v50, 0xbfb8aa3b, v46
	v_add_f32_e32 v33, 1.0, v51
	v_mul_f32_e32 v51, 0xbfb8aa3b, v47
	v_exp_f32_e32 v50, v50
	v_exp_f32_e32 v51, v51
	v_rcp_f32_e32 v32, v32
	v_rcp_f32_e32 v33, v33
	v_add_f32_e32 v50, 1.0, v50
	v_add_f32_e32 v51, 1.0, v51
	v_rcp_f32_e32 v50, v50
; DI unsigned pk_bf16(float lo, float hi) { f32x2 v = {lo, hi}; return __builtin_bit_cast(unsigned, __builtin_convertvector(v, bf16v2)); }
; DI float fast_silu(float x) { return x * fast_sigmoid(x); }
; #define PG8_WAIT_V(n) asm volatile("s_waitcnt vmcnt(" #n ")" ::: "memory")
; #define PG8_BAR __builtin_amdgcn_s_barrier()
; #define PG8_WAIT_V(n) asm volatile("s_waitcnt vmcnt(" #n ")" ::: "memory")
; #define PG8_BAR __builtin_amdgcn_s_barrier()
; template <class Epi>
; DI void gemm_phase(LAS unsigned char* lds, const Gemm g, const StaticOrder S, const Epi E) {
;     ...
;     PG8_WAIT_V(0);
;     if (wr == 0) PG8_BAR;
;     PG8_BAR;
;     DI void operator()(AccRef acc, const Unit& u, int wr, int wc, int fr, int fq) const {
;     ...
;             for (int m = 0; m < 4; ++m) {
;                 const int row = row0 + ai * 128 + m * 16;
;                 const float r = RS ? rsc.r[ai][m] : 1.0f;
;                 const f32x4 a0 = acc[ai][0][m][0] * r, a1 = acc[ai][0][m][1] * r, b0 = acc[ai][1][m][0] * r, b1 = acc[ai][1][m][1] * r;
;                 u32x4 w;
;                 w.x = pk_bf16(fast_silu(a0[0]) * b0[0], fast_silu(a0[1]) * b0[1]); w.y = pk_bf16(fast_silu(a0[2]) * b0[2], fast_silu(a0[3]) * b0[3]);
;                 w.z = pk_bf16(fast_silu(a1[0]) * b1[0], fast_silu(a1[1]) * b1[1]); w.w = pk_bf16(fast_silu(a1[2]) * b1[2], fast_silu(a1[3]) * b1[3]);
;                 *(u32x4*)(G + (size_t)row * DFF + col) = w;
;             }
	v_rcp_f32_e32 v51, v51
	v_pk_mul_f32 v[32:33], v[44:45], v[32:33]
	v_pk_mul_f32 v[40:41], v[40:41], v[152:153] op_sel_hi:[1,0]
	v_pk_mul_f32 v[32:33], v[36:37], v[32:33]
	v_pk_mul_f32 v[38:39], v[38:39], v[152:153] op_sel_hi:[1,0]
	v_cvt_pk_bf16_f32 v32, v32, v33
	v_pk_mul_f32 v[36:37], v[46:47], v[50:51]
	v_mul_f32_e32 v33, 0xbfb8aa3b, v40
	v_pk_mul_f32 v[36:37], v[38:39], v[36:37]
	v_exp_f32_e32 v38, v33
	v_mul_f32_e32 v33, 0xbfb8aa3b, v41
	v_exp_f32_e32 v39, v33
	v_pk_mul_f32 v[42:43], v[42:43], v[152:153] op_sel_hi:[1,0]
	v_cvt_pk_bf16_f32 v33, v36, v37
	v_add_f32_e32 v36, 1.0, v38
	v_add_f32_e32 v37, 1.0, v39
	v_mul_f32_e32 v38, 0xbfb8aa3b, v42
	v_mul_f32_e32 v39, 0xbfb8aa3b, v43
	v_exp_f32_e32 v38, v38
	v_exp_f32_e32 v39, v39
	v_rcp_f32_e32 v36, v36
	v_rcp_f32_e32 v37, v37
	v_add_f32_e32 v38, 1.0, v38
	v_add_f32_e32 v39, 1.0, v39
	v_rcp_f32_e32 v38, v38
	v_rcp_f32_e32 v39, v39
	v_pk_mul_f32 v[36:37], v[40:41], v[36:37]
	v_add_u32_e32 v52, 0x90, v146
	v_pk_mul_f32 v[34:35], v[34:35], v[36:37]
	v_pk_mul_f32 v[36:37], v[42:43], v[38:39]
	v_cvt_pk_bf16_f32 v34, v34, v35
	v_pk_mul_f32 v[36:37], v[48:49], v[36:37]
	v_pk_mul_f32 v[28:29], v[28:29], v[150:151] op_sel_hi:[1,0]
	v_cvt_pk_bf16_f32 v35, v36, v37
	v_mad_i64_i32 v[36:37], s[4:5], v52, s52, v[144:145]
	global_store_dwordx4 v[36:37], v[32:35], off
	v_pk_mul_f32 v[30:31], v[30:31], v[150:151] op_sel_hi:[1,0]
	v_pk_mul_f32 v[20:21], v[20:21], v[150:151] op_sel_hi:[1,0]
	v_pk_mul_f32 v[32:33], v[18:19], v[150:151] op_sel_hi:[1,0]
	v_mul_f32_e32 v18, 0xbfb8aa3b, v28
	v_exp_f32_e32 v34, v18
	v_mul_f32_e32 v18, 0xbfb8aa3b, v29
	v_exp_f32_e32 v35, v18
	v_pk_mul_f32 v[18:19], v[16:17], v[150:151] op_sel_hi:[1,0]
	v_add_f32_e32 v16, 1.0, v34
	v_mul_f32_e32 v34, 0xbfb8aa3b, v30
	v_add_f32_e32 v17, 1.0, v35
	v_mul_f32_e32 v35, 0xbfb8aa3b, v31
	v_exp_f32_e32 v34, v34
	v_exp_f32_e32 v35, v35
	v_rcp_f32_e32 v16, v16
	v_rcp_f32_e32 v17, v17
	v_add_f32_e32 v34, 1.0, v34
	v_add_f32_e32 v35, 1.0, v35
	v_rcp_f32_e32 v34, v34
	v_rcp_f32_e32 v35, v35
	v_pk_mul_f32 v[16:17], v[28:29], v[16:17]
	v_pk_mul_f32 v[24:25], v[24:25], v[150:151] op_sel_hi:[1,0]
	v_pk_mul_f32 v[16:17], v[20:21], v[16:17]
	v_pk_mul_f32 v[22:23], v[22:23], v[150:151] op_sel_hi:[1,0]
	v_cvt_pk_bf16_f32 v16, v16, v17
	v_pk_mul_f32 v[20:21], v[30:31], v[34:35]
	v_mul_f32_e32 v17, 0xbfb8aa3b, v24
	v_pk_mul_f32 v[20:21], v[22:23], v[20:21]
	v_exp_f32_e32 v22, v17
	v_mul_f32_e32 v17, 0xbfb8aa3b, v25
	v_exp_f32_e32 v23, v17
	v_pk_mul_f32 v[26:27], v[26:27], v[150:151] op_sel_hi:[1,0]
	v_cvt_pk_bf16_f32 v17, v20, v21
	v_add_f32_e32 v20, 1.0, v22
	v_add_f32_e32 v21, 1.0, v23
	v_mul_f32_e32 v22, 0xbfb8aa3b, v26
	v_mul_f32_e32 v23, 0xbfb8aa3b, v27
	v_exp_f32_e32 v22, v22
	v_exp_f32_e32 v23, v23
	v_rcp_f32_e32 v20, v20
	v_rcp_f32_e32 v21, v21
	v_add_f32_e32 v22, 1.0, v22
	v_add_f32_e32 v23, 1.0, v23
	v_rcp_f32_e32 v22, v22
	v_rcp_f32_e32 v23, v23
	v_pk_mul_f32 v[20:21], v[24:25], v[20:21]
	v_add_u32_e32 v36, 0xa0, v146
	v_pk_mul_f32 v[18:19], v[18:19], v[20:21]
	v_pk_mul_f32 v[20:21], v[26:27], v[22:23]
	v_cvt_pk_bf16_f32 v18, v18, v19
	v_pk_mul_f32 v[20:21], v[32:33], v[20:21]
	v_pk_mul_f32 v[12:13], v[12:13], v[148:149] op_sel_hi:[1,0]
	v_cvt_pk_bf16_f32 v19, v20, v21
	v_mad_i64_i32 v[20:21], s[4:5], v36, s52, v[144:145]
	global_store_dwordx4 v[20:21], v[16:19], off
	v_pk_mul_f32 v[14:15], v[14:15], v[148:149] op_sel_hi:[1,0]
	v_pk_mul_f32 v[4:5], v[4:5], v[148:149] op_sel_hi:[1,0]
	v_pk_mul_f32 v[16:17], v[2:3], v[148:149] op_sel_hi:[1,0]
	v_mul_f32_e32 v2, 0xbfb8aa3b, v12
	v_exp_f32_e32 v18, v2
	v_mul_f32_e32 v2, 0xbfb8aa3b, v13
	v_exp_f32_e32 v19, v2
	v_pk_mul_f32 v[2:3], v[0:1], v[148:149] op_sel_hi:[1,0]
	v_add_f32_e32 v0, 1.0, v18
	v_mul_f32_e32 v18, 0xbfb8aa3b, v14
	v_add_f32_e32 v1, 1.0, v19
	v_mul_f32_e32 v19, 0xbfb8aa3b, v15
	v_exp_f32_e32 v18, v18
	v_exp_f32_e32 v19, v19
	v_rcp_f32_e32 v0, v0
	v_rcp_f32_e32 v1, v1
	v_add_f32_e32 v18, 1.0, v18
	v_add_f32_e32 v19, 1.0, v19
	v_rcp_f32_e32 v18, v18
	v_rcp_f32_e32 v19, v19
	v_pk_mul_f32 v[0:1], v[12:13], v[0:1]
	v_pk_mul_f32 v[8:9], v[8:9], v[148:149] op_sel_hi:[1,0]
	v_pk_mul_f32 v[0:1], v[4:5], v[0:1]
	v_pk_mul_f32 v[6:7], v[6:7], v[148:149] op_sel_hi:[1,0]
	v_cvt_pk_bf16_f32 v0, v0, v1
	v_pk_mul_f32 v[4:5], v[14:15], v[18:19]
	v_mul_f32_e32 v1, 0xbfb8aa3b, v8
	v_pk_mul_f32 v[4:5], v[6:7], v[4:5]
	v_exp_f32_e32 v6, v1
	v_mul_f32_e32 v1, 0xbfb8aa3b, v9
	v_exp_f32_e32 v7, v1
	v_pk_mul_f32 v[10:11], v[10:11], v[148:149] op_sel_hi:[1,0]
	v_cvt_pk_bf16_f32 v1, v4, v5
	v_add_f32_e32 v4, 1.0, v6
	v_add_f32_e32 v5, 1.0, v7
	v_mul_f32_e32 v6, 0xbfb8aa3b, v10
	v_mul_f32_e32 v7, 0xbfb8aa3b, v11
	v_exp_f32_e32 v6, v6
	v_exp_f32_e32 v7, v7
	v_rcp_f32_e32 v4, v4
	v_rcp_f32_e32 v5, v5
	v_add_f32_e32 v6, 1.0, v6
	v_add_f32_e32 v7, 1.0, v7
	v_rcp_f32_e32 v6, v6
	v_rcp_f32_e32 v7, v7
	v_pk_mul_f32 v[4:5], v[8:9], v[4:5]
	v_add_u32_e32 v20, 0xb0, v146
	v_pk_mul_f32 v[2:3], v[2:3], v[4:5]
	v_pk_mul_f32 v[4:5], v[10:11], v[6:7]
	v_cvt_pk_bf16_f32 v2, v2, v3
	v_pk_mul_f32 v[4:5], v[16:17], v[4:5]
	s_and_b64 vcc, exec, s[0:1]
	v_cvt_pk_bf16_f32 v3, v4, v5
	v_mad_i64_i32 v[4:5], s[4:5], v20, s52, v[144:145]
	s_mov_b32 s5, s24
	s_mov_b32 s4, s28
	s_mov_b64 s[10:11], s[38:39]
	s_mov_b64 s[8:9], s[36:37]
	global_store_dwordx4 v[4:5], v[0:3], off
	s_cbranch_vccz .LBB0_862
	s_waitcnt vmcnt(0)
	s_cmpk_gt_u32 s6, 0xff
	s_cbranch_scc1 .LBB0_869
	s_barrier

; #define PG8_STAGE(bufoff, gbase, voff) do { _Pragma("unroll") for (int _i = 0; _i < 2; ++_i) \
;         __builtin_amdgcn_global_load_lds((const unsigned*)((const char*)(gbase) + (voff)[_i]), (LAS unsigned*)(lds + (bufoff) + ldsw + _i * 8192), 16, 0, 0); } while (0)
; #define PG8_LDA(dst, b, h) do { _Pragma("unroll") for (int m = 0; m < 4; ++m) _Pragma("unroll") for (int k = 0; k < 2; ++k) dst[m][k] = *(const LAS bf16x8*)(lds + PG8_SA(b, h) + aoff + m * 2048 + k * 1024); } while (0)
; #define PG8_LDB(dst, b, h) do { _Pragma("unroll") for (int n = 0; n < 2; ++n) _Pragma("unroll") for (int k = 0; k < 2; ++k) dst[n][k] = *(const LAS bf16x8*)(lds + PG8_SB(b, h) + boff + n * 2048 + k * 1024); } while (0)
; #define PG8_MMA(ai, bj, At, Bt) do { __builtin_amdgcn_s_setprio(1); _Pragma("unroll") for (int m = 0; m < 4; ++m) _Pragma("unroll") for (int n = 0; n < 2; ++n) _Pragma("unroll") for (int k = 0; k < 2; ++k) \
;         acc[ai][bj][m][n] = __builtin_amdgcn_mfma_f32_16x16x32_bf16(Bt[n][k], At[m][k], acc[ai][bj][m][n], 0, 0, 0); __builtin_amdgcn_s_setprio(0); } while (0)
; #define PG8_WAIT_L(n) asm volatile("s_waitcnt lgkmcnt(" #n ")" ::: "memory")
; #define PG8_BAR __builtin_amdgcn_s_barrier()
; #define PG8_SCHED __builtin_amdgcn_sched_barrier(0)
; #define PG8_WAIT_L(n) asm volatile("s_waitcnt lgkmcnt(" #n ")" ::: "memory")
; #define PG8_BAR __builtin_amdgcn_s_barrier()
; #define PG8_SCHED __builtin_amdgcn_sched_barrier(0)
; template <class Epi>
; DI void gemm_phase(LAS unsigned char* lds, const Gemm g, const StaticOrder S, const Epi E) {
;     ...
;             const bool last = (t == nt - 2);
;             const char* a1 = cA + (size_t)(t + 1) * kstep;
;             const char* a2 = last ? nA : cA + (size_t)(t + 2) * kstep; const char* b2 = last ? nB : cB + (size_t)(t + 2) * kstep;
;             const char* a3 = a2 + kstep; const char* b3 = b2 + kstep;
;             PG8_LDB(B0, 0, 0); PG8_SCHED; PG8_LDA(At, 0, 0); PG8_STAGE(PG8_SA(1, 1), a1 + hstep, voffA);
;             PG8_WAIT_L(8); PG8_BAR; PG8_WAIT_L(0); PG8_MMA(0, 0, At, B0); PG8_BAR; PG8_SCHED;
;             PG8_LDB(B1, 0, 1); PG8_STAGE(PG8_SB(0, 0), b2, voffB);
;             PG8_BAR; PG8_WAIT_L(0); PG8_MMA(0, 1, At, B1); PG8_BAR;
;             PG8_LDA(At, 0, 1); PG8_STAGE(PG8_SA(0, 0), a2, voffA);
;             PG8_BAR; PG8_WAIT_L(0); PG8_MMA(1, 0, At, B0); PG8_BAR; PG8_SCHED;
.LBB0_941:
	ds_read_b128 v[144:147], v199
	ds_read_b128 v[148:151], v199 offset:1024
	ds_read_b128 v[152:155], v199 offset:2048
	ds_read_b128 v[156:159], v199 offset:3072
	s_add_u32 s22, s20, 0x100
	s_addc_u32 s23, s21, 0
	s_cmp_eq_u32 s58, 40
	s_cselect_b32 s27, s9, s23
	s_cselect_b32 s26, s8, s22
	s_cselect_b32 s25, s5, s53
	s_cselect_b32 s24, s4, s52
	v_lshl_add_u64 v[192:193], s[20:21], 0, v[136:137]
	s_add_i32 m0, s33, 0xc000
	ds_read_b128 v[160:163], v200
	ds_read_b128 v[164:167], v200 offset:1024
	ds_read_b128 v[168:171], v200 offset:2048
	ds_read_b128 v[172:175], v200 offset:3072
	ds_read_b128 v[176:179], v200 offset:4096
	ds_read_b128 v[180:183], v200 offset:5120
	ds_read_b128 v[184:187], v200 offset:6144
	ds_read_b128 v[188:191], v200 offset:7168
	global_load_lds_dwordx4 v[192:193], off
	v_lshl_add_u64 v[192:193], s[20:21], 0, v[138:139]
	s_add_i32 m0, s33, 0xe000
	s_nop 0
	global_load_lds_dwordx4 v[192:193], off
	s_waitcnt lgkmcnt(8)
	s_barrier
	s_waitcnt lgkmcnt(0)
	s_setprio 1
	s_waitcnt lgkmcnt(0)
	v_mfma_f32_16x16x32_bf16 v[124:127], v[144:147], v[160:163], v[124:127]
	v_mfma_f32_16x16x32_bf16 v[120:123], v[152:155], v[160:163], v[120:123]
	v_mfma_f32_16x16x32_bf16 v[108:111], v[144:147], v[168:171], v[108:111]
	v_mfma_f32_16x16x32_bf16 v[104:107], v[152:155], v[168:171], v[104:107]
	v_mfma_f32_16x16x32_bf16 v[92:95], v[144:147], v[176:179], v[92:95]
	v_mfma_f32_16x16x32_bf16 v[88:91], v[152:155], v[176:179], v[88:91]
	v_mfma_f32_16x16x32_bf16 v[84:87], v[144:147], v[184:187], v[84:87]
	v_mfma_f32_16x16x32_bf16 v[76:79], v[152:155], v[184:187], v[76:79]
	v_mfma_f32_16x16x32_bf16 v[124:127], v[148:151], v[164:167], v[124:127]
	v_mfma_f32_16x16x32_bf16 v[120:123], v[156:159], v[164:167], v[120:123]
	v_mfma_f32_16x16x32_bf16 v[108:111], v[148:151], v[172:175], v[108:111]
	v_mfma_f32_16x16x32_bf16 v[104:107], v[156:159], v[172:175], v[104:107]
	v_mfma_f32_16x16x32_bf16 v[92:95], v[148:151], v[180:183], v[92:95]
	v_mfma_f32_16x16x32_bf16 v[88:91], v[156:159], v[180:183], v[88:91]
	v_mfma_f32_16x16x32_bf16 v[84:87], v[148:151], v[188:191], v[84:87]
	s_barrier
	v_mfma_f32_16x16x32_bf16 v[76:79], v[156:159], v[188:191], v[76:79]
	s_setprio 0
	s_add_i32 s20, s42, s29
	v_lshl_add_u64 v[214:215], s[24:25], 0, v[130:131]
	s_mov_b32 m0, s20
	ds_read_b128 v[192:195], v201
	ds_read_b128 v[202:205], v201 offset:1024
	ds_read_b128 v[206:209], v201 offset:2048
	ds_read_b128 v[210:213], v201 offset:3072
	global_load_lds_dwordx4 v[214:215], off
	v_lshl_add_u64 v[216:217], s[24:25], 0, v[134:135]
	s_add_i32 m0, s20, 0x2000
	s_nop 0
	global_load_lds_dwordx4 v[216:217], off
	s_barrier
	s_waitcnt lgkmcnt(0)
	s_setprio 1
	s_waitcnt lgkmcnt(0)
	v_mfma_f32_16x16x32_bf16 v[116:119], v[192:195], v[160:163], v[116:119]
	v_mfma_f32_16x16x32_bf16 v[112:115], v[206:209], v[160:163], v[112:115]
	v_mfma_f32_16x16x32_bf16 v[100:103], v[192:195], v[168:171], v[100:103]
	v_mfma_f32_16x16x32_bf16 v[96:99], v[206:209], v[168:171], v[96:99]
	v_mfma_f32_16x16x32_bf16 v[80:83], v[192:195], v[176:179], v[80:83]
	v_mfma_f32_16x16x32_bf16 v[72:75], v[206:209], v[176:179], v[72:75]
	v_mfma_f32_16x16x32_bf16 v[68:71], v[192:195], v[184:187], v[68:71]
	v_mfma_f32_16x16x32_bf16 v[64:67], v[206:209], v[184:187], v[64:67]
	v_mfma_f32_16x16x32_bf16 v[116:119], v[202:205], v[164:167], v[116:119]
	v_mfma_f32_16x16x32_bf16 v[112:115], v[210:213], v[164:167], v[112:115]
	v_mfma_f32_16x16x32_bf16 v[100:103], v[202:205], v[172:175], v[100:103]
	v_mfma_f32_16x16x32_bf16 v[96:99], v[210:213], v[172:175], v[96:99]
	v_mfma_f32_16x16x32_bf16 v[80:83], v[202:205], v[180:183], v[80:83]
	v_mfma_f32_16x16x32_bf16 v[72:75], v[210:213], v[180:183], v[72:75]
	v_mfma_f32_16x16x32_bf16 v[68:71], v[202:205], v[188:191], v[68:71]
	s_barrier
	v_mfma_f32_16x16x32_bf16 v[64:67], v[210:213], v[188:191], v[64:67]
	s_setprio 0
	s_mov_b32 m0, s33
	v_lshl_add_u64 v[218:219], s[26:27], 0, v[128:129]
	ds_read_b128 v[160:163], v200 offset:16384
	ds_read_b128 v[164:167], v200 offset:17408
	ds_read_b128 v[168:171], v200 offset:18432
	ds_read_b128 v[172:175], v200 offset:19456
	ds_read_b128 v[176:179], v200 offset:20480
	ds_read_b128 v[180:183], v200 offset:21504
	ds_read_b128 v[184:187], v200 offset:22528
	ds_read_b128 v[188:191], v200 offset:23552
	global_load_lds_dwordx4 v[218:219], off
	v_lshl_add_u64 v[220:221], s[26:27], 0, v[132:133]
	s_mov_b32 m0, s34
	s_nop 0
	global_load_lds_dwordx4 v[220:221], off
	s_barrier
	s_waitcnt lgkmcnt(0)
	s_setprio 1
	s_waitcnt lgkmcnt(0)
	v_mfma_f32_16x16x32_bf16 v[60:63], v[144:147], v[160:163], v[60:63]
	v_mfma_f32_16x16x32_bf16 v[56:59], v[152:155], v[160:163], v[56:59]
	v_mfma_f32_16x16x32_bf16 v[48:51], v[144:147], v[168:171], v[48:51]
	v_mfma_f32_16x16x32_bf16 v[40:43], v[152:155], v[168:171], v[40:43]
	v_mfma_f32_16x16x32_bf16 v[32:35], v[144:147], v[176:179], v[32:35]
	v_mfma_f32_16x16x32_bf16 v[24:27], v[152:155], v[176:179], v[24:27]
	v_mfma_f32_16x16x32_bf16 v[16:19], v[144:147], v[184:187], v[16:19]
	v_mfma_f32_16x16x32_bf16 v[8:11], v[152:155], v[184:187], v[8:11]
	v_mfma_f32_16x16x32_bf16 v[60:63], v[148:151], v[164:167], v[60:63]
	v_mfma_f32_16x16x32_bf16 v[56:59], v[156:159], v[164:167], v[56:59]
	v_mfma_f32_16x16x32_bf16 v[48:51], v[148:151], v[172:175], v[48:51]
	v_mfma_f32_16x16x32_bf16 v[40:43], v[156:159], v[172:175], v[40:43]
	v_mfma_f32_16x16x32_bf16 v[32:35], v[148:151], v[180:183], v[32:35]
	v_mfma_f32_16x16x32_bf16 v[24:27], v[156:159], v[180:183], v[24:27]
	v_mfma_f32_16x16x32_bf16 v[16:19], v[148:151], v[188:191], v[16:19]
	s_barrier
; #define PG8_STAGE(bufoff, gbase, voff) do { _Pragma("unroll") for (int _i = 0; _i < 2; ++_i) \
;         __builtin_amdgcn_global_load_lds((const unsigned*)((const char*)(gbase) + (voff)[_i]), (LAS unsigned*)(lds + (bufoff) + ldsw + _i * 8192), 16, 0, 0); } while (0)
; #define PG8_LDA(dst, b, h) do { _Pragma("unroll") for (int m = 0; m < 4; ++m) _Pragma("unroll") for (int k = 0; k < 2; ++k) dst[m][k] = *(const LAS bf16x8*)(lds + PG8_SA(b, h) + aoff + m * 2048 + k * 1024); } while (0)
; #define PG8_LDB(dst, b, h) do { _Pragma("unroll") for (int n = 0; n < 2; ++n) _Pragma("unroll") for (int k = 0; k < 2; ++k) dst[n][k] = *(const LAS bf16x8*)(lds + PG8_SB(b, h) + boff + n * 2048 + k * 1024); } while (0)
; #define PG8_MMA(ai, bj, At, Bt) do { __builtin_amdgcn_s_setprio(1); _Pragma("unroll") for (int m = 0; m < 4; ++m) _Pragma("unroll") for (int n = 0; n < 2; ++n) _Pragma("unroll") for (int k = 0; k < 2; ++k) \
;         acc[ai][bj][m][n] = __builtin_amdgcn_mfma_f32_16x16x32_bf16(Bt[n][k], At[m][k], acc[ai][bj][m][n], 0, 0, 0); __builtin_amdgcn_s_setprio(0); } while (0)
; #define PG8_WAIT_V(n) asm volatile("s_waitcnt vmcnt(" #n ")" ::: "memory")
; #define PG8_WAIT_L(n) asm volatile("s_waitcnt lgkmcnt(" #n ")" ::: "memory")
; #define PG8_BAR __builtin_amdgcn_s_barrier()
; #define PG8_SCHED __builtin_amdgcn_sched_barrier(0)
; #define PG8_STAGE(bufoff, gbase, voff) do { _Pragma("unroll") for (int _i = 0; _i < 2; ++_i) \
;         __builtin_amdgcn_global_load_lds((const unsigned*)((const char*)(gbase) + (voff)[_i]), (LAS unsigned*)(lds + (bufoff) + ldsw + _i * 8192), 16, 0, 0); } while (0)
; #define PG8_BAR __builtin_amdgcn_s_barrier()
; template <class Epi>
; DI void gemm_phase(LAS unsigned char* lds, const Gemm g, const StaticOrder S, const Epi E) {
;     ...
;             PG8_BAR; PG8_WAIT_L(0); PG8_MMA(1, 0, At, B0); PG8_BAR; PG8_SCHED;
;             PG8_STAGE(PG8_SB(0, 1), b2 + hstep, voffB);
;             PG8_WAIT_V(6); PG8_BAR; PG8_MMA(1, 1, At, B1); PG8_BAR;
;             PG8_LDB(B0, 1, 0); PG8_SCHED; PG8_LDA(At, 1, 0); PG8_STAGE(PG8_SA(0, 1), a2 + hstep, voffA);
;             PG8_WAIT_L(8); PG8_BAR; PG8_WAIT_L(0); PG8_MMA(0, 0, At, B0); PG8_BAR; PG8_SCHED;
;             PG8_LDB(B1, 1, 1); PG8_STAGE(PG8_SB(1, 0), b3, voffB);
;             PG8_BAR; PG8_WAIT_L(0); PG8_MMA(0, 1, At, B1); PG8_BAR;
;             PG8_LDA(At, 1, 1); PG8_STAGE(PG8_SA(1, 0), a3, voffA);
	v_mfma_f32_16x16x32_bf16 v[8:11], v[156:159], v[188:191], v[8:11]
	s_setprio 0
	s_add_u32 s20, s24, 0xb0000
	s_addc_u32 s21, s25, 0
	s_add_i32 s59, s43, s29
	v_lshl_add_u64 v[144:145], s[20:21], 0, v[130:131]
	s_mov_b32 m0, s59
	s_nop 0
	global_load_lds_dwordx4 v[144:145], off
	v_lshl_add_u64 v[144:145], s[20:21], 0, v[134:135]
	s_add_i32 m0, s59, 0x2000
	s_nop 0
	global_load_lds_dwordx4 v[144:145], off
	s_waitcnt vmcnt(6)
	s_barrier
	s_setprio 1
	v_mfma_f32_16x16x32_bf16 v[52:55], v[192:195], v[160:163], v[52:55]
	v_mfma_f32_16x16x32_bf16 v[44:47], v[206:209], v[160:163], v[44:47]
	v_mfma_f32_16x16x32_bf16 v[36:39], v[192:195], v[168:171], v[36:39]
	v_mfma_f32_16x16x32_bf16 v[28:31], v[206:209], v[168:171], v[28:31]
	v_mfma_f32_16x16x32_bf16 v[20:23], v[192:195], v[176:179], v[20:23]
	v_mfma_f32_16x16x32_bf16 v[12:15], v[206:209], v[176:179], v[12:15]
	v_mfma_f32_16x16x32_bf16 v[4:7], v[192:195], v[184:187], v[4:7]
	v_mfma_f32_16x16x32_bf16 v[0:3], v[206:209], v[184:187], v[0:3]
	v_mfma_f32_16x16x32_bf16 v[52:55], v[202:205], v[164:167], v[52:55]
	v_mfma_f32_16x16x32_bf16 v[44:47], v[210:213], v[164:167], v[44:47]
	v_mfma_f32_16x16x32_bf16 v[36:39], v[202:205], v[172:175], v[36:39]
	v_mfma_f32_16x16x32_bf16 v[28:31], v[210:213], v[172:175], v[28:31]
	v_mfma_f32_16x16x32_bf16 v[20:23], v[202:205], v[180:183], v[20:23]
	v_mfma_f32_16x16x32_bf16 v[12:15], v[210:213], v[180:183], v[12:15]
	v_mfma_f32_16x16x32_bf16 v[4:7], v[202:205], v[188:191], v[4:7]
	s_barrier
	v_mfma_f32_16x16x32_bf16 v[0:3], v[210:213], v[188:191], v[0:3]
	s_setprio 0
	s_add_i32 s59, 0, 0x18000
	v_add_u32_e32 v156, s59, v197
	ds_read_b128 v[144:147], v156
	ds_read_b128 v[148:151], v156 offset:1024
	ds_read_b128 v[152:155], v156 offset:2048
	ds_read_b128 v[156:159], v156 offset:3072
	s_add_u32 s20, s26, 0xb0000
	s_addc_u32 s21, s27, 0
	s_mov_b32 m0, s35
	v_lshl_add_u64 v[192:193], s[20:21], 0, v[128:129]
	ds_read_b128 v[160:163], v200 offset:32768
	ds_read_b128 v[164:167], v200 offset:33792
	ds_read_b128 v[168:171], v200 offset:34816
	ds_read_b128 v[172:175], v200 offset:35840
	ds_read_b128 v[176:179], v200 offset:36864
	ds_read_b128 v[180:183], v200 offset:37888
	ds_read_b128 v[184:187], v200 offset:38912
	ds_read_b128 v[188:191], v200 offset:39936
	global_load_lds_dwordx4 v[192:193], off
	v_lshl_add_u64 v[192:193], s[20:21], 0, v[132:133]
	s_mov_b32 m0, s36
	s_nop 0
	global_load_lds_dwordx4 v[192:193], off
	s_waitcnt lgkmcnt(8)
	s_barrier
	s_waitcnt lgkmcnt(0)
	s_setprio 1
	s_waitcnt lgkmcnt(0)
	v_mfma_f32_16x16x32_bf16 v[124:127], v[144:147], v[160:163], v[124:127]
	v_mfma_f32_16x16x32_bf16 v[120:123], v[152:155], v[160:163], v[120:123]
	v_mfma_f32_16x16x32_bf16 v[108:111], v[144:147], v[168:171], v[108:111]
	v_mfma_f32_16x16x32_bf16 v[104:107], v[152:155], v[168:171], v[104:107]
	v_mfma_f32_16x16x32_bf16 v[92:95], v[144:147], v[176:179], v[92:95]
	v_mfma_f32_16x16x32_bf16 v[88:91], v[152:155], v[176:179], v[88:91]
	v_mfma_f32_16x16x32_bf16 v[84:87], v[144:147], v[184:187], v[84:87]
	v_mfma_f32_16x16x32_bf16 v[76:79], v[152:155], v[184:187], v[76:79]
	v_mfma_f32_16x16x32_bf16 v[124:127], v[148:151], v[164:167], v[124:127]
	v_mfma_f32_16x16x32_bf16 v[120:123], v[156:159], v[164:167], v[120:123]
	v_mfma_f32_16x16x32_bf16 v[108:111], v[148:151], v[172:175], v[108:111]
	v_mfma_f32_16x16x32_bf16 v[104:107], v[156:159], v[172:175], v[104:107]
	v_mfma_f32_16x16x32_bf16 v[92:95], v[148:151], v[180:183], v[92:95]
	v_mfma_f32_16x16x32_bf16 v[88:91], v[156:159], v[180:183], v[88:91]
	v_mfma_f32_16x16x32_bf16 v[84:87], v[148:151], v[188:191], v[84:87]
	s_barrier
	v_mfma_f32_16x16x32_bf16 v[76:79], v[156:159], v[188:191], v[76:79]
	s_setprio 0
	s_add_i32 s26, 0, 0x1c000
	s_add_i32 s20, s59, s29
	v_add_u32_e32 v210, s26, v197
	v_lshl_add_u64 v[214:215], v[214:215], 0, s[10:11]
	s_mov_b32 m0, s20
	ds_read_b128 v[192:195], v210
	ds_read_b128 v[202:205], v210 offset:1024
	ds_read_b128 v[206:209], v210 offset:2048
	ds_read_b128 v[210:213], v210 offset:3072
	global_load_lds_dwordx4 v[214:215], off
	v_lshl_add_u64 v[214:215], v[216:217], 0, s[10:11]
	s_add_i32 m0, s20, 0x2000
	s_nop 0
	global_load_lds_dwordx4 v[214:215], off
	s_barrier
	s_waitcnt lgkmcnt(0)
	s_setprio 1
	s_waitcnt lgkmcnt(0)
	v_mfma_f32_16x16x32_bf16 v[116:119], v[192:195], v[160:163], v[116:119]
	v_mfma_f32_16x16x32_bf16 v[112:115], v[206:209], v[160:163], v[112:115]
	v_mfma_f32_16x16x32_bf16 v[100:103], v[192:195], v[168:171], v[100:103]
	v_mfma_f32_16x16x32_bf16 v[96:99], v[206:209], v[168:171], v[96:99]
	v_mfma_f32_16x16x32_bf16 v[80:83], v[192:195], v[176:179], v[80:83]
	v_mfma_f32_16x16x32_bf16 v[72:75], v[206:209], v[176:179], v[72:75]
	v_mfma_f32_16x16x32_bf16 v[68:71], v[192:195], v[184:187], v[68:71]
	v_mfma_f32_16x16x32_bf16 v[64:67], v[206:209], v[184:187], v[64:67]
	v_mfma_f32_16x16x32_bf16 v[116:119], v[202:205], v[164:167], v[116:119]
	v_mfma_f32_16x16x32_bf16 v[112:115], v[210:213], v[164:167], v[112:115]
	v_mfma_f32_16x16x32_bf16 v[100:103], v[202:205], v[172:175], v[100:103]
	v_mfma_f32_16x16x32_bf16 v[96:99], v[210:213], v[172:175], v[96:99]
	v_mfma_f32_16x16x32_bf16 v[80:83], v[202:205], v[180:183], v[80:83]
	v_mfma_f32_16x16x32_bf16 v[72:75], v[210:213], v[180:183], v[72:75]
	v_mfma_f32_16x16x32_bf16 v[68:71], v[202:205], v[188:191], v[68:71]
	s_barrier
	v_mfma_f32_16x16x32_bf16 v[64:67], v[210:213], v[188:191], v[64:67]
	s_setprio 0
	s_mov_b32 m0, s38
	v_lshl_add_u64 v[214:215], v[218:219], 0, s[10:11]
	ds_read_b128 v[160:163], v200 offset:49152
	ds_read_b128 v[164:167], v200 offset:50176
	ds_read_b128 v[168:171], v200 offset:51200
	ds_read_b128 v[172:175], v200 offset:52224
	ds_read_b128 v[176:179], v200 offset:53248
	ds_read_b128 v[180:183], v200 offset:54272
	ds_read_b128 v[184:187], v200 offset:55296
	ds_read_b128 v[188:191], v200 offset:56320
	global_load_lds_dwordx4 v[214:215], off
	v_lshl_add_u64 v[214:215], v[220:221], 0, s[10:11]
	s_mov_b32 m0, s39
	s_nop 0
	global_load_lds_dwordx4 v[214:215], off
	s_barrier
; DI unsigned pk_bf16(float lo, float hi) { f32x2 v = {lo, hi}; return __builtin_bit_cast(unsigned, __builtin_convertvector(v, bf16v2)); }
; DI f32x4 bf_lo4(u32x4 w) { f32x4 r; r[0] = bf_lo(w.x); r[1] = bf_hi(w.x); r[2] = bf_lo(w.y); r[3] = bf_hi(w.y); return r; }
; DI f32x4 bf_hi4(u32x4 w) { f32x4 r; r[0] = bf_lo(w.z); r[1] = bf_hi(w.z); r[2] = bf_lo(w.w); r[3] = bf_hi(w.w); return r; }
; #define PG8_STAGE(bufoff, gbase, voff) do { _Pragma("unroll") for (int _i = 0; _i < 2; ++_i) \
;         __builtin_amdgcn_global_load_lds((const unsigned*)((const char*)(gbase) + (voff)[_i]), (LAS unsigned*)(lds + (bufoff) + ldsw + _i * 8192), 16, 0, 0); } while (0)
; #define PG8_WAIT_V(n) asm volatile("s_waitcnt vmcnt(" #n ")" ::: "memory")
; #define PG8_BAR __builtin_amdgcn_s_barrier()
; template <class Epi>
; DI void gemm_phase(LAS unsigned char* lds, const Gemm g, const StaticOrder S, const Epi E) {
;     ...
;             PG8_BAR; PG8_WAIT_L(0); PG8_MMA(1, 0, At, B0); PG8_BAR; PG8_SCHED;
;             PG8_STAGE(PG8_SB(1, 1), b3 + hstep, voffB);
;             PG8_WAIT_V(6); PG8_BAR; PG8_MMA(1, 1, At, B1); PG8_BAR;
;     DI void operator()(AccRef acc, const Unit& u, int wr, int wc, int fr, int fq) const {
;     ...
;         for (int ai = 0; ai < 2; ++ai) {
;             f32x4 bv[4][2][2];
; #pragma unroll
;             for (int m = 0; m < 4; ++m)
; #pragma unroll
;                 for (int bj = 0; bj < 2; ++bj) {
;                     const size_t o = (size_t)(row0 + ai * 128 + m * 16) * DM + col0 + bj * 128;
;                     if (BASEF32) { bv[m][bj][0] = *(const f32x4*)(basef + o); bv[m][bj][1] = *(const f32x4*)(basef + o + 4); }
;                     else { const u32x4 h = *(const u32x4*)(xnb + o); bv[m][bj][0] = bf_lo4(h); bv[m][bj][1] = bf_hi4(h); }
;                 }
; #pragma unroll
;             for (int m = 0; m < 4; ++m) {
;                 const int row = row0 + ai * 128 + m * 16;
;                 float q = 0.f;
; #pragma unroll
;                 for (int bj = 0; bj < 2; ++bj) {
;                     const size_t o = (size_t)row * DM + col0 + bj * 128;
;                     const f32x4 r0 = bv[m][bj][0] + scale * acc[ai][bj][m][0], r1 = bv[m][bj][1] + scale * acc[ai][bj][m][1];
;                     u32x4 w; w.x = pk_bf16(r0[0], r0[1]); w.y = pk_bf16(r0[2], r0[3]); w.z = pk_bf16(r1[0], r1[1]); w.w = pk_bf16(r1[2], r1[3]);
;                     *(u32x4*)(xnb + o) = w;
	s_waitcnt lgkmcnt(0)
	s_setprio 1
	s_waitcnt lgkmcnt(0)
	v_mfma_f32_16x16x32_bf16 v[60:63], v[144:147], v[160:163], v[60:63]
	v_mfma_f32_16x16x32_bf16 v[56:59], v[152:155], v[160:163], v[56:59]
	v_mfma_f32_16x16x32_bf16 v[48:51], v[144:147], v[168:171], v[48:51]
	v_mfma_f32_16x16x32_bf16 v[40:43], v[152:155], v[168:171], v[40:43]
	v_mfma_f32_16x16x32_bf16 v[32:35], v[144:147], v[176:179], v[32:35]
	v_mfma_f32_16x16x32_bf16 v[24:27], v[152:155], v[176:179], v[24:27]
	v_mfma_f32_16x16x32_bf16 v[16:19], v[144:147], v[184:187], v[16:19]
	v_mfma_f32_16x16x32_bf16 v[8:11], v[152:155], v[184:187], v[8:11]
	v_mfma_f32_16x16x32_bf16 v[60:63], v[148:151], v[164:167], v[60:63]
	v_mfma_f32_16x16x32_bf16 v[56:59], v[156:159], v[164:167], v[56:59]
	v_mfma_f32_16x16x32_bf16 v[48:51], v[148:151], v[172:175], v[48:51]
	v_mfma_f32_16x16x32_bf16 v[40:43], v[156:159], v[172:175], v[40:43]
	v_mfma_f32_16x16x32_bf16 v[32:35], v[148:151], v[180:183], v[32:35]
	v_mfma_f32_16x16x32_bf16 v[24:27], v[156:159], v[180:183], v[24:27]
	v_mfma_f32_16x16x32_bf16 v[16:19], v[148:151], v[188:191], v[16:19]
	s_barrier
	v_mfma_f32_16x16x32_bf16 v[8:11], v[156:159], v[188:191], v[8:11]
	s_setprio 0
	s_add_u32 s20, s24, 0xb0080
	s_addc_u32 s21, s25, 0
	s_add_i32 s24, s26, s29
	v_lshl_add_u64 v[144:145], s[20:21], 0, v[130:131]
	s_mov_b32 m0, s24
	s_nop 0
	global_load_lds_dwordx4 v[144:145], off
	v_lshl_add_u64 v[144:145], s[20:21], 0, v[134:135]
	s_add_i32 m0, s24, 0x2000
	s_nop 0
	global_load_lds_dwordx4 v[144:145], off
	s_waitcnt vmcnt(6)
	s_barrier
	s_setprio 1
	v_mfma_f32_16x16x32_bf16 v[52:55], v[192:195], v[160:163], v[52:55]
	v_mfma_f32_16x16x32_bf16 v[44:47], v[206:209], v[160:163], v[44:47]
	v_mfma_f32_16x16x32_bf16 v[36:39], v[192:195], v[168:171], v[36:39]
	v_mfma_f32_16x16x32_bf16 v[28:31], v[206:209], v[168:171], v[28:31]
	v_mfma_f32_16x16x32_bf16 v[20:23], v[192:195], v[176:179], v[20:23]
	v_mfma_f32_16x16x32_bf16 v[12:15], v[206:209], v[176:179], v[12:15]
	v_mfma_f32_16x16x32_bf16 v[4:7], v[192:195], v[184:187], v[4:7]
	v_mfma_f32_16x16x32_bf16 v[0:3], v[206:209], v[184:187], v[0:3]
	v_mfma_f32_16x16x32_bf16 v[52:55], v[202:205], v[164:167], v[52:55]
	v_mfma_f32_16x16x32_bf16 v[44:47], v[210:213], v[164:167], v[44:47]
	v_mfma_f32_16x16x32_bf16 v[36:39], v[202:205], v[172:175], v[36:39]
	v_mfma_f32_16x16x32_bf16 v[28:31], v[210:213], v[172:175], v[28:31]
	v_mfma_f32_16x16x32_bf16 v[20:23], v[202:205], v[180:183], v[20:23]
	v_mfma_f32_16x16x32_bf16 v[12:15], v[210:213], v[180:183], v[12:15]
	v_mfma_f32_16x16x32_bf16 v[4:7], v[202:205], v[188:191], v[4:7]
	s_barrier
	v_mfma_f32_16x16x32_bf16 v[0:3], v[210:213], v[188:191], v[0:3]
	s_setprio 0
	s_add_i32 s58, s58, 2
	s_add_u32 s52, s52, 0x100
	s_addc_u32 s53, s53, 0
	s_cmp_gt_u32 s58, 41
	s_mov_b64 s[20:21], s[22:23]
	s_cbranch_scc0 .LBB0_941
	v_lshl_add_u32 v148, s50, 8, v196
	v_lshl_or_b32 v144, s51, 8, v198
	v_or_b32_e32 v146, 16, v148
	v_ashrrev_i32_e32 v145, 31, v144
	v_ashrrev_i32_e32 v147, 31, v146
	v_lshl_add_u64 v[176:177], v[144:145], 1, s[56:57]
	v_ashrrev_i32_e32 v149, 31, v148
	v_lshlrev_b64 v[146:147], 11, v[146:147]
	v_lshlrev_b64 v[144:145], 11, v[148:149]
	v_lshl_add_u64 v[150:151], v[176:177], 0, v[146:147]
	v_or_b32_e32 v146, 32, v148
	v_or_b32_e32 v148, 48, v148
	v_ashrrev_i32_e32 v147, 31, v146
	v_ashrrev_i32_e32 v149, 31, v148
	v_lshl_add_u64 v[144:145], v[176:177], 0, v[144:145]
	v_lshlrev_b64 v[146:147], 11, v[146:147]
	v_lshlrev_b64 v[148:149], 11, v[148:149]
	global_load_dwordx4 v[152:155], v[144:145], off
	global_load_dwordx4 v[156:159], v[144:145], off offset:256
	v_lshl_add_u64 v[146:147], v[176:177], 0, v[146:147]
	v_lshl_add_u64 v[148:149], v[176:177], 0, v[148:149]
	global_load_dwordx4 v[160:163], v[150:151], off
	global_load_dwordx4 v[164:167], v[150:151], off offset:256
	global_load_dwordx4 v[168:171], v[146:147], off
	global_load_dwordx4 v[172:175], v[146:147], off offset:256
	global_load_dwordx4 v[202:205], v[148:149], off
	global_load_dwordx4 v[206:209], v[148:149], off offset:256
	s_mov_b32 s51, s48
	s_mov_b32 s50, s49
	s_mov_b64 s[22:23], s[4:5]
	s_mov_b64 s[20:21], s[8:9]
	s_waitcnt vmcnt(0)
	v_lshlrev_b32_e32 v214, 16, v154
	v_and_b32_e32 v215, 0xffff0000, v154
	v_lshlrev_b32_e32 v216, 16, v155
	v_and_b32_e32 v217, 0xffff0000, v155
	v_lshlrev_b32_e32 v210, 16, v152
	v_and_b32_e32 v211, 0xffff0000, v152
	v_lshlrev_b32_e32 v212, 16, v153
	v_and_b32_e32 v213, 0xffff0000, v153
	v_lshlrev_b32_e32 v194, 16, v162
	v_and_b32_e32 v195, 0xffff0000, v162
	v_lshlrev_b32_e32 v230, 16, v163
	v_and_b32_e32 v231, 0xffff0000, v163
	v_lshlrev_b32_e32 v154, 16, v202
	v_and_b32_e32 v155, 0xffff0000, v202
	v_lshlrev_b32_e32 v162, 16, v203
	v_and_b32_e32 v163, 0xffff0000, v203
	v_pk_fma_f32 v[202:203], v[122:123], 0.5, v[216:217] op_sel_hi:[1,0,1]
	v_pk_fma_f32 v[122:123], v[120:121], 0.5, v[214:215] op_sel_hi:[1,0,1]
	v_lshlrev_b32_e32 v218, 16, v156
	v_and_b32_e32 v219, 0xffff0000, v156
	v_lshlrev_b32_e32 v220, 16, v157
	v_and_b32_e32 v221, 0xffff0000, v157
	v_pk_fma_f32 v[126:127], v[126:127], 0.5, v[212:213] op_sel_hi:[1,0,1]
	v_pk_fma_f32 v[124:125], v[124:125], 0.5, v[210:211] op_sel_hi:[1,0,1]
	v_cvt_pk_bf16_f32 v122, v122, v123
	v_cvt_pk_bf16_f32 v123, v202, v203
	v_add_co_u32_e32 v202, vcc, s44, v144
	v_lshlrev_b32_e32 v224, 16, v158
	v_and_b32_e32 v225, 0xffff0000, v158
	v_lshlrev_b32_e32 v226, 16, v159
	v_and_b32_e32 v227, 0xffff0000, v159
	v_cvt_pk_bf16_f32 v120, v124, v125
	v_cvt_pk_bf16_f32 v121, v126, v127
	v_pk_fma_f32 v[118:119], v[118:119], 0.5, v[220:221] op_sel_hi:[1,0,1]
	v_pk_fma_f32 v[116:117], v[116:117], 0.5, v[218:219] op_sel_hi:[1,0,1]
	v_addc_co_u32_e32 v203, vcc, 0, v145, vcc
; DI unsigned pk_bf16(float lo, float hi) { f32x2 v = {lo, hi}; return __builtin_bit_cast(unsigned, __builtin_convertvector(v, bf16v2)); }
;     DI void operator()(AccRef acc, const Unit& u, int wr, int wc, int fr, int fq) const {
;     ...
;             for (int m = 0; m < 4; ++m) {
;                 const int row = row0 + ai * 128 + m * 16;
;                 float q = 0.f;
; #pragma unroll
;                 for (int bj = 0; bj < 2; ++bj) {
;                     const size_t o = (size_t)row * DM + col0 + bj * 128;
;                     const f32x4 r0 = bv[m][bj][0] + scale * acc[ai][bj][m][0], r1 = bv[m][bj][1] + scale * acc[ai][bj][m][1];
;                     u32x4 w; w.x = pk_bf16(r0[0], r0[1]); w.y = pk_bf16(r0[2], r0[3]); w.z = pk_bf16(r1[0], r1[1]); w.w = pk_bf16(r1[2], r1[3]);
;                     *(u32x4*)(xnb + o) = w;
	v_lshlrev_b32_e32 v192, 16, v160
	v_and_b32_e32 v193, 0xffff0000, v160
	global_store_dwordx4 v[144:145], v[120:123], off
	v_pk_fma_f32 v[108:109], v[108:109], 0.5, v[192:193] op_sel_hi:[1,0,1]
	v_lshl_add_u64 v[192:193], v[144:145], 0, s[12:13]
	v_pk_fma_f32 v[120:121], v[114:115], 0.5, v[226:227] op_sel_hi:[1,0,1]
	v_pk_fma_f32 v[114:115], v[112:113], 0.5, v[224:225] op_sel_hi:[1,0,1]
	v_cvt_pk_bf16_f32 v112, v116, v117
	v_cvt_pk_bf16_f32 v113, v118, v119
	global_load_dwordx4 v[116:119], v[202:203], off
	v_cvt_pk_bf16_f32 v114, v114, v115
	v_cvt_pk_bf16_f32 v115, v120, v121
	v_lshlrev_b32_e32 v228, 16, v161
	v_and_b32_e32 v229, 0xffff0000, v161
	global_store_dwordx4 v[144:145], v[112:115], off offset:256
	v_pk_fma_f32 v[120:121], v[106:107], 0.5, v[230:231] op_sel_hi:[1,0,1]
	v_pk_fma_f32 v[110:111], v[110:111], 0.5, v[228:229] op_sel_hi:[1,0,1]
	v_pk_fma_f32 v[112:113], v[104:105], 0.5, v[194:195] op_sel_hi:[1,0,1]
	global_load_dwordx4 v[104:107], v[192:193], off offset:256
	v_add_co_u32_e32 v194, vcc, s45, v144
	v_lshlrev_b32_e32 v184, 16, v164
	s_nop 0
	v_addc_co_u32_e32 v195, vcc, 0, v145, vcc
	v_and_b32_e32 v185, 0xffff0000, v164
	v_lshlrev_b32_e32 v188, 16, v165
	v_and_b32_e32 v189, 0xffff0000, v165
	v_lshlrev_b32_e32 v186, 16, v166
	v_and_b32_e32 v187, 0xffff0000, v166
	v_lshlrev_b32_e32 v190, 16, v167
	v_and_b32_e32 v191, 0xffff0000, v167
	v_cvt_pk_bf16_f32 v108, v108, v109
	v_cvt_pk_bf16_f32 v109, v110, v111
	v_cvt_pk_bf16_f32 v110, v112, v113
	global_load_dwordx4 v[112:115], v[194:195], off
	v_cvt_pk_bf16_f32 v111, v120, v121
	global_store_dwordx4 v[150:151], v[108:111], off
	v_pk_fma_f32 v[124:125], v[98:99], 0.5, v[190:191] op_sel_hi:[1,0,1]
	v_pk_fma_f32 v[96:97], v[96:97], 0.5, v[186:187] op_sel_hi:[1,0,1]
	v_pk_fma_f32 v[110:111], v[102:103], 0.5, v[188:189] op_sel_hi:[1,0,1]
	v_pk_fma_f32 v[108:109], v[100:101], 0.5, v[184:185] op_sel_hi:[1,0,1]
	v_lshl_add_u64 v[98:99], v[144:145], 0, s[14:15]
	global_load_dwordx4 v[100:103], v[98:99], off offset:256
	v_cvt_pk_bf16_f32 v108, v108, v109
	v_cvt_pk_bf16_f32 v109, v110, v111
	v_cvt_pk_bf16_f32 v110, v96, v97
	v_add_co_u32_e32 v96, vcc, s46, v144
	v_lshlrev_b32_e32 v176, 16, v168
	s_nop 0
	v_addc_co_u32_e32 v97, vcc, 0, v145, vcc
	v_and_b32_e32 v177, 0xffff0000, v168
	v_lshlrev_b32_e32 v180, 16, v169
	v_and_b32_e32 v181, 0xffff0000, v169
	v_lshlrev_b32_e32 v178, 16, v170
	v_and_b32_e32 v179, 0xffff0000, v170
	v_lshlrev_b32_e32 v182, 16, v171
	v_and_b32_e32 v183, 0xffff0000, v171
	global_load_dwordx4 v[120:123], v[96:97], off
	v_cvt_pk_bf16_f32 v111, v124, v125
	global_store_dwordx4 v[150:151], v[108:111], off offset:256
	v_pk_fma_f32 v[150:151], v[90:91], 0.5, v[182:183] op_sel_hi:[1,0,1]
	v_pk_fma_f32 v[88:89], v[88:89], 0.5, v[178:179] op_sel_hi:[1,0,1]
	v_pk_fma_f32 v[110:111], v[94:95], 0.5, v[180:181] op_sel_hi:[1,0,1]
	v_pk_fma_f32 v[108:109], v[92:93], 0.5, v[176:177] op_sel_hi:[1,0,1]
	v_lshl_add_u64 v[90:91], v[144:145], 0, s[16:17]
	global_load_dwordx4 v[92:95], v[90:91], off offset:256
	v_cvt_pk_bf16_f32 v108, v108, v109
	v_cvt_pk_bf16_f32 v109, v110, v111
	v_cvt_pk_bf16_f32 v110, v88, v89
	v_add_co_u32_e32 v88, vcc, s47, v144
	v_lshlrev_b32_e32 v170, 16, v174
	s_nop 0
	v_addc_co_u32_e32 v89, vcc, 0, v145, vcc
	v_and_b32_e32 v171, 0xffff0000, v174
	global_load_dwordx4 v[124:127], v[88:89], off
	v_lshlrev_b32_e32 v168, 16, v172
	v_and_b32_e32 v169, 0xffff0000, v172
	v_lshlrev_b32_e32 v172, 16, v173
	v_and_b32_e32 v173, 0xffff0000, v173
	v_cvt_pk_bf16_f32 v111, v150, v151
	v_pk_fma_f32 v[150:151], v[72:73], 0.5, v[170:171] op_sel_hi:[1,0,1]
	v_lshl_add_u64 v[72:73], v[144:145], 0, s[18:19]
	global_store_dwordx4 v[146:147], v[108:111], off
	v_lshlrev_b32_e32 v174, 16, v175
	v_and_b32_e32 v175, 0xffff0000, v175
	v_pk_fma_f32 v[110:111], v[82:83], 0.5, v[172:173] op_sel_hi:[1,0,1]
	v_pk_fma_f32 v[108:109], v[80:81], 0.5, v[168:169] op_sel_hi:[1,0,1]
	global_load_dwordx4 v[80:83], v[72:73], off offset:256
	v_lshlrev_b32_e32 v160, 16, v204
	v_and_b32_e32 v161, 0xffff0000, v204
	v_lshlrev_b32_e32 v166, 16, v205
	v_and_b32_e32 v167, 0xffff0000, v205
	v_pk_fma_f32 v[74:75], v[74:75], 0.5, v[174:175] op_sel_hi:[1,0,1]
	v_cvt_pk_bf16_f32 v108, v108, v109
	v_cvt_pk_bf16_f32 v109, v110, v111
	v_cvt_pk_bf16_f32 v111, v74, v75
	v_pk_fma_f32 v[86:87], v[86:87], 0.5, v[162:163] op_sel_hi:[1,0,1]
	v_pk_fma_f32 v[74:75], v[84:85], 0.5, v[154:155] op_sel_hi:[1,0,1]
	v_pk_fma_f32 v[78:79], v[78:79], 0.5, v[166:167] op_sel_hi:[1,0,1]
	v_pk_fma_f32 v[76:77], v[76:77], 0.5, v[160:161] op_sel_hi:[1,0,1]
	v_lshlrev_b32_e32 v152, 16, v206
	v_and_b32_e32 v153, 0xffff0000, v206
	v_lshlrev_b32_e32 v158, 16, v207
	v_and_b32_e32 v159, 0xffff0000, v207
	v_lshlrev_b32_e32 v156, 16, v208
	v_and_b32_e32 v157, 0xffff0000, v208
	v_lshlrev_b32_e32 v164, 16, v209
	v_and_b32_e32 v165, 0xffff0000, v209
	v_cvt_pk_bf16_f32 v74, v74, v75
	v_cvt_pk_bf16_f32 v75, v86, v87
	v_cvt_pk_bf16_f32 v76, v76, v77
	v_cvt_pk_bf16_f32 v77, v78, v79
	global_store_dwordx4 v[148:149], v[74:77], off
	v_pk_fma_f32 v[70:71], v[70:71], 0.5, v[158:159] op_sel_hi:[1,0,1]
	v_pk_fma_f32 v[68:69], v[68:69], 0.5, v[152:153] op_sel_hi:[1,0,1]
	v_pk_fma_f32 v[74:75], v[66:67], 0.5, v[164:165] op_sel_hi:[1,0,1]
	v_pk_fma_f32 v[66:67], v[64:65], 0.5, v[156:157] op_sel_hi:[1,0,1]
	v_cvt_pk_bf16_f32 v64, v68, v69
	v_cvt_pk_bf16_f32 v65, v70, v71
	v_cvt_pk_bf16_f32 v66, v66, v67
	v_cvt_pk_bf16_f32 v67, v74, v75
	global_store_dwordx4 v[148:149], v[64:67], off offset:256
	s_waitcnt vmcnt(0)
; DI unsigned pk_bf16(float lo, float hi) { f32x2 v = {lo, hi}; return __builtin_bit_cast(unsigned, __builtin_convertvector(v, bf16v2)); }
; #define PG8_WAIT_V(n) asm volatile("s_waitcnt vmcnt(" #n ")" ::: "memory")
; #define PG8_BAR __builtin_amdgcn_s_barrier()
; #define PG8_WAIT_V(n) asm volatile("s_waitcnt vmcnt(" #n ")" ::: "memory")
; #define PG8_BAR __builtin_amdgcn_s_barrier()
; template <class Epi>
; DI void gemm_phase(LAS unsigned char* lds, const Gemm g, const StaticOrder S, const Epi E) {
;     ...
;         if (!has_next) break;
; #pragma unroll
;         for (int a = 0; a < 2; ++a)
; #pragma unroll
;             for (int b = 0; b < 2; ++b)
; #pragma unroll
;                 for (int m = 0; m < 4; ++m)
; #pragma unroll
;                     for (int n = 0; n < 2; ++n) acc[a][b][m][n] = (f32x4){0.f, 0.f, 0.f, 0.f};
;         cur = nxt; cA = nA; cB = nB; ++ui;
;     }
;     PG8_WAIT_V(0);
;     if (wr == 0) PG8_BAR;
;     PG8_BAR;
;     DI void operator()(AccRef acc, const Unit& u, int wr, int wc, int fr, int fq) const {
;     ...
;             for (int m = 0; m < 4; ++m) {
;                 const int row = row0 + ai * 128 + m * 16;
;                 float q = 0.f;
; #pragma unroll
;                 for (int bj = 0; bj < 2; ++bj) {
;                     const size_t o = (size_t)row * DM + col0 + bj * 128;
;                     const f32x4 r0 = bv[m][bj][0] + scale * acc[ai][bj][m][0], r1 = bv[m][bj][1] + scale * acc[ai][bj][m][1];
;                     u32x4 w; w.x = pk_bf16(r0[0], r0[1]); w.y = pk_bf16(r0[2], r0[3]); w.z = pk_bf16(r1[0], r1[1]); w.w = pk_bf16(r1[2], r1[3]);
;                     *(u32x4*)(xnb + o) = w;
;                     if (STATS) q += r0[0] * r0[0] + r0[1] * r0[1] + r0[2] * r0[2] + r0[3] * r0[3] + r1[0] * r1[0] + r1[1] * r1[1] + r1[2] * r1[2] + r1[3] * r1[3];
;                 }
;                 if (STATS) { q += __shfl_xor(q, 16); q += __shfl_xor(q, 32); if (fq == 0) atomicAdd(ss + row, q); }
;             }
	v_lshlrev_b32_e32 v68, 16, v118
	v_and_b32_e32 v69, 0xffff0000, v118
	v_lshlrev_b32_e32 v64, 16, v116
	v_and_b32_e32 v65, 0xffff0000, v116
	v_lshlrev_b32_e32 v66, 16, v117
	v_and_b32_e32 v67, 0xffff0000, v117
	v_lshlrev_b32_e32 v70, 16, v119
	v_and_b32_e32 v71, 0xffff0000, v119
	v_pk_fma_f32 v[62:63], v[62:63], 0.5, v[66:67] op_sel_hi:[1,0,1]
	v_pk_fma_f32 v[60:61], v[60:61], 0.5, v[64:65] op_sel_hi:[1,0,1]
	v_pk_fma_f32 v[64:65], v[58:59], 0.5, v[70:71] op_sel_hi:[1,0,1]
	v_pk_fma_f32 v[58:59], v[56:57], 0.5, v[68:69] op_sel_hi:[1,0,1]
	v_lshlrev_b32_e32 v74, 16, v104
	v_and_b32_e32 v75, 0xffff0000, v104
	v_lshlrev_b32_e32 v76, 16, v105
	v_and_b32_e32 v77, 0xffff0000, v105
	v_lshlrev_b32_e32 v78, 16, v106
	v_and_b32_e32 v79, 0xffff0000, v106
	v_lshlrev_b32_e32 v84, 16, v107
	v_and_b32_e32 v85, 0xffff0000, v107
	v_cvt_pk_bf16_f32 v56, v60, v61
	v_cvt_pk_bf16_f32 v57, v62, v63
	v_cvt_pk_bf16_f32 v58, v58, v59
	v_cvt_pk_bf16_f32 v59, v64, v65
	v_cvt_pk_bf16_f32 v110, v150, v151
	global_store_dwordx4 v[202:203], v[56:59], off
	v_pk_fma_f32 v[54:55], v[54:55], 0.5, v[76:77] op_sel_hi:[1,0,1]
	v_pk_fma_f32 v[52:53], v[52:53], 0.5, v[74:75] op_sel_hi:[1,0,1]
	v_pk_fma_f32 v[56:57], v[46:47], 0.5, v[84:85] op_sel_hi:[1,0,1]
	v_pk_fma_f32 v[46:47], v[44:45], 0.5, v[78:79] op_sel_hi:[1,0,1]
	global_store_dwordx4 v[146:147], v[108:111], off offset:256
	v_lshlrev_b32_e32 v86, 16, v112
	v_and_b32_e32 v87, 0xffff0000, v112
	v_lshlrev_b32_e32 v104, 16, v113
	v_and_b32_e32 v105, 0xffff0000, v113
	v_lshlrev_b32_e32 v106, 16, v114
	v_and_b32_e32 v107, 0xffff0000, v114
	v_lshlrev_b32_e32 v108, 16, v115
	v_and_b32_e32 v109, 0xffff0000, v115
	v_cvt_pk_bf16_f32 v44, v52, v53
	v_cvt_pk_bf16_f32 v45, v54, v55
	v_cvt_pk_bf16_f32 v46, v46, v47
	v_cvt_pk_bf16_f32 v47, v56, v57
	global_store_dwordx4 v[192:193], v[44:47], off offset:256
	v_lshlrev_b32_e32 v110, 16, v100
	v_and_b32_e32 v111, 0xffff0000, v100
	v_pk_fma_f32 v[44:45], v[50:51], 0.5, v[104:105] op_sel_hi:[1,0,1]
	v_pk_fma_f32 v[46:47], v[48:49], 0.5, v[86:87] op_sel_hi:[1,0,1]
	v_pk_fma_f32 v[48:49], v[42:43], 0.5, v[108:109] op_sel_hi:[1,0,1]
	v_pk_fma_f32 v[42:43], v[40:41], 0.5, v[106:107] op_sel_hi:[1,0,1]
	v_lshlrev_b32_e32 v100, 16, v101
	v_and_b32_e32 v101, 0xffff0000, v101
	v_lshlrev_b32_e32 v112, 16, v102
	v_and_b32_e32 v113, 0xffff0000, v102
	v_lshlrev_b32_e32 v102, 16, v103
	v_and_b32_e32 v103, 0xffff0000, v103
	v_cvt_pk_bf16_f32 v40, v46, v47
	v_cvt_pk_bf16_f32 v41, v44, v45
	v_cvt_pk_bf16_f32 v42, v42, v43
	v_cvt_pk_bf16_f32 v43, v48, v49
	global_store_dwordx4 v[194:195], v[40:43], off
	v_pk_fma_f32 v[38:39], v[38:39], 0.5, v[100:101] op_sel_hi:[1,0,1]
	v_pk_fma_f32 v[36:37], v[36:37], 0.5, v[110:111] op_sel_hi:[1,0,1]
	v_pk_fma_f32 v[40:41], v[30:31], 0.5, v[102:103] op_sel_hi:[1,0,1]
	v_pk_fma_f32 v[30:31], v[28:29], 0.5, v[112:113] op_sel_hi:[1,0,1]
	v_lshlrev_b32_e32 v114, 16, v120
	v_and_b32_e32 v115, 0xffff0000, v120
	v_lshlrev_b32_e32 v116, 16, v121
	v_and_b32_e32 v117, 0xffff0000, v121
	v_lshlrev_b32_e32 v118, 16, v122
	v_and_b32_e32 v119, 0xffff0000, v122
	v_lshlrev_b32_e32 v120, 16, v123
	v_and_b32_e32 v121, 0xffff0000, v123
	v_cvt_pk_bf16_f32 v28, v36, v37
	v_cvt_pk_bf16_f32 v29, v38, v39
	v_cvt_pk_bf16_f32 v30, v30, v31
	v_cvt_pk_bf16_f32 v31, v40, v41
	global_store_dwordx4 v[98:99], v[28:31], off offset:256
	v_lshlrev_b32_e32 v122, 16, v92
	v_and_b32_e32 v123, 0xffff0000, v92
	v_pk_fma_f32 v[28:29], v[34:35], 0.5, v[116:117] op_sel_hi:[1,0,1]
	v_pk_fma_f32 v[30:31], v[32:33], 0.5, v[114:115] op_sel_hi:[1,0,1]
	v_pk_fma_f32 v[32:33], v[26:27], 0.5, v[120:121] op_sel_hi:[1,0,1]
	v_pk_fma_f32 v[26:27], v[24:25], 0.5, v[118:119] op_sel_hi:[1,0,1]
	v_lshlrev_b32_e32 v92, 16, v93
	v_and_b32_e32 v93, 0xffff0000, v93
	v_lshlrev_b32_e32 v144, 16, v94
	v_and_b32_e32 v145, 0xffff0000, v94
	v_lshlrev_b32_e32 v94, 16, v95
	v_and_b32_e32 v95, 0xffff0000, v95
	v_cvt_pk_bf16_f32 v24, v30, v31
	v_cvt_pk_bf16_f32 v25, v28, v29
	v_cvt_pk_bf16_f32 v26, v26, v27
	v_cvt_pk_bf16_f32 v27, v32, v33
	global_store_dwordx4 v[96:97], v[24:27], off
	v_pk_fma_f32 v[22:23], v[22:23], 0.5, v[92:93] op_sel_hi:[1,0,1]
	v_pk_fma_f32 v[20:21], v[20:21], 0.5, v[122:123] op_sel_hi:[1,0,1]
	v_pk_fma_f32 v[24:25], v[14:15], 0.5, v[94:95] op_sel_hi:[1,0,1]
	v_pk_fma_f32 v[14:15], v[12:13], 0.5, v[144:145] op_sel_hi:[1,0,1]
	v_lshlrev_b32_e32 v146, 16, v124
	v_and_b32_e32 v147, 0xffff0000, v124
	v_lshlrev_b32_e32 v124, 16, v125
	v_and_b32_e32 v125, 0xffff0000, v125
	v_lshlrev_b32_e32 v148, 16, v126
	v_and_b32_e32 v149, 0xffff0000, v126
	v_lshlrev_b32_e32 v126, 16, v127
	v_and_b32_e32 v127, 0xffff0000, v127
	v_cvt_pk_bf16_f32 v12, v20, v21
	v_cvt_pk_bf16_f32 v13, v22, v23
	v_cvt_pk_bf16_f32 v14, v14, v15
	v_cvt_pk_bf16_f32 v15, v24, v25
	global_store_dwordx4 v[90:91], v[12:15], off offset:256
	v_lshlrev_b32_e32 v150, 16, v80
	v_and_b32_e32 v151, 0xffff0000, v80
	v_pk_fma_f32 v[12:13], v[18:19], 0.5, v[124:125] op_sel_hi:[1,0,1]
	v_pk_fma_f32 v[14:15], v[16:17], 0.5, v[146:147] op_sel_hi:[1,0,1]
	v_pk_fma_f32 v[16:17], v[10:11], 0.5, v[126:127] op_sel_hi:[1,0,1]
	v_pk_fma_f32 v[10:11], v[8:9], 0.5, v[148:149] op_sel_hi:[1,0,1]
	v_lshlrev_b32_e32 v80, 16, v81
	v_and_b32_e32 v81, 0xffff0000, v81
	v_lshlrev_b32_e32 v152, 16, v82
	v_and_b32_e32 v153, 0xffff0000, v82
	v_lshlrev_b32_e32 v82, 16, v83
	v_and_b32_e32 v83, 0xffff0000, v83
	v_cvt_pk_bf16_f32 v8, v14, v15
	v_cvt_pk_bf16_f32 v9, v12, v13
	v_cvt_pk_bf16_f32 v10, v10, v11
	v_cvt_pk_bf16_f32 v11, v16, v17
	global_store_dwordx4 v[88:89], v[8:11], off
	v_pk_fma_f32 v[6:7], v[6:7], 0.5, v[80:81] op_sel_hi:[1,0,1]
	v_pk_fma_f32 v[4:5], v[4:5], 0.5, v[150:151] op_sel_hi:[1,0,1]
	v_pk_fma_f32 v[8:9], v[2:3], 0.5, v[82:83] op_sel_hi:[1,0,1]
	v_pk_fma_f32 v[2:3], v[0:1], 0.5, v[152:153] op_sel_hi:[1,0,1]
	v_cvt_pk_bf16_f32 v0, v4, v5
	v_cvt_pk_bf16_f32 v1, v6, v7
	v_cvt_pk_bf16_f32 v2, v2, v3
	v_cvt_pk_bf16_f32 v3, v8, v9
	s_and_b64 vcc, exec, s[0:1]
	global_store_dwordx4 v[72:73], v[0:3], off offset:256
	s_cbranch_vccz .LBB0_930
	s_waitcnt vmcnt(0)
	s_cmpk_gt_u32 s6, 0xff
	s_cbranch_scc1 .LBB0_945
	s_barrier
